# k4 plus: more f32->bf16 trick pairs matched (early placement when producer is a plain VALU op) and 180 single conversions (bfe+add3 -> v_cvt_pk_bf16_f32 t,x,x where only the high half is consumed)
# speedup vs baseline: 1.0349x; 1.0017x over previous
.LBB0_199:
	ds_read2_b32 v[52:53], v89 offset1:65
	ds_read2_b32 v[78:79], v89 offset0:130 offset1:195
	s_ashr_i32 s28, s35, 31
	s_waitcnt lgkmcnt(1)
	v_cvt_pk_bf16_f32 v106, v52, v53
	s_waitcnt lgkmcnt(0)
	ds_read2_b32 v[52:53], v101 offset0:4 offset1:69
	v_cvt_pk_bf16_f32 v107, v78, v79
	ds_read2_b32 v[78:79], v101 offset0:134 offset1:199
	s_waitcnt lgkmcnt(1)
	v_cvt_pk_bf16_f32 v108, v52, v53
	s_waitcnt lgkmcnt(0)
	v_cvt_pk_bf16_f32 v109, v78, v79
	v_or_b32_e32 v51, s35, v88
	v_mul_lo_u32 v78, s39, v51
	s_mul_i32 s35, s38, s28
	v_mad_u64_u32 v[52:53], s[28:29], s38, v51, 0
	v_add3_u32 v53, v53, s35, v78
	ds_read2_b32 v[78:79], v90 offset1:65
	v_lshl_add_u64 v[52:53], v[52:53], 1, s[36:37]
	s_ashr_i32 s35, s34, 31
	v_lshl_add_u64 v[52:53], s[34:35], 1, v[52:53]
	v_lshl_add_u64 v[110:111], v[70:71], 1, v[52:53]
	global_store_dwordx4 v[110:111], v[106:109], off
	s_waitcnt lgkmcnt(0)
	s_nop 0
	ds_read2_b32 v[108:109], v90 offset0:130 offset1:195
	v_cvt_pk_bf16_f32 v106, v78, v79
	ds_read2_b32 v[78:79], v102 offset0:4 offset1:69
	s_waitcnt lgkmcnt(1)
	v_cvt_pk_bf16_f32 v107, v108, v109
	ds_read2_b32 v[110:111], v102 offset0:134 offset1:199
	s_waitcnt lgkmcnt(1)
	v_cvt_pk_bf16_f32 v108, v78, v79
	ds_read2_b32 v[78:79], v91 offset1:65
	s_waitcnt lgkmcnt(1)
	v_cvt_pk_bf16_f32 v109, v110, v111
	v_lshl_add_u64 v[110:111], v[72:73], 1, v[52:53]
	global_store_dwordx4 v[110:111], v[106:109], off
	s_waitcnt lgkmcnt(0)
	v_cvt_pk_bf16_f32 v106, v78, v79
	ds_read2_b32 v[108:109], v91 offset0:130 offset1:195
	ds_read2_b32 v[78:79], v103 offset0:4 offset1:69
	s_waitcnt lgkmcnt(1)
	v_cvt_pk_bf16_f32 v107, v108, v109
	ds_read2_b32 v[102:103], v103 offset0:134 offset1:199
	s_waitcnt lgkmcnt(1)
	v_cvt_pk_bf16_f32 v108, v78, v79
	ds_read2_b32 v[78:79], v92 offset1:65
	s_waitcnt lgkmcnt(1)
	v_cvt_pk_bf16_f32 v109, v102, v103
	v_lshl_add_u64 v[102:103], v[74:75], 1, v[52:53]
	global_store_dwordx4 v[102:103], v[106:109], off
	s_waitcnt lgkmcnt(0)
	v_cvt_pk_bf16_f32 v102, v78, v79
	ds_read2_b32 v[106:107], v92 offset0:130 offset1:195
	ds_read2_b32 v[78:79], v104 offset0:4 offset1:69
	s_waitcnt lgkmcnt(1)
	v_cvt_pk_bf16_f32 v103, v106, v107
	ds_read2_b32 v[106:107], v104 offset0:134 offset1:199
	s_waitcnt lgkmcnt(1)
	v_cvt_pk_bf16_f32 v104, v78, v79
	s_waitcnt lgkmcnt(0)
	v_cvt_pk_bf16_f32 v51, v106, v106
	v_bfe_u32 v78, v107, 16, 1
	v_lshrrev_b32_e32 v51, 16, v51
	v_add3_u32 v78, v107, v78, s84
	v_and_or_b32 v105, v78, s85, v51
	v_lshl_add_u64 v[52:53], v[76:77], 1, v[52:53]
	global_store_dwordx4 v[52:53], v[102:105], off
	s_waitcnt lgkmcnt(0)
	s_barrier

.LBB0_308:
	ds_read2_b32 v[52:53], v89 offset1:65
	ds_read2_b32 v[78:79], v89 offset0:130 offset1:195
	s_ashr_i32 s28, s35, 31
	s_waitcnt lgkmcnt(1)
	v_cvt_pk_bf16_f32 v102, v52, v53
	v_add_u32_e32 v101, 0x400, v89
	s_waitcnt lgkmcnt(0)
	v_cvt_pk_bf16_f32 v103, v78, v79
	ds_read2_b32 v[52:53], v101 offset0:4 offset1:69
	ds_read2_b32 v[78:79], v101 offset0:134 offset1:199
	s_waitcnt lgkmcnt(1)
	v_cvt_pk_bf16_f32 v104, v52, v53
	s_waitcnt lgkmcnt(0)
	v_cvt_pk_bf16_f32 v105, v78, v79
	v_or_b32_e32 v51, s35, v88
	v_mul_lo_u32 v78, s39, v51
	s_mul_i32 s35, s38, s28
	v_mad_u64_u32 v[52:53], s[28:29], s38, v51, 0
	v_add3_u32 v53, v53, s35, v78
	v_lshl_add_u64 v[52:53], v[52:53], 1, s[36:37]
	ds_read2_b32 v[78:79], v90 offset1:65
	s_ashr_i32 s35, s34, 31
	v_lshl_add_u64 v[52:53], s[34:35], 1, v[52:53]
	v_lshl_add_u64 v[106:107], v[70:71], 1, v[52:53]
	global_store_dwordx4 v[106:107], v[102:105], off
	ds_read2_b32 v[102:103], v90 offset0:130 offset1:195
	s_waitcnt lgkmcnt(1)
	v_cvt_pk_bf16_f32 v104, v78, v79
	s_waitcnt lgkmcnt(0)
	v_cvt_pk_bf16_f32 v105, v102, v103
	v_add_u32_e32 v102, 0x400, v90
	ds_read2_b32 v[78:79], v102 offset0:4 offset1:69
	ds_read2_b32 v[108:109], v102 offset0:134 offset1:199
	s_waitcnt lgkmcnt(1)
	v_cvt_pk_bf16_f32 v106, v78, v79
	ds_read2_b32 v[78:79], v91 offset1:65
	s_waitcnt lgkmcnt(1)
	v_cvt_pk_bf16_f32 v107, v108, v109
	v_lshl_add_u64 v[108:109], v[72:73], 1, v[52:53]
	global_store_dwordx4 v[108:109], v[104:107], off
	s_waitcnt lgkmcnt(0)
	v_cvt_pk_bf16_f32 v104, v78, v79
	ds_read2_b32 v[106:107], v91 offset0:130 offset1:195
	v_add_u32_e32 v103, 0x400, v91
	ds_read2_b32 v[78:79], v103 offset0:4 offset1:69
	s_waitcnt lgkmcnt(1)
	v_cvt_pk_bf16_f32 v105, v106, v107
	ds_read2_b32 v[108:109], v103 offset0:134 offset1:199
	s_waitcnt lgkmcnt(1)
	v_cvt_pk_bf16_f32 v106, v78, v79
	s_waitcnt lgkmcnt(0)
	v_cvt_pk_bf16_f32 v107, v108, v109
	ds_read2_b32 v[78:79], v92 offset1:65
	v_lshl_add_u64 v[108:109], v[74:75], 1, v[52:53]
	global_store_dwordx4 v[108:109], v[104:107], off
	ds_read2_b32 v[104:105], v92 offset0:130 offset1:195
	s_waitcnt lgkmcnt(1)
	v_cvt_pk_bf16_f32 v106, v78, v79
	s_waitcnt lgkmcnt(0)
	v_cvt_pk_bf16_f32 v107, v104, v105
	v_add_u32_e32 v104, 0x400, v92
	ds_read2_b32 v[78:79], v104 offset0:4 offset1:69
	ds_read2_b32 v[110:111], v104 offset0:134 offset1:199
	s_waitcnt lgkmcnt(1)
	v_cvt_pk_bf16_f32 v108, v78, v79
	s_waitcnt lgkmcnt(0)
	v_cvt_pk_bf16_f32 v51, v110, v110
	v_bfe_u32 v78, v111, 16, 1
	v_lshrrev_b32_e32 v51, 16, v51
	v_add3_u32 v78, v111, v78, s84
	v_and_or_b32 v109, v78, s85, v51
	v_lshl_add_u64 v[52:53], v[76:77], 1, v[52:53]
	global_store_dwordx4 v[52:53], v[106:109], off
	s_waitcnt lgkmcnt(0)
	s_barrier
	s_add_i32 s28, s24, s87
	s_cmpk_gt_i32 s28, 0x127f
	s_cbranch_scc1 .LBB0_200
	s_cmpk_gt_i32 s28, 0xe3f
	s_cbranch_scc0 .LBB0_312
	s_add_i32 s29, s80, s67
	s_cmpk_gt_u32 s28, 0x123f
	s_cbranch_scc0 .LBB0_313
	s_add_i32 s34, s78, s68
	s_and_b32 s34, s34, 0x7fffff00
	s_and_b32 s35, s29, 0x3c0
	s_add_i32 s34, s34, 0xfffedc00
	s_mov_b64 s[36:37], s[22:23]
	s_mov_b64 s[38:39], 0x400
	s_cbranch_execz .LBB0_314
	s_branch .LBB0_315

.LBB0_424:
	s_or_b64 exec, exec, s[0:1]
	v_lshlrev_b32_e32 v15, 30, v14
	v_xor_b32_e32 v13, v13, v12
	v_and_b32_e32 v15, 0x80000000, v15
	v_xor_b32_e32 v13, v13, v15
	v_mul_f32_e32 v15, v2, v2
	v_fmamk_f32 v16, v15, 0xb94c1982, v6
	v_fmaak_f32 v16, v15, v16, 0xbe2aaa9d
	v_mul_f32_e32 v16, v15, v16
	v_fmac_f32_e32 v2, v2, v16
	v_fmamk_f32 v16, v15, 0x37d75334, v7
	v_fmaak_f32 v16, v15, v16, 0x3d2aabf7
	v_and_b32_e32 v14, 1, v14
	v_fmaak_f32 v16, v15, v16, 0xbf000004
	v_fma_f32 v15, v15, v16, 1.0
	v_cmp_eq_u32_e32 vcc, 0, v14
	s_ashr_i32 s19, s18, 31
	s_and_b64 s[0:1], s[20:21], exec
	v_cndmask_b32_e32 v2, v15, v2, vcc
	v_xor_b32_e32 v2, v13, v2
	v_cmp_class_f32_e64 vcc, v12, s60
	s_cselect_b32 s0, 17, 21
	s_cselect_b32 s4, s57, s55
	v_cndmask_b32_e32 v2, v10, v2, vcc
	v_cvt_pk_bf16_f32 v12, v2, v2
	s_cselect_b32 s5, s58, s56
	s_lshl_b64 s[0:1], s[18:19], s0
	v_and_b32_e32 v13, 0xffff0000, v12
	v_ashrrev_i32_e32 v5, 31, v4
	s_add_u32 s0, s5, s0
	v_sub_f32_e32 v2, v2, v13
	v_lshlrev_b64 v[4:5], 9, v[4:5]
	s_addc_u32 s1, s4, s1
	v_bfe_u32 v13, v2, 16, 1
	v_lshl_add_u64 v[4:5], s[0:1], 0, v[4:5]
	v_add3_u32 v13, v2, v13, s63
	v_lshlrev_b32_e32 v2, 1, v11
	s_add_i32 s64, s64, s24
	s_add_i32 s36, s36, s37
	v_lshrrev_b32_e32 v12, 16, v12
	v_lshl_add_u64 v[4:5], v[4:5], 0, v[2:3]
	s_cmpk_gt_i32 s64, 0x21f
	global_store_short v[4:5], v12, off
	global_store_short v[4:5], v12, off offset:128
	global_store_short_d16_hi v[4:5], v13, off offset:256
	global_store_short v[4:5], v3, off offset:384
	s_barrier
	s_cbranch_scc1 .LBB0_438

.LBB0_443:
	s_andn2_saveexec_b64 s[6:7], s[6:7]
	s_cbranch_execz .LBB0_440
	v_ashrrev_i32_e32 v2, 31, v1
	v_lshrrev_b32_e32 v2, 14, v2
	v_add_u32_e32 v2, v1, v2
	v_ashrrev_i32_e32 v8, 18, v2
	v_mul_i32_i24_e32 v2, 0x40000, v8
	v_ashrrev_i32_e32 v9, 31, v8
	v_sub_u32_e32 v10, v1, v2
	v_lshlrev_b64 v[12:13], 20, v[8:9]
	v_ashrrev_i32_e32 v11, 31, v10
	v_lshl_add_u64 v[12:13], s[12:13], 0, v[12:13]
	v_lshl_add_u64 v[12:13], v[10:11], 2, v[12:13]
	global_load_dword v2, v[12:13], off
	v_lshlrev_b64 v[12:13], 21, v[8:9]
	v_lshrrev_b32_e32 v9, 20, v11
	v_add_u32_e32 v9, v10, v9
	v_ashrrev_i32_e32 v10, 12, v9
	v_mul_i32_i24_e32 v9, 0x1000, v10
	v_mad_i32_i24 v8, v8, s22, v9
	v_sub_u32_e32 v8, v1, v8
	v_ashrrev_i32_e32 v9, 31, v8
	v_lshl_add_u64 v[12:13], s[16:17], 0, v[12:13]
	v_lshlrev_b64 v[8:9], 9, v[8:9]
	v_ashrrev_i32_e32 v11, 31, v10
	v_lshl_add_u64 v[8:9], v[12:13], 0, v[8:9]
	v_lshl_add_u64 v[8:9], v[10:11], 1, v[8:9]
	s_waitcnt vmcnt(0)
	v_cvt_pk_bf16_f32 v10, v2, v2
	v_lshrrev_b32_e32 v11, 16, v10
	v_and_b32_e32 v10, 0xffff0000, v10
	v_sub_f32_e32 v2, v2, v10
	v_bfe_u32 v10, v2, 16, 1
	v_add3_u32 v2, v2, v10, s21
	global_store_short v[8:9], v11, off
	global_store_short v[8:9], v11, off offset:256
	global_store_short_d16_hi v[8:9], v2, off offset:128
	global_store_short v[8:9], v3, off offset:384
	s_branch .LBB0_440

.LBB0_596:
	s_or_b64 exec, exec, s[14:15]
	v_lshl_add_u64 v[52:53], v[52:53], 2, s[6:7]
	v_lshl_add_u64 v[76:77], v[52:53], 0, s[8:9]
	s_waitcnt lgkmcnt(0)
	s_barrier
	v_lshl_add_u64 v[64:65], v[76:77], 0, v[34:35]
	s_waitcnt lgkmcnt(0)
	global_load_dwordx4 v[60:63], v[38:39], off
	v_lshl_add_u64 v[68:69], v[52:53], 0, v[34:35]
	global_load_dwordx4 v[64:67], v[64:65], off
	v_ashrrev_i32_e32 v34, 6, v51
	global_load_dwordx4 v[68:71], v[68:69], off
	v_lshlrev_b32_e32 v34, 2, v34
	v_and_b32_e32 v51, -16, v34
	v_add_u32_e32 v51, 0, v51
	ds_read_b96 v[72:74], v51
	v_or_b32_e32 v34, 12, v34
	v_add_u32_e32 v34, 0, v34
	v_lshlrev_b64 v[54:55], 13, v[54:55]
	v_mov_b32_e32 v51, v35
	s_waitcnt lgkmcnt(0)
	v_mov_b32_e32 v78, v73
	ds_read_b32 v73, v34
	v_mov_b32_e32 v79, v74
	v_add_u32_e32 v1, s21, v1
	s_waitcnt lgkmcnt(0)
	v_pk_add_f32 v[72:73], v[78:79], v[72:73]
	s_nop 0
	v_add_f32_e32 v34, v72, v73
	v_fmamk_f32 v34, v34, 0x39800000, v59
	v_mul_f32_e32 v72, 0x4b800000, v34
	v_cmp_gt_f32_e32 vcc, s22, v34
	s_nop 1
	v_cndmask_b32_e32 v34, v34, v72, vcc
	v_rsq_f32_e32 v74, v34
	v_lshl_add_u64 v[72:73], s[4:5], 0, v[54:55]
	v_lshlrev_b32_e32 v34, 1, v36
	v_lshl_add_u64 v[54:55], v[72:73], 0, v[34:35]
	v_mul_f32_e32 v34, 0x45800000, v74
	v_cndmask_b32_e32 v74, v74, v34, vcc
	v_pk_mul_f32 v[20:21], v[20:21], v[74:75] op_sel_hi:[1,0]
	v_pk_mul_f32 v[18:19], v[18:19], v[74:75] op_sel_hi:[1,0]
	v_pk_mul_f32 v[12:13], v[12:13], v[74:75] op_sel_hi:[1,0]
	v_pk_mul_f32 v[10:11], v[10:11], v[74:75] op_sel_hi:[1,0]
	v_pk_mul_f32 v[8:9], v[8:9], v[74:75] op_sel_hi:[1,0]
	v_pk_mul_f32 v[6:7], v[6:7], v[74:75] op_sel_hi:[1,0]
	s_andn2_b64 vcc, exec, s[12:13]
	s_waitcnt vmcnt(2)
	v_pk_mul_f32 v[18:19], v[60:61], v[18:19]
	v_pk_mul_f32 v[20:21], v[62:63], v[20:21]
	s_waitcnt vmcnt(1)
	v_pk_add_f32 v[60:61], v[66:67], 1.0 op_sel_hi:[1,0]
	v_pk_add_f32 v[62:63], v[64:65], 1.0 op_sel_hi:[1,0]
	s_waitcnt vmcnt(0)
	v_pk_fma_f32 v[20:21], v[60:61], v[20:21], v[70:71]
	v_pk_fma_f32 v[18:19], v[62:63], v[18:19], v[68:69]
	v_cvt_pk_bf16_f32 v18, v18, v19
	v_cvt_pk_bf16_f32 v20, v20, v20
	v_cvt_pk_bf16_f32 v21, v21, v21
	v_lshrrev_b32_e32 v20, 16, v20
	v_and_or_b32 v19, v21, s25, v20
	global_store_dwordx2 v[54:55], v[18:19], off
	v_lshl_add_u64 v[60:61], v[76:77], 0, v[50:51]
	global_load_dwordx4 v[18:21], v[44:45], off
	v_lshl_add_u64 v[64:65], v[52:53], 0, v[50:51]
	global_load_dwordx4 v[60:63], v[60:61], off
	v_lshlrev_b32_e32 v34, 2, v40
	global_load_dwordx4 v[64:67], v[64:65], off
	v_pk_mul_f32 v[70:71], v[4:5], v[74:75] op_sel_hi:[1,0]
	v_mov_b32_e32 v4, v16
	s_waitcnt vmcnt(2)
	v_pk_mul_f32 v[10:11], v[18:19], v[10:11]
	v_pk_mul_f32 v[12:13], v[20:21], v[12:13]
	s_waitcnt vmcnt(1)
	v_pk_add_f32 v[18:19], v[62:63], 1.0 op_sel_hi:[1,0]
	v_pk_add_f32 v[20:21], v[60:61], 1.0 op_sel_hi:[1,0]
	s_waitcnt vmcnt(0)
	v_pk_fma_f32 v[12:13], v[18:19], v[12:13], v[66:67]
	v_pk_fma_f32 v[10:11], v[20:21], v[10:11], v[64:65]
	v_cvt_pk_bf16_f32 v10, v10, v11
	v_cvt_pk_bf16_f32 v12, v12, v12
	v_cvt_pk_bf16_f32 v13, v13, v13
	v_lshrrev_b32_e32 v12, 16, v12
	v_and_or_b32 v11, v13, s25, v12
	global_store_dwordx2 v[54:55], v[10:11], off offset:2048
	v_lshl_add_u64 v[18:19], v[76:77], 0, v[34:35]
	global_load_dwordx4 v[10:13], v[46:47], off
	v_lshl_add_u64 v[54:55], v[52:53], 0, v[34:35]
	global_load_dwordx4 v[18:21], v[18:19], off
	v_lshlrev_b32_e32 v34, 1, v40
	global_load_dwordx4 v[60:63], v[54:55], off
	v_lshl_add_u64 v[54:55], v[72:73], 0, v[34:35]
	v_lshlrev_b32_e32 v34, 2, v42
	s_waitcnt vmcnt(2)
	v_pk_mul_f32 v[6:7], v[10:11], v[6:7]
	v_pk_mul_f32 v[8:9], v[12:13], v[8:9]
	s_waitcnt vmcnt(1)
	v_pk_add_f32 v[10:11], v[20:21], 1.0 op_sel_hi:[1,0]
	v_pk_add_f32 v[12:13], v[18:19], 1.0 op_sel_hi:[1,0]
	s_waitcnt vmcnt(0)
	v_pk_fma_f32 v[8:9], v[10:11], v[8:9], v[62:63]
	v_pk_fma_f32 v[6:7], v[12:13], v[6:7], v[60:61]
	v_cvt_pk_bf16_f32 v6, v6, v7
	v_cvt_pk_bf16_f32 v8, v8, v8
	v_cvt_pk_bf16_f32 v9, v9, v9
	v_lshrrev_b32_e32 v8, 16, v8
	v_and_or_b32 v7, v9, s25, v8
	global_store_dwordx2 v[54:55], v[6:7], off
	v_lshl_add_u64 v[6:7], v[76:77], 0, v[34:35]
	global_load_dwordx4 v[60:63], v[48:49], off
	global_load_dwordx4 v[64:67], v[6:7], off
	v_lshl_add_u64 v[6:7], v[52:53], 0, v[34:35]
	global_load_dwordx4 v[52:55], v[6:7], off
	v_lshlrev_b32_e32 v34, 1, v42
	v_lshl_add_u64 v[68:69], v[72:73], 0, v[34:35]
	v_pk_mul_f32 v[72:73], v[2:3], v[74:75] op_sel_hi:[1,0]
	v_mov_b32_e32 v10, v22
	v_mov_b32_e32 v11, v23
	v_mov_b32_e32 v12, v24
	v_mov_b32_e32 v13, v25
	v_mov_b32_e32 v6, v26
	v_mov_b32_e32 v7, v27
	v_mov_b32_e32 v2, v14
	v_mov_b32_e32 v3, v15
	v_mov_b32_e32 v18, v30
	v_mov_b32_e32 v19, v31
	v_mov_b32_e32 v20, v32
	v_mov_b32_e32 v21, v33
	v_mov_b32_e32 v8, v28
	v_mov_b32_e32 v9, v29
	s_waitcnt vmcnt(2)
	v_pk_mul_f32 v[14:15], v[72:73], v[60:61]
	v_pk_mul_f32 v[22:23], v[70:71], v[62:63]
	s_waitcnt vmcnt(1)
	v_pk_add_f32 v[24:25], v[66:67], 1.0 op_sel_hi:[1,0]
	v_pk_add_f32 v[26:27], v[64:65], 1.0 op_sel_hi:[1,0]
	s_waitcnt vmcnt(0)
	v_pk_fma_f32 v[22:23], v[22:23], v[24:25], v[54:55]
	v_pk_fma_f32 v[14:15], v[14:15], v[26:27], v[52:53]
	v_bfe_u32 v24, v22, 16, 1
	v_cvt_pk_bf16_f32 v14, v14, v15
	v_bfe_u32 v25, v23, 16, 1
	v_add3_u32 v15, v22, v24, s23
	v_add3_u32 v16, v23, v25, s23
	v_lshrrev_b32_e32 v15, 16, v15
	v_and_or_b32 v15, v16, s25, v15
	v_mov_b32_e32 v5, v17
	global_store_dwordx2 v[68:69], v[14:15], off
	s_cbranch_vccz .LBB0_603

.LBB0_885:
	ds_read2_b32 v[52:53], v89 offset1:65
	ds_read2_b32 v[78:79], v89 offset0:130 offset1:195
	s_waitcnt lgkmcnt(1)
	v_cvt_pk_bf16_f32 v106, v52, v53
	s_waitcnt lgkmcnt(0)
	ds_read2_b32 v[52:53], v101 offset0:4 offset1:69
	v_cvt_pk_bf16_f32 v107, v78, v79
	ds_read2_b32 v[78:79], v101 offset0:134 offset1:199
	s_waitcnt lgkmcnt(1)
	v_cvt_pk_bf16_f32 v108, v52, v53
	s_waitcnt lgkmcnt(0)
	v_cvt_pk_bf16_f32 v109, v78, v79
	v_or_b32_e32 v51, s21, v88
	s_ashr_i32 s21, s21, 31
	v_mul_lo_u32 v78, s23, v51
	s_mul_i32 s21, s22, s21
	v_mad_u64_u32 v[52:53], s[22:23], s22, v51, 0
	v_add3_u32 v53, v53, s21, v78
	ds_read2_b32 v[78:79], v90 offset1:65
	v_lshl_add_u64 v[52:53], v[52:53], 1, s[26:27]
	s_ashr_i32 s21, s20, 31
	v_lshl_add_u64 v[52:53], s[20:21], 1, v[52:53]
	v_lshl_add_u64 v[110:111], v[70:71], 1, v[52:53]
	global_store_dwordx4 v[110:111], v[106:109], off
	s_waitcnt lgkmcnt(0)
	s_nop 0
	ds_read2_b32 v[108:109], v90 offset0:130 offset1:195
	v_cvt_pk_bf16_f32 v106, v78, v79
	ds_read2_b32 v[78:79], v102 offset0:4 offset1:69
	s_waitcnt lgkmcnt(1)
	v_cvt_pk_bf16_f32 v107, v108, v109
	ds_read2_b32 v[110:111], v102 offset0:134 offset1:199
	s_waitcnt lgkmcnt(1)
	v_cvt_pk_bf16_f32 v108, v78, v79
	ds_read2_b32 v[78:79], v91 offset1:65
	s_waitcnt lgkmcnt(1)
	v_cvt_pk_bf16_f32 v109, v110, v111
	v_lshl_add_u64 v[110:111], v[72:73], 1, v[52:53]
	global_store_dwordx4 v[110:111], v[106:109], off
	s_waitcnt lgkmcnt(0)
	v_cvt_pk_bf16_f32 v106, v78, v79
	ds_read2_b32 v[108:109], v91 offset0:130 offset1:195
	ds_read2_b32 v[78:79], v103 offset0:4 offset1:69
	s_waitcnt lgkmcnt(1)
	v_cvt_pk_bf16_f32 v107, v108, v109
	ds_read2_b32 v[102:103], v103 offset0:134 offset1:199
	s_waitcnt lgkmcnt(1)
	v_cvt_pk_bf16_f32 v108, v78, v79
	ds_read2_b32 v[78:79], v92 offset1:65
	s_waitcnt lgkmcnt(1)
	v_cvt_pk_bf16_f32 v109, v102, v103
	v_lshl_add_u64 v[102:103], v[74:75], 1, v[52:53]
	global_store_dwordx4 v[102:103], v[106:109], off
	s_waitcnt lgkmcnt(0)
	v_cvt_pk_bf16_f32 v102, v78, v79
	ds_read2_b32 v[106:107], v92 offset0:130 offset1:195
	ds_read2_b32 v[78:79], v104 offset0:4 offset1:69
	s_waitcnt lgkmcnt(1)
	v_cvt_pk_bf16_f32 v103, v106, v107
	ds_read2_b32 v[106:107], v104 offset0:134 offset1:199
	s_waitcnt lgkmcnt(1)
	v_cvt_pk_bf16_f32 v104, v78, v79
	s_waitcnt lgkmcnt(0)
	v_cvt_pk_bf16_f32 v51, v106, v106
	v_bfe_u32 v78, v107, 16, 1
	v_lshrrev_b32_e32 v51, 16, v51
	v_add3_u32 v78, v107, v78, s80
	v_and_or_b32 v105, v78, s81, v51
	v_lshl_add_u64 v[52:53], v[76:77], 1, v[52:53]
	global_store_dwordx4 v[52:53], v[102:105], off
	s_waitcnt lgkmcnt(0)
	s_barrier

.LBB0_994:
	ds_read2_b32 v[52:53], v89 offset1:65
	ds_read2_b32 v[78:79], v89 offset0:130 offset1:195
	s_add_i32 s28, s62, s83
	s_waitcnt lgkmcnt(1)
	v_cvt_pk_bf16_f32 v102, v52, v53
	v_add_u32_e32 v101, 0x400, v89
	s_waitcnt lgkmcnt(0)
	v_cvt_pk_bf16_f32 v103, v78, v79
	ds_read2_b32 v[52:53], v101 offset0:4 offset1:69
	ds_read2_b32 v[78:79], v101 offset0:134 offset1:199
	s_waitcnt lgkmcnt(1)
	v_cvt_pk_bf16_f32 v104, v52, v53
	s_waitcnt lgkmcnt(0)
	v_cvt_pk_bf16_f32 v105, v78, v79
	v_or_b32_e32 v51, s21, v88
	s_ashr_i32 s21, s21, 31
	v_mul_lo_u32 v78, s23, v51
	s_mul_i32 s21, s22, s21
	v_mad_u64_u32 v[52:53], s[22:23], s22, v51, 0
	v_add3_u32 v53, v53, s21, v78
	v_lshl_add_u64 v[52:53], v[52:53], 1, s[26:27]
	ds_read2_b32 v[78:79], v90 offset1:65
	s_ashr_i32 s21, s20, 31
	v_lshl_add_u64 v[52:53], s[20:21], 1, v[52:53]
	v_lshl_add_u64 v[106:107], v[70:71], 1, v[52:53]
	global_store_dwordx4 v[106:107], v[102:105], off
	ds_read2_b32 v[102:103], v90 offset0:130 offset1:195
	s_waitcnt lgkmcnt(1)
	v_cvt_pk_bf16_f32 v104, v78, v79
	s_waitcnt lgkmcnt(0)
	v_cvt_pk_bf16_f32 v105, v102, v103
	v_add_u32_e32 v102, 0x400, v90
	ds_read2_b32 v[78:79], v102 offset0:4 offset1:69
	ds_read2_b32 v[108:109], v102 offset0:134 offset1:199
	s_waitcnt lgkmcnt(1)
	v_cvt_pk_bf16_f32 v106, v78, v79
	ds_read2_b32 v[78:79], v91 offset1:65
	s_waitcnt lgkmcnt(1)
	v_cvt_pk_bf16_f32 v107, v108, v109
	v_lshl_add_u64 v[108:109], v[72:73], 1, v[52:53]
	global_store_dwordx4 v[108:109], v[104:107], off
	s_waitcnt lgkmcnt(0)
	v_cvt_pk_bf16_f32 v104, v78, v79
	ds_read2_b32 v[106:107], v91 offset0:130 offset1:195
	v_add_u32_e32 v103, 0x400, v91
	ds_read2_b32 v[78:79], v103 offset0:4 offset1:69
	s_waitcnt lgkmcnt(1)
	v_cvt_pk_bf16_f32 v105, v106, v107
	ds_read2_b32 v[108:109], v103 offset0:134 offset1:199
	s_waitcnt lgkmcnt(1)
	v_cvt_pk_bf16_f32 v106, v78, v79
	s_waitcnt lgkmcnt(0)
	v_cvt_pk_bf16_f32 v107, v108, v109
	ds_read2_b32 v[78:79], v92 offset1:65
	v_lshl_add_u64 v[108:109], v[74:75], 1, v[52:53]
	global_store_dwordx4 v[108:109], v[104:107], off
	ds_read2_b32 v[104:105], v92 offset0:130 offset1:195
	s_waitcnt lgkmcnt(1)
	v_cvt_pk_bf16_f32 v106, v78, v79
	s_waitcnt lgkmcnt(0)
	v_cvt_pk_bf16_f32 v107, v104, v105
	v_add_u32_e32 v104, 0x400, v92
	ds_read2_b32 v[78:79], v104 offset0:4 offset1:69
	ds_read2_b32 v[110:111], v104 offset0:134 offset1:199
	s_waitcnt lgkmcnt(1)
	v_cvt_pk_bf16_f32 v108, v78, v79
	s_waitcnt lgkmcnt(0)
	v_cvt_pk_bf16_f32 v51, v110, v110
	v_bfe_u32 v78, v111, 16, 1
	v_lshrrev_b32_e32 v51, 16, v51
	v_add3_u32 v78, v111, v78, s80
	v_and_or_b32 v109, v78, s81, v51
	v_lshl_add_u64 v[52:53], v[76:77], 1, v[52:53]
	global_store_dwordx4 v[52:53], v[106:109], off
	s_waitcnt lgkmcnt(0)
	s_barrier
	s_cmpk_gt_i32 s28, 0x43f
	s_cbranch_scc1 .LBB0_886
	s_addk_i32 s28, 0xe40
	s_cmpk_gt_i32 s28, 0xe3f
	s_mov_b64 s[34:35], -1
	s_cbranch_scc0 .LBB0_1001
	s_add_i32 s29, s76, s69
	s_cmpk_gt_u32 s28, 0x123f
	s_mov_b64 s[26:27], -1
	s_cbranch_scc0 .LBB0_998
	s_add_i32 s20, s74, s64
	s_and_b32 s20, s20, 0xffffff00
	s_and_b32 s21, s29, 0x3c0
	s_add_i32 s20, s20, 0xfffedc00
	s_mov_b64 s[26:27], 0

.LBB0_1110:
	s_or_b64 exec, exec, s[0:1]
	v_lshlrev_b32_e32 v15, 30, v14
	v_xor_b32_e32 v13, v13, v12
	v_and_b32_e32 v15, 0x80000000, v15
	v_xor_b32_e32 v13, v13, v15
	v_mul_f32_e32 v15, v2, v2
	v_fmamk_f32 v16, v15, 0xb94c1982, v6
	v_fmaak_f32 v16, v15, v16, 0xbe2aaa9d
	v_mul_f32_e32 v16, v15, v16
	v_fmac_f32_e32 v2, v2, v16
	v_fmamk_f32 v16, v15, 0x37d75334, v7
	v_fmaak_f32 v16, v15, v16, 0x3d2aabf7
	v_and_b32_e32 v14, 1, v14
	v_fmaak_f32 v16, v15, v16, 0xbf000004
	v_fma_f32 v15, v15, v16, 1.0
	v_cmp_eq_u32_e32 vcc, 0, v14
	s_ashr_i32 s13, s12, 31
	s_and_b64 s[0:1], s[14:15], exec
	v_cndmask_b32_e32 v2, v15, v2, vcc
	v_xor_b32_e32 v2, v13, v2
	v_cmp_class_f32_e64 vcc, v12, s45
	s_cselect_b32 s0, 17, 21
	s_cselect_b32 s4, s51, s49
	v_cndmask_b32_e32 v2, v10, v2, vcc
	v_cvt_pk_bf16_f32 v12, v2, v2
	s_cselect_b32 s5, s52, s50
	s_lshl_b64 s[0:1], s[12:13], s0
	v_and_b32_e32 v13, 0xffff0000, v12
	v_ashrrev_i32_e32 v5, 31, v4
	s_add_u32 s0, s5, s0
	v_sub_f32_e32 v2, v2, v13
	v_lshlrev_b64 v[4:5], 9, v[4:5]
	s_addc_u32 s1, s4, s1
	v_bfe_u32 v13, v2, 16, 1
	v_lshl_add_u64 v[4:5], s[0:1], 0, v[4:5]
	v_add3_u32 v13, v2, v13, s55
	v_lshlrev_b32_e32 v2, 1, v11
	s_add_i32 s61, s61, s62
	v_lshrrev_b32_e32 v12, 16, v12
	v_lshl_add_u64 v[4:5], v[4:5], 0, v[2:3]
	s_cmpk_lt_i32 s61, 0x220
	global_store_short v[4:5], v12, off
	global_store_short v[4:5], v12, off offset:128
	global_store_short_d16_hi v[4:5], v13, off offset:256
	global_store_short v[4:5], v3, off offset:384
	s_barrier
	s_cbranch_scc0 .LBB0_1124

.LBB0_1630:
	s_or_b64 exec, exec, s[12:13]
	v_lshlrev_b32_e32 v2, 2, v9
	v_add_u32_e32 v37, s31, v2
	v_add_u32_e32 v2, 0, v2
	v_add_u32_e32 v54, 0x1bc00, v2
	v_lshl_add_u32 v2, v26, 9, v37
	s_waitcnt lgkmcnt(0)
	s_barrier
	ds_read_b128 v[40:43], v2
	ds_read_b128 v[44:47], v54
	s_lshl_b64 s[12:13], s[8:9], 14
	s_add_u32 s0, s85, s12
	s_addc_u32 s1, s84, s13
	v_mov_b32_e32 v33, v3
	s_waitcnt lgkmcnt(1)
	v_mul_f32_e32 v15, 0x3fb8aa3b, v40
	v_lshl_add_u64 v[34:35], s[0:1], 0, v[32:33]
	v_add_u32_e32 v2, 0, v32
	v_exp_f32_e32 v32, v15
	s_waitcnt lgkmcnt(0)
	v_sub_f32_e32 v15, v40, v44
	v_mul_f32_e32 v15, 0x3fb8aa3b, v15
	v_exp_f32_e32 v48, v15
	v_sub_f32_e32 v15, v44, v40
	v_mul_f32_e32 v15, 0x3fb8aa3b, v15
	v_exp_f32_e32 v40, v15
	v_mul_f32_e32 v15, 0x3fb8aa3b, v41
	v_exp_f32_e32 v44, v15
	v_sub_f32_e32 v15, v41, v45
	v_mul_f32_e32 v15, 0x3fb8aa3b, v15
	v_exp_f32_e32 v50, v15
	v_sub_f32_e32 v15, v45, v41
	v_mul_f32_e32 v15, 0x3fb8aa3b, v15
	v_exp_f32_e32 v52, v15
	v_mul_f32_e32 v15, 0x3fb8aa3b, v42
	v_exp_f32_e32 v33, v15
	v_sub_f32_e32 v15, v42, v46
	v_mul_f32_e32 v15, 0x3fb8aa3b, v15
	v_exp_f32_e32 v49, v15
	v_sub_f32_e32 v15, v46, v42
	v_mul_f32_e32 v15, 0x3fb8aa3b, v15
	v_exp_f32_e32 v41, v15
	v_mul_f32_e32 v15, 0x3fb8aa3b, v43
	v_exp_f32_e32 v45, v15
	v_sub_f32_e32 v15, v43, v47
	v_mul_f32_e32 v15, 0x3fb8aa3b, v15
	v_exp_f32_e32 v51, v15
	v_sub_f32_e32 v15, v47, v43
	v_lshlrev_b32_e32 v43, 16, v31
	v_lshlrev_b32_e32 v42, 16, v30
	v_and_b32_e32 v31, 0xffff0000, v31
	v_and_b32_e32 v30, 0xffff0000, v30
	v_pk_mul_f32 v[30:31], v[30:31], s[6:7] op_sel_hi:[1,0]
	v_pk_mul_f32 v[42:43], v[42:43], s[6:7] op_sel_hi:[1,0]
	v_pk_mul_f32 v[44:45], v[30:31], v[44:45]
	v_mul_f32_e32 v15, 0x3fb8aa3b, v15
	v_pk_mul_f32 v[32:33], v[42:43], v[32:33]
	v_cvt_pk_bf16_f32 v33, v33, v45
	v_exp_f32_e32 v53, v15
	v_cvt_pk_bf16_f32 v32, v32, v44
	v_ashrrev_i32_e32 v27, 31, v26
	v_lshlrev_b64 v[44:45], 8, v[26:27]
	v_lshl_add_u64 v[44:45], v[34:35], 0, v[44:45]
	global_store_dwordx2 v[44:45], v[32:33], off
	v_pk_mul_f32 v[32:33], v[42:43], v[48:49]
	v_pk_mul_f32 v[30:31], v[30:31], v[50:51]
	v_cvt_pk_bf16_f32 v30, v32, v30
	v_cvt_pk_bf16_f32 v31, v33, v31
	v_lshlrev_b32_e32 v43, 16, v29
	v_lshlrev_b32_e32 v42, 16, v28
	v_and_b32_e32 v29, 0xffff0000, v29
	v_and_b32_e32 v28, 0xffff0000, v28
	v_mad_u64_u32 v[32:33], s[0:1], v26, s46, v[2:3]
	v_pk_mul_f32 v[40:41], v[40:41], v[42:43]
	v_pk_mul_f32 v[28:29], v[52:53], v[28:29]
	v_cvt_pk_bf16_f32 v21, v40, v40
	v_cvt_pk_bf16_f32 v40, v29, v29
	v_cvt_pk_bf16_f32 v33, v28, v28
	v_cvt_pk_bf16_f32 v15, v41, v41
	v_and_b32_e32 v27, 0xffff0000, v40
	v_and_b32_e32 v28, 0xffff0000, v33
	v_lshlrev_b32_e32 v26, 1, v26
	v_mul_u32_u24_e32 v48, 0x90, v9
	v_or_b32_sdwa v29, v27, v15 dst_sel:DWORD dst_unused:UNUSED_PAD src0_sel:DWORD src1_sel:WORD_1
	v_or_b32_sdwa v28, v28, v21 dst_sel:DWORD dst_unused:UNUSED_PAD src0_sel:DWORD src1_sel:WORD_1
	v_add3_u32 v9, s22, v26, v48
	ds_write2st64_b64 v32, v[30:31], v[28:29] offset1:66
	ds_write_b16_d16_hi v9, v21
	v_lshl_add_u32 v21, v20, 9, v37
	ds_read_b128 v[26:29], v21
	ds_write_b16_d16_hi v9, v33 offset:144
	ds_read_b128 v[30:33], v54
	ds_write_b16_d16_hi v9, v15 offset:288
	ds_write_b16_d16_hi v9, v40 offset:432
	v_ashrrev_i32_e32 v36, 6, v6
	s_waitcnt lgkmcnt(4)
	v_mul_f32_e32 v9, 0x3fb8aa3b, v26
	v_exp_f32_e32 v40, v9
	s_waitcnt lgkmcnt(2)
	v_sub_f32_e32 v9, v26, v30
	v_mul_f32_e32 v9, 0x3fb8aa3b, v9
	v_exp_f32_e32 v42, v9
	v_sub_f32_e32 v9, v30, v26
	v_mul_f32_e32 v9, 0x3fb8aa3b, v9
	v_exp_f32_e32 v26, v9
	v_mul_f32_e32 v9, 0x3fb8aa3b, v27
	v_exp_f32_e32 v30, v9
	v_sub_f32_e32 v9, v27, v31
	v_mul_f32_e32 v9, 0x3fb8aa3b, v9
	v_exp_f32_e32 v44, v9
	v_sub_f32_e32 v9, v31, v27
	v_mul_f32_e32 v9, 0x3fb8aa3b, v9
	v_exp_f32_e32 v46, v9
	v_mul_f32_e32 v9, 0x3fb8aa3b, v28
	v_exp_f32_e32 v41, v9
	v_sub_f32_e32 v9, v28, v32
	v_mul_f32_e32 v9, 0x3fb8aa3b, v9
	v_exp_f32_e32 v43, v9
	v_sub_f32_e32 v9, v32, v28
	v_mul_f32_e32 v9, 0x3fb8aa3b, v9
	v_exp_f32_e32 v27, v9
	v_mul_f32_e32 v9, 0x3fb8aa3b, v29
	v_exp_f32_e32 v31, v9
	v_sub_f32_e32 v9, v29, v33
	v_mul_f32_e32 v9, 0x3fb8aa3b, v9
	v_exp_f32_e32 v45, v9
	v_sub_f32_e32 v9, v33, v29
	v_lshlrev_b32_e32 v29, 16, v25
	v_lshlrev_b32_e32 v28, 16, v24
	v_and_b32_e32 v25, 0xffff0000, v25
	v_and_b32_e32 v24, 0xffff0000, v24
	v_pk_mul_f32 v[28:29], v[28:29], s[6:7] op_sel_hi:[1,0]
	v_pk_mul_f32 v[24:25], v[24:25], s[6:7] op_sel_hi:[1,0]
	v_pk_mul_f32 v[32:33], v[28:29], v[40:41]
	v_pk_mul_f32 v[30:31], v[24:25], v[30:31]
	v_mul_f32_e32 v9, 0x3fb8aa3b, v9
	v_cvt_pk_bf16_f32 v30, v32, v30
	v_cvt_pk_bf16_f32 v31, v33, v31
	v_exp_f32_e32 v47, v9
	v_ashrrev_i32_e32 v21, 31, v20
	v_pk_mul_f32 v[28:29], v[28:29], v[42:43]
	v_lshlrev_b64 v[32:33], 8, v[20:21]
	v_pk_mul_f32 v[24:25], v[24:25], v[44:45]
	v_cvt_pk_bf16_f32 v24, v28, v24
	v_lshl_add_u64 v[32:33], v[34:35], 0, v[32:33]
	global_store_dwordx2 v[32:33], v[30:31], off
	v_cvt_pk_bf16_f32 v25, v29, v25
	v_lshlrev_b32_e32 v31, 16, v23
	v_lshlrev_b32_e32 v30, 16, v22
	v_and_b32_e32 v23, 0xffff0000, v23
	v_and_b32_e32 v22, 0xffff0000, v22
	v_pk_mul_f32 v[26:27], v[26:27], v[30:31]
	v_pk_mul_f32 v[22:23], v[46:47], v[22:23]
	v_mad_u64_u32 v[28:29], s[0:1], v20, s46, v[2:3]
	v_cvt_pk_bf16_f32 v15, v26, v26
	v_cvt_pk_bf16_f32 v29, v23, v23
	v_cvt_pk_bf16_f32 v26, v22, v22
	v_cvt_pk_bf16_f32 v9, v27, v27
	v_and_b32_e32 v21, 0xffff0000, v29
	v_and_b32_e32 v22, 0xffff0000, v26
	v_or_b32_sdwa v23, v21, v9 dst_sel:DWORD dst_unused:UNUSED_PAD src0_sel:DWORD src1_sel:WORD_1
	v_or_b32_sdwa v22, v22, v15 dst_sel:DWORD dst_unused:UNUSED_PAD src0_sel:DWORD src1_sel:WORD_1
	v_lshlrev_b32_e32 v20, 1, v20
	ds_write2st64_b64 v28, v[24:25], v[22:23] offset1:66
	v_add3_u32 v28, s22, v20, v48
	ds_write_b16_d16_hi v28, v15
	v_lshl_add_u32 v15, v14, 9, v37
	ds_read_b128 v[20:23], v15
	ds_write_b16_d16_hi v28, v26 offset:144
	ds_read_b128 v[24:27], v54
	ds_write_b16_d16_hi v28, v9 offset:288
	ds_write_b16_d16_hi v28, v29 offset:432
	v_bfe_u32 v7, v6, 4, 2
	s_waitcnt lgkmcnt(4)
	v_mul_f32_e32 v9, 0x3fb8aa3b, v20
	v_exp_f32_e32 v28, v9
	s_waitcnt lgkmcnt(2)
	v_sub_f32_e32 v9, v20, v24
	v_mul_f32_e32 v9, 0x3fb8aa3b, v9
	v_exp_f32_e32 v30, v9
	v_sub_f32_e32 v9, v24, v20
	v_mul_f32_e32 v9, 0x3fb8aa3b, v9
	v_exp_f32_e32 v20, v9
	v_mul_f32_e32 v9, 0x3fb8aa3b, v21
	v_exp_f32_e32 v24, v9
	v_sub_f32_e32 v9, v21, v25
	v_mul_f32_e32 v9, 0x3fb8aa3b, v9
	v_exp_f32_e32 v32, v9
	v_sub_f32_e32 v9, v25, v21
	v_mul_f32_e32 v9, 0x3fb8aa3b, v9
	v_exp_f32_e32 v40, v9
	v_mul_f32_e32 v9, 0x3fb8aa3b, v22
	v_exp_f32_e32 v29, v9
	v_sub_f32_e32 v9, v22, v26
	v_mul_f32_e32 v9, 0x3fb8aa3b, v9
	v_exp_f32_e32 v31, v9
	v_sub_f32_e32 v9, v26, v22
	v_mul_f32_e32 v9, 0x3fb8aa3b, v9
	v_exp_f32_e32 v21, v9
	v_mul_f32_e32 v9, 0x3fb8aa3b, v23
	v_exp_f32_e32 v25, v9
	v_sub_f32_e32 v9, v23, v27
	v_mul_f32_e32 v9, 0x3fb8aa3b, v9
	v_exp_f32_e32 v33, v9
	v_sub_f32_e32 v9, v27, v23
	v_lshlrev_b32_e32 v23, 16, v19
	v_lshlrev_b32_e32 v22, 16, v18
	v_and_b32_e32 v19, 0xffff0000, v19
	v_and_b32_e32 v18, 0xffff0000, v18
	v_pk_mul_f32 v[22:23], v[22:23], s[6:7] op_sel_hi:[1,0]
	v_mul_f32_e32 v9, 0x3fb8aa3b, v9
	v_pk_mul_f32 v[18:19], v[18:19], s[6:7] op_sel_hi:[1,0]
	v_pk_mul_f32 v[26:27], v[22:23], v[28:29]
	v_exp_f32_e32 v41, v9
	v_pk_mul_f32 v[24:25], v[18:19], v[24:25]
	v_cvt_pk_bf16_f32 v25, v27, v25
	v_cvt_pk_bf16_f32 v24, v26, v24
	v_ashrrev_i32_e32 v15, 31, v14
	v_pk_mul_f32 v[22:23], v[22:23], v[30:31]
	v_lshlrev_b64 v[26:27], 8, v[14:15]
	v_pk_mul_f32 v[18:19], v[18:19], v[32:33]
	v_cvt_pk_bf16_f32 v19, v23, v19
	v_cvt_pk_bf16_f32 v18, v22, v18
	v_lshl_add_u64 v[26:27], v[34:35], 0, v[26:27]
	global_store_dwordx2 v[26:27], v[24:25], off
	v_lshlrev_b32_e32 v25, 16, v17
	v_lshlrev_b32_e32 v24, 16, v16
	v_and_b32_e32 v17, 0xffff0000, v17
	v_and_b32_e32 v16, 0xffff0000, v16
	v_pk_mul_f32 v[20:21], v[20:21], v[24:25]
	v_pk_mul_f32 v[16:17], v[40:41], v[16:17]
	v_mad_u64_u32 v[22:23], s[0:1], v14, s46, v[2:3]
	v_cvt_pk_bf16_f32 v15, v20, v20
	v_cvt_pk_bf16_f32 v9, v21, v21
	v_cvt_pk_bf16_f32 v23, v17, v17
	v_cvt_pk_bf16_f32 v20, v16, v16
	v_and_b32_e32 v16, 0xffff0000, v23
	v_and_b32_e32 v21, 0xffff0000, v20
	v_or_b32_sdwa v17, v16, v9 dst_sel:DWORD dst_unused:UNUSED_PAD src0_sel:DWORD src1_sel:WORD_1
	v_or_b32_sdwa v16, v21, v15 dst_sel:DWORD dst_unused:UNUSED_PAD src0_sel:DWORD src1_sel:WORD_1
	v_lshlrev_b32_e32 v14, 1, v14
	ds_write2st64_b64 v22, v[18:19], v[16:17] offset1:66
	v_add3_u32 v22, s22, v14, v48
	v_lshl_add_u32 v14, v8, 9, v37
	ds_write_b16_d16_hi v22, v15
	ds_read_b128 v[14:17], v14
	ds_write_b16_d16_hi v22, v20 offset:144
	ds_read_b128 v[18:21], v54
	ds_write_b16_d16_hi v22, v9 offset:288
	ds_write_b16_d16_hi v22, v23 offset:432
	s_waitcnt lgkmcnt(4)
	v_mul_f32_e32 v9, 0x3fb8aa3b, v14
	v_exp_f32_e32 v22, v9
	s_waitcnt lgkmcnt(2)
	v_sub_f32_e32 v9, v14, v18
	v_mul_f32_e32 v9, 0x3fb8aa3b, v9
	v_exp_f32_e32 v24, v9
	v_sub_f32_e32 v9, v18, v14
	v_mul_f32_e32 v9, 0x3fb8aa3b, v9
	v_exp_f32_e32 v14, v9
	v_mul_f32_e32 v9, 0x3fb8aa3b, v15
	v_exp_f32_e32 v18, v9
	v_sub_f32_e32 v9, v15, v19
	v_mul_f32_e32 v9, 0x3fb8aa3b, v9
	v_exp_f32_e32 v26, v9
	v_sub_f32_e32 v9, v19, v15
	v_mul_f32_e32 v9, 0x3fb8aa3b, v9
	v_exp_f32_e32 v28, v9
	v_mul_f32_e32 v9, 0x3fb8aa3b, v16
	v_exp_f32_e32 v23, v9
	v_sub_f32_e32 v9, v16, v20
	v_mul_f32_e32 v9, 0x3fb8aa3b, v9
	v_exp_f32_e32 v25, v9
	v_sub_f32_e32 v9, v20, v16
	v_mul_f32_e32 v9, 0x3fb8aa3b, v9
	v_exp_f32_e32 v15, v9
	v_mul_f32_e32 v9, 0x3fb8aa3b, v17
	v_exp_f32_e32 v19, v9
	v_sub_f32_e32 v9, v17, v21
	v_mul_f32_e32 v9, 0x3fb8aa3b, v9
	v_exp_f32_e32 v27, v9
	v_sub_f32_e32 v9, v21, v17
	v_lshlrev_b32_e32 v17, 16, v13
	v_lshlrev_b32_e32 v16, 16, v12
	v_and_b32_e32 v13, 0xffff0000, v13
	v_and_b32_e32 v12, 0xffff0000, v12
	v_pk_mul_f32 v[16:17], v[16:17], s[6:7] op_sel_hi:[1,0]
	v_mul_f32_e32 v9, 0x3fb8aa3b, v9
	v_pk_mul_f32 v[12:13], v[12:13], s[6:7] op_sel_hi:[1,0]
	v_pk_mul_f32 v[20:21], v[16:17], v[22:23]
	v_exp_f32_e32 v29, v9
	v_pk_mul_f32 v[18:19], v[12:13], v[18:19]
	v_cvt_pk_bf16_f32 v19, v21, v19
	v_cvt_pk_bf16_f32 v18, v20, v18
	v_ashrrev_i32_e32 v9, 31, v8
	v_lshlrev_b64 v[20:21], 8, v[8:9]
	v_lshl_add_u64 v[20:21], v[34:35], 0, v[20:21]
	v_pk_mul_f32 v[16:17], v[16:17], v[24:25]
	global_store_dwordx2 v[20:21], v[18:19], off
	v_pk_mul_f32 v[12:13], v[12:13], v[26:27]
	v_cvt_pk_bf16_f32 v13, v17, v13
	v_cvt_pk_bf16_f32 v12, v16, v12
	v_lshlrev_b32_e32 v19, 16, v11
	v_lshlrev_b32_e32 v18, 16, v10
	v_and_b32_e32 v11, 0xffff0000, v11
	v_and_b32_e32 v10, 0xffff0000, v10
	v_pk_mul_f32 v[14:15], v[14:15], v[18:19]
	v_mad_u64_u32 v[16:17], s[0:1], v8, s46, v[2:3]
	v_pk_mul_f32 v[10:11], v[28:29], v[10:11]
	v_cvt_pk_bf16_f32 v9, v14, v14
	v_cvt_pk_bf16_f32 v2, v15, v15
	v_cvt_pk_bf16_f32 v14, v11, v11
	v_cvt_pk_bf16_f32 v15, v10, v10
	v_and_b32_e32 v10, 0xffff0000, v14
	v_and_b32_e32 v17, 0xffff0000, v15
	v_lshlrev_b32_e32 v8, 1, v8
	v_or_b32_sdwa v11, v10, v2 dst_sel:DWORD dst_unused:UNUSED_PAD src0_sel:DWORD src1_sel:WORD_1
	v_or_b32_sdwa v10, v17, v9 dst_sel:DWORD dst_unused:UNUSED_PAD src0_sel:DWORD src1_sel:WORD_1
	v_add3_u32 v8, s22, v8, v48
	ds_write2st64_b64 v16, v[12:13], v[10:11] offset1:66
	ds_write_b16_d16_hi v8, v9
	ds_write_b16_d16_hi v8, v15 offset:144
	ds_write_b16_d16_hi v8, v2 offset:288
	ds_write_b16_d16_hi v8, v14 offset:432
	v_lshlrev_b32_e32 v2, 3, v36
	v_and_or_b32 v8, v2, s48, v39
	v_lshl_add_u32 v2, v7, 4, 0
	v_mad_u64_u32 v[28:29], s[0:1], v8, s46, v[2:3]
	s_waitcnt lgkmcnt(0)
	s_barrier
	ds_read_b128 v[8:11], v28
	v_lshlrev_b32_e32 v12, 5, v36
	v_and_or_b32 v36, v12, 32, v39
	v_mad_u32_u24 v2, v36, s46, v2
	ds_read_b128 v[12:15], v28 offset:64
	ds_read_b128 v[16:19], v2 offset:33792
	ds_read_b128 v[20:23], v2 offset:33856
	ds_read_b128 v[24:27], v28 offset:128
	s_waitcnt lgkmcnt(2)
	v_mfma_f32_16x16x32_bf16 v[16:19], v[8:11], v[16:19], 0
	s_waitcnt lgkmcnt(1)
	v_mfma_f32_16x16x32_bf16 v[16:19], v[12:15], v[20:23], v[16:19]
	ds_read_b128 v[20:23], v28 offset:192
	ds_read_b128 v[28:31], v2 offset:33920
	ds_read_b128 v[32:35], v2 offset:33984
	s_waitcnt lgkmcnt(1)
	v_mfma_f32_16x16x32_bf16 v[16:19], v[24:27], v[28:31], v[16:19]
	s_waitcnt lgkmcnt(0)
	v_mfma_f32_16x16x32_bf16 v[16:19], v[20:23], v[32:35], v[16:19]
	ds_read_b128 v[28:31], v2 offset:42240
	ds_read_b128 v[32:35], v2 offset:42304
	s_waitcnt lgkmcnt(1)
	v_mfma_f32_16x16x32_bf16 v[8:11], v[8:11], v[28:31], 0
	s_waitcnt lgkmcnt(0)
	v_mfma_f32_16x16x32_bf16 v[8:11], v[12:15], v[32:35], v[8:11]
	ds_read_b128 v[12:15], v2 offset:42368
	ds_read_b128 v[28:31], v2 offset:42432
	v_ashrrev_i32_e32 v2, 3, v6
	v_and_b32_e32 v2, -16, v2
	v_lshl_or_b32 v2, v7, 2, v2
	v_cmp_le_i32_e64 s[0:1], v36, v2
	s_waitcnt lgkmcnt(1)
	v_mfma_f32_16x16x32_bf16 v[8:11], v[24:27], v[12:15], v[8:11]
	v_lshl_add_u32 v6, v36, 1, s49
	v_cndmask_b32_e64 v7, 0, 1, s[0:1]
	v_cmp_ge_i32_e64 s[0:1], v36, v2
	s_waitcnt lgkmcnt(0)
	v_mfma_f32_16x16x32_bf16 v[8:11], v[20:23], v[28:31], v[8:11]
	v_cndmask_b32_e64 v12, 0, 1, s[0:1]
	v_cndmask_b32_e32 v7, v12, v7, vcc
	v_and_b32_e32 v7, 1, v7
	v_cmp_eq_u32_e64 s[0:1], 1, v7
	s_nop 1
	v_cndmask_b32_e64 v7, 0, v16, s[0:1]
	v_cvt_pk_bf16_f32 v7, v7, v7
	v_mul_lo_u32 v12, v2, s47
	v_add_u32_e32 v13, v6, v12
	ds_write_b16_d16_hi v13, v7
	v_or_b32_e32 v7, 1, v2
	v_cmp_gt_i32_e64 s[0:1], v36, v2
	s_nop 1
	v_cndmask_b32_e64 v13, 0, 1, s[0:1]
	v_cmp_le_i32_e64 s[0:1], v36, v7
	s_nop 1
	v_cndmask_b32_e64 v14, 0, 1, s[0:1]
	v_cndmask_b32_e32 v13, v13, v14, vcc
	v_and_b32_e32 v13, 1, v13
	v_cmp_eq_u32_e64 s[0:1], 1, v13
	s_nop 1
	v_cndmask_b32_e64 v13, 0, v17, s[0:1]
	v_cvt_pk_bf16_f32 v13, v13, v13
	v_add_u32_e32 v14, 0x90, v12
	v_add_u32_e32 v15, v6, v14
	ds_write_b16_d16_hi v15, v13
	v_or_b32_e32 v13, 2, v2
	v_cmp_le_i32_e64 s[0:1], v36, v13
	s_nop 1
	v_cndmask_b32_e64 v15, 0, 1, s[0:1]
	v_cmp_ge_i32_e64 s[0:1], v36, v13
	s_nop 1
	v_cndmask_b32_e64 v16, 0, 1, s[0:1]
	v_cndmask_b32_e32 v15, v16, v15, vcc
	v_and_b32_e32 v15, 1, v15
	v_cmp_eq_u32_e64 s[0:1], 1, v15
	s_nop 1
	v_cndmask_b32_e64 v15, 0, v18, s[0:1]
	v_cvt_pk_bf16_f32 v15, v15, v15
	v_add_u32_e32 v16, 0x120, v12
	v_add_u32_e32 v17, v6, v16
	ds_write_b16_d16_hi v17, v15
	v_or_b32_e32 v15, 3, v2
	v_cmp_le_i32_e64 s[0:1], v36, v15
	s_nop 1
	v_cndmask_b32_e64 v17, 0, 1, s[0:1]
	v_cmp_ge_i32_e64 s[0:1], v36, v15
	s_nop 1
	v_cndmask_b32_e64 v18, 0, 1, s[0:1]
	v_cndmask_b32_e32 v17, v18, v17, vcc
	v_and_b32_e32 v17, 1, v17
	v_cmp_eq_u32_e64 s[0:1], 1, v17
	s_nop 1
	v_cndmask_b32_e64 v17, 0, v19, s[0:1]
	v_cvt_pk_bf16_f32 v17, v17, v17
	v_add_u32_e32 v18, 0x1b0, v12
	v_add_u32_e32 v6, v6, v18
	ds_write_b16_d16_hi v6, v17
	v_or_b32_e32 v6, 16, v36
	v_cmp_le_i32_e64 s[0:1], v6, v2
	s_nop 1
	v_cndmask_b32_e64 v17, 0, 1, s[0:1]
	v_cmp_ge_i32_e64 s[0:1], v6, v2
	s_nop 1
	v_cndmask_b32_e64 v19, 0, 1, s[0:1]
	v_cndmask_b32_e32 v17, v19, v17, vcc
	v_and_b32_e32 v17, 1, v17
	v_cmp_eq_u32_e64 s[0:1], 1, v17
	s_nop 1
	v_cndmask_b32_e64 v8, 0, v8, s[0:1]
	v_cmp_le_i32_e64 s[0:1], v6, v7
	s_nop 0
	v_cvt_pk_bf16_f32 v8, v8, v8
	v_cndmask_b32_e64 v7, 0, 1, s[0:1]
	v_cmp_gt_i32_e64 s[0:1], v6, v2
	v_lshlrev_b32_e32 v17, 1, v6
	v_add3_u32 v12, s49, v12, v17
	v_cndmask_b32_e64 v2, 0, 1, s[0:1]
	v_cndmask_b32_e32 v2, v2, v7, vcc
	v_and_b32_e32 v2, 1, v2
	v_cmp_eq_u32_e64 s[0:1], 1, v2
	ds_write_b16_d16_hi v12, v8
	s_nop 0
	v_cndmask_b32_e64 v2, 0, v9, s[0:1]
	v_cvt_pk_bf16_f32 v2, v2, v2
	v_add3_u32 v7, s49, v14, v17
	v_cmp_le_i32_e64 s[0:1], v6, v13
	ds_write_b16_d16_hi v7, v2
	s_nop 0
	v_cndmask_b32_e64 v2, 0, 1, s[0:1]
	v_cmp_ge_i32_e64 s[0:1], v6, v13
	s_nop 1
	v_cndmask_b32_e64 v7, 0, 1, s[0:1]
	v_cndmask_b32_e32 v2, v7, v2, vcc
	v_and_b32_e32 v2, 1, v2
	v_cmp_eq_u32_e64 s[0:1], 1, v2
	s_nop 1
	v_cndmask_b32_e64 v2, 0, v10, s[0:1]
	v_cvt_pk_bf16_f32 v2, v2, v2
	v_add3_u32 v7, s49, v16, v17
	v_cmp_le_i32_e64 s[0:1], v6, v15
	ds_write_b16_d16_hi v7, v2
	s_nop 0
	v_cndmask_b32_e64 v2, 0, 1, s[0:1]
	v_cmp_ge_i32_e64 s[0:1], v6, v15
	s_nop 1
	v_cndmask_b32_e64 v6, 0, 1, s[0:1]
	v_cndmask_b32_e32 v2, v6, v2, vcc
	v_and_b32_e32 v2, 1, v2
	v_cmp_eq_u32_e64 s[0:1], 1, v2
	s_nop 1
	v_cndmask_b32_e64 v2, 0, v11, s[0:1]
	v_cvt_pk_bf16_f32 v2, v2, v2
	v_add3_u32 v6, s49, v18, v17
	ds_write_b16_d16_hi v6, v2
	v_mov_b32_e32 v6, v0
	s_waitcnt lgkmcnt(0)
	s_barrier
	s_nop 0
	v_cmp_gt_i32_e64 s[0:1], s19, v6
	s_and_saveexec_b64 s[14:15], s[0:1]
	s_cbranch_execz .LBB0_1633
	s_lshl_b64 s[0:1], s[8:9], 13
	v_readlane_b32 s8, v238, 9
	s_add_u32 s8, s8, s0
	v_readlane_b32 s0, v238, 7
	s_addc_u32 s9, s0, s1
	v_lshlrev_b32_e32 v7, 3, v6
	s_mov_b64 s[16:17], 0

.LBB0_1701:
	v_add_u32_e32 v27, 0x400, v26
	v_lshlrev_b32_e32 v38, 16, v10
	ds_read2_b32 v[30:31], v26 offset1:65
	ds_read2_b32 v[32:33], v26 offset0:130 offset1:195
	ds_read2_b32 v[34:35], v27 offset0:4 offset1:69
	ds_read2_b32 v[36:37], v27 offset0:134 offset1:199
	v_mul_f32_e32 v27, 0xbfb8aa3b, v38
	v_exp_f32_e32 v27, v27
	v_lshlrev_b32_e32 v39, 16, v11
	v_mul_f32_e32 v40, 0xbfb8aa3b, v39
	v_exp_f32_e32 v41, v40
	v_and_b32_e32 v10, 0xffff0000, v10
	v_add_f32_e32 v27, 1.0, v27
	v_and_b32_e32 v11, 0xffff0000, v11
	v_rcp_f32_e32 v40, v27
	v_mul_f32_e32 v27, 0xbfb8aa3b, v10
	v_exp_f32_e32 v27, v27
	v_add_f32_e32 v41, 1.0, v41
	v_mul_f32_e32 v42, 0xbfb8aa3b, v11
	v_rcp_f32_e32 v41, v41
	v_exp_f32_e32 v43, v42
	v_add_f32_e32 v27, 1.0, v27
	v_rcp_f32_e32 v42, v27
	v_pk_mul_f32 v[38:39], v[40:41], v[38:39]
	v_add_f32_e32 v27, 1.0, v43
	s_waitcnt lgkmcnt(3)
	v_mov_b32_e32 v40, v30
	v_lshlrev_b32_e32 v30, 16, v12
	v_rcp_f32_e32 v43, v27
	v_mul_f32_e32 v27, 0xbfb8aa3b, v30
	v_exp_f32_e32 v27, v27
	s_waitcnt lgkmcnt(2)
	v_mov_b32_e32 v41, v32
	v_pk_mul_f32 v[10:11], v[42:43], v[10:11]
	v_mov_b32_e32 v32, v31
	v_lshlrev_b32_e32 v31, 16, v13
	v_pk_mul_f32 v[10:11], v[10:11], v[32:33]
	v_and_b32_e32 v12, 0xffff0000, v12
	v_add_f32_e32 v27, 1.0, v27
	v_mul_f32_e32 v32, 0xbfb8aa3b, v31
	v_and_b32_e32 v13, 0xffff0000, v13
	v_exp_f32_e32 v33, v32
	v_rcp_f32_e32 v32, v27
	v_mul_f32_e32 v27, 0xbfb8aa3b, v12
	v_pk_mul_f32 v[38:39], v[38:39], v[40:41]
	v_exp_f32_e32 v27, v27
	v_mul_f32_e32 v40, 0xbfb8aa3b, v13
	v_exp_f32_e32 v41, v40
	v_add_f32_e32 v33, 1.0, v33
	v_add_f32_e32 v27, 1.0, v27
	v_rcp_f32_e32 v40, v27
	v_add_f32_e32 v27, 1.0, v41
	v_rcp_f32_e32 v33, v33
	v_rcp_f32_e32 v41, v27
	s_and_b32 s26, s47, 0xffffffc0
	v_add_u32_e32 v28, s26, v23
	v_pk_mul_f32 v[30:31], v[32:33], v[30:31]
	s_waitcnt lgkmcnt(0)
	v_mov_b32_e32 v33, v36
	v_pk_mul_f32 v[12:13], v[40:41], v[12:13]
	v_mov_b32_e32 v36, v35
	v_mov_b32_e32 v32, v34
	v_pk_mul_f32 v[12:13], v[12:13], v[36:37]
	v_ashrrev_i32_e32 v29, 31, v28
	v_pk_mul_f32 v[30:31], v[30:31], v[32:33]
	v_cvt_pk_bf16_f32 v10, v38, v10
	s_and_b32 s36, s46, 0x3c0
	v_cvt_pk_bf16_f32 v11, v11, v11
	v_cvt_pk_bf16_f32 v12, v12, v12
	v_cvt_pk_bf16_f32 v13, v13, v13
	v_bfe_u32 v33, v30, 16, 1
	v_bfe_u32 v34, v31, 16, 1
	v_lshlrev_b64 v[28:29], 13, v[28:29]
	v_add3_u32 v31, v31, v34, s44
	v_add3_u32 v30, v30, v33, s44
	v_cvt_pk_bf16_f32 v32, v39, v39
	v_lshl_add_u64 v[28:29], s[12:13], 0, v[28:29]
	s_lshl_b32 s26, s36, 1
	v_lshrrev_b32_e32 v32, 16, v32
	v_lshrrev_b32_e32 v30, 16, v30
	v_lshrrev_b32_e32 v31, 16, v31
	v_lshl_add_u64 v[28:29], v[28:29], 0, s[26:27]
	v_and_or_b32 v13, v13, s41, v31
	v_and_or_b32 v12, v12, s41, v30
	v_and_or_b32 v11, v11, s41, v32
	v_lshl_add_u64 v[28:29], v[28:29], 0, v[18:19]
	global_store_dwordx4 v[28:29], v[10:13], off offset:2048
	s_waitcnt lgkmcnt(0)
	s_barrier
	s_andn2_b64 vcc, exec, s[34:35]
	s_mov_b32 s46, s45
	s_waitcnt vmcnt(1)
	v_mov_b64_e32 v[10:11], v[14:15]
	s_mov_b32 s47, s29
	v_mov_b64_e32 v[12:13], v[16:17]
	s_cbranch_vccz .LBB0_1706

.LBB0_1709:
	v_ashrrev_i32_e32 v37, 8, v18
	v_and_b32_e32 v34, 0xff, v18
	v_lshlrev_b32_e32 v19, 13, v37
	v_lshlrev_b32_e32 v20, 1, v34
	v_add3_u32 v38, s25, v19, v20
	v_add3_u32 v19, s54, v19, v20
	ds_read_u16 v20, v38
	ds_read_u16 v22, v38 offset:512
	ds_read_u16 v24, v38 offset:1024
	ds_read_u16 v26, v38 offset:1536
	ds_read_u16 v28, v38 offset:2048
	ds_read_u16 v39, v38 offset:2560
	ds_read_u16 v42, v38 offset:3072
	ds_read_u16 v44, v38 offset:3584
	ds_read_u16 v21, v19
	ds_read_u16 v23, v19 offset:512
	ds_read_u16 v25, v19 offset:1024
	ds_read_u16 v27, v19 offset:1536
	ds_read_u16 v29, v19 offset:2048
	ds_read_u16 v41, v19 offset:2560
	ds_read_u16 v43, v19 offset:3072
	ds_read_u16 v45, v19 offset:3584
	s_waitcnt lgkmcnt(7)
	v_lshlrev_b32_e32 v21, 16, v21
	v_lshlrev_b32_e32 v40, 16, v39
	s_waitcnt lgkmcnt(2)
	v_lshlrev_b32_e32 v39, 16, v41
	v_xor_b32_e32 v41, 0x80000000, v39
	s_waitcnt lgkmcnt(1)
	v_lshlrev_b32_e32 v39, 16, v43
	v_xor_b32_e32 v43, 0x80000000, v39
	s_waitcnt lgkmcnt(0)
	v_lshlrev_b32_e32 v39, 16, v45
	v_xor_b32_e32 v45, 0x80000000, v39
	ds_read_u16 v39, v38 offset:4096
	ds_read_u16 v48, v38 offset:4608
	ds_read_u16 v50, v38 offset:5120
	ds_read_u16 v52, v38 offset:5632
	ds_read_u16 v54, v38 offset:6144
	ds_read_u16 v56, v38 offset:6656
	ds_read_u16 v58, v38 offset:7168
	ds_read_u16 v38, v38 offset:7680
	s_waitcnt lgkmcnt(7)
	v_lshlrev_b32_e32 v46, 16, v39
	ds_read_u16 v39, v19 offset:4096
	ds_read_u16 v49, v19 offset:4608
	ds_read_u16 v51, v19 offset:5120
	ds_read_u16 v53, v19 offset:5632
	ds_read_u16 v55, v19 offset:6144
	ds_read_u16 v57, v19 offset:6656
	ds_read_u16 v59, v19 offset:7168
	ds_read_u16 v19, v19 offset:7680
	s_waitcnt lgkmcnt(7)
	v_lshlrev_b32_e32 v39, 16, v39
	v_xor_b32_e32 v47, 0x80000000, v39
	s_waitcnt lgkmcnt(6)
	v_lshlrev_b32_e32 v39, 16, v49
	v_xor_b32_e32 v49, 0x80000000, v39
	s_waitcnt lgkmcnt(5)
	v_lshlrev_b32_e32 v39, 16, v51
	v_xor_b32_e32 v51, 0x80000000, v39
	s_waitcnt lgkmcnt(4)
	v_lshlrev_b32_e32 v39, 16, v53
	v_lshlrev_b32_e32 v29, 16, v29
	v_xor_b32_e32 v53, 0x80000000, v39
	s_waitcnt lgkmcnt(3)
	v_lshlrev_b32_e32 v39, 16, v55
	v_lshlrev_b32_e32 v20, 16, v20
	v_xor_b32_e32 v21, 0x80000000, v21
	v_lshlrev_b32_e32 v23, 16, v23
	v_lshlrev_b32_e32 v28, 16, v28
	v_xor_b32_e32 v29, 0x80000000, v29
	v_lshlrev_b32_e32 v54, 16, v54
	v_xor_b32_e32 v55, 0x80000000, v39
	s_waitcnt lgkmcnt(2)
	v_lshlrev_b32_e32 v39, 16, v57
	s_waitcnt lgkmcnt(0)
	v_lshlrev_b32_e32 v19, 16, v19
	v_lshlrev_b32_e32 v22, 16, v22
	v_xor_b32_e32 v23, 0x80000000, v23
	v_lshlrev_b32_e32 v25, 16, v25
	v_lshlrev_b32_e32 v48, 16, v48
	v_lshlrev_b32_e32 v56, 16, v56
	v_xor_b32_e32 v57, 0x80000000, v39
	v_lshlrev_b32_e32 v39, 16, v59
	v_lshlrev_b32_e32 v60, 16, v38
	v_xor_b32_e32 v61, 0x80000000, v19
	v_bfe_u32 v38, v18, 4, 4
	v_pk_add_f32 v[18:19], v[20:21], v[46:47]
	v_pk_add_f32 v[20:21], v[20:21], v[46:47] neg_lo:[0,1] neg_hi:[0,1]
	v_pk_add_f32 v[46:47], v[28:29], v[54:55]
	v_pk_add_f32 v[28:29], v[28:29], v[54:55] neg_lo:[0,1] neg_hi:[0,1]
	v_lshlrev_b32_e32 v24, 16, v24
	v_xor_b32_e32 v25, 0x80000000, v25
	v_lshlrev_b32_e32 v27, 16, v27
	v_lshlrev_b32_e32 v42, 16, v42
	v_lshlrev_b32_e32 v50, 16, v50
	v_lshlrev_b32_e32 v58, 16, v58
	v_xor_b32_e32 v59, 0x80000000, v39
	v_pk_add_f32 v[54:55], v[18:19], v[46:47]
	v_pk_add_f32 v[46:47], v[18:19], v[46:47] neg_lo:[0,1] neg_hi:[0,1]
	v_pk_add_f32 v[62:63], v[20:21], v[28:29] op_sel:[0,1] op_sel_hi:[1,0] neg_hi:[0,1]
	v_pk_add_f32 v[64:65], v[20:21], v[28:29] op_sel:[0,1] op_sel_hi:[1,0] neg_lo:[0,1]
	v_pk_add_f32 v[18:19], v[22:23], v[48:49]
	v_pk_add_f32 v[20:21], v[22:23], v[48:49] neg_lo:[0,1] neg_hi:[0,1]
	v_pk_add_f32 v[22:23], v[40:41], v[56:57]
	v_pk_add_f32 v[28:29], v[40:41], v[56:57] neg_lo:[0,1] neg_hi:[0,1]
	v_lshlrev_b32_e32 v26, 16, v26
	v_xor_b32_e32 v27, 0x80000000, v27
	v_lshlrev_b32_e32 v44, 16, v44
	v_lshlrev_b32_e32 v52, 16, v52
	v_pk_add_f32 v[40:41], v[18:19], v[22:23]
	v_pk_add_f32 v[22:23], v[18:19], v[22:23] neg_lo:[0,1] neg_hi:[0,1]
	v_pk_add_f32 v[18:19], v[20:21], v[28:29] op_sel:[0,1] op_sel_hi:[1,0] neg_hi:[0,1]
	v_pk_add_f32 v[28:29], v[20:21], v[28:29] op_sel:[0,1] op_sel_hi:[1,0] neg_lo:[0,1]
	v_pk_add_f32 v[20:21], v[24:25], v[50:51]
	v_pk_add_f32 v[24:25], v[24:25], v[50:51] neg_lo:[0,1] neg_hi:[0,1]
	v_pk_add_f32 v[48:49], v[42:43], v[58:59]
	v_pk_add_f32 v[42:43], v[42:43], v[58:59] neg_lo:[0,1] neg_hi:[0,1]
	v_pk_add_f32 v[50:51], v[20:21], v[48:49]
	v_pk_add_f32 v[48:49], v[20:21], v[48:49] neg_lo:[0,1] neg_hi:[0,1]
	v_pk_add_f32 v[56:57], v[24:25], v[42:43] op_sel:[0,1] op_sel_hi:[1,0] neg_hi:[0,1]
	v_pk_add_f32 v[42:43], v[24:25], v[42:43] op_sel:[0,1] op_sel_hi:[1,0] neg_lo:[0,1]
	v_pk_add_f32 v[20:21], v[26:27], v[52:53]
	v_pk_add_f32 v[24:25], v[26:27], v[52:53] neg_lo:[0,1] neg_hi:[0,1]
	v_pk_add_f32 v[26:27], v[44:45], v[60:61]
	v_pk_add_f32 v[44:45], v[44:45], v[60:61] neg_lo:[0,1] neg_hi:[0,1]
	v_pk_add_f32 v[52:53], v[20:21], v[26:27]
	v_pk_add_f32 v[58:59], v[20:21], v[26:27] neg_lo:[0,1] neg_hi:[0,1]
	v_pk_add_f32 v[26:27], v[24:25], v[44:45] op_sel:[0,1] op_sel_hi:[1,0] neg_hi:[0,1]
	v_pk_add_f32 v[44:45], v[24:25], v[44:45] op_sel:[0,1] op_sel_hi:[1,0] neg_lo:[0,1]
	v_mov_b64_e32 v[24:25], s[38:39]
	v_pk_mul_f32 v[20:21], v[18:19], v[24:25] op_sel:[0,0] op_sel_hi:[0,1]
	v_mad_i32_i24 v35, v37, s3, 0
	v_pk_fma_f32 v[60:61], v[18:19], v[24:25], v[20:21] op_sel:[1,1,0] op_sel_hi:[1,0,1] neg_lo:[0,1,0]
	v_mov_b64_e32 v[20:21], s[40:41]
	v_pk_mul_f32 v[18:19], v[56:57], v[20:21] op_sel:[0,0] op_sel_hi:[0,1]
	v_lshlrev_b32_e32 v39, 3, v34
	v_pk_fma_f32 v[56:57], v[56:57], v[20:21], v[18:19] op_sel:[1,1,0] op_sel_hi:[1,0,1] neg_lo:[0,1,0]
	v_mov_b64_e32 v[18:19], s[44:45]
	v_pk_mul_f32 v[66:67], v[26:27], v[18:19] op_sel:[0,0] op_sel_hi:[0,1]
	v_lshlrev_b32_e32 v74, 3, v38
	v_pk_fma_f32 v[66:67], v[26:27], v[18:19], v[66:67] op_sel:[1,1,0] op_sel_hi:[1,0,1] neg_lo:[0,1,0]
	v_pk_mul_f32 v[26:27], v[22:23], v[20:21] op_sel:[0,0] op_sel_hi:[0,1]
	v_add3_u32 v74, v35, v39, v74
	v_pk_fma_f32 v[68:69], v[22:23], v[20:21], v[26:27] op_sel:[1,1,0] op_sel_hi:[1,0,1] neg_lo:[0,1,0]
	v_mov_b64_e32 v[26:27], s[36:37]
	v_pk_mul_f32 v[22:23], v[48:49], v[26:27] op_sel:[0,0] op_sel_hi:[0,1]
	v_lshl_add_u32 v78, v38, 11, v35
	v_pk_fma_f32 v[48:49], v[48:49], v[26:27], v[22:23] op_sel:[1,1,0] op_sel_hi:[1,0,1] neg_lo:[0,1,0]
	v_mov_b64_e32 v[22:23], s[46:47]
	v_pk_mul_f32 v[70:71], v[58:59], v[22:23] op_sel:[0,0] op_sel_hi:[0,1]
	v_add_u32_e32 v39, v78, v39
	v_pk_fma_f32 v[58:59], v[58:59], v[22:23], v[70:71] op_sel:[1,1,0] op_sel_hi:[1,0,1] neg_lo:[0,1,0]
	v_pk_mul_f32 v[70:71], v[28:29], v[18:19] op_sel:[0,0] op_sel_hi:[0,1]
	v_pk_fma_f32 v[70:71], v[28:29], v[18:19], v[70:71] op_sel:[1,1,0] op_sel_hi:[1,0,1] neg_lo:[0,1,0]
	v_pk_mul_f32 v[28:29], v[42:43], v[22:23] op_sel:[0,0] op_sel_hi:[0,1]
	v_pk_fma_f32 v[42:43], v[42:43], v[22:23], v[28:29] op_sel:[1,1,0] op_sel_hi:[1,0,1] neg_lo:[0,1,0]
	v_mov_b64_e32 v[28:29], s[48:49]
	v_pk_mul_f32 v[72:73], v[44:45], v[28:29] op_sel:[0,0] op_sel_hi:[0,1]
	v_pk_fma_f32 v[44:45], v[44:45], v[28:29], v[72:73] op_sel:[1,1,0] op_sel_hi:[1,0,1] neg_lo:[0,1,0]
	v_pk_add_f32 v[72:73], v[54:55], v[50:51]
	v_pk_add_f32 v[50:51], v[54:55], v[50:51] neg_lo:[0,1] neg_hi:[0,1]
	v_pk_add_f32 v[54:55], v[40:41], v[52:53]
	v_pk_add_f32 v[40:41], v[40:41], v[52:53] neg_lo:[0,1] neg_hi:[0,1]
	v_pk_add_f32 v[52:53], v[72:73], v[54:55]
	v_pk_add_f32 v[54:55], v[72:73], v[54:55] neg_lo:[0,1] neg_hi:[0,1]
	v_pk_add_f32 v[72:73], v[50:51], v[40:41] op_sel:[0,1] op_sel_hi:[1,0] neg_hi:[0,1]
	v_pk_add_f32 v[40:41], v[50:51], v[40:41] op_sel:[0,1] op_sel_hi:[1,0] neg_lo:[0,1]
	v_pk_add_f32 v[50:51], v[62:63], v[56:57]
	v_pk_add_f32 v[56:57], v[62:63], v[56:57] neg_lo:[0,1] neg_hi:[0,1]
	v_pk_add_f32 v[62:63], v[60:61], v[66:67]
	v_pk_add_f32 v[60:61], v[60:61], v[66:67] neg_lo:[0,1] neg_hi:[0,1]
	v_pk_add_f32 v[66:67], v[50:51], v[62:63]
	v_pk_add_f32 v[50:51], v[50:51], v[62:63] neg_lo:[0,1] neg_hi:[0,1]
	v_pk_add_f32 v[62:63], v[56:57], v[60:61] op_sel:[0,1] op_sel_hi:[1,0] neg_hi:[0,1]
	v_pk_add_f32 v[56:57], v[56:57], v[60:61] op_sel:[0,1] op_sel_hi:[1,0] neg_lo:[0,1]
	v_pk_add_f32 v[60:61], v[46:47], v[48:49]
	v_pk_add_f32 v[46:47], v[46:47], v[48:49] neg_lo:[0,1] neg_hi:[0,1]
	v_pk_add_f32 v[48:49], v[68:69], v[58:59]
	v_pk_add_f32 v[58:59], v[68:69], v[58:59] neg_lo:[0,1] neg_hi:[0,1]
	v_pk_add_f32 v[68:69], v[60:61], v[48:49]
	v_pk_add_f32 v[48:49], v[60:61], v[48:49] neg_lo:[0,1] neg_hi:[0,1]
	v_pk_add_f32 v[60:61], v[46:47], v[58:59] op_sel:[0,1] op_sel_hi:[1,0] neg_hi:[0,1]
	v_pk_add_f32 v[46:47], v[46:47], v[58:59] op_sel:[0,1] op_sel_hi:[1,0] neg_lo:[0,1]
	v_pk_add_f32 v[58:59], v[64:65], v[42:43]
	v_pk_add_f32 v[42:43], v[64:65], v[42:43] neg_lo:[0,1] neg_hi:[0,1]
	v_pk_add_f32 v[64:65], v[70:71], v[44:45]
	v_pk_add_f32 v[44:45], v[70:71], v[44:45] neg_lo:[0,1] neg_hi:[0,1]
	v_pk_add_f32 v[70:71], v[58:59], v[64:65]
	v_pk_add_f32 v[58:59], v[58:59], v[64:65] neg_lo:[0,1] neg_hi:[0,1]
	v_pk_add_f32 v[64:65], v[42:43], v[44:45] op_sel:[0,1] op_sel_hi:[1,0] neg_hi:[0,1]
	v_pk_add_f32 v[42:43], v[42:43], v[44:45] op_sel:[0,1] op_sel_hi:[1,0] neg_lo:[0,1]
	v_mov_b32_e32 v44, v1
	v_mov_b32_e32 v45, v31
	ds_write_b64 v74, v[52:53]
	v_pk_mul_f32 v[52:53], v[66:67], v[44:45] op_sel:[0,0] op_sel_hi:[0,1]
	v_pk_fma_f32 v[52:53], v[66:67], v[44:45], v[52:53] op_sel:[1,1,0] op_sel_hi:[1,0,1] neg_lo:[0,1,0]
	ds_write_b64 v74, v[52:53] offset:2176
	v_pk_mul_f32 v[52:53], v[44:45], v[44:45] op_sel:[0,0] op_sel_hi:[0,1]
	v_pk_fma_f32 v[52:53], v[44:45], v[44:45], v[52:53] op_sel:[1,1,0] op_sel_hi:[1,0,1] neg_lo:[0,1,0]
	v_pk_mul_f32 v[66:67], v[68:69], v[52:53] op_sel:[0,0] op_sel_hi:[0,1]
	v_pk_fma_f32 v[66:67], v[68:69], v[52:53], v[66:67] op_sel:[1,1,0] op_sel_hi:[1,0,1] neg_lo:[0,1,0]
	ds_write_b64 v74, v[66:67] offset:4352
	v_pk_mul_f32 v[66:67], v[52:53], v[44:45] op_sel:[0,0] op_sel_hi:[0,1]
	v_pk_fma_f32 v[52:53], v[52:53], v[44:45], v[66:67] op_sel:[1,1,0] op_sel_hi:[1,0,1] neg_lo:[0,1,0]
	v_pk_mul_f32 v[66:67], v[70:71], v[52:53] op_sel:[0,0] op_sel_hi:[0,1]
	v_pk_fma_f32 v[66:67], v[70:71], v[52:53], v[66:67] op_sel:[1,1,0] op_sel_hi:[1,0,1] neg_lo:[0,1,0]
	ds_write_b64 v74, v[66:67] offset:6528
	v_pk_mul_f32 v[66:67], v[52:53], v[44:45] op_sel:[0,0] op_sel_hi:[0,1]
	v_pk_fma_f32 v[52:53], v[52:53], v[44:45], v[66:67] op_sel:[1,1,0] op_sel_hi:[1,0,1] neg_lo:[0,1,0]
	v_pk_mul_f32 v[66:67], v[72:73], v[52:53] op_sel:[0,0] op_sel_hi:[0,1]
	v_pk_fma_f32 v[66:67], v[72:73], v[52:53], v[66:67] op_sel:[1,1,0] op_sel_hi:[1,0,1] neg_lo:[0,1,0]
	ds_write_b64 v74, v[66:67] offset:8704
	v_pk_mul_f32 v[66:67], v[52:53], v[44:45] op_sel:[0,0] op_sel_hi:[0,1]
	v_pk_fma_f32 v[52:53], v[52:53], v[44:45], v[66:67] op_sel:[1,1,0] op_sel_hi:[1,0,1] neg_lo:[0,1,0]
	v_pk_mul_f32 v[66:67], v[62:63], v[52:53] op_sel:[0,0] op_sel_hi:[0,1]
	v_pk_fma_f32 v[62:63], v[62:63], v[52:53], v[66:67] op_sel:[1,1,0] op_sel_hi:[1,0,1] neg_lo:[0,1,0]
	ds_write_b64 v74, v[62:63] offset:10880
	v_pk_mul_f32 v[62:63], v[52:53], v[44:45] op_sel:[0,0] op_sel_hi:[0,1]
	v_pk_fma_f32 v[52:53], v[52:53], v[44:45], v[62:63] op_sel:[1,1,0] op_sel_hi:[1,0,1] neg_lo:[0,1,0]
	v_pk_mul_f32 v[62:63], v[60:61], v[52:53] op_sel:[0,0] op_sel_hi:[0,1]
	v_pk_fma_f32 v[60:61], v[60:61], v[52:53], v[62:63] op_sel:[1,1,0] op_sel_hi:[1,0,1] neg_lo:[0,1,0]
	ds_write_b64 v74, v[60:61] offset:13056
	v_pk_mul_f32 v[60:61], v[52:53], v[44:45] op_sel:[0,0] op_sel_hi:[0,1]
	v_pk_fma_f32 v[52:53], v[52:53], v[44:45], v[60:61] op_sel:[1,1,0] op_sel_hi:[1,0,1] neg_lo:[0,1,0]
	v_pk_mul_f32 v[60:61], v[64:65], v[52:53] op_sel:[0,0] op_sel_hi:[0,1]
	v_pk_fma_f32 v[60:61], v[64:65], v[52:53], v[60:61] op_sel:[1,1,0] op_sel_hi:[1,0,1] neg_lo:[0,1,0]
	ds_write_b64 v74, v[60:61] offset:15232
	v_pk_mul_f32 v[60:61], v[52:53], v[44:45] op_sel:[0,0] op_sel_hi:[0,1]
	v_pk_fma_f32 v[52:53], v[52:53], v[44:45], v[60:61] op_sel:[1,1,0] op_sel_hi:[1,0,1] neg_lo:[0,1,0]
	v_pk_mul_f32 v[60:61], v[54:55], v[52:53] op_sel:[0,0] op_sel_hi:[0,1]
	v_pk_fma_f32 v[54:55], v[54:55], v[52:53], v[60:61] op_sel:[1,1,0] op_sel_hi:[1,0,1] neg_lo:[0,1,0]
	ds_write_b64 v74, v[54:55] offset:17408
	v_pk_mul_f32 v[54:55], v[52:53], v[44:45] op_sel:[0,0] op_sel_hi:[0,1]
	v_pk_fma_f32 v[52:53], v[52:53], v[44:45], v[54:55] op_sel:[1,1,0] op_sel_hi:[1,0,1] neg_lo:[0,1,0]
	v_pk_mul_f32 v[54:55], v[50:51], v[52:53] op_sel:[0,0] op_sel_hi:[0,1]
	v_pk_fma_f32 v[50:51], v[50:51], v[52:53], v[54:55] op_sel:[1,1,0] op_sel_hi:[1,0,1] neg_lo:[0,1,0]
	ds_write_b64 v74, v[50:51] offset:19584
	v_pk_mul_f32 v[50:51], v[52:53], v[44:45] op_sel:[0,0] op_sel_hi:[0,1]
	v_pk_fma_f32 v[50:51], v[52:53], v[44:45], v[50:51] op_sel:[1,1,0] op_sel_hi:[1,0,1] neg_lo:[0,1,0]
	v_pk_mul_f32 v[52:53], v[48:49], v[50:51] op_sel:[0,0] op_sel_hi:[0,1]
	v_pk_fma_f32 v[48:49], v[48:49], v[50:51], v[52:53] op_sel:[1,1,0] op_sel_hi:[1,0,1] neg_lo:[0,1,0]
	ds_write_b64 v74, v[48:49] offset:21760
	v_pk_mul_f32 v[48:49], v[50:51], v[44:45] op_sel:[0,0] op_sel_hi:[0,1]
	v_pk_fma_f32 v[48:49], v[50:51], v[44:45], v[48:49] op_sel:[1,1,0] op_sel_hi:[1,0,1] neg_lo:[0,1,0]
	v_pk_mul_f32 v[50:51], v[58:59], v[48:49] op_sel:[0,0] op_sel_hi:[0,1]
	v_pk_fma_f32 v[50:51], v[58:59], v[48:49], v[50:51] op_sel:[1,1,0] op_sel_hi:[1,0,1] neg_lo:[0,1,0]
	ds_write_b64 v74, v[50:51] offset:23936
	v_pk_mul_f32 v[50:51], v[48:49], v[44:45] op_sel:[0,0] op_sel_hi:[0,1]
	v_pk_fma_f32 v[48:49], v[48:49], v[44:45], v[50:51] op_sel:[1,1,0] op_sel_hi:[1,0,1] neg_lo:[0,1,0]
	v_pk_mul_f32 v[50:51], v[40:41], v[48:49] op_sel:[0,0] op_sel_hi:[0,1]
	v_pk_fma_f32 v[40:41], v[40:41], v[48:49], v[50:51] op_sel:[1,1,0] op_sel_hi:[1,0,1] neg_lo:[0,1,0]
	ds_write_b64 v74, v[40:41] offset:26112
	v_pk_mul_f32 v[40:41], v[48:49], v[44:45] op_sel:[0,0] op_sel_hi:[0,1]
	v_pk_fma_f32 v[40:41], v[48:49], v[44:45], v[40:41] op_sel:[1,1,0] op_sel_hi:[1,0,1] neg_lo:[0,1,0]
	v_pk_mul_f32 v[48:49], v[56:57], v[40:41] op_sel:[0,0] op_sel_hi:[0,1]
	v_pk_fma_f32 v[48:49], v[56:57], v[40:41], v[48:49] op_sel:[1,1,0] op_sel_hi:[1,0,1] neg_lo:[0,1,0]
	ds_write_b64 v74, v[48:49] offset:28288
	v_pk_mul_f32 v[48:49], v[40:41], v[44:45] op_sel:[0,0] op_sel_hi:[0,1]
	v_pk_fma_f32 v[40:41], v[40:41], v[44:45], v[48:49] op_sel:[1,1,0] op_sel_hi:[1,0,1] neg_lo:[0,1,0]
	v_pk_mul_f32 v[48:49], v[46:47], v[40:41] op_sel:[0,0] op_sel_hi:[0,1]
	v_pk_fma_f32 v[46:47], v[46:47], v[40:41], v[48:49] op_sel:[1,1,0] op_sel_hi:[1,0,1] neg_lo:[0,1,0]
	ds_write_b64 v74, v[46:47] offset:30464
	v_pk_mul_f32 v[46:47], v[40:41], v[44:45] op_sel:[0,0] op_sel_hi:[0,1]
	v_pk_fma_f32 v[40:41], v[40:41], v[44:45], v[46:47] op_sel:[1,1,0] op_sel_hi:[1,0,1] neg_lo:[0,1,0]
	v_pk_mul_f32 v[44:45], v[42:43], v[40:41] op_sel:[0,0] op_sel_hi:[0,1]
	v_pk_fma_f32 v[40:41], v[42:43], v[40:41], v[44:45] op_sel:[1,1,0] op_sel_hi:[1,0,1] neg_lo:[0,1,0]
	ds_write_b64 v74, v[40:41] offset:32640
	s_waitcnt lgkmcnt(0)
	s_barrier
	ds_read2_b64 v[40:43], v39 offset1:17
	ds_read2_b64 v[44:47], v39 offset0:34 offset1:51
	ds_read2_b64 v[48:51], v39 offset0:68 offset1:85
	ds_read2_b64 v[52:55], v39 offset0:136 offset1:153
	ds_read2_b64 v[56:59], v39 offset0:102 offset1:119
	ds_read2_b64 v[60:63], v39 offset0:204 offset1:221
	ds_read2_b64 v[64:67], v39 offset0:170 offset1:187
	ds_read2_b64 v[68:71], v39 offset0:238 offset1:255
	s_waitcnt lgkmcnt(4)
	v_pk_add_f32 v[72:73], v[40:41], v[52:53]
	v_pk_add_f32 v[40:41], v[40:41], v[52:53] neg_lo:[0,1] neg_hi:[0,1]
	s_waitcnt lgkmcnt(2)
	v_pk_add_f32 v[52:53], v[48:49], v[60:61]
	v_pk_add_f32 v[48:49], v[48:49], v[60:61] neg_lo:[0,1] neg_hi:[0,1]
	v_pk_add_f32 v[60:61], v[72:73], v[52:53]
	v_pk_add_f32 v[52:53], v[72:73], v[52:53] neg_lo:[0,1] neg_hi:[0,1]
	v_pk_add_f32 v[72:73], v[40:41], v[48:49] op_sel:[0,1] op_sel_hi:[1,0] neg_hi:[0,1]
	v_pk_add_f32 v[40:41], v[40:41], v[48:49] op_sel:[0,1] op_sel_hi:[1,0] neg_lo:[0,1]
	v_pk_add_f32 v[48:49], v[42:43], v[54:55]
	v_pk_add_f32 v[42:43], v[42:43], v[54:55] neg_lo:[0,1] neg_hi:[0,1]
	v_pk_add_f32 v[54:55], v[50:51], v[62:63]
	v_pk_add_f32 v[50:51], v[50:51], v[62:63] neg_lo:[0,1] neg_hi:[0,1]
	v_pk_add_f32 v[62:63], v[48:49], v[54:55]
	v_pk_add_f32 v[48:49], v[48:49], v[54:55] neg_lo:[0,1] neg_hi:[0,1]
	v_pk_add_f32 v[54:55], v[42:43], v[50:51] op_sel:[0,1] op_sel_hi:[1,0] neg_hi:[0,1]
	v_pk_add_f32 v[42:43], v[42:43], v[50:51] op_sel:[0,1] op_sel_hi:[1,0] neg_lo:[0,1]
	s_waitcnt lgkmcnt(1)
	v_pk_add_f32 v[50:51], v[44:45], v[64:65]
	v_pk_add_f32 v[44:45], v[44:45], v[64:65] neg_lo:[0,1] neg_hi:[0,1]
	s_waitcnt lgkmcnt(0)
	v_pk_add_f32 v[64:65], v[56:57], v[68:69]
	v_pk_add_f32 v[56:57], v[56:57], v[68:69] neg_lo:[0,1] neg_hi:[0,1]
	v_pk_add_f32 v[68:69], v[50:51], v[64:65]
	v_pk_add_f32 v[50:51], v[50:51], v[64:65] neg_lo:[0,1] neg_hi:[0,1]
	v_pk_add_f32 v[64:65], v[44:45], v[56:57] op_sel:[0,1] op_sel_hi:[1,0] neg_hi:[0,1]
	v_pk_add_f32 v[44:45], v[44:45], v[56:57] op_sel:[0,1] op_sel_hi:[1,0] neg_lo:[0,1]
	v_pk_add_f32 v[56:57], v[46:47], v[66:67]
	v_pk_add_f32 v[46:47], v[46:47], v[66:67] neg_lo:[0,1] neg_hi:[0,1]
	v_pk_add_f32 v[66:67], v[58:59], v[70:71]
	v_pk_add_f32 v[58:59], v[58:59], v[70:71] neg_lo:[0,1] neg_hi:[0,1]
	v_pk_add_f32 v[70:71], v[56:57], v[66:67]
	v_pk_add_f32 v[56:57], v[56:57], v[66:67] neg_lo:[0,1] neg_hi:[0,1]
	v_pk_add_f32 v[66:67], v[46:47], v[58:59] op_sel:[0,1] op_sel_hi:[1,0] neg_hi:[0,1]
	v_pk_add_f32 v[46:47], v[46:47], v[58:59] op_sel:[0,1] op_sel_hi:[1,0] neg_lo:[0,1]
	v_pk_mul_f32 v[58:59], v[54:55], v[24:25] op_sel:[0,0] op_sel_hi:[0,1]
	v_pk_fma_f32 v[54:55], v[54:55], v[24:25], v[58:59] op_sel:[1,1,0] op_sel_hi:[1,0,1] neg_lo:[0,1,0]
	v_pk_mul_f32 v[58:59], v[64:65], v[20:21] op_sel:[0,0] op_sel_hi:[0,1]
	v_pk_fma_f32 v[58:59], v[64:65], v[20:21], v[58:59] op_sel:[1,1,0] op_sel_hi:[1,0,1] neg_lo:[0,1,0]
	v_pk_mul_f32 v[64:65], v[66:67], v[18:19] op_sel:[0,0] op_sel_hi:[0,1]
	v_pk_fma_f32 v[64:65], v[66:67], v[18:19], v[64:65] op_sel:[1,1,0] op_sel_hi:[1,0,1] neg_lo:[0,1,0]
	v_pk_mul_f32 v[66:67], v[48:49], v[20:21] op_sel:[0,0] op_sel_hi:[0,1]
	v_pk_fma_f32 v[48:49], v[48:49], v[20:21], v[66:67] op_sel:[1,1,0] op_sel_hi:[1,0,1] neg_lo:[0,1,0]
	v_pk_mul_f32 v[66:67], v[50:51], v[26:27] op_sel:[0,0] op_sel_hi:[0,1]
	v_pk_fma_f32 v[50:51], v[50:51], v[26:27], v[66:67] op_sel:[1,1,0] op_sel_hi:[1,0,1] neg_lo:[0,1,0]
	v_pk_mul_f32 v[66:67], v[56:57], v[22:23] op_sel:[0,0] op_sel_hi:[0,1]
	v_pk_fma_f32 v[56:57], v[56:57], v[22:23], v[66:67] op_sel:[1,1,0] op_sel_hi:[1,0,1] neg_lo:[0,1,0]
	v_pk_mul_f32 v[66:67], v[42:43], v[18:19] op_sel:[0,0] op_sel_hi:[0,1]
	v_pk_fma_f32 v[42:43], v[42:43], v[18:19], v[66:67] op_sel:[1,1,0] op_sel_hi:[1,0,1] neg_lo:[0,1,0]
	v_pk_mul_f32 v[66:67], v[44:45], v[22:23] op_sel:[0,0] op_sel_hi:[0,1]
	v_pk_fma_f32 v[44:45], v[44:45], v[22:23], v[66:67] op_sel:[1,1,0] op_sel_hi:[1,0,1] neg_lo:[0,1,0]
	v_pk_mul_f32 v[66:67], v[46:47], v[28:29] op_sel:[0,0] op_sel_hi:[0,1]
	v_pk_fma_f32 v[46:47], v[46:47], v[28:29], v[66:67] op_sel:[1,1,0] op_sel_hi:[1,0,1] neg_lo:[0,1,0]
	v_pk_add_f32 v[66:67], v[60:61], v[68:69]
	v_pk_add_f32 v[60:61], v[60:61], v[68:69] neg_lo:[0,1] neg_hi:[0,1]
	v_pk_add_f32 v[68:69], v[62:63], v[70:71]
	v_pk_add_f32 v[62:63], v[62:63], v[70:71] neg_lo:[0,1] neg_hi:[0,1]
	v_pk_add_f32 v[70:71], v[66:67], v[68:69]
	v_pk_add_f32 v[66:67], v[66:67], v[68:69] neg_lo:[0,1] neg_hi:[0,1]
	v_pk_add_f32 v[68:69], v[60:61], v[62:63] op_sel:[0,1] op_sel_hi:[1,0] neg_hi:[0,1]
	v_pk_add_f32 v[60:61], v[60:61], v[62:63] op_sel:[0,1] op_sel_hi:[1,0] neg_lo:[0,1]
	v_pk_add_f32 v[62:63], v[72:73], v[58:59]
	v_pk_add_f32 v[58:59], v[72:73], v[58:59] neg_lo:[0,1] neg_hi:[0,1]
	v_pk_add_f32 v[72:73], v[54:55], v[64:65]
	v_pk_add_f32 v[54:55], v[54:55], v[64:65] neg_lo:[0,1] neg_hi:[0,1]
	v_pk_add_f32 v[64:65], v[62:63], v[72:73]
	v_pk_add_f32 v[62:63], v[62:63], v[72:73] neg_lo:[0,1] neg_hi:[0,1]
	v_pk_add_f32 v[72:73], v[58:59], v[54:55] op_sel:[0,1] op_sel_hi:[1,0] neg_hi:[0,1]
	v_pk_add_f32 v[54:55], v[58:59], v[54:55] op_sel:[0,1] op_sel_hi:[1,0] neg_lo:[0,1]
	v_pk_add_f32 v[58:59], v[52:53], v[50:51]
	v_pk_add_f32 v[50:51], v[52:53], v[50:51] neg_lo:[0,1] neg_hi:[0,1]
	v_pk_add_f32 v[52:53], v[48:49], v[56:57]
	v_pk_add_f32 v[48:49], v[48:49], v[56:57] neg_lo:[0,1] neg_hi:[0,1]
	v_pk_add_f32 v[56:57], v[58:59], v[52:53]
	v_pk_add_f32 v[52:53], v[58:59], v[52:53] neg_lo:[0,1] neg_hi:[0,1]
	v_pk_add_f32 v[58:59], v[50:51], v[48:49] op_sel:[0,1] op_sel_hi:[1,0] neg_hi:[0,1]
	v_pk_add_f32 v[48:49], v[50:51], v[48:49] op_sel:[0,1] op_sel_hi:[1,0] neg_lo:[0,1]
	v_pk_add_f32 v[50:51], v[40:41], v[44:45]
	v_pk_add_f32 v[40:41], v[40:41], v[44:45] neg_lo:[0,1] neg_hi:[0,1]
	v_pk_add_f32 v[44:45], v[42:43], v[46:47]
	v_pk_add_f32 v[42:43], v[42:43], v[46:47] neg_lo:[0,1] neg_hi:[0,1]
	v_pk_add_f32 v[46:47], v[50:51], v[44:45]
	v_pk_add_f32 v[44:45], v[50:51], v[44:45] neg_lo:[0,1] neg_hi:[0,1]
	v_pk_add_f32 v[50:51], v[40:41], v[42:43] op_sel:[0,1] op_sel_hi:[1,0] neg_hi:[0,1]
	v_pk_add_f32 v[40:41], v[40:41], v[42:43] op_sel:[0,1] op_sel_hi:[1,0] neg_lo:[0,1]
	v_mov_b32_e32 v42, v30
	v_mov_b32_e32 v43, v32
	s_nop 0
	v_pk_mul_f32 v[74:75], v[64:65], v[42:43] op_sel:[0,0] op_sel_hi:[0,1]
	v_pk_fma_f32 v[64:65], v[64:65], v[42:43], v[74:75] op_sel:[1,1,0] op_sel_hi:[1,0,1] neg_lo:[0,1,0]
	ds_write2_b64 v39, v[70:71], v[64:65] offset1:17
	v_pk_mul_f32 v[64:65], v[42:43], v[42:43] op_sel:[0,0] op_sel_hi:[0,1]
	v_pk_fma_f32 v[64:65], v[42:43], v[42:43], v[64:65] op_sel:[1,1,0] op_sel_hi:[1,0,1] neg_lo:[0,1,0]
	v_pk_mul_f32 v[70:71], v[56:57], v[64:65] op_sel:[0,0] op_sel_hi:[0,1]
	v_pk_fma_f32 v[56:57], v[56:57], v[64:65], v[70:71] op_sel:[1,1,0] op_sel_hi:[1,0,1] neg_lo:[0,1,0]
	v_pk_mul_f32 v[70:71], v[64:65], v[42:43] op_sel:[0,0] op_sel_hi:[0,1]
	v_pk_fma_f32 v[64:65], v[64:65], v[42:43], v[70:71] op_sel:[1,1,0] op_sel_hi:[1,0,1] neg_lo:[0,1,0]
	v_pk_mul_f32 v[70:71], v[46:47], v[64:65] op_sel:[0,0] op_sel_hi:[0,1]
	v_pk_fma_f32 v[46:47], v[46:47], v[64:65], v[70:71] op_sel:[1,1,0] op_sel_hi:[1,0,1] neg_lo:[0,1,0]
	ds_write2_b64 v39, v[56:57], v[46:47] offset0:34 offset1:51
	v_pk_mul_f32 v[46:47], v[64:65], v[42:43] op_sel:[0,0] op_sel_hi:[0,1]
	v_pk_fma_f32 v[46:47], v[64:65], v[42:43], v[46:47] op_sel:[1,1,0] op_sel_hi:[1,0,1] neg_lo:[0,1,0]
	v_pk_mul_f32 v[56:57], v[68:69], v[46:47] op_sel:[0,0] op_sel_hi:[0,1]
	v_pk_mul_f32 v[64:65], v[46:47], v[42:43] op_sel:[0,0] op_sel_hi:[0,1]
	v_pk_fma_f32 v[56:57], v[68:69], v[46:47], v[56:57] op_sel:[1,1,0] op_sel_hi:[1,0,1] neg_lo:[0,1,0]
	v_pk_fma_f32 v[46:47], v[46:47], v[42:43], v[64:65] op_sel:[1,1,0] op_sel_hi:[1,0,1] neg_lo:[0,1,0]
	v_pk_mul_f32 v[64:65], v[72:73], v[46:47] op_sel:[0,0] op_sel_hi:[0,1]
	v_pk_fma_f32 v[64:65], v[72:73], v[46:47], v[64:65] op_sel:[1,1,0] op_sel_hi:[1,0,1] neg_lo:[0,1,0]
	ds_write2_b64 v39, v[56:57], v[64:65] offset0:68 offset1:85
	v_pk_mul_f32 v[56:57], v[46:47], v[42:43] op_sel:[0,0] op_sel_hi:[0,1]
	v_pk_fma_f32 v[46:47], v[46:47], v[42:43], v[56:57] op_sel:[1,1,0] op_sel_hi:[1,0,1] neg_lo:[0,1,0]
	v_pk_mul_f32 v[56:57], v[58:59], v[46:47] op_sel:[0,0] op_sel_hi:[0,1]
	v_pk_fma_f32 v[56:57], v[58:59], v[46:47], v[56:57] op_sel:[1,1,0] op_sel_hi:[1,0,1] neg_lo:[0,1,0]
	v_pk_mul_f32 v[58:59], v[46:47], v[42:43] op_sel:[0,0] op_sel_hi:[0,1]
	v_pk_fma_f32 v[46:47], v[46:47], v[42:43], v[58:59] op_sel:[1,1,0] op_sel_hi:[1,0,1] neg_lo:[0,1,0]
	v_pk_mul_f32 v[58:59], v[50:51], v[46:47] op_sel:[0,0] op_sel_hi:[0,1]
	v_pk_fma_f32 v[50:51], v[50:51], v[46:47], v[58:59] op_sel:[1,1,0] op_sel_hi:[1,0,1] neg_lo:[0,1,0]
	ds_write2_b64 v39, v[56:57], v[50:51] offset0:102 offset1:119
	v_pk_mul_f32 v[50:51], v[46:47], v[42:43] op_sel:[0,0] op_sel_hi:[0,1]
	v_pk_fma_f32 v[46:47], v[46:47], v[42:43], v[50:51] op_sel:[1,1,0] op_sel_hi:[1,0,1] neg_lo:[0,1,0]
	v_pk_mul_f32 v[50:51], v[66:67], v[46:47] op_sel:[0,0] op_sel_hi:[0,1]
	v_pk_mul_f32 v[56:57], v[46:47], v[42:43] op_sel:[0,0] op_sel_hi:[0,1]
	v_pk_fma_f32 v[50:51], v[66:67], v[46:47], v[50:51] op_sel:[1,1,0] op_sel_hi:[1,0,1] neg_lo:[0,1,0]
	v_pk_fma_f32 v[46:47], v[46:47], v[42:43], v[56:57] op_sel:[1,1,0] op_sel_hi:[1,0,1] neg_lo:[0,1,0]
	v_pk_mul_f32 v[56:57], v[62:63], v[46:47] op_sel:[0,0] op_sel_hi:[0,1]
	v_pk_fma_f32 v[56:57], v[62:63], v[46:47], v[56:57] op_sel:[1,1,0] op_sel_hi:[1,0,1] neg_lo:[0,1,0]
	ds_write2_b64 v39, v[50:51], v[56:57] offset0:136 offset1:153
	v_pk_mul_f32 v[50:51], v[46:47], v[42:43] op_sel:[0,0] op_sel_hi:[0,1]
	v_pk_fma_f32 v[46:47], v[46:47], v[42:43], v[50:51] op_sel:[1,1,0] op_sel_hi:[1,0,1] neg_lo:[0,1,0]
	v_pk_mul_f32 v[50:51], v[52:53], v[46:47] op_sel:[0,0] op_sel_hi:[0,1]
	v_pk_fma_f32 v[50:51], v[52:53], v[46:47], v[50:51] op_sel:[1,1,0] op_sel_hi:[1,0,1] neg_lo:[0,1,0]
	v_pk_mul_f32 v[52:53], v[46:47], v[42:43] op_sel:[0,0] op_sel_hi:[0,1]
	v_pk_fma_f32 v[46:47], v[46:47], v[42:43], v[52:53] op_sel:[1,1,0] op_sel_hi:[1,0,1] neg_lo:[0,1,0]
	v_pk_mul_f32 v[52:53], v[44:45], v[46:47] op_sel:[0,0] op_sel_hi:[0,1]
	v_pk_fma_f32 v[44:45], v[44:45], v[46:47], v[52:53] op_sel:[1,1,0] op_sel_hi:[1,0,1] neg_lo:[0,1,0]
	ds_write2_b64 v39, v[50:51], v[44:45] offset0:170 offset1:187
	v_pk_mul_f32 v[44:45], v[46:47], v[42:43] op_sel:[0,0] op_sel_hi:[0,1]
	v_pk_fma_f32 v[44:45], v[46:47], v[42:43], v[44:45] op_sel:[1,1,0] op_sel_hi:[1,0,1] neg_lo:[0,1,0]
	v_pk_mul_f32 v[46:47], v[60:61], v[44:45] op_sel:[0,0] op_sel_hi:[0,1]
	v_pk_mul_f32 v[50:51], v[44:45], v[42:43] op_sel:[0,0] op_sel_hi:[0,1]
	v_pk_fma_f32 v[46:47], v[60:61], v[44:45], v[46:47] op_sel:[1,1,0] op_sel_hi:[1,0,1] neg_lo:[0,1,0]
	v_pk_fma_f32 v[44:45], v[44:45], v[42:43], v[50:51] op_sel:[1,1,0] op_sel_hi:[1,0,1] neg_lo:[0,1,0]
	v_pk_mul_f32 v[50:51], v[54:55], v[44:45] op_sel:[0,0] op_sel_hi:[0,1]
	v_pk_fma_f32 v[50:51], v[54:55], v[44:45], v[50:51] op_sel:[1,1,0] op_sel_hi:[1,0,1] neg_lo:[0,1,0]
	ds_write2_b64 v39, v[46:47], v[50:51] offset0:204 offset1:221
	v_pk_mul_f32 v[46:47], v[44:45], v[42:43] op_sel:[0,0] op_sel_hi:[0,1]
	v_pk_fma_f32 v[44:45], v[44:45], v[42:43], v[46:47] op_sel:[1,1,0] op_sel_hi:[1,0,1] neg_lo:[0,1,0]
	v_pk_mul_f32 v[46:47], v[48:49], v[44:45] op_sel:[0,0] op_sel_hi:[0,1]
	v_pk_fma_f32 v[46:47], v[48:49], v[44:45], v[46:47] op_sel:[1,1,0] op_sel_hi:[1,0,1] neg_lo:[0,1,0]
	v_pk_mul_f32 v[48:49], v[44:45], v[42:43] op_sel:[0,0] op_sel_hi:[0,1]
	v_pk_fma_f32 v[42:43], v[44:45], v[42:43], v[48:49] op_sel:[1,1,0] op_sel_hi:[1,0,1] neg_lo:[0,1,0]
	v_pk_mul_f32 v[44:45], v[40:41], v[42:43] op_sel:[0,0] op_sel_hi:[0,1]
	v_pk_fma_f32 v[40:41], v[40:41], v[42:43], v[44:45] op_sel:[1,1,0] op_sel_hi:[1,0,1] neg_lo:[0,1,0]
	ds_write2_b64 v39, v[46:47], v[40:41] offset0:238 offset1:255
	v_mad_u32_u24 v39, v34, s55, v35
	s_waitcnt lgkmcnt(0)
	s_barrier
	ds_read2_b64 v[40:43], v39 offset1:1
	ds_read2_b64 v[44:47], v39 offset0:2 offset1:3
	ds_read2_b64 v[48:51], v39 offset0:8 offset1:9
	ds_read2_b64 v[52:55], v39 offset0:4 offset1:5
	ds_read2_b64 v[56:59], v39 offset0:6 offset1:7
	ds_read2_b64 v[60:63], v39 offset0:12 offset1:13
	ds_read2_b64 v[64:67], v39 offset0:10 offset1:11
	ds_read2_b64 v[68:71], v39 offset0:14 offset1:15
	s_waitcnt lgkmcnt(5)
	v_pk_add_f32 v[72:73], v[40:41], v[48:49]
	v_pk_add_f32 v[40:41], v[40:41], v[48:49] neg_lo:[0,1] neg_hi:[0,1]
	s_waitcnt lgkmcnt(2)
	v_pk_add_f32 v[48:49], v[52:53], v[60:61]
	v_pk_add_f32 v[52:53], v[52:53], v[60:61] neg_lo:[0,1] neg_hi:[0,1]
	v_pk_add_f32 v[60:61], v[72:73], v[48:49]
	v_pk_add_f32 v[48:49], v[72:73], v[48:49] neg_lo:[0,1] neg_hi:[0,1]
	v_pk_add_f32 v[72:73], v[40:41], v[52:53] op_sel:[0,1] op_sel_hi:[1,0] neg_hi:[0,1]
	v_pk_add_f32 v[40:41], v[40:41], v[52:53] op_sel:[0,1] op_sel_hi:[1,0] neg_lo:[0,1]
	v_pk_add_f32 v[52:53], v[42:43], v[50:51]
	v_pk_add_f32 v[42:43], v[42:43], v[50:51] neg_lo:[0,1] neg_hi:[0,1]
	v_pk_add_f32 v[50:51], v[54:55], v[62:63]
	v_pk_add_f32 v[54:55], v[54:55], v[62:63] neg_lo:[0,1] neg_hi:[0,1]
	v_pk_add_f32 v[62:63], v[52:53], v[50:51]
	v_pk_add_f32 v[50:51], v[52:53], v[50:51] neg_lo:[0,1] neg_hi:[0,1]
	v_pk_add_f32 v[52:53], v[42:43], v[54:55] op_sel:[0,1] op_sel_hi:[1,0] neg_hi:[0,1]
	v_pk_add_f32 v[42:43], v[42:43], v[54:55] op_sel:[0,1] op_sel_hi:[1,0] neg_lo:[0,1]
	s_waitcnt lgkmcnt(1)
	v_pk_add_f32 v[54:55], v[44:45], v[64:65]
	v_pk_add_f32 v[44:45], v[44:45], v[64:65] neg_lo:[0,1] neg_hi:[0,1]
	s_waitcnt lgkmcnt(0)
	v_pk_add_f32 v[64:65], v[56:57], v[68:69]
	v_pk_add_f32 v[56:57], v[56:57], v[68:69] neg_lo:[0,1] neg_hi:[0,1]
	v_pk_add_f32 v[68:69], v[54:55], v[64:65]
	v_pk_add_f32 v[54:55], v[54:55], v[64:65] neg_lo:[0,1] neg_hi:[0,1]
	v_pk_add_f32 v[64:65], v[44:45], v[56:57] op_sel:[0,1] op_sel_hi:[1,0] neg_hi:[0,1]
	v_pk_add_f32 v[44:45], v[44:45], v[56:57] op_sel:[0,1] op_sel_hi:[1,0] neg_lo:[0,1]
	v_pk_add_f32 v[56:57], v[46:47], v[66:67]
	v_pk_add_f32 v[46:47], v[46:47], v[66:67] neg_lo:[0,1] neg_hi:[0,1]
	v_pk_add_f32 v[66:67], v[58:59], v[70:71]
	v_pk_add_f32 v[58:59], v[58:59], v[70:71] neg_lo:[0,1] neg_hi:[0,1]
	v_pk_add_f32 v[70:71], v[56:57], v[66:67]
	v_pk_add_f32 v[56:57], v[56:57], v[66:67] neg_lo:[0,1] neg_hi:[0,1]
	v_pk_add_f32 v[66:67], v[46:47], v[58:59] op_sel:[0,1] op_sel_hi:[1,0] neg_hi:[0,1]
	v_pk_add_f32 v[46:47], v[46:47], v[58:59] op_sel:[0,1] op_sel_hi:[1,0] neg_lo:[0,1]
	v_pk_mul_f32 v[58:59], v[52:53], v[24:25] op_sel:[0,0] op_sel_hi:[0,1]
	v_pk_fma_f32 v[24:25], v[52:53], v[24:25], v[58:59] op_sel:[1,1,0] op_sel_hi:[1,0,1] neg_lo:[0,1,0]
	v_pk_mul_f32 v[52:53], v[64:65], v[20:21] op_sel:[0,0] op_sel_hi:[0,1]
	v_pk_mul_f32 v[58:59], v[66:67], v[18:19] op_sel:[0,0] op_sel_hi:[0,1]
	s_barrier
	v_pk_fma_f32 v[52:53], v[64:65], v[20:21], v[52:53] op_sel:[1,1,0] op_sel_hi:[1,0,1] neg_lo:[0,1,0]
	v_pk_mul_f32 v[64:65], v[50:51], v[20:21] op_sel:[0,0] op_sel_hi:[0,1]
	v_pk_fma_f32 v[58:59], v[66:67], v[18:19], v[58:59] op_sel:[1,1,0] op_sel_hi:[1,0,1] neg_lo:[0,1,0]
	v_pk_fma_f32 v[20:21], v[50:51], v[20:21], v[64:65] op_sel:[1,1,0] op_sel_hi:[1,0,1] neg_lo:[0,1,0]
	v_pk_mul_f32 v[50:51], v[54:55], v[26:27] op_sel:[0,0] op_sel_hi:[0,1]
	v_pk_fma_f32 v[26:27], v[54:55], v[26:27], v[50:51] op_sel:[1,1,0] op_sel_hi:[1,0,1] neg_lo:[0,1,0]
	v_pk_mul_f32 v[50:51], v[56:57], v[22:23] op_sel:[0,0] op_sel_hi:[0,1]
	v_pk_mul_f32 v[54:55], v[42:43], v[18:19] op_sel:[0,0] op_sel_hi:[0,1]
	v_pk_fma_f32 v[18:19], v[42:43], v[18:19], v[54:55] op_sel:[1,1,0] op_sel_hi:[1,0,1] neg_lo:[0,1,0]
	v_pk_mul_f32 v[42:43], v[44:45], v[22:23] op_sel:[0,0] op_sel_hi:[0,1]
	v_pk_fma_f32 v[50:51], v[56:57], v[22:23], v[50:51] op_sel:[1,1,0] op_sel_hi:[1,0,1] neg_lo:[0,1,0]
	v_pk_add_f32 v[54:55], v[24:25], v[58:59] neg_lo:[0,1] neg_hi:[0,1]
	v_pk_fma_f32 v[22:23], v[44:45], v[22:23], v[42:43] op_sel:[1,1,0] op_sel_hi:[1,0,1] neg_lo:[0,1,0]
	v_pk_mul_f32 v[42:43], v[46:47], v[28:29] op_sel:[0,0] op_sel_hi:[0,1]
	v_pk_add_f32 v[44:45], v[62:63], v[70:71] neg_lo:[0,1] neg_hi:[0,1]
	v_pk_fma_f32 v[28:29], v[46:47], v[28:29], v[42:43] op_sel:[1,1,0] op_sel_hi:[1,0,1] neg_lo:[0,1,0]
	v_pk_add_f32 v[42:43], v[60:61], v[68:69] neg_lo:[0,1] neg_hi:[0,1]
	v_pk_add_f32 v[74:75], v[18:19], v[28:29] neg_lo:[0,1] neg_hi:[0,1]
	v_pk_add_f32 v[46:47], v[42:43], v[44:45] op_sel:[0,1] op_sel_hi:[1,0] neg_hi:[0,1]
	v_pk_add_f32 v[42:43], v[42:43], v[44:45] op_sel:[0,1] op_sel_hi:[1,0] neg_lo:[0,1]
	v_pk_add_f32 v[44:45], v[72:73], v[52:53] neg_lo:[0,1] neg_hi:[0,1]
	v_and_b32_e32 v19, 0xf0, v36
	v_pk_add_f32 v[56:57], v[44:45], v[54:55] op_sel:[0,1] op_sel_hi:[1,0] neg_hi:[0,1]
	v_pk_add_f32 v[44:45], v[44:45], v[54:55] op_sel:[0,1] op_sel_hi:[1,0] neg_lo:[0,1]
	v_pk_add_f32 v[54:55], v[48:49], v[26:27] neg_lo:[0,1] neg_hi:[0,1]
	v_pk_add_f32 v[64:65], v[20:21], v[50:51] neg_lo:[0,1] neg_hi:[0,1]
	v_mul_i32_i24_e32 v21, 0xfffff804, v38
	v_lshlrev_b32_e32 v19, 2, v19
	v_pk_add_f32 v[66:67], v[54:55], v[64:65] op_sel:[0,1] op_sel_hi:[1,0] neg_hi:[0,1]
	v_pk_add_f32 v[54:55], v[54:55], v[64:65] op_sel:[0,1] op_sel_hi:[1,0] neg_lo:[0,1]
	v_pk_add_f32 v[64:65], v[40:41], v[22:23] neg_lo:[0,1] neg_hi:[0,1]
	v_add3_u32 v19, v78, v21, v19
	v_add_f32_e32 v21, v62, v70
	v_add_f32_e32 v23, v60, v68
	v_add_f32_e32 v24, v24, v58
	v_add_f32_e32 v27, v72, v52
	v_add_f32_e32 v25, v23, v21
	v_add_f32_e32 v29, v27, v24
	v_mul_f32_e32 v25, 0x3a800000, v25
	v_mul_f32_e32 v29, 0x3a800000, v29
	ds_write2st64_b32 v19, v25, v29 offset1:4
	v_add_f32_e32 v20, v20, v50
	v_add_f32_e32 v25, v48, v26
	v_add_f32_e32 v18, v18, v28
	v_add_f32_e32 v22, v40, v22
	v_add_f32_e32 v26, v25, v20
	v_add_f32_e32 v28, v22, v18
	v_sub_f32_e32 v20, v25, v20
	v_sub_f32_e32 v18, v22, v18
	v_mul_f32_e32 v26, 0x3a800000, v26
	v_mul_f32_e32 v28, 0x3a800000, v28
	v_mul_f32_e32 v20, 0x3a800000, v20
	v_mul_f32_e32 v18, 0x3a800000, v18
	ds_write2st64_b32 v19, v26, v28 offset0:8 offset1:12
	v_mul_f32_e32 v26, 0x3a800000, v46
	v_mul_f32_e32 v28, 0x3a800000, v56
	v_sub_f32_e32 v21, v23, v21
	v_sub_f32_e32 v23, v27, v24
	ds_write2st64_b32 v19, v20, v18 offset0:40 offset1:44
	v_mul_f32_e32 v18, 0x3a800000, v42
	v_mul_f32_e32 v20, 0x3a800000, v44
	v_pk_add_f32 v[76:77], v[64:65], v[74:75] op_sel:[0,1] op_sel_hi:[1,0] neg_hi:[0,1]
	v_pk_add_f32 v[64:65], v[64:65], v[74:75] op_sel:[0,1] op_sel_hi:[1,0] neg_lo:[0,1]
	ds_write2st64_b32 v19, v26, v28 offset0:16 offset1:20
	v_mul_f32_e32 v26, 0x3a800000, v66
	v_mul_f32_e32 v28, 0x3a800000, v76
	v_mul_f32_e32 v21, 0x3a800000, v21
	v_mul_f32_e32 v23, 0x3a800000, v23
	ds_write2st64_b32 v19, v18, v20 offset0:48 offset1:52
	v_mul_f32_e32 v18, 0x3a800000, v54
	v_mul_f32_e32 v20, 0x3a800000, v64
	v_mov_b32_e32 v22, v34
	ds_write2st64_b32 v19, v26, v28 offset0:24 offset1:28
	ds_write2st64_b32 v19, v21, v23 offset0:32 offset1:36
	ds_write2st64_b32 v19, v18, v20 offset0:56 offset1:60
	s_waitcnt lgkmcnt(0)
	s_barrier
	v_lshlrev_b32_e32 v26, 12, v37
	v_lshl_add_u32 v23, v22, 5, v35
	ds_read_b128 v[18:21], v23
	v_lshlrev_b32_e32 v28, 3, v22
	ds_read_b128 v[22:25], v23 offset:16
	v_ashrrev_i32_e32 v27, 31, v26
	v_lshlrev_b64 v[26:27], 1, v[26:27]
	s_waitcnt lgkmcnt(1)
	v_cvt_pk_bf16_f32 v18, v18, v18
	v_lshrrev_b32_e32 v18, 16, v18
	v_cvt_pk_bf16_f32 v19, v19, v19
	v_and_or_b32 v18, v19, s57, v18
	v_cvt_pk_bf16_f32 v19, v20, v21
	s_waitcnt lgkmcnt(0)
	v_cvt_pk_bf16_f32 v20, v22, v23
	v_cvt_pk_bf16_f32 v21, v24, v25
	v_ashrrev_i32_e32 v29, 31, v28
	v_lshl_add_u64 v[22:23], v[28:29], 1, v[26:27]
	v_lshl_add_u64 v[22:23], s[26:27], 0, v[22:23]
	global_store_dwordx4 v[22:23], v[18:21], off
	s_nop 0
	v_lshl_add_u32 v22, v34, 5, v35
	ds_read_b128 v[18:21], v22 offset:8192
	ds_read_b128 v[22:25], v22 offset:8208
	v_lshl_add_u32 v28, v34, 3, v33
	s_waitcnt lgkmcnt(1)
	v_cvt_pk_bf16_f32 v18, v18, v18
	v_lshrrev_b32_e32 v18, 16, v18
	v_cvt_pk_bf16_f32 v19, v19, v19
	v_and_or_b32 v18, v19, s57, v18
	v_cvt_pk_bf16_f32 v19, v20, v21
	s_waitcnt lgkmcnt(0)
	v_cvt_pk_bf16_f32 v20, v22, v23
	v_cvt_pk_bf16_f32 v21, v24, v25
	v_ashrrev_i32_e32 v29, 31, v28
	v_lshl_add_u64 v[22:23], v[28:29], 1, v[26:27]
	v_lshl_add_u64 v[22:23], s[26:27], 0, v[22:23]
	s_add_u32 s26, s26, s34
	s_addc_u32 s27, s27, s35
	s_andn2_b64 vcc, exec, s[50:51]
	global_store_dwordx4 v[22:23], v[18:21], off
	s_barrier
	s_cbranch_vccz .LBB0_1712

.LBB0_1768:
	s_or_b64 exec, exec, s[52:53]
	s_lshl_b64 s[52:53], s[50:51], 15
	v_ashrrev_i32_e32 v91, 6, v38
	s_add_u32 s28, s65, s52
	v_lshlrev_b32_e32 v50, 3, v91
	v_lshlrev_b32_e32 v34, 1, v34
	s_addc_u32 s29, s64, s53
	v_add_u32_e32 v90, 0, v34
	v_lshl_add_u64 v[54:55], s[28:29], 0, v[34:35]
	v_add_u32_e32 v34, s91, v50
	v_and_b32_e32 v34, 0xfffffef8, v34
	v_cmp_eq_u32_e32 vcc, 0, v34
	s_waitcnt vmcnt(25)
	v_lshlrev_b32_e32 v96, 16, v66
	v_and_b32_e32 v94, 0xffff0000, v66
	v_lshlrev_b32_e32 v97, 16, v67
	v_and_b32_e32 v95, 0xffff0000, v67
	v_lshlrev_b32_e32 v67, 16, v59
	v_lshlrev_b32_e32 v66, 16, v58
	v_and_b32_e32 v101, 0xffff0000, v59
	v_and_b32_e32 v100, 0xffff0000, v58
	s_waitcnt vmcnt(3)
	v_mov_b32_e32 v58, v2
	v_mov_b32_e32 v59, v4
	v_mov_b32_e32 v4, v3
	v_mov_b32_e32 v2, v30
	v_mov_b32_e32 v3, v32
	v_cndmask_b32_e64 v34, 1.0, 0, vcc
	v_lshlrev_b32_e32 v87, 16, v65
	v_lshlrev_b32_e32 v86, 16, v64
	v_and_b32_e32 v105, 0xffff0000, v65
	v_and_b32_e32 v104, 0xffff0000, v64
	v_pk_mul_f32 v[64:65], v[2:3], v[66:67]
	v_pk_mul_f32 v[102:103], v[58:59], v[86:87]
	v_pk_mul_f32 v[66:67], v[64:65], v[34:35] op_sel_hi:[1,0]
	v_mov_b32_e32 v64, v26
	v_mov_b32_e32 v65, v28
	v_lshlrev_b32_e32 v89, 16, v69
	v_lshlrev_b32_e32 v88, 16, v68
	v_and_b32_e32 v87, 0xffff0000, v69
	v_and_b32_e32 v86, 0xffff0000, v68
	v_pk_fma_f32 v[68:69], v[64:65], v[96:97], v[66:67]
	v_mov_b32_e32 v66, v18
	v_mov_b32_e32 v67, v20
	v_mov_b32_e32 v32, v31
	v_pk_fma_f32 v[106:107], v[66:67], v[88:89], v[68:69]
	v_mov_b32_e32 v68, v22
	v_mov_b32_e32 v69, v24
	v_pk_mul_f32 v[30:31], v[32:33], v[100:101]
	v_pk_add_f32 v[106:107], v[68:69], v[106:107]
	v_pk_mul_f32 v[30:31], v[30:31], v[34:35] op_sel_hi:[1,0]
	v_mov_b32_e32 v28, v27
	v_mul_f32_e32 v18, 0xbfb8aa3b, v106
	v_pk_fma_f32 v[26:27], v[28:29], v[94:95], v[30:31]
	v_mov_b32_e32 v20, v19
	v_exp_f32_e32 v22, v18
	v_pk_fma_f32 v[18:19], v[20:21], v[86:87], v[26:27]
	v_mov_b32_e32 v24, v23
	v_pk_add_f32 v[18:19], v[24:25], v[18:19]
	v_mul_f32_e32 v26, 0xbfb8aa3b, v107
	v_mul_f32_e32 v23, 0xbfb8aa3b, v18
	v_exp_f32_e32 v23, v23
	v_exp_f32_e32 v27, v26
	v_mul_f32_e32 v26, 0xbfb8aa3b, v19
	v_exp_f32_e32 v51, v26
	v_add_f32_e32 v23, 1.0, v23
	v_add_f32_e32 v22, 1.0, v22
	v_rcp_f32_e32 v26, v23
	v_add_f32_e32 v23, 1.0, v27
	v_rcp_f32_e32 v22, v22
	v_rcp_f32_e32 v23, v23
	v_add_f32_e32 v27, 1.0, v51
	v_rcp_f32_e32 v27, v27
	v_lshlrev_b32_e32 v93, 16, v81
	v_lshlrev_b32_e32 v92, 16, v80
	v_and_b32_e32 v101, 0xffff0000, v81
	v_and_b32_e32 v100, 0xffff0000, v80
	v_pk_mul_f32 v[80:81], v[106:107], v[22:23]
	v_pk_mul_f32 v[30:31], v[4:5], v[104:105]
	v_pk_mul_f32 v[104:105], v[18:19], v[26:27]
	v_cvt_pk_bf16_f32 v106, v80, v104
	v_cvt_pk_bf16_f32 v107, v81, v105
	v_pk_mul_f32 v[22:23], v[34:35], v[102:103] op_sel_hi:[0,1]
	s_waitcnt vmcnt(2)
	v_mov_b32_e32 v18, v14
	v_mov_b32_e32 v19, v16
	v_lshlrev_b32_e32 v84, 16, v82
	v_lshlrev_b32_e32 v85, 16, v83
	v_pk_fma_f32 v[26:27], v[18:19], v[92:93], v[22:23]
	s_waitcnt vmcnt(1)
	v_mov_b32_e32 v22, v10
	v_mov_b32_e32 v23, v12
	v_pk_fma_f32 v[102:103], v[22:23], v[84:85], v[26:27]
	s_waitcnt vmcnt(0)
	v_mov_b32_e32 v26, v6
	v_mov_b32_e32 v27, v8
	v_pk_mul_f32 v[30:31], v[34:35], v[30:31] op_sel_hi:[0,1]
	v_mov_b32_e32 v16, v15
	v_and_b32_e32 v82, 0xffff0000, v82
	v_and_b32_e32 v83, 0xffff0000, v83
	v_pk_add_f32 v[102:103], v[26:27], v[102:103]
	v_pk_fma_f32 v[14:15], v[16:17], v[100:101], v[30:31]
	v_mov_b32_e32 v12, v11
	v_mul_f32_e32 v6, 0xbfb8aa3b, v102
	v_pk_fma_f32 v[10:11], v[12:13], v[82:83], v[14:15]
	v_mov_b32_e32 v8, v7
	v_exp_f32_e32 v108, v6
	v_pk_add_f32 v[6:7], v[8:9], v[10:11]
	v_mul_f32_e32 v14, 0xbfb8aa3b, v103
	v_mul_f32_e32 v10, 0xbfb8aa3b, v6
	v_exp_f32_e32 v11, v10
	v_exp_f32_e32 v15, v14
	v_mul_f32_e32 v14, 0xbfb8aa3b, v7
	v_exp_f32_e32 v30, v14
	v_add_f32_e32 v11, 1.0, v11
	v_add_f32_e32 v10, 1.0, v108
	v_rcp_f32_e32 v14, v11
	v_add_f32_e32 v11, 1.0, v15
	v_rcp_f32_e32 v10, v10
	v_rcp_f32_e32 v11, v11
	v_add_f32_e32 v15, 1.0, v30
	v_rcp_f32_e32 v15, v15
	s_movk_i32 s28, 0x1080
	v_pk_mul_f32 v[10:11], v[102:103], v[10:11]
	v_mad_u64_u32 v[30:31], s[28:29], v91, s28, v[90:91]
	v_pk_mul_f32 v[10:11], v[10:11], s[48:49] op_sel_hi:[1,0]
	v_pk_mul_f32 v[6:7], v[6:7], v[14:15]
	v_pk_mul_f32 v[6:7], v[6:7], s[48:49] op_sel_hi:[1,0]
	v_cvt_pk_bf16_f32 v15, v11, v7
	v_cvt_pk_bf16_f32 v14, v10, v6
	s_add_i32 s54, 0, 0x1be00
	v_lshlrev_b32_e32 v34, 5, v91
	s_waitcnt lgkmcnt(0)
	s_barrier
	ds_write2st64_b64 v30, v[106:107], v[14:15] offset1:66
	v_add_u32_e32 v14, s54, v34
	ds_read_b32 v14, v14
	s_add_i32 s55, 0, 0x1bf00
	v_add_u32_e32 v15, s55, v34
	ds_read_b32 v102, v15
	v_ashrrev_i32_e32 v51, 31, v50
	s_waitcnt lgkmcnt(1)
	v_pk_mul_f32 v[30:31], v[80:81], v[14:15] op_sel_hi:[1,0]
	v_pk_mul_f32 v[14:15], v[104:105], v[14:15] op_sel_hi:[1,0]
	v_cvt_pk_bf16_f32 v15, v31, v15
	v_cvt_pk_bf16_f32 v14, v30, v14
	v_lshlrev_b64 v[30:31], 9, v[50:51]
	v_lshl_add_u64 v[30:31], v[54:55], 0, v[30:31]
	s_waitcnt lgkmcnt(0)
	v_mul_f32_e32 v10, v10, v102
	global_store_dwordx2 v[30:31], v[14:15], off
	v_cvt_pk_bf16_f32 v10, v10, v10
	v_mov_b32_e32 v14, s80
	s_movk_i32 s28, 0x240
	v_mad_u32_u24 v51, v99, s28, v14
	v_lshl_add_u32 v14, v91, 4, v51
	v_mul_f32_e32 v6, v6, v102
	ds_write_b16_d16_hi v14, v10
	v_cvt_pk_bf16_f32 v6, v6, v6
	ds_write_b16_d16_hi v14, v6 offset:144
	v_mul_f32_e32 v6, v11, v102
	v_cvt_pk_bf16_f32 v6, v6, v6
	ds_write_b16_d16_hi v14, v6 offset:288
	v_mul_f32_e32 v6, v7, v102
	v_cvt_pk_bf16_f32 v6, v6, v6
	ds_write_b16_d16_hi v14, v6 offset:432
	v_pk_mul_f32 v[6:7], v[64:65], v[88:89]
	v_lshlrev_b32_e32 v81, 16, v79
	v_lshlrev_b32_e32 v80, 16, v78
	v_pk_fma_f32 v[6:7], v[2:3], v[96:97], v[6:7]
	v_pk_mul_f32 v[14:15], v[28:29], v[86:87]
	v_and_b32_e32 v79, 0xffff0000, v79
	v_and_b32_e32 v78, 0xffff0000, v78
	v_pk_fma_f32 v[6:7], v[66:67], v[80:81], v[6:7]
	v_pk_fma_f32 v[14:15], v[32:33], v[94:95], v[14:15]
	v_pk_add_f32 v[6:7], v[68:69], v[6:7]
	v_pk_fma_f32 v[14:15], v[20:21], v[78:79], v[14:15]
	v_mul_f32_e32 v11, 0xbfb8aa3b, v6
	v_pk_add_f32 v[94:95], v[24:25], v[14:15]
	v_exp_f32_e32 v11, v11
	v_mul_f32_e32 v14, 0xbfb8aa3b, v94
	v_exp_f32_e32 v15, v14
	v_mul_f32_e32 v31, 0xbfb8aa3b, v95
	v_add_f32_e32 v11, 1.0, v11
	v_rcp_f32_e32 v96, v11
	v_add_f32_e32 v11, 1.0, v15
	v_mul_f32_e32 v15, 0xbfb8aa3b, v7
	v_exp_f32_e32 v15, v15
	v_exp_f32_e32 v31, v31
	v_rcp_f32_e32 v102, v11
	v_lshlrev_b32_e32 v10, 16, v76
	v_add_f32_e32 v11, 1.0, v15
	v_rcp_f32_e32 v97, v11
	v_add_f32_e32 v11, 1.0, v31
	v_rcp_f32_e32 v103, v11
	v_and_b32_e32 v14, 0xffff0000, v76
	v_lshlrev_b32_e32 v11, 16, v77
	v_and_b32_e32 v15, 0xffff0000, v77
	v_pk_mul_f32 v[94:95], v[94:95], v[102:103]
	v_pk_mul_f32 v[76:77], v[6:7], v[96:97]
	v_cvt_pk_bf16_f32 v97, v77, v95
	v_cvt_pk_bf16_f32 v96, v76, v94
	v_pk_mul_f32 v[6:7], v[18:19], v[84:85]
	v_or_b32_e32 v30, 1, v50
	v_pk_fma_f32 v[6:7], v[58:59], v[92:93], v[6:7]
	v_and_b32_e32 v39, 15, v38
	v_pk_fma_f32 v[6:7], v[22:23], v[10:11], v[6:7]
	s_nop 0
	v_pk_add_f32 v[92:93], v[26:27], v[6:7]
	s_nop 0
	v_mul_f32_e32 v6, 0xbfb8aa3b, v92
	v_exp_f32_e32 v31, v6
	v_pk_mul_f32 v[6:7], v[16:17], v[82:83]
	s_nop 0
	v_pk_fma_f32 v[6:7], v[4:5], v[100:101], v[6:7]
	s_nop 0
	v_pk_fma_f32 v[6:7], v[12:13], v[14:15], v[6:7]
	s_nop 0
	v_pk_add_f32 v[100:101], v[8:9], v[6:7]
	s_nop 0
	v_mul_f32_e32 v6, 0xbfb8aa3b, v100
	v_exp_f32_e32 v91, v6
	s_nop 0
	v_mad_u64_u32 v[6:7], s[28:29], v30, s81, v[90:91]
	v_add_f32_e32 v7, 1.0, v31
	v_mul_f32_e32 v31, 0xbfb8aa3b, v93
	v_rcp_f32_e32 v90, v7
	v_add_f32_e32 v7, 1.0, v91
	v_exp_f32_e32 v31, v31
	v_mul_f32_e32 v91, 0xbfb8aa3b, v101
	v_exp_f32_e32 v103, v91
	v_rcp_f32_e32 v102, v7
	v_add_f32_e32 v7, 1.0, v31
	v_rcp_f32_e32 v91, v7
	v_add_f32_e32 v7, 1.0, v103
	v_rcp_f32_e32 v103, v7
	ds_write_b64 v6, v[96:97]
	v_pk_mul_f32 v[90:91], v[92:93], v[90:91]
	s_mov_b32 s28, 0xffffff0
	v_pk_mul_f32 v[92:93], v[100:101], v[102:103]
	v_pk_mul_f32 v[90:91], v[90:91], s[48:49] op_sel_hi:[1,0]
	v_pk_mul_f32 v[92:93], v[92:93], s[48:49] op_sel_hi:[1,0]
	v_cvt_pk_bf16_f32 v97, v91, v93
	v_cvt_pk_bf16_f32 v96, v90, v92
	ds_write_b64 v6, v[96:97] offset:33792
	v_lshlrev_b32_e32 v97, 2, v30
	v_add_u32_e32 v7, s54, v97
	ds_read_b32 v96, v7
	v_add_u32_e32 v97, s55, v97
	ds_read_b32 v100, v97
	v_ashrrev_i32_e32 v31, 31, v30
	v_mul_u32_u24_e32 v7, 0x240, v99
	s_waitcnt lgkmcnt(1)
	v_pk_mul_f32 v[76:77], v[76:77], v[96:97] op_sel_hi:[1,0]
	v_pk_mul_f32 v[94:95], v[94:95], v[96:97] op_sel_hi:[1,0]
	v_cvt_pk_bf16_f32 v95, v77, v95
	v_cvt_pk_bf16_f32 v94, v76, v94
	v_lshlrev_b64 v[76:77], 9, v[30:31]
	s_waitcnt lgkmcnt(0)
	v_mul_f32_e32 v31, v90, v100
	v_lshl_add_u64 v[96:97], v[54:55], 0, v[76:77]
	v_lshlrev_b32_e32 v30, 1, v30
	v_cvt_pk_bf16_f32 v31, v31, v31
	v_add_u32_e32 v76, v51, v30
	ds_write_b16_d16_hi v76, v31
	v_mul_f32_e32 v31, v92, v100
	v_cvt_pk_bf16_f32 v31, v31, v31
	v_add3_u32 v30, s80, v30, v7
	ds_write_b16_d16_hi v30, v31 offset:144
	v_mul_f32_e32 v31, v91, v100
	v_cvt_pk_bf16_f32 v31, v31, v31
	ds_write_b16_d16_hi v30, v31 offset:288
	v_mul_f32_e32 v31, v93, v100
	v_pk_mul_f32 v[92:93], v[64:65], v[80:81]
	v_lshlrev_b32_e32 v91, 16, v75
	v_lshlrev_b32_e32 v90, 16, v74
	v_pk_fma_f32 v[88:89], v[2:3], v[88:89], v[92:93]
	v_pk_mul_f32 v[92:93], v[28:29], v[78:79]
	v_and_b32_e32 v75, 0xffff0000, v75
	v_and_b32_e32 v74, 0xffff0000, v74
	v_pk_fma_f32 v[88:89], v[66:67], v[90:91], v[88:89]
	v_pk_fma_f32 v[86:87], v[32:33], v[86:87], v[92:93]
	v_cvt_pk_bf16_f32 v31, v31, v31
	v_pk_add_f32 v[88:89], v[68:69], v[88:89]
	v_pk_fma_f32 v[86:87], v[20:21], v[74:75], v[86:87]
	ds_write_b16_d16_hi v30, v31 offset:432
	v_mul_f32_e32 v31, 0xbfb8aa3b, v88
	v_pk_add_f32 v[86:87], v[24:25], v[86:87]
	v_exp_f32_e32 v31, v31
	v_mul_f32_e32 v77, 0xbfb8aa3b, v86
	v_exp_f32_e32 v77, v77
	v_mul_f32_e32 v93, 0xbfb8aa3b, v87
	v_add_f32_e32 v31, 1.0, v31
	v_rcp_f32_e32 v92, v31
	v_add_f32_e32 v31, 1.0, v77
	v_mul_f32_e32 v77, 0xbfb8aa3b, v89
	v_exp_f32_e32 v77, v77
	v_exp_f32_e32 v101, v93
	v_rcp_f32_e32 v100, v31
	v_lshlrev_b32_e32 v76, 16, v72
	v_add_f32_e32 v31, 1.0, v77
	v_rcp_f32_e32 v93, v31
	v_add_f32_e32 v31, 1.0, v101
	v_rcp_f32_e32 v101, v31
	v_lshlrev_b32_e32 v77, 16, v73
	v_pk_mul_f32 v[88:89], v[88:89], v[92:93]
	v_and_b32_e32 v72, 0xffff0000, v72
	v_pk_mul_f32 v[86:87], v[86:87], v[100:101]
	v_and_b32_e32 v73, 0xffff0000, v73
	v_cvt_pk_bf16_f32 v92, v88, v86
	v_pk_mul_f32 v[100:101], v[18:19], v[10:11]
	v_cvt_pk_bf16_f32 v93, v89, v87
	v_pk_fma_f32 v[84:85], v[58:59], v[84:85], v[100:101]
	v_pk_mul_f32 v[100:101], v[16:17], v[14:15]
	v_pk_fma_f32 v[84:85], v[22:23], v[76:77], v[84:85]
	v_pk_fma_f32 v[82:83], v[4:5], v[82:83], v[100:101]
	v_pk_add_f32 v[84:85], v[26:27], v[84:85]
	v_pk_fma_f32 v[82:83], v[12:13], v[72:73], v[82:83]
	v_mul_f32_e32 v31, 0xbfb8aa3b, v84
	v_pk_add_f32 v[82:83], v[8:9], v[82:83]
	v_exp_f32_e32 v31, v31
	v_mul_f32_e32 v100, 0xbfb8aa3b, v82
	v_exp_f32_e32 v101, v100
	v_add_f32_e32 v31, 1.0, v31
	v_rcp_f32_e32 v100, v31
	v_add_f32_e32 v31, 1.0, v101
	v_mul_f32_e32 v101, 0xbfb8aa3b, v85
	v_exp_f32_e32 v101, v101
	v_mul_f32_e32 v102, 0xbfb8aa3b, v83
	v_exp_f32_e32 v103, v102
	v_rcp_f32_e32 v102, v31
	v_add_f32_e32 v31, 1.0, v101
	v_rcp_f32_e32 v101, v31
	v_add_f32_e32 v31, 1.0, v103
	v_rcp_f32_e32 v103, v31
	ds_write_b64 v6, v[92:93] offset:528
	v_pk_mul_f32 v[84:85], v[84:85], v[100:101]
	v_or_b32_e32 v30, 2, v50
	v_pk_mul_f32 v[82:83], v[82:83], v[102:103]
	v_pk_mul_f32 v[84:85], v[84:85], s[48:49] op_sel_hi:[1,0]
	v_pk_mul_f32 v[82:83], v[82:83], s[48:49] op_sel_hi:[1,0]
	v_cvt_pk_bf16_f32 v93, v85, v83
	v_cvt_pk_bf16_f32 v92, v84, v82
	ds_write_b64 v6, v[92:93] offset:34320
	v_lshlrev_b32_e32 v93, 2, v30
	v_add_u32_e32 v31, s54, v93
	v_add_u32_e32 v93, s55, v93
	ds_read_b32 v92, v31
	ds_read_b32 v93, v93
	global_store_dwordx2 v[96:97], v[94:95], off
	v_ashrrev_i32_e32 v31, 31, v30
	s_waitcnt lgkmcnt(0)
	v_pk_mul_f32 v[88:89], v[88:89], v[92:93] op_sel_hi:[1,0]
	v_pk_mul_f32 v[86:87], v[86:87], v[92:93] op_sel_hi:[1,0]
	v_cvt_pk_bf16_f32 v87, v89, v87
	v_cvt_pk_bf16_f32 v86, v88, v86
	v_lshlrev_b64 v[88:89], 9, v[30:31]
	v_mul_f32_e32 v31, v84, v93
	v_lshlrev_b32_e32 v30, 1, v30
	v_cvt_pk_bf16_f32 v31, v31, v31
	v_add_u32_e32 v84, v51, v30
	ds_write_b16_d16_hi v84, v31
	v_mul_f32_e32 v31, v82, v93
	v_cvt_pk_bf16_f32 v31, v31, v31
	v_add3_u32 v30, s80, v30, v7
	ds_write_b16_d16_hi v30, v31 offset:144
	v_mul_f32_e32 v31, v85, v93
	v_cvt_pk_bf16_f32 v31, v31, v31
	ds_write_b16_d16_hi v30, v31 offset:288
	v_mul_f32_e32 v31, v83, v93
	v_pk_mul_f32 v[92:93], v[64:65], v[90:91]
	v_cvt_pk_bf16_f32 v31, v31, v31
	v_lshlrev_b32_e32 v83, 16, v71
	v_lshlrev_b32_e32 v82, 16, v70
	v_pk_fma_f32 v[80:81], v[2:3], v[80:81], v[92:93]
	v_pk_mul_f32 v[92:93], v[28:29], v[74:75]
	v_and_b32_e32 v71, 0xffff0000, v71
	v_and_b32_e32 v70, 0xffff0000, v70
	v_pk_fma_f32 v[80:81], v[66:67], v[82:83], v[80:81]
	v_pk_fma_f32 v[78:79], v[32:33], v[78:79], v[92:93]
	v_pk_add_f32 v[80:81], v[68:69], v[80:81]
	v_pk_fma_f32 v[78:79], v[20:21], v[70:71], v[78:79]
	ds_write_b16_d16_hi v30, v31 offset:432
	v_mul_f32_e32 v31, 0xbfb8aa3b, v80
	v_pk_add_f32 v[78:79], v[24:25], v[78:79]
	v_exp_f32_e32 v31, v31
	v_mul_f32_e32 v85, 0xbfb8aa3b, v78
	v_exp_f32_e32 v85, v85
	v_mul_f32_e32 v93, 0xbfb8aa3b, v79
	v_add_f32_e32 v31, 1.0, v31
	v_rcp_f32_e32 v92, v31
	v_add_f32_e32 v31, 1.0, v85
	v_mul_f32_e32 v85, 0xbfb8aa3b, v81
	v_exp_f32_e32 v85, v85
	v_exp_f32_e32 v95, v93
	v_rcp_f32_e32 v94, v31
	v_lshlrev_b32_e32 v30, 16, v62
	v_add_f32_e32 v31, 1.0, v85
	v_rcp_f32_e32 v93, v31
	v_add_f32_e32 v31, 1.0, v95
	v_rcp_f32_e32 v95, v31
	v_lshlrev_b32_e32 v31, 16, v63
	v_pk_mul_f32 v[80:81], v[80:81], v[92:93]
	v_and_b32_e32 v62, 0xffff0000, v62
	v_pk_mul_f32 v[78:79], v[78:79], v[94:95]
	v_and_b32_e32 v63, 0xffff0000, v63
	v_cvt_pk_bf16_f32 v92, v80, v78
	v_pk_mul_f32 v[94:95], v[18:19], v[76:77]
	v_cvt_pk_bf16_f32 v93, v81, v79
	v_pk_fma_f32 v[10:11], v[58:59], v[10:11], v[94:95]
	v_pk_mul_f32 v[94:95], v[16:17], v[72:73]
	v_pk_fma_f32 v[10:11], v[22:23], v[30:31], v[10:11]
	v_pk_fma_f32 v[14:15], v[4:5], v[14:15], v[94:95]
	v_pk_add_f32 v[10:11], v[26:27], v[10:11]
	v_pk_fma_f32 v[14:15], v[12:13], v[62:63], v[14:15]
	v_mul_f32_e32 v85, 0xbfb8aa3b, v10
	v_pk_add_f32 v[14:15], v[8:9], v[14:15]
	v_exp_f32_e32 v85, v85
	v_mul_f32_e32 v94, 0xbfb8aa3b, v14
	v_exp_f32_e32 v95, v94
	v_add_f32_e32 v85, 1.0, v85
	v_rcp_f32_e32 v94, v85
	v_add_f32_e32 v85, 1.0, v95
	v_mul_f32_e32 v95, 0xbfb8aa3b, v11
	v_exp_f32_e32 v95, v95
	v_mul_f32_e32 v96, 0xbfb8aa3b, v15
	v_exp_f32_e32 v97, v96
	v_rcp_f32_e32 v96, v85
	v_add_f32_e32 v85, 1.0, v95
	v_rcp_f32_e32 v95, v85
	v_add_f32_e32 v85, 1.0, v97
	v_rcp_f32_e32 v97, v85
	ds_write_b64 v6, v[92:93] offset:1056
	v_pk_mul_f32 v[10:11], v[10:11], v[94:95]
	v_or_b32_e32 v84, 3, v50
	v_pk_mul_f32 v[14:15], v[14:15], v[96:97]
	v_pk_mul_f32 v[10:11], v[10:11], s[48:49] op_sel_hi:[1,0]
	v_pk_mul_f32 v[14:15], v[14:15], s[48:49] op_sel_hi:[1,0]
	v_cvt_pk_bf16_f32 v93, v11, v15
	v_cvt_pk_bf16_f32 v94, v14, v14
	v_cvt_pk_bf16_f32 v92, v10, v10
	v_and_b32_e32 v94, 0xffff0000, v94
	v_or_b32_sdwa v92, v94, v92 dst_sel:DWORD dst_unused:UNUSED_PAD src0_sel:DWORD src1_sel:WORD_1
	ds_write_b64 v6, v[92:93] offset:34848
	v_lshlrev_b32_e32 v93, 2, v84
	v_add_u32_e32 v85, s54, v93
	ds_read_b32 v92, v85
	v_lshl_add_u64 v[88:89], v[54:55], 0, v[88:89]
	global_store_dwordx2 v[88:89], v[86:87], off
	v_add_u32_e32 v86, s55, v93
	ds_read_b32 v88, v86
	s_waitcnt lgkmcnt(1)
	v_pk_mul_f32 v[80:81], v[80:81], v[92:93] op_sel_hi:[1,0]
	v_pk_mul_f32 v[78:79], v[78:79], v[92:93] op_sel_hi:[1,0]
	v_cvt_pk_bf16_f32 v81, v81, v79
	v_cvt_pk_bf16_f32 v80, v80, v78
	v_ashrrev_i32_e32 v85, 31, v84
	v_lshlrev_b64 v[78:79], 9, v[84:85]
	s_waitcnt lgkmcnt(0)
	v_mul_f32_e32 v10, v10, v88
	v_lshl_add_u64 v[86:87], v[54:55], 0, v[78:79]
	v_lshlrev_b32_e32 v78, 1, v84
	v_cvt_pk_bf16_f32 v10, v10, v10
	v_add_u32_e32 v79, v51, v78
	ds_write_b16_d16_hi v79, v10
	v_mul_f32_e32 v10, v14, v88
	v_cvt_pk_bf16_f32 v10, v10, v10
	v_add3_u32 v14, s80, v78, v7
	ds_write_b16_d16_hi v14, v10 offset:144
	v_mul_f32_e32 v10, v11, v88
	v_cvt_pk_bf16_f32 v10, v10, v10
	v_pk_mul_f32 v[84:85], v[64:65], v[82:83]
	ds_write_b16_d16_hi v14, v10 offset:288
	v_mul_f32_e32 v10, v15, v88
	v_lshlrev_b32_e32 v79, 16, v61
	v_lshlrev_b32_e32 v78, 16, v60
	v_pk_fma_f32 v[84:85], v[2:3], v[90:91], v[84:85]
	v_pk_mul_f32 v[88:89], v[28:29], v[70:71]
	v_and_b32_e32 v61, 0xffff0000, v61
	v_and_b32_e32 v60, 0xffff0000, v60
	v_pk_fma_f32 v[84:85], v[66:67], v[78:79], v[84:85]
	v_pk_fma_f32 v[74:75], v[32:33], v[74:75], v[88:89]
	v_pk_add_f32 v[84:85], v[68:69], v[84:85]
	v_pk_fma_f32 v[74:75], v[20:21], v[60:61], v[74:75]
	v_cvt_pk_bf16_f32 v10, v10, v10
	v_mul_f32_e32 v11, 0xbfb8aa3b, v84
	v_pk_add_f32 v[74:75], v[24:25], v[74:75]
	v_exp_f32_e32 v11, v11
	v_mul_f32_e32 v15, 0xbfb8aa3b, v74
	v_exp_f32_e32 v15, v15
	v_mul_f32_e32 v89, 0xbfb8aa3b, v75
	v_add_f32_e32 v11, 1.0, v11
	v_rcp_f32_e32 v88, v11
	v_add_f32_e32 v11, 1.0, v15
	v_mul_f32_e32 v15, 0xbfb8aa3b, v85
	v_exp_f32_e32 v15, v15
	v_exp_f32_e32 v91, v89
	v_rcp_f32_e32 v90, v11
	ds_write_b16_d16_hi v14, v10 offset:432
	v_add_f32_e32 v11, 1.0, v15
	v_rcp_f32_e32 v89, v11
	v_add_f32_e32 v11, 1.0, v91
	v_rcp_f32_e32 v91, v11
	v_lshlrev_b32_e32 v14, 16, v56
	v_lshlrev_b32_e32 v15, 16, v57
	v_pk_mul_f32 v[84:85], v[84:85], v[88:89]
	v_pk_mul_f32 v[74:75], v[74:75], v[90:91]
	v_and_b32_e32 v56, 0xffff0000, v56
	v_cvt_pk_bf16_f32 v88, v84, v74
	v_pk_mul_f32 v[90:91], v[18:19], v[30:31]
	v_cvt_pk_bf16_f32 v89, v85, v75
	v_pk_fma_f32 v[76:77], v[58:59], v[76:77], v[90:91]
	v_pk_mul_f32 v[90:91], v[16:17], v[62:63]
	v_and_b32_e32 v57, 0xffff0000, v57
	v_pk_fma_f32 v[76:77], v[22:23], v[14:15], v[76:77]
	v_pk_fma_f32 v[72:73], v[4:5], v[72:73], v[90:91]
	v_pk_add_f32 v[76:77], v[26:27], v[76:77]
	v_pk_fma_f32 v[72:73], v[12:13], v[56:57], v[72:73]
	v_mul_f32_e32 v11, 0xbfb8aa3b, v76
	v_pk_add_f32 v[72:73], v[8:9], v[72:73]
	v_exp_f32_e32 v11, v11
	v_mul_f32_e32 v90, 0xbfb8aa3b, v72
	v_exp_f32_e32 v91, v90
	v_add_f32_e32 v11, 1.0, v11
	v_rcp_f32_e32 v90, v11
	v_add_f32_e32 v11, 1.0, v91
	v_mul_f32_e32 v91, 0xbfb8aa3b, v77
	v_exp_f32_e32 v91, v91
	v_mul_f32_e32 v92, 0xbfb8aa3b, v73
	v_exp_f32_e32 v93, v92
	v_rcp_f32_e32 v92, v11
	v_add_f32_e32 v11, 1.0, v91
	v_rcp_f32_e32 v91, v11
	v_add_f32_e32 v11, 1.0, v93
	v_rcp_f32_e32 v93, v11
	ds_write_b64 v6, v[88:89] offset:1584
	v_pk_mul_f32 v[76:77], v[76:77], v[90:91]
	v_or_b32_e32 v10, 4, v50
	v_pk_mul_f32 v[72:73], v[72:73], v[92:93]
	v_pk_mul_f32 v[76:77], v[76:77], s[48:49] op_sel_hi:[1,0]
	v_pk_mul_f32 v[72:73], v[72:73], s[48:49] op_sel_hi:[1,0]
	v_cvt_pk_bf16_f32 v89, v77, v73
	v_cvt_pk_bf16_f32 v90, v72, v72
	v_cvt_pk_bf16_f32 v88, v76, v76
	v_and_b32_e32 v90, 0xffff0000, v90
	v_or_b32_sdwa v88, v90, v88 dst_sel:DWORD dst_unused:UNUSED_PAD src0_sel:DWORD src1_sel:WORD_1
	ds_write_b64 v6, v[88:89] offset:35376
	v_lshlrev_b32_e32 v89, 2, v10
	v_add_u32_e32 v11, s54, v89
	ds_read_b32 v88, v11
	global_store_dwordx2 v[86:87], v[80:81], off
	v_add_u32_e32 v80, s55, v89
	ds_read_b32 v86, v80
	v_ashrrev_i32_e32 v11, 31, v10
	s_waitcnt lgkmcnt(1)
	v_pk_mul_f32 v[80:81], v[84:85], v[88:89] op_sel_hi:[1,0]
	v_pk_mul_f32 v[74:75], v[74:75], v[88:89] op_sel_hi:[1,0]
	v_cvt_pk_bf16_f32 v75, v81, v75
	v_cvt_pk_bf16_f32 v74, v80, v74
	v_lshlrev_b64 v[80:81], 9, v[10:11]
	s_waitcnt lgkmcnt(0)
	v_mul_f32_e32 v11, v76, v86
	v_lshlrev_b32_e32 v10, 1, v10
	v_cvt_pk_bf16_f32 v11, v11, v11
	v_add_u32_e32 v76, v51, v10
	ds_write_b16_d16_hi v76, v11
	v_mul_f32_e32 v11, v72, v86
	v_cvt_pk_bf16_f32 v11, v11, v11
	v_add3_u32 v10, s80, v10, v7
	ds_write_b16_d16_hi v10, v11 offset:144
	v_mul_f32_e32 v11, v77, v86
	v_cvt_pk_bf16_f32 v11, v11, v11
	ds_write_b16_d16_hi v10, v11 offset:288
	v_mul_f32_e32 v11, v73, v86
	v_pk_mul_f32 v[84:85], v[64:65], v[78:79]
	v_cvt_pk_bf16_f32 v11, v11, v11
	v_lshlrev_b32_e32 v73, 16, v53
	v_lshlrev_b32_e32 v72, 16, v52
	v_pk_fma_f32 v[82:83], v[2:3], v[82:83], v[84:85]
	v_pk_mul_f32 v[84:85], v[28:29], v[60:61]
	v_and_b32_e32 v53, 0xffff0000, v53
	v_and_b32_e32 v52, 0xffff0000, v52
	v_pk_fma_f32 v[82:83], v[66:67], v[72:73], v[82:83]
	v_pk_fma_f32 v[70:71], v[32:33], v[70:71], v[84:85]
	v_pk_add_f32 v[82:83], v[68:69], v[82:83]
	v_pk_fma_f32 v[70:71], v[20:21], v[52:53], v[70:71]
	ds_write_b16_d16_hi v10, v11 offset:432
	v_mul_f32_e32 v11, 0xbfb8aa3b, v82
	v_pk_add_f32 v[70:71], v[24:25], v[70:71]
	v_exp_f32_e32 v11, v11
	v_mul_f32_e32 v77, 0xbfb8aa3b, v70
	v_exp_f32_e32 v77, v77
	v_mul_f32_e32 v85, 0xbfb8aa3b, v71
	v_add_f32_e32 v11, 1.0, v11
	v_rcp_f32_e32 v84, v11
	v_add_f32_e32 v11, 1.0, v77
	v_mul_f32_e32 v77, 0xbfb8aa3b, v83
	v_exp_f32_e32 v77, v77
	v_exp_f32_e32 v87, v85
	v_rcp_f32_e32 v86, v11
	v_lshlrev_b32_e32 v10, 16, v48
	v_add_f32_e32 v11, 1.0, v77
	v_rcp_f32_e32 v85, v11
	v_add_f32_e32 v11, 1.0, v87
	v_rcp_f32_e32 v87, v11
	v_lshlrev_b32_e32 v11, 16, v49
	v_pk_mul_f32 v[82:83], v[82:83], v[84:85]
	v_and_b32_e32 v48, 0xffff0000, v48
	v_pk_mul_f32 v[70:71], v[70:71], v[86:87]
	v_and_b32_e32 v49, 0xffff0000, v49
	v_cvt_pk_bf16_f32 v84, v82, v70
	v_pk_mul_f32 v[86:87], v[18:19], v[14:15]
	v_cvt_pk_bf16_f32 v85, v83, v71
	v_pk_fma_f32 v[30:31], v[58:59], v[30:31], v[86:87]
	v_pk_mul_f32 v[86:87], v[16:17], v[56:57]
	v_pk_fma_f32 v[30:31], v[22:23], v[10:11], v[30:31]
	v_pk_fma_f32 v[62:63], v[4:5], v[62:63], v[86:87]
	v_pk_add_f32 v[30:31], v[26:27], v[30:31]
	v_pk_fma_f32 v[62:63], v[12:13], v[48:49], v[62:63]
	v_mul_f32_e32 v77, 0xbfb8aa3b, v30
	v_pk_add_f32 v[62:63], v[8:9], v[62:63]
	v_exp_f32_e32 v77, v77
	v_mul_f32_e32 v86, 0xbfb8aa3b, v62
	v_exp_f32_e32 v87, v86
	v_add_f32_e32 v77, 1.0, v77
	v_rcp_f32_e32 v86, v77
	v_add_f32_e32 v77, 1.0, v87
	v_mul_f32_e32 v87, 0xbfb8aa3b, v31
	v_exp_f32_e32 v87, v87
	v_mul_f32_e32 v88, 0xbfb8aa3b, v63
	v_exp_f32_e32 v89, v88
	v_rcp_f32_e32 v88, v77
	v_add_f32_e32 v77, 1.0, v87
	v_rcp_f32_e32 v87, v77
	v_add_f32_e32 v77, 1.0, v89
	v_rcp_f32_e32 v89, v77
	ds_write_b64 v6, v[84:85] offset:2112
	v_pk_mul_f32 v[30:31], v[30:31], v[86:87]
	v_or_b32_e32 v76, 5, v50
	v_pk_mul_f32 v[62:63], v[62:63], v[88:89]
	v_pk_mul_f32 v[30:31], v[30:31], s[48:49] op_sel_hi:[1,0]
	v_pk_mul_f32 v[62:63], v[62:63], s[48:49] op_sel_hi:[1,0]
	v_cvt_pk_bf16_f32 v85, v31, v63
	v_cvt_pk_bf16_f32 v86, v62, v62
	v_cvt_pk_bf16_f32 v84, v30, v30
	v_and_b32_e32 v86, 0xffff0000, v86
	v_or_b32_sdwa v84, v86, v84 dst_sel:DWORD dst_unused:UNUSED_PAD src0_sel:DWORD src1_sel:WORD_1
	ds_write_b64 v6, v[84:85] offset:35904
	v_lshlrev_b32_e32 v85, 2, v76
	v_add_u32_e32 v77, s54, v85
	ds_read_b32 v84, v77
	v_lshl_add_u64 v[80:81], v[54:55], 0, v[80:81]
	global_store_dwordx2 v[80:81], v[74:75], off
	v_add_u32_e32 v74, s55, v85
	ds_read_b32 v80, v74
	s_waitcnt lgkmcnt(1)
	v_pk_mul_f32 v[74:75], v[82:83], v[84:85] op_sel_hi:[1,0]
	v_pk_mul_f32 v[70:71], v[70:71], v[84:85] op_sel_hi:[1,0]
	v_cvt_pk_bf16_f32 v71, v75, v71
	v_cvt_pk_bf16_f32 v70, v74, v70
	v_ashrrev_i32_e32 v77, 31, v76
	s_waitcnt lgkmcnt(0)
	v_mul_f32_e32 v30, v30, v80
	v_lshlrev_b64 v[74:75], 9, v[76:77]
	v_lshlrev_b32_e32 v76, 1, v76
	v_cvt_pk_bf16_f32 v30, v30, v30
	v_add_u32_e32 v77, v51, v76
	ds_write_b16_d16_hi v77, v30
	v_mul_f32_e32 v30, v62, v80
	v_cvt_pk_bf16_f32 v30, v30, v30
	v_add3_u32 v62, s80, v76, v7
	ds_write_b16_d16_hi v62, v30 offset:144
	v_mul_f32_e32 v30, v31, v80
	v_cvt_pk_bf16_f32 v30, v30, v30
	ds_write_b16_d16_hi v62, v30 offset:288
	v_mul_f32_e32 v30, v63, v80
	v_pk_mul_f32 v[80:81], v[64:65], v[72:73]
	v_lshlrev_b32_e32 v77, 16, v47
	v_lshlrev_b32_e32 v76, 16, v46
	v_pk_fma_f32 v[78:79], v[2:3], v[78:79], v[80:81]
	v_pk_mul_f32 v[80:81], v[28:29], v[52:53]
	v_and_b32_e32 v47, 0xffff0000, v47
	v_and_b32_e32 v46, 0xffff0000, v46
	v_pk_fma_f32 v[78:79], v[66:67], v[76:77], v[78:79]
	v_pk_fma_f32 v[60:61], v[32:33], v[60:61], v[80:81]
	v_pk_add_f32 v[78:79], v[68:69], v[78:79]
	v_pk_fma_f32 v[60:61], v[20:21], v[46:47], v[60:61]
	v_cvt_pk_bf16_f32 v30, v30, v30
	v_mul_f32_e32 v31, 0xbfb8aa3b, v78
	v_pk_add_f32 v[60:61], v[24:25], v[60:61]
	v_exp_f32_e32 v31, v31
	v_mul_f32_e32 v63, 0xbfb8aa3b, v60
	v_exp_f32_e32 v63, v63
	v_mul_f32_e32 v81, 0xbfb8aa3b, v61
	v_add_f32_e32 v31, 1.0, v31
	v_rcp_f32_e32 v80, v31
	v_add_f32_e32 v31, 1.0, v63
	v_mul_f32_e32 v63, 0xbfb8aa3b, v79
	v_exp_f32_e32 v63, v63
	v_exp_f32_e32 v83, v81
	v_rcp_f32_e32 v82, v31
	ds_write_b16_d16_hi v62, v30 offset:432
	v_add_f32_e32 v31, 1.0, v63
	v_rcp_f32_e32 v81, v31
	v_add_f32_e32 v31, 1.0, v83
	v_rcp_f32_e32 v83, v31
	v_lshlrev_b32_e32 v62, 16, v44
	v_lshlrev_b32_e32 v63, 16, v45
	v_pk_mul_f32 v[78:79], v[78:79], v[80:81]
	v_pk_mul_f32 v[60:61], v[60:61], v[82:83]
	v_and_b32_e32 v44, 0xffff0000, v44
	v_cvt_pk_bf16_f32 v80, v78, v60
	v_pk_mul_f32 v[82:83], v[18:19], v[10:11]
	v_cvt_pk_bf16_f32 v81, v79, v61
	v_pk_fma_f32 v[14:15], v[58:59], v[14:15], v[82:83]
	v_pk_mul_f32 v[82:83], v[16:17], v[48:49]
	v_and_b32_e32 v45, 0xffff0000, v45
	v_pk_fma_f32 v[14:15], v[22:23], v[62:63], v[14:15]
	v_pk_fma_f32 v[56:57], v[4:5], v[56:57], v[82:83]
	v_pk_add_f32 v[14:15], v[26:27], v[14:15]
	v_pk_fma_f32 v[56:57], v[12:13], v[44:45], v[56:57]
	v_mul_f32_e32 v31, 0xbfb8aa3b, v14
	v_pk_add_f32 v[56:57], v[8:9], v[56:57]
	v_exp_f32_e32 v31, v31
	v_mul_f32_e32 v82, 0xbfb8aa3b, v56
	v_exp_f32_e32 v83, v82
	v_add_f32_e32 v31, 1.0, v31
	v_rcp_f32_e32 v82, v31
	v_add_f32_e32 v31, 1.0, v83
	v_mul_f32_e32 v83, 0xbfb8aa3b, v15
	v_exp_f32_e32 v83, v83
	v_mul_f32_e32 v84, 0xbfb8aa3b, v57
	v_exp_f32_e32 v85, v84
	v_rcp_f32_e32 v84, v31
	v_add_f32_e32 v31, 1.0, v83
	v_rcp_f32_e32 v83, v31
	v_add_f32_e32 v31, 1.0, v85
	v_rcp_f32_e32 v85, v31
	ds_write_b64 v6, v[80:81] offset:2640
	v_pk_mul_f32 v[14:15], v[14:15], v[82:83]
	v_or_b32_e32 v30, 6, v50
	v_pk_mul_f32 v[56:57], v[56:57], v[84:85]
	v_pk_mul_f32 v[14:15], v[14:15], s[48:49] op_sel_hi:[1,0]
	v_pk_mul_f32 v[56:57], v[56:57], s[48:49] op_sel_hi:[1,0]
	v_cvt_pk_bf16_f32 v81, v15, v57
	v_cvt_pk_bf16_f32 v82, v56, v56
	v_cvt_pk_bf16_f32 v80, v14, v14
	v_and_b32_e32 v82, 0xffff0000, v82
	v_or_b32_sdwa v80, v82, v80 dst_sel:DWORD dst_unused:UNUSED_PAD src0_sel:DWORD src1_sel:WORD_1
	ds_write_b64 v6, v[80:81] offset:36432
	v_lshlrev_b32_e32 v81, 2, v30
	v_add_u32_e32 v31, s54, v81
	ds_read_b32 v80, v31
	v_lshl_add_u64 v[74:75], v[54:55], 0, v[74:75]
	global_store_dwordx2 v[74:75], v[70:71], off
	v_add_u32_e32 v70, s55, v81
	ds_read_b32 v74, v70
	s_waitcnt lgkmcnt(1)
	v_pk_mul_f32 v[70:71], v[78:79], v[80:81] op_sel_hi:[1,0]
	v_pk_mul_f32 v[60:61], v[60:61], v[80:81] op_sel_hi:[1,0]
	v_cvt_pk_bf16_f32 v61, v71, v61
	v_cvt_pk_bf16_f32 v70, v70, v70
	v_and_b32_sdwa v78, v60, v98 dst_sel:DWORD dst_unused:UNUSED_PAD src0_sel:WORD_1 src1_sel:DWORD
	v_add3_u32 v60, v60, v78, s49
	v_ashrrev_i32_e32 v31, 31, v30
	v_and_b32_e32 v60, 0xffff0000, v60
	s_waitcnt lgkmcnt(0)
	v_mul_f32_e32 v14, v14, v74
	v_or_b32_sdwa v60, v60, v70 dst_sel:DWORD dst_unused:UNUSED_PAD src0_sel:DWORD src1_sel:WORD_1
	v_lshlrev_b64 v[70:71], 9, v[30:31]
	v_lshlrev_b32_e32 v30, 1, v30
	v_cvt_pk_bf16_f32 v14, v14, v14
	v_add_u32_e32 v31, v51, v30
	ds_write_b16_d16_hi v31, v14
	v_mul_f32_e32 v14, v56, v74
	v_bfe_u32 v31, v14, 16, 1
	v_add3_u32 v14, v14, v31, s49
	v_add3_u32 v30, s80, v30, v7
	ds_write_b16_d16_hi v30, v14 offset:144
	v_mul_f32_e32 v14, v15, v74
	v_cvt_pk_bf16_f32 v14, v14, v14
	ds_write_b16_d16_hi v30, v14 offset:288
	v_mul_f32_e32 v14, v57, v74
	v_cvt_pk_bf16_f32 v14, v14, v14
	ds_write_b16_d16_hi v30, v14 offset:432
	v_or_b32_e32 v14, 7, v50
	v_add_u32_e32 v15, s91, v14
	v_and_b32_e32 v15, 0xffffefff, v15
	v_cmp_eq_u32_e32 vcc, s82, v15
	v_lshlrev_b32_e32 v56, 16, v42
	v_lshlrev_b32_e32 v57, 16, v43
	v_pk_mul_f32 v[64:65], v[64:65], v[76:77]
	v_cndmask_b32_e64 v30, 1.0, 0, vcc
	v_and_b32_e32 v42, 0xffff0000, v42
	v_and_b32_e32 v43, 0xffff0000, v43
	v_pk_fma_f32 v[2:3], v[2:3], v[72:73], v[64:65]
	v_pk_mul_f32 v[56:57], v[66:67], v[56:57]
	v_pk_mul_f32 v[28:29], v[28:29], v[46:47]
	v_pk_fma_f32 v[2:3], v[56:57], v[30:31], v[2:3] op_sel_hi:[1,0,1]
	v_pk_fma_f32 v[28:29], v[32:33], v[52:53], v[28:29]
	v_pk_mul_f32 v[20:21], v[20:21], v[42:43]
	v_pk_add_f32 v[2:3], v[68:69], v[2:3]
	v_pk_fma_f32 v[20:21], v[20:21], v[30:31], v[28:29] op_sel_hi:[1,0,1]
	v_mul_f32_e32 v15, 0xbfb8aa3b, v2
	v_pk_add_f32 v[20:21], v[24:25], v[20:21]
	v_exp_f32_e32 v15, v15
	v_mul_f32_e32 v24, 0xbfb8aa3b, v20
	v_exp_f32_e32 v25, v24
	v_mul_f32_e32 v28, 0xbfb8aa3b, v21
	v_add_f32_e32 v15, 1.0, v15
	v_rcp_f32_e32 v24, v15
	v_add_f32_e32 v15, 1.0, v25
	v_mul_f32_e32 v25, 0xbfb8aa3b, v3
	v_exp_f32_e32 v25, v25
	v_exp_f32_e32 v29, v28
	v_rcp_f32_e32 v28, v15
	v_lshlrev_b32_e32 v75, 16, v41
	v_add_f32_e32 v15, 1.0, v25
	v_rcp_f32_e32 v25, v15
	v_add_f32_e32 v15, 1.0, v29
	v_rcp_f32_e32 v29, v15
	v_lshlrev_b32_e32 v74, 16, v40
	v_pk_mul_f32 v[18:19], v[18:19], v[62:63]
	v_pk_mul_f32 v[2:3], v[2:3], v[24:25]
	v_pk_mul_f32 v[20:21], v[20:21], v[28:29]
	v_pk_fma_f32 v[10:11], v[58:59], v[10:11], v[18:19]
	v_cvt_pk_bf16_f32 v25, v3, v21
	v_pk_mul_f32 v[18:19], v[22:23], v[74:75]
	v_and_b32_e32 v33, 0xffff0000, v41
	v_and_b32_e32 v32, 0xffff0000, v40
	v_pk_fma_f32 v[10:11], v[30:31], v[18:19], v[10:11] op_sel_hi:[0,1,1]
	v_pk_mul_f32 v[16:17], v[16:17], v[44:45]
	v_pk_add_f32 v[10:11], v[26:27], v[10:11]
	v_pk_fma_f32 v[4:5], v[4:5], v[48:49], v[16:17]
	v_pk_mul_f32 v[12:13], v[12:13], v[32:33]
	v_mul_f32_e32 v15, 0xbfb8aa3b, v10
	v_pk_fma_f32 v[4:5], v[30:31], v[12:13], v[4:5] op_sel_hi:[0,1,1]
	v_exp_f32_e32 v15, v15
	v_pk_add_f32 v[4:5], v[8:9], v[4:5]
	v_mul_f32_e32 v12, 0xbfb8aa3b, v11
	v_mul_f32_e32 v8, 0xbfb8aa3b, v4
	v_exp_f32_e32 v9, v8
	v_exp_f32_e32 v13, v12
	v_mul_f32_e32 v12, 0xbfb8aa3b, v5
	v_add_f32_e32 v8, 1.0, v15
	v_exp_f32_e32 v15, v12
	v_add_f32_e32 v9, 1.0, v9
	v_rcp_f32_e32 v12, v9
	v_add_f32_e32 v9, 1.0, v13
	v_rcp_f32_e32 v8, v8
	v_rcp_f32_e32 v9, v9
	v_add_f32_e32 v13, 1.0, v15
	v_rcp_f32_e32 v13, v13
	v_cvt_pk_bf16_f32 v24, v2, v20
	v_pk_mul_f32 v[8:9], v[10:11], v[8:9]
	v_pk_mul_f32 v[8:9], v[8:9], s[48:49] op_sel_hi:[1,0]
	v_pk_mul_f32 v[4:5], v[4:5], v[12:13]
	v_pk_mul_f32 v[4:5], v[4:5], s[48:49] op_sel_hi:[1,0]
	v_cvt_pk_bf16_f32 v11, v9, v5
	v_cvt_pk_bf16_f32 v10, v8, v4
	ds_write_b64 v6, v[10:11] offset:36960
	v_lshlrev_b32_e32 v10, 2, v14
	ds_write_b64 v6, v[24:25] offset:3168
	v_add_u32_e32 v6, s54, v10
	ds_read_b32 v6, v6
	v_add_u32_e32 v10, s55, v10
	ds_read_b32 v12, v10
	v_ashrrev_i32_e32 v15, 31, v14
	v_lshl_add_u64 v[70:71], v[54:55], 0, v[70:71]
	s_waitcnt lgkmcnt(1)
	v_pk_mul_f32 v[2:3], v[2:3], v[6:7] op_sel_hi:[1,0]
	v_pk_mul_f32 v[10:11], v[20:21], v[6:7] op_sel_hi:[1,0]
	v_cvt_pk_bf16_f32 v2, v2, v10
	v_cvt_pk_bf16_f32 v3, v3, v11
	v_lshlrev_b64 v[10:11], 9, v[14:15]
	v_lshl_add_u64 v[10:11], v[54:55], 0, v[10:11]
	global_store_dwordx2 v[10:11], v[2:3], off
	s_waitcnt lgkmcnt(0)
	v_mul_f32_e32 v3, v8, v12
	v_lshlrev_b32_e32 v2, 1, v14
	v_cvt_pk_bf16_f32 v3, v3, v3
	v_add_u32_e32 v6, v51, v2
	ds_write_b16_d16_hi v6, v3
	v_mul_f32_e32 v3, v4, v12
	v_cvt_pk_bf16_f32 v3, v3, v3
	v_add3_u32 v2, s80, v2, v7
	ds_write_b16_d16_hi v2, v3 offset:144
	v_mul_f32_e32 v3, v9, v12
	v_cvt_pk_bf16_f32 v3, v3, v3
	ds_write_b16_d16_hi v2, v3 offset:288
	v_mul_f32_e32 v3, v5, v12
	v_cvt_pk_bf16_f32 v3, v3, v3
	ds_write_b16_d16_hi v2, v3 offset:432
	v_and_b32_e32 v3, 48, v99
	v_and_or_b32 v2, v50, s28, v39
	v_add_u32_e32 v6, 0, v3
	v_mad_u64_u32 v[32:33], s[28:29], v2, s81, v[6:7]
	global_store_dwordx2 v[70:71], v[60:61], off
	s_waitcnt lgkmcnt(0)
	s_barrier
	ds_read_b128 v[2:5], v32
	v_and_or_b32 v10, v34, 32, v39
	v_mad_u32_u24 v11, v10, s81, v6
	ds_read_b128 v[12:15], v32 offset:64
	ds_read_b128 v[6:9], v11 offset:33792
	ds_read_b128 v[16:19], v11 offset:33856
	ds_read_b128 v[20:23], v32 offset:128
	s_waitcnt lgkmcnt(2)
	v_mfma_f32_16x16x32_bf16 v[6:9], v[2:5], v[6:9], 0
	s_add_i32 s28, 0, 0x1bd00
	s_waitcnt lgkmcnt(1)
	v_mfma_f32_16x16x32_bf16 v[6:9], v[12:15], v[16:19], v[6:9]
	ds_read_b128 v[16:19], v32 offset:192
	ds_read_b128 v[24:27], v11 offset:33920
	ds_read_b128 v[28:31], v11 offset:33984
	s_waitcnt lgkmcnt(1)
	v_mfma_f32_16x16x32_bf16 v[6:9], v[20:23], v[24:27], v[6:9]
	ds_read_b128 v[24:27], v32 offset:256
	s_waitcnt lgkmcnt(1)
	v_mfma_f32_16x16x32_bf16 v[6:9], v[16:19], v[28:31], v[6:9]
	ds_read_b128 v[28:31], v32 offset:320
	ds_read_b128 v[40:43], v11 offset:34048
	ds_read_b128 v[44:47], v11 offset:34112
	s_waitcnt lgkmcnt(1)
	v_mfma_f32_16x16x32_bf16 v[6:9], v[24:27], v[40:43], v[6:9]
	ds_read_b128 v[40:43], v32 offset:384
	s_waitcnt lgkmcnt(1)
	v_mfma_f32_16x16x32_bf16 v[6:9], v[28:31], v[44:47], v[6:9]
	ds_read_b128 v[44:47], v32 offset:448
	ds_read_b128 v[48:51], v11 offset:34176
	ds_read_b128 v[52:55], v11 offset:34240
	s_waitcnt lgkmcnt(1)
	v_mfma_f32_16x16x32_bf16 v[6:9], v[40:43], v[48:51], v[6:9]
	s_waitcnt lgkmcnt(0)
	v_mfma_f32_16x16x32_bf16 v[6:9], v[44:47], v[52:55], v[6:9]
	ds_read_b128 v[48:51], v11 offset:42240
	ds_read_b128 v[52:55], v11 offset:42304
	s_waitcnt lgkmcnt(1)
	v_mfma_f32_16x16x32_bf16 v[2:5], v[2:5], v[48:51], 0
	s_waitcnt lgkmcnt(0)
	v_mfma_f32_16x16x32_bf16 v[2:5], v[12:15], v[52:55], v[2:5]
	ds_read_b128 v[12:15], v11 offset:42368
	ds_read_b128 v[48:51], v11 offset:42432
	s_waitcnt lgkmcnt(1)
	v_mfma_f32_16x16x32_bf16 v[2:5], v[20:23], v[12:15], v[2:5]
	s_waitcnt lgkmcnt(0)
	v_mfma_f32_16x16x32_bf16 v[2:5], v[16:19], v[48:51], v[2:5]
	ds_read_b128 v[12:15], v11 offset:42496
	ds_read_b128 v[16:19], v11 offset:42560
	s_waitcnt lgkmcnt(1)
	v_mfma_f32_16x16x32_bf16 v[2:5], v[24:27], v[12:15], v[2:5]
	s_waitcnt lgkmcnt(0)
	v_mfma_f32_16x16x32_bf16 v[2:5], v[28:31], v[16:19], v[2:5]
	ds_read_b128 v[12:15], v11 offset:42624
	ds_read_b128 v[16:19], v11 offset:42688
	v_ashrrev_i32_e32 v11, 3, v38
	v_and_b32_e32 v11, -16, v11
	s_waitcnt lgkmcnt(1)
	v_mfma_f32_16x16x32_bf16 v[2:5], v[40:43], v[12:15], v[2:5]
	v_lshrrev_b32_e32 v12, 2, v99
	v_and_or_b32 v11, v12, 12, v11
	v_cmp_le_i32_e32 vcc, v10, v11
	s_waitcnt lgkmcnt(0)
	v_mfma_f32_16x16x32_bf16 v[2:5], v[44:47], v[16:19], v[2:5]
	v_mov_b32_e32 v15, 0
	v_cndmask_b32_e64 v12, 0, 1, vcc
	v_cmp_ge_i32_e32 vcc, v10, v11
	v_lshl_add_u32 v19, v10, 2, s28
	s_nop 0
	v_cndmask_b32_e64 v13, 0, 1, vcc
	v_cndmask_b32_e64 v12, v13, v12, s[6:7]
	v_and_b32_e32 v12, 1, v12
	v_cmp_eq_u32_e32 vcc, 1, v12
	v_lshl_add_u32 v12, v11, 2, 0
	v_mov_b32_e32 v13, 0
	s_and_saveexec_b64 s[54:55], vcc
	s_cbranch_execz .LBB0_1770
	v_add_u32_e32 v13, 0x1bc00, v12
	ds_read_b32 v13, v13
	ds_read_b32 v14, v19
	s_waitcnt lgkmcnt(0)
	v_add_f32_e32 v13, v13, v14
	v_mul_f32_e32 v13, 0x3fb8aa3b, v13
	v_exp_f32_e32 v13, v13
	s_nop 0
	v_mul_f32_e32 v13, v6, v13
.LBB0_1770:
	s_or_b64 exec, exec, s[54:55]
	v_lshl_add_u32 v20, v10, 1, s83
	v_cvt_pk_bf16_f32 v6, v13, v13
	v_mul_lo_u32 v13, v11, s84
	v_add_u32_e32 v14, v20, v13
	ds_write_b16_d16_hi v14, v6
	v_or_b32_e32 v14, 1, v11
	v_cmp_gt_i32_e32 vcc, v10, v11
	s_nop 1
	v_cndmask_b32_e64 v6, 0, 1, vcc
	v_cmp_le_i32_e32 vcc, v10, v14
	s_nop 1
	v_cndmask_b32_e64 v16, 0, 1, vcc
	v_cndmask_b32_e64 v6, v6, v16, s[6:7]
	v_and_b32_e32 v6, 1, v6
	v_cmp_eq_u32_e32 vcc, 1, v6
	v_lshl_add_u32 v6, v14, 2, 0
	s_and_saveexec_b64 s[54:55], vcc
	s_cbranch_execz .LBB0_1772
	v_add_u32_e32 v15, 0x1bc00, v6
	ds_read_b32 v15, v15
	ds_read_b32 v16, v19
	s_waitcnt lgkmcnt(0)
	v_add_f32_e32 v15, v15, v16
	v_mul_f32_e32 v15, 0x3fb8aa3b, v15
	v_exp_f32_e32 v15, v15
	s_nop 0
	v_mul_f32_e32 v15, v7, v15
.LBB0_1772:
	s_or_b64 exec, exec, s[54:55]
	v_add_u32_e32 v16, 0x90, v13
	v_cvt_pk_bf16_f32 v7, v15, v15
	v_add_u32_e32 v15, v20, v16
	ds_write_b16_d16_hi v15, v7
	v_or_b32_e32 v15, 2, v11
	v_cmp_le_i32_e32 vcc, v10, v15
	v_mov_b32_e32 v21, 0
	s_nop 0
	v_cndmask_b32_e64 v7, 0, 1, vcc
	v_cmp_ge_i32_e32 vcc, v10, v15
	s_nop 1
	v_cndmask_b32_e64 v17, 0, 1, vcc
	v_cndmask_b32_e64 v7, v17, v7, s[6:7]
	v_and_b32_e32 v7, 1, v7
	v_cmp_eq_u32_e32 vcc, 1, v7
	v_lshl_add_u32 v7, v15, 2, 0
	v_mov_b32_e32 v17, 0
	s_and_saveexec_b64 s[54:55], vcc
	s_cbranch_execz .LBB0_1774
	v_add_u32_e32 v17, 0x1bc00, v7
	ds_read_b32 v17, v17
	ds_read_b32 v18, v19
	s_waitcnt lgkmcnt(0)
	v_add_f32_e32 v17, v17, v18
	v_mul_f32_e32 v17, 0x3fb8aa3b, v17
	v_exp_f32_e32 v17, v17
	s_nop 0
	v_mul_f32_e32 v17, v8, v17
.LBB0_1774:
	s_or_b64 exec, exec, s[54:55]
	v_add_u32_e32 v18, 0x90, v16
	v_cvt_pk_bf16_f32 v8, v17, v17
	v_add_u32_e32 v17, v20, v18
	ds_write_b16_d16_hi v17, v8
	v_or_b32_e32 v17, 3, v11
	v_cmp_le_i32_e32 vcc, v10, v17
	s_nop 1
	v_cndmask_b32_e64 v8, 0, 1, vcc
	v_cmp_ge_i32_e32 vcc, v10, v17
	s_nop 1
	v_cndmask_b32_e64 v22, 0, 1, vcc
	v_cndmask_b32_e64 v8, v22, v8, s[6:7]
	v_and_b32_e32 v8, 1, v8
	v_cmp_eq_u32_e32 vcc, 1, v8
	v_lshl_add_u32 v8, v17, 2, 0
	s_and_saveexec_b64 s[54:55], vcc
	s_cbranch_execz .LBB0_1776
	v_add_u32_e32 v21, 0x1bc00, v8
	ds_read_b32 v21, v21
	ds_read_b32 v19, v19
	s_waitcnt lgkmcnt(0)
	v_add_f32_e32 v19, v21, v19
	v_mul_f32_e32 v19, 0x3fb8aa3b, v19
	v_exp_f32_e32 v19, v19
	s_nop 0
	v_mul_f32_e32 v21, v9, v19
.LBB0_1776:
	s_or_b64 exec, exec, s[54:55]
	v_cvt_pk_bf16_f32 v19, v21, v21
	v_add_u32_e32 v9, 0x90, v18
	v_add_u32_e32 v20, v20, v9
	ds_write_b16_d16_hi v20, v19
	v_or_b32_e32 v19, 16, v10
	v_cmp_le_i32_e32 vcc, v19, v11
	v_lshl_add_u32 v10, v19, 2, s28
	s_nop 0
	v_cndmask_b32_e64 v20, 0, 1, vcc
	v_cmp_ge_i32_e32 vcc, v19, v11
	s_nop 1
	v_cndmask_b32_e64 v21, 0, 1, vcc
	v_cndmask_b32_e64 v20, v21, v20, s[6:7]
	v_and_b32_e32 v20, 1, v20
	v_cmp_eq_u32_e32 vcc, 1, v20
	v_mov_b32_e32 v20, 0
	v_mov_b32_e32 v21, 0
	s_and_saveexec_b64 s[54:55], vcc
	s_cbranch_execz .LBB0_1778
	v_add_u32_e32 v12, 0x1bc00, v12
	ds_read_b32 v12, v12
	ds_read_b32 v21, v10
	s_waitcnt lgkmcnt(0)
	v_add_f32_e32 v12, v12, v21
	v_mul_f32_e32 v12, 0x3fb8aa3b, v12
	v_exp_f32_e32 v12, v12
	s_nop 0
	v_mul_f32_e32 v21, v2, v12
.LBB0_1778:
	s_or_b64 exec, exec, s[54:55]
	v_cvt_pk_bf16_f32 v12, v21, v21
	v_lshlrev_b32_e32 v2, 1, v19
	v_add3_u32 v13, s83, v13, v2
	v_cmp_le_i32_e32 vcc, v19, v14
	ds_write_b16_d16_hi v13, v12
	s_nop 0
	v_cndmask_b32_e64 v12, 0, 1, vcc
	v_cmp_gt_i32_e32 vcc, v19, v11
	s_nop 1
	v_cndmask_b32_e64 v11, 0, 1, vcc
	v_cndmask_b32_e64 v11, v11, v12, s[6:7]
	v_and_b32_e32 v11, 1, v11
	v_cmp_eq_u32_e32 vcc, 1, v11
	s_and_saveexec_b64 s[54:55], vcc
	s_cbranch_execz .LBB0_1780
	v_add_u32_e32 v6, 0x1bc00, v6
	ds_read_b32 v6, v6
	ds_read_b32 v11, v10
	s_waitcnt lgkmcnt(0)
	v_add_f32_e32 v6, v6, v11
	v_mul_f32_e32 v6, 0x3fb8aa3b, v6
	v_exp_f32_e32 v6, v6
	s_nop 0
	v_mul_f32_e32 v20, v3, v6
.LBB0_1780:
	s_or_b64 exec, exec, s[54:55]
	v_cvt_pk_bf16_f32 v3, v20, v20
	v_add3_u32 v6, s83, v16, v2
	v_cmp_le_i32_e32 vcc, v19, v15
	ds_write_b16_d16_hi v6, v3
	s_nop 0
	v_cndmask_b32_e64 v3, 0, 1, vcc
	v_cmp_ge_i32_e32 vcc, v19, v15
	s_nop 1
	v_cndmask_b32_e64 v6, 0, 1, vcc
	v_cndmask_b32_e64 v3, v6, v3, s[6:7]
	v_and_b32_e32 v3, 1, v3
	v_cmp_eq_u32_e32 vcc, 1, v3
	v_mov_b32_e32 v3, 0
	v_mov_b32_e32 v6, 0
	s_and_saveexec_b64 s[54:55], vcc
	s_cbranch_execz .LBB0_1782
	v_add_u32_e32 v6, 0x1bc00, v7
	ds_read_b32 v6, v6
	ds_read_b32 v7, v10
	s_waitcnt lgkmcnt(0)
	v_add_f32_e32 v6, v6, v7
	v_mul_f32_e32 v6, 0x3fb8aa3b, v6
	v_exp_f32_e32 v6, v6
	s_nop 0
	v_mul_f32_e32 v6, v4, v6
.LBB0_1782:
	s_or_b64 exec, exec, s[54:55]
	v_cvt_pk_bf16_f32 v4, v6, v6
	v_add3_u32 v6, s83, v18, v2
	v_cmp_le_i32_e32 vcc, v19, v17
	ds_write_b16_d16_hi v6, v4
	s_nop 0
	v_cndmask_b32_e64 v4, 0, 1, vcc
	v_cmp_ge_i32_e32 vcc, v19, v17
	s_nop 1
	v_cndmask_b32_e64 v6, 0, 1, vcc
	v_cndmask_b32_e64 v4, v6, v4, s[6:7]
	v_and_b32_e32 v4, 1, v4
	v_cmp_eq_u32_e32 vcc, 1, v4
	s_and_saveexec_b64 s[54:55], vcc
	s_cbranch_execz .LBB0_1784
	v_add_u32_e32 v3, 0x1bc00, v8
	ds_read_b32 v3, v3
	ds_read_b32 v4, v10
	s_waitcnt lgkmcnt(0)
	v_add_f32_e32 v3, v3, v4
	v_mul_f32_e32 v3, 0x3fb8aa3b, v3
	v_exp_f32_e32 v3, v3
	s_nop 0
	v_mul_f32_e32 v3, v5, v3

.LBB0_1805:
	v_add_u32_e32 v27, 0x400, v26
	v_lshlrev_b32_e32 v38, 16, v10
	ds_read2_b32 v[30:31], v26 offset1:65
	ds_read2_b32 v[32:33], v26 offset0:130 offset1:195
	ds_read2_b32 v[34:35], v27 offset0:4 offset1:69
	ds_read2_b32 v[36:37], v27 offset0:134 offset1:199
	v_mul_f32_e32 v27, 0xbfb8aa3b, v38
	v_exp_f32_e32 v27, v27
	v_lshlrev_b32_e32 v39, 16, v11
	v_mul_f32_e32 v40, 0xbfb8aa3b, v39
	v_exp_f32_e32 v41, v40
	v_and_b32_e32 v10, 0xffff0000, v10
	v_add_f32_e32 v27, 1.0, v27
	v_and_b32_e32 v11, 0xffff0000, v11
	v_rcp_f32_e32 v40, v27
	v_mul_f32_e32 v27, 0xbfb8aa3b, v10
	v_exp_f32_e32 v27, v27
	v_add_f32_e32 v41, 1.0, v41
	v_mul_f32_e32 v42, 0xbfb8aa3b, v11
	v_rcp_f32_e32 v41, v41
	v_exp_f32_e32 v43, v42
	v_add_f32_e32 v27, 1.0, v27
	v_rcp_f32_e32 v42, v27
	v_pk_mul_f32 v[38:39], v[40:41], v[38:39]
	v_add_f32_e32 v27, 1.0, v43
	s_waitcnt lgkmcnt(3)
	v_mov_b32_e32 v40, v30
	v_lshlrev_b32_e32 v30, 16, v12
	v_rcp_f32_e32 v43, v27
	v_mul_f32_e32 v27, 0xbfb8aa3b, v30
	v_exp_f32_e32 v27, v27
	s_waitcnt lgkmcnt(2)
	v_mov_b32_e32 v41, v32
	v_pk_mul_f32 v[10:11], v[42:43], v[10:11]
	v_mov_b32_e32 v32, v31
	v_lshlrev_b32_e32 v31, 16, v13
	v_pk_mul_f32 v[10:11], v[10:11], v[32:33]
	v_and_b32_e32 v12, 0xffff0000, v12
	v_add_f32_e32 v27, 1.0, v27
	v_mul_f32_e32 v32, 0xbfb8aa3b, v31
	v_and_b32_e32 v13, 0xffff0000, v13
	v_exp_f32_e32 v33, v32
	v_rcp_f32_e32 v32, v27
	v_mul_f32_e32 v27, 0xbfb8aa3b, v12
	v_pk_mul_f32 v[38:39], v[38:39], v[40:41]
	v_exp_f32_e32 v27, v27
	v_mul_f32_e32 v40, 0xbfb8aa3b, v13
	v_exp_f32_e32 v41, v40
	v_add_f32_e32 v33, 1.0, v33
	v_add_f32_e32 v27, 1.0, v27
	v_rcp_f32_e32 v40, v27
	v_add_f32_e32 v27, 1.0, v41
	v_rcp_f32_e32 v33, v33
	v_rcp_f32_e32 v41, v27
	s_and_b32 s4, s33, 0xffffffc0
	v_add_u32_e32 v28, s4, v23
	v_pk_mul_f32 v[30:31], v[32:33], v[30:31]
	s_waitcnt lgkmcnt(0)
	v_mov_b32_e32 v33, v36
	v_pk_mul_f32 v[12:13], v[40:41], v[12:13]
	v_mov_b32_e32 v36, v35
	v_mov_b32_e32 v32, v34
	v_pk_mul_f32 v[12:13], v[12:13], v[36:37]
	v_ashrrev_i32_e32 v29, 31, v28
	v_pk_mul_f32 v[30:31], v[30:31], v[32:33]
	v_cvt_pk_bf16_f32 v10, v38, v10
	s_and_b32 s14, s31, 0x3c0
	v_cvt_pk_bf16_f32 v11, v11, v11
	v_cvt_pk_bf16_f32 v12, v12, v12
	v_cvt_pk_bf16_f32 v13, v13, v13
	v_bfe_u32 v33, v30, 16, 1
	v_bfe_u32 v34, v31, 16, 1
	v_lshlrev_b64 v[28:29], 13, v[28:29]
	v_add3_u32 v31, v31, v34, s19
	v_add3_u32 v30, v30, v33, s19
	v_cvt_pk_bf16_f32 v32, v39, v39
	v_lshl_add_u64 v[28:29], s[12:13], 0, v[28:29]
	s_lshl_b32 s4, s14, 1
	v_lshrrev_b32_e32 v32, 16, v32
	v_lshrrev_b32_e32 v30, 16, v30
	v_lshrrev_b32_e32 v31, 16, v31
	v_lshl_add_u64 v[28:29], v[28:29], 0, s[4:5]
	v_and_or_b32 v13, v13, s18, v31
	v_and_or_b32 v12, v12, s18, v30
	v_and_or_b32 v11, v11, s18, v32
	v_lshl_add_u64 v[28:29], v[28:29], 0, v[18:19]
	global_store_dwordx4 v[28:29], v[10:13], off offset:2048
	s_waitcnt lgkmcnt(0)
	s_barrier
	s_andn2_b64 vcc, exec, s[6:7]
	s_mov_b32 s31, s21
	s_waitcnt vmcnt(1)
	v_mov_b64_e32 v[10:11], v[14:15]
	s_mov_b32 s33, s20
	v_mov_b64_e32 v[12:13], v[16:17]
	s_cbranch_vccz .LBB0_1810

.LBB0_1869:
	ds_read2_b32 v[20:21], v18 offset1:65
	ds_read2_b32 v[22:23], v18 offset0:130 offset1:195
	v_add_u32_e32 v19, 0x400, v18
	ds_read2_b32 v[26:27], v19 offset0:4 offset1:69
	ds_read2_b32 v[28:29], v19 offset0:134 offset1:199
	s_and_b32 s8, s46, 0xffffffc0
	s_waitcnt lgkmcnt(3)
	v_cvt_pk_bf16_f32 v20, v20, v21
	s_waitcnt lgkmcnt(2)
	v_cvt_pk_bf16_f32 v21, v22, v23
	s_waitcnt lgkmcnt(1)
	v_cvt_pk_bf16_f32 v22, v26, v27
	v_add_u32_e32 v24, s8, v15
	v_ashrrev_i32_e32 v25, 31, v24
	s_and_b32 s0, s0, 0x3c0
	s_waitcnt lgkmcnt(0)
	v_lshlrev_b64 v[24:25], 11, v[24:25]
	v_cvt_pk_bf16_f32 v19, v28, v28
	v_lshl_add_u64 v[24:25], s[14:15], 0, v[24:25]
	s_lshl_b32 s0, s0, 1
	v_lshrrev_b32_e32 v19, 16, v19
	v_cvt_pk_bf16_f32 v23, v29, v29
	v_lshl_add_u64 v[24:25], v[24:25], 0, s[0:1]
	v_and_or_b32 v23, v23, s28, v19
	v_lshl_add_u64 v[24:25], v[24:25], 0, v[10:11]
	global_store_dwordx4 v[24:25], v[20:23], off
	s_waitcnt lgkmcnt(0)
	s_barrier
	s_andn2_b64 vcc, exec, s[6:7]
	s_mov_b32 s0, s47
	s_mov_b32 s46, s45
	s_cbranch_vccz .LBB0_1874

.LBB0_1889:
	v_cvt_pk_bf16_f32 v90, v30, v31
	v_cvt_pk_bf16_f32 v91, v32, v33
	v_cvt_pk_bf16_f32 v92, v38, v39
	v_cvt_pk_bf16_f32 v93, v40, v41
	ds_write_b128 v78, v[90:93] offset:49664
	v_cvt_pk_bf16_f32 v90, v34, v35
	v_cvt_pk_bf16_f32 v91, v36, v37
	v_cvt_pk_bf16_f32 v92, v42, v43
	v_cvt_pk_bf16_f32 v2, v44, v44
	v_bfe_u32 v4, v45, 16, 1
	v_lshrrev_b32_e32 v2, 16, v2
	v_add3_u32 v4, v45, v4, s66
	v_and_or_b32 v93, v4, s67, v2
	ds_write_b128 v78, v[90:93] offset:50688

.LBB0_1915:
	v_cvt_pk_bf16_f32 v154, v58, v59
	v_cvt_pk_bf16_f32 v155, v60, v61
	v_cvt_pk_bf16_f32 v156, v62, v63
	v_cvt_pk_bf16_f32 v157, v64, v65
	ds_write_b128 v141, v[154:157]
	v_cvt_pk_bf16_f32 v154, v54, v55
	v_cvt_pk_bf16_f32 v155, v56, v57
	v_cvt_pk_bf16_f32 v156, v74, v75
	v_cvt_pk_bf16_f32 v157, v76, v77
	ds_write_b128 v141, v[154:157] offset:1024
	v_cvt_pk_bf16_f32 v154, v50, v51
	v_cvt_pk_bf16_f32 v155, v52, v53
	v_cvt_pk_bf16_f32 v156, v90, v91
	v_cvt_pk_bf16_f32 v157, v92, v93
	ds_write_b128 v141, v[154:157] offset:2048
	v_cvt_pk_bf16_f32 v154, v66, v67
	v_cvt_pk_bf16_f32 v155, v68, v69
	v_cvt_pk_bf16_f32 v156, v82, v83
	v_cvt_pk_bf16_f32 v157, v84, v85
	ds_write_b128 v141, v[154:157] offset:3072
	v_cvt_pk_bf16_f32 v154, v70, v71
	v_cvt_pk_bf16_f32 v155, v72, v73
	v_cvt_pk_bf16_f32 v156, v86, v87
	v_cvt_pk_bf16_f32 v157, v88, v89
	ds_write_b128 v141, v[154:157] offset:4096
	v_cvt_pk_bf16_f32 v154, v78, v79
	v_cvt_pk_bf16_f32 v155, v80, v81
	v_cvt_pk_bf16_f32 v156, v94, v95
	v_cvt_pk_bf16_f32 v2, v96, v96
	v_bfe_u32 v4, v97, 16, 1
	v_lshrrev_b32_e32 v2, 16, v2
	v_add3_u32 v4, v97, v4, s66
	v_and_or_b32 v157, v4, s67, v2
	ds_write_b128 v141, v[154:157] offset:5120

.LBB0_1933:
	ds_read2_b32 v[20:21], v18 offset1:65
	ds_read2_b32 v[22:23], v18 offset0:130 offset1:195
	v_add_u32_e32 v19, 0x400, v18
	ds_read2_b32 v[26:27], v19 offset0:4 offset1:69
	ds_read2_b32 v[28:29], v19 offset0:134 offset1:199
	s_and_b32 s0, s10, 0xffffffc0
	s_waitcnt lgkmcnt(3)
	v_cvt_pk_bf16_f32 v20, v20, v21
	s_waitcnt lgkmcnt(2)
	v_cvt_pk_bf16_f32 v21, v22, v23
	s_waitcnt lgkmcnt(1)
	v_cvt_pk_bf16_f32 v22, v26, v27
	v_add_u32_e32 v24, s0, v15
	v_ashrrev_i32_e32 v25, 31, v24
	s_and_b32 s3, s3, 0x3c0
	s_waitcnt lgkmcnt(0)
	v_lshlrev_b64 v[24:25], 11, v[24:25]
	v_cvt_pk_bf16_f32 v19, v28, v28
	v_lshl_add_u64 v[24:25], s[14:15], 0, v[24:25]
	s_lshl_b32 s0, s3, 1
	v_lshrrev_b32_e32 v19, 16, v19
	v_cvt_pk_bf16_f32 v23, v29, v29
	v_lshl_add_u64 v[24:25], v[24:25], 0, s[0:1]
	v_and_or_b32 v23, v23, s8, v19
	v_lshl_add_u64 v[24:25], v[24:25], 0, v[10:11]
	global_store_dwordx4 v[24:25], v[20:23], off
	s_waitcnt lgkmcnt(0)
	s_barrier
	s_andn2_b64 vcc, exec, s[4:5]
	s_mov_b32 s3, s19
	s_mov_b32 s10, s17
	s_cbranch_vccz .LBB0_1938

.LBB0_2009:
	v_pk_add_f32 v[28:29], v[28:29], v[32:33]
	v_pk_add_f32 v[30:31], v[30:31], v[34:35]
	v_pk_mul_f32 v[34:35], v[28:29], v[28:29]
	v_pk_mul_f32 v[32:33], v[30:31], v[30:31]
	v_add_f32_e32 v34, v34, v35
	v_add_f32_e32 v32, v32, v34
	v_add_f32_e32 v32, v33, v32
	ds_bpermute_b32 v33, v1, v32
	v_pk_add_f32 v[22:23], v[22:23], v[26:27]
	v_pk_add_f32 v[20:21], v[20:21], v[24:25]
	v_lshlrev_b32_e32 v25, 16, v60
	v_mul_f32_e32 v25, 0xbfb8aa3b, v25
	s_waitcnt lgkmcnt(0)
	v_add_f32_e32 v26, v32, v33
	ds_bpermute_b32 v27, v62, v26
	v_and_b32_e32 v32, 0xffff0000, v60
	v_exp_f32_e32 v25, v25
	v_lshlrev_b32_e32 v33, 16, v61
	v_and_b32_e32 v34, 0xffff0000, v61
	s_waitcnt lgkmcnt(0)
	v_add_f32_e32 v26, v26, v27
	ds_bpermute_b32 v27, v63, v26
	v_add_f32_e32 v25, 1.0, v25
	v_mul_f32_e32 v33, 0xbfb8aa3b, v33
	v_mul_f32_e32 v34, 0xbfb8aa3b, v34
	v_lshlrev_b32_e32 v24, 16, v52
	s_waitcnt lgkmcnt(0)
	v_add_f32_e32 v26, v26, v27
	ds_bpermute_b32 v27, v64, v26
	v_exp_f32_e32 v33, v33
	v_exp_f32_e32 v34, v34
	v_mul_f32_e32 v35, 0xbfb8aa3b, v24
	v_exp_f32_e32 v35, v35
	s_waitcnt lgkmcnt(0)
	v_add_f32_e32 v26, v26, v27
	ds_bpermute_b32 v27, v65, v26
	v_add_f32_e32 v33, 1.0, v33
	v_add_f32_e32 v34, 1.0, v34
	v_and_b32_e32 v52, 0xffff0000, v52
	v_add_f32_e32 v35, 1.0, v35
	s_waitcnt lgkmcnt(0)
	v_add_f32_e32 v27, v26, v27
	ds_bpermute_b32 v60, v66, v27
	v_rcp_f32_e32 v26, v25
	v_mov_b32_e32 v72, v20
	v_mul_f32_e32 v32, 0xbfb8aa3b, v32
	v_exp_f32_e32 v32, v32
	s_waitcnt lgkmcnt(0)
	v_add_f32_e32 v25, v27, v60
	v_fmamk_f32 v25, v25, 0x3b800000, v67
	v_mul_f32_e32 v27, 0x4b800000, v25
	v_cmp_gt_f32_e32 vcc, s3, v25
	v_mul_f32_e32 v60, 0xbfb8aa3b, v52
	v_exp_f32_e32 v61, v60
	v_cndmask_b32_e32 v25, v25, v27, vcc
	v_rsq_f32_e32 v25, v25
	v_rcp_f32_e32 v27, v33
	v_rcp_f32_e32 v33, v34
	v_rcp_f32_e32 v60, v35
	v_mul_f32_e32 v34, 0x45800000, v25
	v_cndmask_b32_e32 v34, v25, v34, vcc
	v_lshlrev_b32_e32 v25, 16, v53
	v_mul_f32_e32 v35, 0xbfb8aa3b, v25
	v_exp_f32_e32 v35, v35
	v_and_b32_e32 v53, 0xffff0000, v53
	v_add_f32_e32 v61, 1.0, v61
	v_rcp_f32_e32 v70, v61
	v_add_f32_e32 v20, 1.0, v35
	v_rcp_f32_e32 v61, v20
	v_mul_f32_e32 v20, 0xbfb8aa3b, v53
	v_exp_f32_e32 v20, v20
	v_add_f32_e32 v32, 1.0, v32
	v_rcp_f32_e32 v32, v32
	v_mov_b32_e32 v73, v22
	v_add_f32_e32 v20, 1.0, v20
	v_rcp_f32_e32 v71, v20
	v_pk_mul_f32 v[26:27], v[72:73], v[26:27]
	v_pk_mul_f32 v[24:25], v[60:61], v[24:25]
	v_mov_b32_e32 v22, v21
	v_pk_mul_f32 v[24:25], v[26:27], v[24:25]
	v_pk_mul_f32 v[20:21], v[22:23], v[32:33]
	v_pk_mul_f32 v[22:23], v[70:71], v[52:53]
	v_lshl_add_u64 v[42:43], v[42:43], 0, s[0:1]
	v_pk_mul_f32 v[20:21], v[20:21], v[22:23]
	v_cvt_pk_bf16_f32 v21, v25, v21
	v_cvt_pk_bf16_f32 v20, v24, v20
	v_lshl_add_u64 v[22:23], v[50:51], 0, v[36:37]
	v_add_co_u32_e32 v22, vcc, s11, v22
	v_and_b32_e32 v24, 0xffff0000, v40
	s_nop 0
	v_addc_co_u32_e32 v23, vcc, 0, v23, vcc
	global_store_dwordx2 v[22:23], v[20:21], off
	v_lshlrev_b32_e32 v20, 16, v40
	v_mul_f32_e32 v25, 0xbfb8aa3b, v20
	v_exp_f32_e32 v26, v25
	v_mul_f32_e32 v25, 0xbfb8aa3b, v24
	v_exp_f32_e32 v27, v25
	v_lshlrev_b32_e32 v21, 16, v41
	v_and_b32_e32 v25, 0xffff0000, v41
	v_add_f32_e32 v26, 1.0, v26
	v_add_f32_e32 v27, 1.0, v27
	v_rcp_f32_e32 v32, v27
	v_mul_f32_e32 v27, 0xbfb8aa3b, v21
	v_exp_f32_e32 v27, v27
	v_mov_b32_e32 v40, v28
	v_mul_f32_e32 v28, 0xbfb8aa3b, v25
	v_rcp_f32_e32 v26, v26
	v_add_f32_e32 v27, 1.0, v27
	v_rcp_f32_e32 v27, v27
	v_exp_f32_e32 v28, v28
	v_mov_b32_e32 v41, v30
	v_pk_mul_f32 v[40:41], v[40:41], v[34:35] op_sel_hi:[1,0]
	v_pk_mul_f32 v[20:21], v[26:27], v[20:21]
	v_add_f32_e32 v26, 1.0, v28
	v_rcp_f32_e32 v33, v26
	v_mov_b32_e32 v30, v29
	v_pk_mul_f32 v[40:41], v[2:3], v[40:41]
	v_pk_mul_f32 v[26:27], v[30:31], v[34:35] op_sel_hi:[1,0]
	v_pk_mul_f32 v[20:21], v[20:21], v[40:41]
	v_pk_mul_f32 v[26:27], v[38:39], v[26:27]
	v_pk_mul_f32 v[24:25], v[32:33], v[24:25]
	s_waitcnt vmcnt(5)
	v_mov_b64_e32 v[30:31], v[14:15]
	v_pk_mul_f32 v[24:25], v[24:25], v[26:27]
	v_cvt_pk_bf16_f32 v21, v21, v25
	v_cvt_pk_bf16_f32 v20, v20, v24
	global_store_dwordx2 v[22:23], v[20:21], off offset:2048
	v_mov_b64_e32 v[22:23], v[6:7]
	v_mov_b64_e32 v[26:27], v[10:11]
	s_waitcnt vmcnt(5)
	v_mov_b64_e32 v[34:35], v[18:19]
	v_lshl_add_u64 v[46:47], v[46:47], 0, s[34:35]
	v_lshl_add_u64 v[48:49], v[48:49], 0, s[34:35]
	v_lshl_add_u64 v[50:51], v[50:51], 0, s[36:37]
	s_andn2_b64 vcc, exec, s[38:39]
	v_mov_b64_e32 v[20:21], v[4:5]
	v_mov_b64_e32 v[24:25], v[8:9]
	v_mov_b64_e32 v[28:29], v[12:13]
	v_mov_b64_e32 v[32:33], v[16:17]
	s_waitcnt vmcnt(4)
	v_mov_b64_e32 v[60:61], v[56:57]
	s_waitcnt vmcnt(3)
	v_mov_b64_e32 v[52:53], v[54:55]
	s_waitcnt vmcnt(2)
	v_mov_b64_e32 v[40:41], v[58:59]
	s_cbranch_vccz .LBB0_2012

.LBB0_2016:
	v_pk_add_f32 v[20:21], v[20:21], v[24:25]
	v_pk_add_f32 v[22:23], v[22:23], v[26:27]
	v_pk_mul_f32 v[26:27], v[20:21], v[20:21]
	v_pk_mul_f32 v[24:25], v[22:23], v[22:23]
	v_add_f32_e32 v26, v26, v27
	v_add_f32_e32 v24, v24, v26
	v_add_f32_e32 v26, v25, v24
	ds_bpermute_b32 v27, v1, v26
	v_pk_add_f32 v[24:25], v[30:31], v[34:35]
	v_and_b32_e32 v34, 0xffff0000, v61
	v_mul_f32_e32 v34, 0xbfb8aa3b, v34
	v_exp_f32_e32 v34, v34
	s_waitcnt lgkmcnt(0)
	v_add_f32_e32 v30, v26, v27
	ds_bpermute_b32 v31, v62, v30
	v_pk_add_f32 v[26:27], v[28:29], v[32:33]
	v_lshlrev_b32_e32 v29, 16, v60
	v_mul_f32_e32 v29, 0xbfb8aa3b, v29
	v_exp_f32_e32 v29, v29
	s_waitcnt lgkmcnt(0)
	v_add_f32_e32 v30, v30, v31
	ds_bpermute_b32 v31, v63, v30
	v_lshlrev_b32_e32 v33, 16, v61
	v_add_f32_e32 v29, 1.0, v29
	v_mul_f32_e32 v33, 0xbfb8aa3b, v33
	v_exp_f32_e32 v33, v33
	s_waitcnt lgkmcnt(0)
	v_add_f32_e32 v30, v30, v31
	ds_bpermute_b32 v31, v64, v30
	v_add_f32_e32 v34, 1.0, v34
	v_add_f32_e32 v33, 1.0, v33
	v_lshlrev_b32_e32 v28, 16, v58
	v_and_b32_e32 v58, 0xffff0000, v58
	s_waitcnt lgkmcnt(0)
	v_add_f32_e32 v30, v30, v31
	ds_bpermute_b32 v31, v65, v30
	v_and_b32_e32 v32, 0xffff0000, v60
	v_mul_f32_e32 v60, 0xbfb8aa3b, v58
	v_exp_f32_e32 v61, v60
	v_mov_b32_e32 v72, v26
	s_waitcnt lgkmcnt(0)
	v_add_f32_e32 v31, v30, v31
	ds_bpermute_b32 v35, v66, v31
	v_rcp_f32_e32 v30, v29
	v_add_f32_e32 v61, 1.0, v61
	v_mul_f32_e32 v32, 0xbfb8aa3b, v32
	v_rcp_f32_e32 v70, v61
	s_waitcnt lgkmcnt(0)
	v_add_f32_e32 v29, v31, v35
	v_fmamk_f32 v29, v29, 0x3b800000, v67
	v_mul_f32_e32 v31, 0x4b800000, v29
	v_cmp_gt_f32_e32 vcc, s1, v29
	v_exp_f32_e32 v32, v32
	v_mov_b32_e32 v73, v24
	v_cndmask_b32_e32 v29, v29, v31, vcc
	v_rsq_f32_e32 v29, v29
	v_rcp_f32_e32 v31, v33
	v_rcp_f32_e32 v33, v34
	v_add_f32_e32 v32, 1.0, v32
	v_mul_f32_e32 v34, 0x45800000, v29
	v_cndmask_b32_e32 v34, v29, v34, vcc
	v_mul_f32_e32 v29, 0xbfb8aa3b, v28
	v_exp_f32_e32 v35, v29
	v_lshlrev_b32_e32 v29, 16, v59
	v_and_b32_e32 v59, 0xffff0000, v59
	v_rcp_f32_e32 v32, v32
	v_add_f32_e32 v35, 1.0, v35
	v_rcp_f32_e32 v60, v35
	v_mul_f32_e32 v35, 0xbfb8aa3b, v29
	v_exp_f32_e32 v35, v35
	v_pk_mul_f32 v[30:31], v[72:73], v[30:31]
	s_addk_i32 s0, 0x88
	v_lshl_add_u64 v[42:43], v[42:43], 0, s[34:35]
	v_add_f32_e32 v26, 1.0, v35
	v_rcp_f32_e32 v61, v26
	v_mul_f32_e32 v26, 0xbfb8aa3b, v59
	v_exp_f32_e32 v26, v26
	v_lshl_add_u64 v[46:47], v[46:47], 0, s[36:37]
	v_pk_mul_f32 v[28:29], v[60:61], v[28:29]
	v_lshl_add_u64 v[48:49], v[48:49], 0, s[36:37]
	v_add_f32_e32 v24, 1.0, v26
	v_rcp_f32_e32 v71, v24
	v_mov_b32_e32 v24, v27
	v_pk_mul_f32 v[28:29], v[30:31], v[28:29]
	v_pk_mul_f32 v[24:25], v[24:25], v[32:33]
	v_pk_mul_f32 v[26:27], v[70:71], v[58:59]
	s_waitcnt vmcnt(2)
	v_mov_b64_e32 v[60:61], v[54:55]
	v_pk_mul_f32 v[24:25], v[24:25], v[26:27]
	v_cvt_pk_bf16_f32 v25, v29, v25
	v_cvt_pk_bf16_f32 v24, v28, v24
	v_lshl_add_u64 v[26:27], v[50:51], 0, v[36:37]
	v_add_co_u32_e32 v26, vcc, s10, v26
	v_and_b32_e32 v28, 0xffff0000, v40
	s_nop 0
	v_addc_co_u32_e32 v27, vcc, 0, v27, vcc
	global_store_dwordx2 v[26:27], v[24:25], off
	v_lshlrev_b32_e32 v24, 16, v40
	v_mul_f32_e32 v29, 0xbfb8aa3b, v24
	v_exp_f32_e32 v30, v29
	v_mul_f32_e32 v29, 0xbfb8aa3b, v28
	v_exp_f32_e32 v31, v29
	v_lshlrev_b32_e32 v25, 16, v41
	v_and_b32_e32 v29, 0xffff0000, v41
	v_mov_b32_e32 v40, v20
	v_add_f32_e32 v31, 1.0, v31
	v_rcp_f32_e32 v32, v31
	v_mul_f32_e32 v31, 0xbfb8aa3b, v25
	v_exp_f32_e32 v31, v31
	v_add_f32_e32 v30, 1.0, v30
	v_rcp_f32_e32 v30, v30
	v_mov_b32_e32 v41, v22
	v_add_f32_e32 v20, 1.0, v31
	v_rcp_f32_e32 v31, v20
	v_mul_f32_e32 v20, 0xbfb8aa3b, v29
	v_exp_f32_e32 v20, v20
	v_pk_mul_f32 v[40:41], v[40:41], v[34:35] op_sel_hi:[1,0]
	v_mov_b32_e32 v22, v21
	v_pk_mul_f32 v[40:41], v[2:3], v[40:41]
	v_add_f32_e32 v20, 1.0, v20
	v_rcp_f32_e32 v33, v20
	v_pk_mul_f32 v[24:25], v[30:31], v[24:25]
	v_pk_mul_f32 v[20:21], v[22:23], v[34:35] op_sel_hi:[1,0]
	v_pk_mul_f32 v[24:25], v[24:25], v[40:41]
	v_pk_mul_f32 v[20:21], v[38:39], v[20:21]
	v_pk_mul_f32 v[22:23], v[32:33], v[28:29]
	v_mov_b64_e32 v[30:31], v[6:7]
	v_pk_mul_f32 v[20:21], v[22:23], v[20:21]
	v_cvt_pk_bf16_f32 v21, v25, v21
	v_cvt_pk_bf16_f32 v20, v24, v20
	global_store_dwordx2 v[26:27], v[20:21], off offset:2048
	v_mov_b64_e32 v[34:35], v[10:11]
	v_mov_b64_e32 v[22:23], v[14:15]
	v_mov_b64_e32 v[26:27], v[18:19]
	v_lshl_add_u64 v[50:51], v[50:51], 0, s[38:39]
	s_and_b64 vcc, exec, s[40:41]
	v_mov_b64_e32 v[28:29], v[4:5]
	v_mov_b64_e32 v[32:33], v[8:9]
	v_mov_b64_e32 v[20:21], v[12:13]
	v_mov_b64_e32 v[24:25], v[16:17]
	s_waitcnt vmcnt(3)
	v_mov_b64_e32 v[58:59], v[52:53]
	s_waitcnt vmcnt(2)
	v_mov_b64_e32 v[40:41], v[56:57]
	s_cbranch_vccnz .LBB0_2019

.LBB0_2023:
	v_pk_add_f32 v[20:21], v[20:21], v[24:25]
	v_pk_add_f32 v[22:23], v[22:23], v[26:27]
	v_pk_mul_f32 v[26:27], v[20:21], v[20:21]
	v_pk_mul_f32 v[24:25], v[22:23], v[22:23]
	v_add_f32_e32 v26, v26, v27
	v_add_f32_e32 v24, v24, v26
	v_add_f32_e32 v26, v25, v24
	ds_bpermute_b32 v27, v1, v26
	v_pk_add_f32 v[24:25], v[30:31], v[34:35]
	v_and_b32_e32 v34, 0xffff0000, v61
	v_mul_f32_e32 v34, 0xbfb8aa3b, v34
	v_exp_f32_e32 v34, v34
	s_waitcnt lgkmcnt(0)
	v_add_f32_e32 v30, v26, v27
	ds_bpermute_b32 v31, v62, v30
	v_pk_add_f32 v[26:27], v[28:29], v[32:33]
	v_lshlrev_b32_e32 v29, 16, v60
	v_mul_f32_e32 v29, 0xbfb8aa3b, v29
	v_and_b32_e32 v32, 0xffff0000, v60
	s_waitcnt lgkmcnt(0)
	v_add_f32_e32 v30, v30, v31
	ds_bpermute_b32 v31, v63, v30
	v_exp_f32_e32 v29, v29
	v_lshlrev_b32_e32 v33, 16, v61
	v_mul_f32_e32 v33, 0xbfb8aa3b, v33
	v_lshlrev_b32_e32 v28, 16, v58
	s_waitcnt lgkmcnt(0)
	v_add_f32_e32 v30, v30, v31
	ds_bpermute_b32 v31, v64, v30
	v_add_f32_e32 v29, 1.0, v29
	v_exp_f32_e32 v33, v33
	v_mul_f32_e32 v35, 0xbfb8aa3b, v28
	v_exp_f32_e32 v35, v35
	s_waitcnt lgkmcnt(0)
	v_add_f32_e32 v30, v30, v31
	ds_bpermute_b32 v31, v65, v30
	v_add_f32_e32 v33, 1.0, v33
	v_add_f32_e32 v34, 1.0, v34
	v_and_b32_e32 v58, 0xffff0000, v58
	v_add_f32_e32 v35, 1.0, v35
	s_waitcnt lgkmcnt(0)
	v_add_f32_e32 v31, v30, v31
	ds_bpermute_b32 v60, v66, v31
	v_rcp_f32_e32 v30, v29
	v_mov_b32_e32 v72, v26
	v_mul_f32_e32 v32, 0xbfb8aa3b, v32
	v_exp_f32_e32 v32, v32
	s_waitcnt lgkmcnt(0)
	v_add_f32_e32 v29, v31, v60
	v_fmamk_f32 v29, v29, 0x3b800000, v67
	v_mul_f32_e32 v31, 0x4b800000, v29
	v_cmp_gt_f32_e32 vcc, s1, v29
	v_mul_f32_e32 v60, 0xbfb8aa3b, v58
	v_exp_f32_e32 v61, v60
	v_cndmask_b32_e32 v29, v29, v31, vcc
	v_rsq_f32_e32 v29, v29
	v_rcp_f32_e32 v31, v33
	v_rcp_f32_e32 v33, v34
	v_rcp_f32_e32 v60, v35
	v_mul_f32_e32 v34, 0x45800000, v29
	v_cndmask_b32_e32 v34, v29, v34, vcc
	v_lshlrev_b32_e32 v29, 16, v59
	v_mul_f32_e32 v35, 0xbfb8aa3b, v29
	v_exp_f32_e32 v35, v35
	v_and_b32_e32 v59, 0xffff0000, v59
	v_add_f32_e32 v61, 1.0, v61
	v_rcp_f32_e32 v70, v61
	v_add_f32_e32 v26, 1.0, v35
	v_rcp_f32_e32 v61, v26
	v_mul_f32_e32 v26, 0xbfb8aa3b, v59
	v_exp_f32_e32 v26, v26
	v_add_f32_e32 v32, 1.0, v32
	v_mov_b32_e32 v73, v24
	v_rcp_f32_e32 v32, v32
	v_add_f32_e32 v24, 1.0, v26
	v_rcp_f32_e32 v71, v24
	v_pk_mul_f32 v[30:31], v[72:73], v[30:31]
	v_pk_mul_f32 v[28:29], v[60:61], v[28:29]
	v_mov_b32_e32 v24, v27
	v_pk_mul_f32 v[28:29], v[30:31], v[28:29]
	v_pk_mul_f32 v[24:25], v[24:25], v[32:33]
	v_pk_mul_f32 v[26:27], v[70:71], v[58:59]
	s_add_i32 s0, s0, s34
	v_pk_mul_f32 v[24:25], v[24:25], v[26:27]
	v_cvt_pk_bf16_f32 v25, v29, v25
	v_cvt_pk_bf16_f32 v24, v28, v24
	v_lshl_add_u64 v[26:27], v[50:51], 0, v[36:37]
	v_add_co_u32_e32 v26, vcc, s11, v26
	v_and_b32_e32 v28, 0xffff0000, v44
	s_nop 0
	v_addc_co_u32_e32 v27, vcc, 0, v27, vcc
	global_store_dwordx2 v[26:27], v[24:25], off
	v_lshlrev_b32_e32 v24, 16, v44
	v_mul_f32_e32 v29, 0xbfb8aa3b, v24
	v_exp_f32_e32 v30, v29
	v_mul_f32_e32 v29, 0xbfb8aa3b, v28
	v_exp_f32_e32 v31, v29
	v_lshlrev_b32_e32 v25, 16, v45
	v_and_b32_e32 v29, 0xffff0000, v45
	v_mov_b32_e32 v44, v20
	v_add_f32_e32 v31, 1.0, v31
	v_rcp_f32_e32 v32, v31
	v_mul_f32_e32 v31, 0xbfb8aa3b, v25
	v_exp_f32_e32 v31, v31
	v_add_f32_e32 v30, 1.0, v30
	v_rcp_f32_e32 v30, v30
	v_mov_b32_e32 v45, v22
	v_add_f32_e32 v20, 1.0, v31
	v_rcp_f32_e32 v31, v20
	v_mul_f32_e32 v20, 0xbfb8aa3b, v29
	v_exp_f32_e32 v20, v20
	v_pk_mul_f32 v[44:45], v[44:45], v[34:35] op_sel_hi:[1,0]
	v_mov_b32_e32 v22, v21
	v_pk_mul_f32 v[44:45], v[2:3], v[44:45]
	v_add_f32_e32 v20, 1.0, v20
	v_rcp_f32_e32 v33, v20
	v_pk_mul_f32 v[24:25], v[30:31], v[24:25]
	v_pk_mul_f32 v[20:21], v[22:23], v[34:35] op_sel_hi:[1,0]
	v_pk_mul_f32 v[24:25], v[24:25], v[44:45]
	v_pk_mul_f32 v[20:21], v[38:39], v[20:21]
	v_pk_mul_f32 v[22:23], v[32:33], v[28:29]
	s_waitcnt vmcnt(7)
	v_mov_b64_e32 v[30:31], v[6:7]
	v_pk_mul_f32 v[20:21], v[22:23], v[20:21]
	v_cvt_pk_bf16_f32 v21, v25, v21
	v_cvt_pk_bf16_f32 v20, v24, v20
	global_store_dwordx2 v[26:27], v[20:21], off offset:2048
	s_waitcnt vmcnt(7)
	v_mov_b64_e32 v[34:35], v[10:11]
	s_waitcnt vmcnt(6)
	v_mov_b64_e32 v[22:23], v[14:15]
	s_waitcnt vmcnt(5)
	v_mov_b64_e32 v[26:27], v[18:19]
	v_lshl_add_u64 v[40:41], v[40:41], 0, s[4:5]
	v_lshl_add_u64 v[46:47], v[46:47], 0, s[18:19]
	v_lshl_add_u64 v[48:49], v[48:49], 0, s[18:19]
	v_lshl_add_u64 v[50:51], v[50:51], 0, s[16:17]
	s_cmp_ge_i32 s0, s3
	v_mov_b64_e32 v[28:29], v[4:5]
	v_mov_b64_e32 v[32:33], v[8:9]
	v_mov_b64_e32 v[20:21], v[12:13]
	v_mov_b64_e32 v[24:25], v[16:17]
	s_waitcnt vmcnt(4)
	v_mov_b64_e32 v[60:61], v[54:55]
	s_waitcnt vmcnt(3)
	v_mov_b64_e32 v[58:59], v[52:53]
	s_waitcnt vmcnt(2)
	v_mov_b64_e32 v[44:45], v[56:57]
	s_cbranch_scc1 .LBB0_2026

.LBB0_2289:
	ds_read2_b32 v[52:53], v89 offset1:65
	ds_read2_b32 v[78:79], v89 offset0:130 offset1:195
	s_mul_hi_i32 s6, s51, 0x8fb823ef
	s_add_i32 s6, s6, s51
	s_lshr_b32 s7, s6, 31
	s_waitcnt lgkmcnt(1)
	v_cvt_pk_bf16_f32 v106, v52, v53
	s_waitcnt lgkmcnt(0)
	v_cvt_pk_bf16_f32 v107, v78, v79
	ds_read2_b32 v[52:53], v102 offset0:4 offset1:69
	ds_read2_b32 v[78:79], v102 offset0:134 offset1:199
	s_waitcnt lgkmcnt(1)
	v_cvt_pk_bf16_f32 v108, v52, v53
	s_ashr_i32 s6, s6, 7
	s_add_i32 s6, s6, s7
	s_waitcnt lgkmcnt(0)
	v_cvt_pk_bf16_f32 v109, v78, v79
	s_mul_i32 s7, s6, 0xe4
	s_sub_i32 s7, s51, s7
	v_lshl_or_b32 v52, s7, 6, v88
	v_ashrrev_i32_e32 v53, 31, v52
	s_lshl_b32 s6, s6, 8
	v_lshlrev_b64 v[52:53], 13, v[52:53]
	v_lshl_add_u64 v[52:53], s[20:21], 0, v[52:53]
	ds_read2_b32 v[78:79], v90 offset1:65
	s_ashr_i32 s7, s6, 31
	v_lshl_add_u64 v[52:53], s[6:7], 1, v[52:53]
	v_lshl_add_u64 v[110:111], v[70:71], 1, v[52:53]
	global_store_dwordx4 v[110:111], v[106:109], off
	ds_read2_b32 v[108:109], v90 offset0:130 offset1:195
	s_waitcnt lgkmcnt(1)
	v_cvt_pk_bf16_f32 v106, v78, v79
	s_waitcnt lgkmcnt(0)
	ds_read2_b32 v[78:79], v103 offset0:4 offset1:69
	v_cvt_pk_bf16_f32 v107, v108, v109
	ds_read2_b32 v[102:103], v103 offset0:134 offset1:199
	s_waitcnt lgkmcnt(1)
	v_cvt_pk_bf16_f32 v108, v78, v79
	s_waitcnt lgkmcnt(0)
	ds_read2_b32 v[78:79], v91 offset1:65
	v_cvt_pk_bf16_f32 v109, v102, v103
	v_lshl_add_u64 v[102:103], v[72:73], 1, v[52:53]
	global_store_dwordx4 v[102:103], v[106:109], off
	ds_read2_b32 v[102:103], v91 offset0:130 offset1:195
	s_waitcnt lgkmcnt(1)
	v_cvt_pk_bf16_f32 v106, v78, v79
	ds_read2_b32 v[78:79], v104 offset0:4 offset1:69
	s_waitcnt lgkmcnt(1)
	v_cvt_pk_bf16_f32 v107, v102, v103
	ds_read2_b32 v[102:103], v104 offset0:134 offset1:199
	s_waitcnt lgkmcnt(1)
	v_cvt_pk_bf16_f32 v108, v78, v79
	ds_read2_b32 v[78:79], v92 offset1:65
	s_waitcnt lgkmcnt(1)
	v_cvt_pk_bf16_f32 v109, v102, v103
	v_lshl_add_u64 v[102:103], v[74:75], 1, v[52:53]
	global_store_dwordx4 v[102:103], v[106:109], off
	s_waitcnt lgkmcnt(0)
	v_cvt_pk_bf16_f32 v102, v78, v79
	ds_read2_b32 v[106:107], v92 offset0:130 offset1:195
	ds_read2_b32 v[78:79], v105 offset0:4 offset1:69
	s_waitcnt lgkmcnt(1)
	v_cvt_pk_bf16_f32 v103, v106, v107
	ds_read2_b32 v[106:107], v105 offset0:134 offset1:199
	s_waitcnt lgkmcnt(1)
	v_cvt_pk_bf16_f32 v104, v78, v79
	s_waitcnt lgkmcnt(0)
	v_cvt_pk_bf16_f32 v51, v106, v106
	v_bfe_u32 v78, v107, 16, 1
	v_lshrrev_b32_e32 v51, 16, v51
	v_add3_u32 v78, v107, v78, s47
	v_and_or_b32 v105, v78, s48, v51
	v_lshl_add_u64 v[52:53], v[76:77], 1, v[52:53]
	global_store_dwordx4 v[52:53], v[102:105], off
	s_waitcnt lgkmcnt(0)
	s_barrier

.LBB0_2382:
	ds_read2_b32 v[52:53], v89 offset1:65
	ds_read2_b32 v[78:79], v89 offset0:130 offset1:195
	v_add_u32_e32 v102, 0x400, v89
	s_mul_hi_i32 s6, s50, 0x8fb823ef
	s_add_i32 s6, s6, s50
	s_waitcnt lgkmcnt(1)
	v_cvt_pk_bf16_f32 v104, v52, v53
	s_waitcnt lgkmcnt(0)
	v_cvt_pk_bf16_f32 v105, v78, v79
	ds_read2_b32 v[52:53], v102 offset0:4 offset1:69
	ds_read2_b32 v[78:79], v102 offset0:134 offset1:199
	s_waitcnt lgkmcnt(1)
	v_cvt_pk_bf16_f32 v106, v52, v53
	s_lshr_b32 s7, s6, 31
	s_ashr_i32 s6, s6, 7
	s_add_i32 s7, s6, s7
	s_waitcnt lgkmcnt(0)
	v_cvt_pk_bf16_f32 v107, v78, v79
	s_lshl_b32 s6, s7, 8
	s_mulk_i32 s7, 0xc700
	s_add_i32 s7, s7, s38
	v_add_u32_e32 v52, s7, v88
	v_ashrrev_i32_e32 v53, 31, v52
	ds_read2_b32 v[78:79], v90 offset1:65
	v_lshlrev_b64 v[52:53], 13, v[52:53]
	v_lshl_add_u64 v[52:53], s[20:21], 0, v[52:53]
	s_ashr_i32 s7, s6, 31
	v_lshl_add_u64 v[52:53], s[6:7], 1, v[52:53]
	v_lshl_add_u64 v[108:109], v[70:71], 1, v[52:53]
	global_store_dwordx4 v[108:109], v[104:107], off
	s_waitcnt lgkmcnt(0)
	s_nop 0
	ds_read2_b32 v[106:107], v90 offset0:130 offset1:195
	v_cvt_pk_bf16_f32 v104, v78, v79
	v_add_u32_e32 v103, 0x400, v90
	ds_read2_b32 v[78:79], v103 offset0:4 offset1:69
	s_waitcnt lgkmcnt(1)
	v_cvt_pk_bf16_f32 v105, v106, v107
	ds_read2_b32 v[108:109], v103 offset0:134 offset1:199
	s_waitcnt lgkmcnt(1)
	v_cvt_pk_bf16_f32 v106, v78, v79
	s_waitcnt lgkmcnt(0)
	v_cvt_pk_bf16_f32 v107, v108, v109
	ds_read2_b32 v[78:79], v91 offset1:65
	v_lshl_add_u64 v[108:109], v[72:73], 1, v[52:53]
	global_store_dwordx4 v[108:109], v[104:107], off
	ds_read2_b32 v[104:105], v91 offset0:130 offset1:195
	s_waitcnt lgkmcnt(1)
	v_cvt_pk_bf16_f32 v106, v78, v79
	s_waitcnt lgkmcnt(0)
	v_cvt_pk_bf16_f32 v107, v104, v105
	v_add_u32_e32 v104, 0x400, v91
	ds_read2_b32 v[78:79], v104 offset0:4 offset1:69
	ds_read2_b32 v[110:111], v104 offset0:134 offset1:199
	s_waitcnt lgkmcnt(1)
	v_cvt_pk_bf16_f32 v108, v78, v79
	ds_read2_b32 v[78:79], v92 offset1:65
	s_waitcnt lgkmcnt(1)
	v_cvt_pk_bf16_f32 v109, v110, v111
	v_lshl_add_u64 v[110:111], v[74:75], 1, v[52:53]
	global_store_dwordx4 v[110:111], v[106:109], off
	s_waitcnt lgkmcnt(0)
	v_cvt_pk_bf16_f32 v106, v78, v79
	ds_read2_b32 v[108:109], v92 offset0:130 offset1:195
	v_add_u32_e32 v105, 0x400, v92
	ds_read2_b32 v[78:79], v105 offset0:4 offset1:69
	s_waitcnt lgkmcnt(1)
	v_cvt_pk_bf16_f32 v107, v108, v109
	ds_read2_b32 v[110:111], v105 offset0:134 offset1:199
	s_waitcnt lgkmcnt(1)
	v_cvt_pk_bf16_f32 v108, v78, v79
	s_waitcnt lgkmcnt(0)
	v_cvt_pk_bf16_f32 v51, v110, v110
	v_bfe_u32 v78, v111, 16, 1
	v_lshrrev_b32_e32 v51, 16, v51
	v_add3_u32 v78, v111, v78, s47
	v_and_or_b32 v109, v78, s48, v51
	v_lshl_add_u64 v[52:53], v[76:77], 1, v[52:53]
	global_store_dwordx4 v[52:53], v[106:109], off
	s_waitcnt lgkmcnt(0)
	s_barrier
	s_add_i32 s51, s24, s50
	s_cmpk_gt_i32 s51, 0xe3f
	s_cbranch_scc1 .LBB0_2290
	ds_write2_b32 v94, v22, v23 offset1:1
	ds_write2_b32 v94, v24, v25 offset0:2 offset1:3
	ds_write2_b32 v95, v30, v31 offset1:1
	ds_write2_b32 v95, v32, v33 offset0:2 offset1:3
	ds_write2_b32 v96, v38, v39 offset1:1
	ds_write2_b32 v96, v40, v41 offset0:2 offset1:3
	ds_write2_b32 v97, v46, v47 offset1:1
	ds_write2_b32 v97, v48, v49 offset0:2 offset1:3
	ds_write2_b32 v98, v54, v55 offset1:1
	ds_write2_b32 v98, v56, v57 offset0:2 offset1:3
	ds_write2_b32 v99, v58, v59 offset1:1
	ds_write2_b32 v99, v60, v61 offset0:2 offset1:3
	ds_write2_b32 v100, v62, v63 offset1:1
	ds_write2_b32 v100, v64, v65 offset0:2 offset1:3
	ds_write2_b32 v101, v66, v67 offset1:1
	ds_write2_b32 v101, v68, v69 offset0:2 offset1:3
	s_waitcnt lgkmcnt(0)
	s_barrier
	s_add_i32 s6, s40, s50
	s_cmpk_gt_i32 s6, 0xe3f
	s_cbranch_scc1 .LBB0_2289
	s_mul_hi_i32 s7, s6, 0x8fb823ef
	s_add_i32 s7, s7, s6
	s_lshr_b32 s28, s7, 31
	s_ashr_i32 s7, s7, 7
	s_add_i32 s28, s7, s28
	s_mul_i32 s7, s28, 0xe4
	s_sub_i32 s6, s6, s7
	s_lshl_b32 s50, s6, 6
	v_or_b32_e32 v78, s50, v1
	v_cmp_lt_i32_e64 s[6:7], s41, v78
	v_mov_b32_e32 v30, v78
	s_and_saveexec_b64 s[34:35], s[6:7]
	s_cbranch_execz .LBB0_2393
	s_cmpk_gt_u32 s50, 0x37ff
	s_mov_b64 s[36:37], -1
	s_cbranch_scc0 .LBB0_2391
	v_cmp_lt_u32_e32 vcc, s44, v78
	s_and_saveexec_b64 s[36:37], vcc
	s_xor_b64 s[36:37], exec, s[36:37]
	v_cmp_gt_u32_e32 vcc, s45, v78
	s_nop 1
	v_cndmask_b32_e32 v30, -1, v78, vcc
	s_andn2_saveexec_b64 s[36:37], s[36:37]
	v_add_u32_e32 v30, 0xfffff400, v78
	s_or_b64 exec, exec, s[36:37]
	s_mov_b64 s[36:37], 0

.LBB0_2704:
	ds_read2_b32 v[52:53], v89 offset1:65
	ds_read2_b32 v[78:79], v89 offset0:130 offset1:195
	s_mul_hi_i32 s4, s30, 0x8fb823ef
	s_add_i32 s4, s4, s30
	s_lshr_b32 s5, s4, 31
	s_waitcnt lgkmcnt(1)
	v_cvt_pk_bf16_f32 v106, v52, v53
	s_waitcnt lgkmcnt(0)
	v_cvt_pk_bf16_f32 v107, v78, v79
	ds_read2_b32 v[52:53], v102 offset0:4 offset1:69
	ds_read2_b32 v[78:79], v102 offset0:134 offset1:199
	s_waitcnt lgkmcnt(1)
	v_cvt_pk_bf16_f32 v108, v52, v53
	s_ashr_i32 s4, s4, 7
	s_add_i32 s4, s4, s5
	s_waitcnt lgkmcnt(0)
	v_cvt_pk_bf16_f32 v109, v78, v79
	s_mul_i32 s5, s4, 0xe4
	s_sub_i32 s5, s30, s5
	v_lshl_or_b32 v52, s5, 6, v88
	v_ashrrev_i32_e32 v53, 31, v52
	s_lshl_b32 s4, s4, 8
	v_lshlrev_b64 v[52:53], 13, v[52:53]
	v_lshl_add_u64 v[52:53], s[6:7], 0, v[52:53]
	ds_read2_b32 v[78:79], v90 offset1:65
	s_ashr_i32 s5, s4, 31
	v_lshl_add_u64 v[52:53], s[4:5], 1, v[52:53]
	v_lshl_add_u64 v[110:111], v[70:71], 1, v[52:53]
	global_store_dwordx4 v[110:111], v[106:109], off
	ds_read2_b32 v[108:109], v90 offset0:130 offset1:195
	s_waitcnt lgkmcnt(1)
	v_cvt_pk_bf16_f32 v106, v78, v79
	s_waitcnt lgkmcnt(0)
	ds_read2_b32 v[78:79], v103 offset0:4 offset1:69
	v_cvt_pk_bf16_f32 v107, v108, v109
	ds_read2_b32 v[102:103], v103 offset0:134 offset1:199
	s_waitcnt lgkmcnt(1)
	v_cvt_pk_bf16_f32 v108, v78, v79
	s_waitcnt lgkmcnt(0)
	ds_read2_b32 v[78:79], v91 offset1:65
	v_cvt_pk_bf16_f32 v109, v102, v103
	v_lshl_add_u64 v[102:103], v[72:73], 1, v[52:53]
	global_store_dwordx4 v[102:103], v[106:109], off
	ds_read2_b32 v[102:103], v91 offset0:130 offset1:195
	s_waitcnt lgkmcnt(1)
	v_cvt_pk_bf16_f32 v106, v78, v79
	ds_read2_b32 v[78:79], v104 offset0:4 offset1:69
	s_waitcnt lgkmcnt(1)
	v_cvt_pk_bf16_f32 v107, v102, v103
	ds_read2_b32 v[102:103], v104 offset0:134 offset1:199
	s_waitcnt lgkmcnt(1)
	v_cvt_pk_bf16_f32 v108, v78, v79
	ds_read2_b32 v[78:79], v92 offset1:65
	s_waitcnt lgkmcnt(1)
	v_cvt_pk_bf16_f32 v109, v102, v103
	v_lshl_add_u64 v[102:103], v[74:75], 1, v[52:53]
	global_store_dwordx4 v[102:103], v[106:109], off
	s_waitcnt lgkmcnt(0)
	v_cvt_pk_bf16_f32 v102, v78, v79
	ds_read2_b32 v[106:107], v92 offset0:130 offset1:195
	ds_read2_b32 v[78:79], v105 offset0:4 offset1:69
	s_waitcnt lgkmcnt(1)
	v_cvt_pk_bf16_f32 v103, v106, v107
	ds_read2_b32 v[106:107], v105 offset0:134 offset1:199
	s_waitcnt lgkmcnt(1)
	v_cvt_pk_bf16_f32 v104, v78, v79
	s_waitcnt lgkmcnt(0)
	v_cvt_pk_bf16_f32 v51, v106, v106
	v_bfe_u32 v78, v107, 16, 1
	v_lshrrev_b32_e32 v51, 16, v51
	v_add3_u32 v78, v107, v78, s23
	v_and_or_b32 v105, v78, s25, v51
	v_lshl_add_u64 v[52:53], v[76:77], 1, v[52:53]
	global_store_dwordx4 v[52:53], v[102:105], off
	s_waitcnt lgkmcnt(0)
	s_barrier

.LBB0_2797:
	ds_read2_b32 v[52:53], v89 offset1:65
	ds_read2_b32 v[78:79], v89 offset0:130 offset1:195
	v_add_u32_e32 v102, 0x400, v89
	s_mul_hi_i32 s4, s27, 0x8fb823ef
	s_add_i32 s4, s4, s27
	s_waitcnt lgkmcnt(1)
	v_cvt_pk_bf16_f32 v104, v52, v53
	s_waitcnt lgkmcnt(0)
	v_cvt_pk_bf16_f32 v105, v78, v79
	ds_read2_b32 v[52:53], v102 offset0:4 offset1:69
	ds_read2_b32 v[78:79], v102 offset0:134 offset1:199
	s_waitcnt lgkmcnt(1)
	v_cvt_pk_bf16_f32 v106, v52, v53
	s_lshr_b32 s5, s4, 31
	s_ashr_i32 s4, s4, 7
	s_add_i32 s5, s4, s5
	s_waitcnt lgkmcnt(0)
	v_cvt_pk_bf16_f32 v107, v78, v79
	s_lshl_b32 s4, s5, 8
	s_mulk_i32 s5, 0xc700
	s_add_i32 s5, s5, s10
	v_add_u32_e32 v52, s5, v88
	v_ashrrev_i32_e32 v53, 31, v52
	ds_read2_b32 v[78:79], v90 offset1:65
	v_lshlrev_b64 v[52:53], 13, v[52:53]
	v_lshl_add_u64 v[52:53], s[6:7], 0, v[52:53]
	s_ashr_i32 s5, s4, 31
	v_lshl_add_u64 v[52:53], s[4:5], 1, v[52:53]
	v_lshl_add_u64 v[108:109], v[70:71], 1, v[52:53]
	global_store_dwordx4 v[108:109], v[104:107], off
	s_waitcnt lgkmcnt(0)
	s_nop 0
	ds_read2_b32 v[106:107], v90 offset0:130 offset1:195
	v_cvt_pk_bf16_f32 v104, v78, v79
	v_add_u32_e32 v103, 0x400, v90
	ds_read2_b32 v[78:79], v103 offset0:4 offset1:69
	s_waitcnt lgkmcnt(1)
	v_cvt_pk_bf16_f32 v105, v106, v107
	ds_read2_b32 v[108:109], v103 offset0:134 offset1:199
	s_waitcnt lgkmcnt(1)
	v_cvt_pk_bf16_f32 v106, v78, v79
	s_waitcnt lgkmcnt(0)
	v_cvt_pk_bf16_f32 v107, v108, v109
	ds_read2_b32 v[78:79], v91 offset1:65
	v_lshl_add_u64 v[108:109], v[72:73], 1, v[52:53]
	global_store_dwordx4 v[108:109], v[104:107], off
	ds_read2_b32 v[104:105], v91 offset0:130 offset1:195
	s_waitcnt lgkmcnt(1)
	v_cvt_pk_bf16_f32 v106, v78, v79
	s_waitcnt lgkmcnt(0)
	v_cvt_pk_bf16_f32 v107, v104, v105
	v_add_u32_e32 v104, 0x400, v91
	ds_read2_b32 v[78:79], v104 offset0:4 offset1:69
	ds_read2_b32 v[110:111], v104 offset0:134 offset1:199
	s_waitcnt lgkmcnt(1)
	v_cvt_pk_bf16_f32 v108, v78, v79
	ds_read2_b32 v[78:79], v92 offset1:65
	s_waitcnt lgkmcnt(1)
	v_cvt_pk_bf16_f32 v109, v110, v111
	v_lshl_add_u64 v[110:111], v[74:75], 1, v[52:53]
	global_store_dwordx4 v[110:111], v[106:109], off
	s_waitcnt lgkmcnt(0)
	v_cvt_pk_bf16_f32 v106, v78, v79
	ds_read2_b32 v[108:109], v92 offset0:130 offset1:195
	v_add_u32_e32 v105, 0x400, v92
	ds_read2_b32 v[78:79], v105 offset0:4 offset1:69
	s_waitcnt lgkmcnt(1)
	v_cvt_pk_bf16_f32 v107, v108, v109
	ds_read2_b32 v[110:111], v105 offset0:134 offset1:199
	s_waitcnt lgkmcnt(1)
	v_cvt_pk_bf16_f32 v108, v78, v79
	s_waitcnt lgkmcnt(0)
	v_cvt_pk_bf16_f32 v51, v110, v110
	v_bfe_u32 v78, v111, 16, 1
	v_lshrrev_b32_e32 v51, 16, v51
	v_add3_u32 v78, v111, v78, s23
	v_and_or_b32 v109, v78, s25, v51
	v_lshl_add_u64 v[52:53], v[76:77], 1, v[52:53]
	global_store_dwordx4 v[52:53], v[106:109], off
	s_waitcnt lgkmcnt(0)
	s_barrier
	s_add_i32 s30, s24, s27
	s_cmpk_gt_i32 s30, 0xe3f
	s_cbranch_scc1 .LBB0_2705
	ds_write2_b32 v94, v22, v23 offset1:1
	ds_write2_b32 v94, v24, v25 offset0:2 offset1:3
	ds_write2_b32 v95, v30, v31 offset1:1
	ds_write2_b32 v95, v32, v33 offset0:2 offset1:3
	ds_write2_b32 v96, v38, v39 offset1:1
	ds_write2_b32 v96, v40, v41 offset0:2 offset1:3
	ds_write2_b32 v97, v46, v47 offset1:1
	ds_write2_b32 v97, v48, v49 offset0:2 offset1:3
	ds_write2_b32 v98, v54, v55 offset1:1
	ds_write2_b32 v98, v56, v57 offset0:2 offset1:3
	ds_write2_b32 v99, v58, v59 offset1:1
	ds_write2_b32 v99, v60, v61 offset0:2 offset1:3
	ds_write2_b32 v100, v62, v63 offset1:1
	ds_write2_b32 v100, v64, v65 offset0:2 offset1:3
	ds_write2_b32 v101, v66, v67 offset1:1
	ds_write2_b32 v101, v68, v69 offset0:2 offset1:3
	s_waitcnt lgkmcnt(0)
	s_barrier
	s_add_i32 s4, s18, s27
	s_cmpk_gt_i32 s4, 0xe3f
	s_cbranch_scc1 .LBB0_2704
	s_mul_hi_i32 s5, s4, 0x8fb823ef
	s_add_i32 s5, s5, s4
	s_lshr_b32 s14, s5, 31
	s_ashr_i32 s28, s5, 7
	s_add_i32 s28, s28, s14
	s_mul_i32 s5, s28, 0xe4
	s_sub_i32 s4, s4, s5
	s_lshl_b32 s27, s4, 6
	v_or_b32_e32 v78, s27, v1
	v_cmp_lt_i32_e64 s[4:5], s19, v78
	v_mov_b32_e32 v30, v78
	s_and_saveexec_b64 s[14:15], s[4:5]
	s_cbranch_execz .LBB0_2808
	s_cmpk_gt_u32 s27, 0x37ff
	s_mov_b64 s[16:17], -1
	s_cbranch_scc0 .LBB0_2806
	v_cmp_lt_u32_e32 vcc, s20, v78
	s_and_saveexec_b64 s[16:17], vcc
	s_xor_b64 s[16:17], exec, s[16:17]
	v_cmp_gt_u32_e32 vcc, s21, v78
	s_nop 1
	v_cndmask_b32_e32 v30, -1, v78, vcc
	s_andn2_saveexec_b64 s[16:17], s[16:17]
	v_add_u32_e32 v30, 0xfffff400, v78
	s_or_b64 exec, exec, s[16:17]
	s_mov_b64 s[16:17], 0

.LBB0_2950:
	s_or_b64 exec, exec, s[22:23]
	v_lshl_add_u64 v[104:105], v[80:81], 2, s[18:19]
	v_lshl_add_u64 v[106:107], v[104:105], 0, s[16:17]
	s_waitcnt lgkmcnt(0)
	s_barrier
	v_lshl_add_u64 v[92:93], v[106:107], 0, v[50:51]
	s_waitcnt lgkmcnt(0)
	global_load_dwordx4 v[80:83], v[54:55], off
	v_lshl_add_u64 v[96:97], v[104:105], 0, v[50:51]
	global_load_dwordx4 v[92:95], v[92:93], off
	v_ashrrev_i32_e32 v49, 6, v49
	global_load_dwordx4 v[96:99], v[96:97], off
	v_lshlrev_b32_e32 v49, 2, v49
	v_and_b32_e32 v91, -16, v49
	v_add_u32_e32 v91, 0, v91
	ds_read_b96 v[100:102], v91
	v_or_b32_e32 v49, 12, v49
	v_add_u32_e32 v49, 0, v49
	v_lshlrev_b64 v[78:79], 13, v[78:79]
	v_add_u32_e32 v1, s11, v1
	s_waitcnt lgkmcnt(0)
	v_mov_b32_e32 v108, v101
	ds_read_b32 v101, v49
	v_mov_b32_e32 v109, v102
	s_waitcnt lgkmcnt(0)
	v_pk_add_f32 v[100:101], v[108:109], v[100:101]
	s_nop 0
	v_add_f32_e32 v49, v100, v101
	v_fmamk_f32 v49, v49, 0x39800000, v90
	v_mul_f32_e32 v91, 0x4b800000, v49
	v_cmp_gt_f32_e32 vcc, s27, v49
	v_lshl_add_u64 v[100:101], s[8:9], 0, v[78:79]
	s_nop 0
	v_cndmask_b32_e32 v49, v49, v91, vcc
	v_rsq_f32_e32 v91, v49
	v_mov_b32_e32 v49, v51
	v_lshl_add_u64 v[78:79], v[100:101], 0, v[48:49]
	v_mul_f32_e32 v49, 0x45800000, v91
	v_cndmask_b32_e32 v102, v91, v49, vcc
	v_pk_mul_f32 v[20:21], v[20:21], v[102:103] op_sel_hi:[1,0]
	v_pk_mul_f32 v[18:19], v[18:19], v[102:103] op_sel_hi:[1,0]
	v_pk_mul_f32 v[30:31], v[30:31], v[102:103] op_sel_hi:[1,0]
	v_pk_mul_f32 v[32:33], v[32:33], v[102:103] op_sel_hi:[1,0]
	v_pk_mul_f32 v[26:27], v[26:27], v[102:103] op_sel_hi:[1,0]
	v_pk_mul_f32 v[28:29], v[28:29], v[102:103] op_sel_hi:[1,0]
	v_pk_mul_f32 v[22:23], v[22:23], v[102:103] op_sel_hi:[1,0]
	v_pk_mul_f32 v[24:25], v[24:25], v[102:103] op_sel_hi:[1,0]
	s_andn2_b64 vcc, exec, s[0:1]
	s_waitcnt vmcnt(2)
	v_pk_mul_f32 v[18:19], v[80:81], v[18:19]
	v_pk_mul_f32 v[20:21], v[82:83], v[20:21]
	s_waitcnt vmcnt(1)
	v_pk_add_f32 v[80:81], v[94:95], 1.0 op_sel_hi:[1,0]
	v_pk_add_f32 v[82:83], v[92:93], 1.0 op_sel_hi:[1,0]
	s_waitcnt vmcnt(0)
	v_pk_fma_f32 v[20:21], v[80:81], v[20:21], v[98:99]
	v_pk_fma_f32 v[18:19], v[82:83], v[18:19], v[96:97]
	v_cvt_pk_bf16_f32 v18, v18, v19
	v_cvt_pk_bf16_f32 v20, v20, v20
	v_cvt_pk_bf16_f32 v21, v21, v21
	v_lshrrev_b32_e32 v20, 16, v20
	v_and_or_b32 v19, v21, s26, v20
	global_store_dwordx2 v[78:79], v[18:19], off
	v_lshl_add_u64 v[78:79], v[106:107], 0, v[58:59]
	global_load_dwordx4 v[18:21], v[70:71], off
	v_lshl_add_u64 v[82:83], v[104:105], 0, v[58:59]
	global_load_dwordx4 v[78:81], v[78:79], off
	s_waitcnt vmcnt(1)
	v_pk_mul_f32 v[18:19], v[18:19], v[32:33]
	global_load_dwordx4 v[92:95], v[82:83], off
	v_pk_mul_f32 v[20:21], v[20:21], v[30:31]
	s_waitcnt vmcnt(1)
	v_pk_add_f32 v[30:31], v[80:81], 1.0 op_sel_hi:[1,0]
	v_pk_add_f32 v[32:33], v[78:79], 1.0 op_sel_hi:[1,0]
	v_lshl_add_u64 v[82:83], v[34:35], 1, v[100:101]
	v_lshl_add_u64 v[78:79], v[104:105], 0, v[62:63]
	s_waitcnt vmcnt(0)
	v_pk_fma_f32 v[20:21], v[30:31], v[20:21], v[94:95]
	v_pk_fma_f32 v[18:19], v[32:33], v[18:19], v[92:93]
	v_cvt_pk_bf16_f32 v18, v18, v19
	v_cvt_pk_bf16_f32 v20, v20, v20
	v_cvt_pk_bf16_f32 v21, v21, v21
	v_lshrrev_b32_e32 v20, 16, v20
	v_and_or_b32 v19, v21, s26, v20
	global_store_dwordx2 v[82:83], v[18:19], off
	v_lshl_add_u64 v[30:31], v[106:107], 0, v[62:63]
	global_load_dwordx4 v[18:21], v[72:73], off
	v_lshl_add_u64 v[82:83], v[36:37], 1, v[100:101]
	global_load_dwordx4 v[30:33], v[30:31], off
	s_waitcnt vmcnt(1)
	v_pk_mul_f32 v[18:19], v[18:19], v[28:29]
	global_load_dwordx4 v[78:81], v[78:79], off
	v_pk_mul_f32 v[20:21], v[20:21], v[26:27]
	s_waitcnt vmcnt(1)
	v_pk_add_f32 v[26:27], v[32:33], 1.0 op_sel_hi:[1,0]
	v_pk_add_f32 v[28:29], v[30:31], 1.0 op_sel_hi:[1,0]
	v_lshl_add_u64 v[30:31], v[104:105], 0, v[66:67]
	s_waitcnt vmcnt(0)
	v_pk_fma_f32 v[20:21], v[26:27], v[20:21], v[80:81]
	v_pk_fma_f32 v[18:19], v[28:29], v[18:19], v[78:79]
	v_cvt_pk_bf16_f32 v18, v18, v19
	v_cvt_pk_bf16_f32 v20, v20, v20
	v_cvt_pk_bf16_f32 v21, v21, v21
	v_lshrrev_b32_e32 v20, 16, v20
	v_and_or_b32 v19, v21, s26, v20
	global_store_dwordx2 v[82:83], v[18:19], off
	v_lshl_add_u64 v[26:27], v[106:107], 0, v[66:67]
	global_load_dwordx4 v[18:21], v[74:75], off
	v_lshl_add_u64 v[78:79], v[38:39], 1, v[100:101]
	global_load_dwordx4 v[26:29], v[26:27], off
	s_waitcnt vmcnt(1)
	v_pk_mul_f32 v[18:19], v[24:25], v[18:19]
	global_load_dwordx4 v[30:33], v[30:31], off
	v_pk_mul_f32 v[20:21], v[22:23], v[20:21]
	s_waitcnt vmcnt(1)
	v_pk_add_f32 v[22:23], v[28:29], 1.0 op_sel_hi:[1,0]
	v_pk_add_f32 v[24:25], v[26:27], 1.0 op_sel_hi:[1,0]
	s_waitcnt vmcnt(0)
	v_pk_fma_f32 v[20:21], v[20:21], v[22:23], v[32:33]
	v_pk_fma_f32 v[18:19], v[18:19], v[24:25], v[30:31]
	v_bfe_u32 v24, v20, 16, 1
	v_bfe_u32 v22, v18, 16, 1
	v_bfe_u32 v23, v19, 16, 1
	v_bfe_u32 v25, v21, 16, 1
	v_add3_u32 v18, v18, v22, s37
	v_add3_u32 v20, v20, v24, s37
	v_add3_u32 v19, v19, v23, s37
	v_add3_u32 v21, v21, v25, s37
	v_lshrrev_b32_e32 v18, 16, v18
	v_lshrrev_b32_e32 v20, 16, v20
	v_and_or_b32 v18, v19, s26, v18
	v_and_or_b32 v19, v21, s26, v20
	global_store_dwordx2 v[78:79], v[18:19], off
	s_cbranch_vccz .LBB0_2969

.LBB0_3673:
	s_or_b64 exec, exec, s[16:17]
	v_lshlrev_b32_e32 v2, 2, v9
	v_add_u32_e32 v37, s38, v2
	v_add_u32_e32 v2, 0, v2
	v_add_u32_e32 v54, 0x1bc00, v2
	v_lshl_add_u32 v2, v26, 9, v37
	s_waitcnt lgkmcnt(0)
	s_barrier
	ds_read_b128 v[40:43], v2
	ds_read_b128 v[44:47], v54
	s_lshl_b64 s[16:17], s[14:15], 14
	s_add_u32 s0, s85, s16
	s_addc_u32 s1, s84, s17
	v_mov_b32_e32 v33, v3
	s_waitcnt lgkmcnt(1)
	v_mul_f32_e32 v15, 0x3fb8aa3b, v40
	v_lshl_add_u64 v[34:35], s[0:1], 0, v[32:33]
	v_add_u32_e32 v2, 0, v32
	v_exp_f32_e32 v32, v15
	s_waitcnt lgkmcnt(0)
	v_sub_f32_e32 v15, v40, v44
	v_mul_f32_e32 v15, 0x3fb8aa3b, v15
	v_exp_f32_e32 v48, v15
	v_sub_f32_e32 v15, v44, v40
	v_mul_f32_e32 v15, 0x3fb8aa3b, v15
	v_exp_f32_e32 v40, v15
	v_mul_f32_e32 v15, 0x3fb8aa3b, v41
	v_exp_f32_e32 v44, v15
	v_sub_f32_e32 v15, v41, v45
	v_mul_f32_e32 v15, 0x3fb8aa3b, v15
	v_exp_f32_e32 v50, v15
	v_sub_f32_e32 v15, v45, v41
	v_mul_f32_e32 v15, 0x3fb8aa3b, v15
	v_exp_f32_e32 v52, v15
	v_mul_f32_e32 v15, 0x3fb8aa3b, v42
	v_exp_f32_e32 v33, v15
	v_sub_f32_e32 v15, v42, v46
	v_mul_f32_e32 v15, 0x3fb8aa3b, v15
	v_exp_f32_e32 v49, v15
	v_sub_f32_e32 v15, v46, v42
	v_mul_f32_e32 v15, 0x3fb8aa3b, v15
	v_exp_f32_e32 v41, v15
	v_mul_f32_e32 v15, 0x3fb8aa3b, v43
	v_exp_f32_e32 v45, v15
	v_sub_f32_e32 v15, v43, v47
	v_mul_f32_e32 v15, 0x3fb8aa3b, v15
	v_exp_f32_e32 v51, v15
	v_sub_f32_e32 v15, v47, v43
	v_lshlrev_b32_e32 v43, 16, v31
	v_lshlrev_b32_e32 v42, 16, v30
	v_and_b32_e32 v31, 0xffff0000, v31
	v_and_b32_e32 v30, 0xffff0000, v30
	v_pk_mul_f32 v[30:31], v[30:31], s[12:13] op_sel_hi:[1,0]
	v_pk_mul_f32 v[42:43], v[42:43], s[12:13] op_sel_hi:[1,0]
	v_pk_mul_f32 v[44:45], v[30:31], v[44:45]
	v_mul_f32_e32 v15, 0x3fb8aa3b, v15
	v_pk_mul_f32 v[32:33], v[42:43], v[32:33]
	v_cvt_pk_bf16_f32 v33, v33, v45
	v_exp_f32_e32 v53, v15
	v_cvt_pk_bf16_f32 v32, v32, v44
	v_ashrrev_i32_e32 v27, 31, v26
	v_lshlrev_b64 v[44:45], 8, v[26:27]
	v_lshl_add_u64 v[44:45], v[34:35], 0, v[44:45]
	global_store_dwordx2 v[44:45], v[32:33], off
	v_pk_mul_f32 v[32:33], v[42:43], v[48:49]
	v_pk_mul_f32 v[30:31], v[30:31], v[50:51]
	v_cvt_pk_bf16_f32 v30, v32, v30
	v_cvt_pk_bf16_f32 v31, v33, v31
	v_lshlrev_b32_e32 v43, 16, v29
	v_lshlrev_b32_e32 v42, 16, v28
	v_and_b32_e32 v29, 0xffff0000, v29
	v_and_b32_e32 v28, 0xffff0000, v28
	v_mad_u64_u32 v[32:33], s[0:1], v26, s46, v[2:3]
	v_pk_mul_f32 v[40:41], v[40:41], v[42:43]
	v_pk_mul_f32 v[28:29], v[52:53], v[28:29]
	v_cvt_pk_bf16_f32 v21, v40, v40
	v_cvt_pk_bf16_f32 v40, v29, v29
	v_cvt_pk_bf16_f32 v33, v28, v28
	v_cvt_pk_bf16_f32 v15, v41, v41
	v_and_b32_e32 v27, 0xffff0000, v40
	v_and_b32_e32 v28, 0xffff0000, v33
	v_lshlrev_b32_e32 v26, 1, v26
	v_mul_u32_u24_e32 v48, 0x90, v9
	v_or_b32_sdwa v29, v27, v15 dst_sel:DWORD dst_unused:UNUSED_PAD src0_sel:DWORD src1_sel:WORD_1
	v_or_b32_sdwa v28, v28, v21 dst_sel:DWORD dst_unused:UNUSED_PAD src0_sel:DWORD src1_sel:WORD_1
	v_add3_u32 v9, s27, v26, v48
	ds_write2st64_b64 v32, v[30:31], v[28:29] offset1:66
	ds_write_b16_d16_hi v9, v21
	v_lshl_add_u32 v21, v20, 9, v37
	ds_read_b128 v[26:29], v21
	ds_write_b16_d16_hi v9, v33 offset:144
	ds_read_b128 v[30:33], v54
	ds_write_b16_d16_hi v9, v15 offset:288
	ds_write_b16_d16_hi v9, v40 offset:432
	v_ashrrev_i32_e32 v36, 6, v6
	s_waitcnt lgkmcnt(4)
	v_mul_f32_e32 v9, 0x3fb8aa3b, v26
	v_exp_f32_e32 v40, v9
	s_waitcnt lgkmcnt(2)
	v_sub_f32_e32 v9, v26, v30
	v_mul_f32_e32 v9, 0x3fb8aa3b, v9
	v_exp_f32_e32 v42, v9
	v_sub_f32_e32 v9, v30, v26
	v_mul_f32_e32 v9, 0x3fb8aa3b, v9
	v_exp_f32_e32 v26, v9
	v_mul_f32_e32 v9, 0x3fb8aa3b, v27
	v_exp_f32_e32 v30, v9
	v_sub_f32_e32 v9, v27, v31
	v_mul_f32_e32 v9, 0x3fb8aa3b, v9
	v_exp_f32_e32 v44, v9
	v_sub_f32_e32 v9, v31, v27
	v_mul_f32_e32 v9, 0x3fb8aa3b, v9
	v_exp_f32_e32 v46, v9
	v_mul_f32_e32 v9, 0x3fb8aa3b, v28
	v_exp_f32_e32 v41, v9
	v_sub_f32_e32 v9, v28, v32
	v_mul_f32_e32 v9, 0x3fb8aa3b, v9
	v_exp_f32_e32 v43, v9
	v_sub_f32_e32 v9, v32, v28
	v_mul_f32_e32 v9, 0x3fb8aa3b, v9
	v_exp_f32_e32 v27, v9
	v_mul_f32_e32 v9, 0x3fb8aa3b, v29
	v_exp_f32_e32 v31, v9
	v_sub_f32_e32 v9, v29, v33
	v_mul_f32_e32 v9, 0x3fb8aa3b, v9
	v_exp_f32_e32 v45, v9
	v_sub_f32_e32 v9, v33, v29
	v_lshlrev_b32_e32 v29, 16, v25
	v_lshlrev_b32_e32 v28, 16, v24
	v_and_b32_e32 v25, 0xffff0000, v25
	v_and_b32_e32 v24, 0xffff0000, v24
	v_pk_mul_f32 v[28:29], v[28:29], s[12:13] op_sel_hi:[1,0]
	v_pk_mul_f32 v[24:25], v[24:25], s[12:13] op_sel_hi:[1,0]
	v_pk_mul_f32 v[32:33], v[28:29], v[40:41]
	v_pk_mul_f32 v[30:31], v[24:25], v[30:31]
	v_mul_f32_e32 v9, 0x3fb8aa3b, v9
	v_cvt_pk_bf16_f32 v30, v32, v30
	v_cvt_pk_bf16_f32 v31, v33, v31
	v_exp_f32_e32 v47, v9
	v_ashrrev_i32_e32 v21, 31, v20
	v_pk_mul_f32 v[28:29], v[28:29], v[42:43]
	v_lshlrev_b64 v[32:33], 8, v[20:21]
	v_pk_mul_f32 v[24:25], v[24:25], v[44:45]
	v_cvt_pk_bf16_f32 v24, v28, v24
	v_lshl_add_u64 v[32:33], v[34:35], 0, v[32:33]
	global_store_dwordx2 v[32:33], v[30:31], off
	v_cvt_pk_bf16_f32 v25, v29, v25
	v_lshlrev_b32_e32 v31, 16, v23
	v_lshlrev_b32_e32 v30, 16, v22
	v_and_b32_e32 v23, 0xffff0000, v23
	v_and_b32_e32 v22, 0xffff0000, v22
	v_pk_mul_f32 v[26:27], v[26:27], v[30:31]
	v_pk_mul_f32 v[22:23], v[46:47], v[22:23]
	v_mad_u64_u32 v[28:29], s[0:1], v20, s46, v[2:3]
	v_cvt_pk_bf16_f32 v15, v26, v26
	v_cvt_pk_bf16_f32 v29, v23, v23
	v_cvt_pk_bf16_f32 v26, v22, v22
	v_cvt_pk_bf16_f32 v9, v27, v27
	v_and_b32_e32 v21, 0xffff0000, v29
	v_and_b32_e32 v22, 0xffff0000, v26
	v_or_b32_sdwa v23, v21, v9 dst_sel:DWORD dst_unused:UNUSED_PAD src0_sel:DWORD src1_sel:WORD_1
	v_or_b32_sdwa v22, v22, v15 dst_sel:DWORD dst_unused:UNUSED_PAD src0_sel:DWORD src1_sel:WORD_1
	v_lshlrev_b32_e32 v20, 1, v20
	ds_write2st64_b64 v28, v[24:25], v[22:23] offset1:66
	v_add3_u32 v28, s27, v20, v48
	ds_write_b16_d16_hi v28, v15
	v_lshl_add_u32 v15, v14, 9, v37
	ds_read_b128 v[20:23], v15
	ds_write_b16_d16_hi v28, v26 offset:144
	ds_read_b128 v[24:27], v54
	ds_write_b16_d16_hi v28, v9 offset:288
	ds_write_b16_d16_hi v28, v29 offset:432
	v_bfe_u32 v7, v6, 4, 2
	s_waitcnt lgkmcnt(4)
	v_mul_f32_e32 v9, 0x3fb8aa3b, v20
	v_exp_f32_e32 v28, v9
	s_waitcnt lgkmcnt(2)
	v_sub_f32_e32 v9, v20, v24
	v_mul_f32_e32 v9, 0x3fb8aa3b, v9
	v_exp_f32_e32 v30, v9
	v_sub_f32_e32 v9, v24, v20
	v_mul_f32_e32 v9, 0x3fb8aa3b, v9
	v_exp_f32_e32 v20, v9
	v_mul_f32_e32 v9, 0x3fb8aa3b, v21
	v_exp_f32_e32 v24, v9
	v_sub_f32_e32 v9, v21, v25
	v_mul_f32_e32 v9, 0x3fb8aa3b, v9
	v_exp_f32_e32 v32, v9
	v_sub_f32_e32 v9, v25, v21
	v_mul_f32_e32 v9, 0x3fb8aa3b, v9
	v_exp_f32_e32 v40, v9
	v_mul_f32_e32 v9, 0x3fb8aa3b, v22
	v_exp_f32_e32 v29, v9
	v_sub_f32_e32 v9, v22, v26
	v_mul_f32_e32 v9, 0x3fb8aa3b, v9
	v_exp_f32_e32 v31, v9
	v_sub_f32_e32 v9, v26, v22
	v_mul_f32_e32 v9, 0x3fb8aa3b, v9
	v_exp_f32_e32 v21, v9
	v_mul_f32_e32 v9, 0x3fb8aa3b, v23
	v_exp_f32_e32 v25, v9
	v_sub_f32_e32 v9, v23, v27
	v_mul_f32_e32 v9, 0x3fb8aa3b, v9
	v_exp_f32_e32 v33, v9
	v_sub_f32_e32 v9, v27, v23
	v_lshlrev_b32_e32 v23, 16, v19
	v_lshlrev_b32_e32 v22, 16, v18
	v_and_b32_e32 v19, 0xffff0000, v19
	v_and_b32_e32 v18, 0xffff0000, v18
	v_pk_mul_f32 v[22:23], v[22:23], s[12:13] op_sel_hi:[1,0]
	v_mul_f32_e32 v9, 0x3fb8aa3b, v9
	v_pk_mul_f32 v[18:19], v[18:19], s[12:13] op_sel_hi:[1,0]
	v_pk_mul_f32 v[26:27], v[22:23], v[28:29]
	v_exp_f32_e32 v41, v9
	v_pk_mul_f32 v[24:25], v[18:19], v[24:25]
	v_cvt_pk_bf16_f32 v25, v27, v25
	v_cvt_pk_bf16_f32 v24, v26, v24
	v_ashrrev_i32_e32 v15, 31, v14
	v_pk_mul_f32 v[22:23], v[22:23], v[30:31]
	v_lshlrev_b64 v[26:27], 8, v[14:15]
	v_pk_mul_f32 v[18:19], v[18:19], v[32:33]
	v_cvt_pk_bf16_f32 v19, v23, v19
	v_cvt_pk_bf16_f32 v18, v22, v18
	v_lshl_add_u64 v[26:27], v[34:35], 0, v[26:27]
	global_store_dwordx2 v[26:27], v[24:25], off
	v_lshlrev_b32_e32 v25, 16, v17
	v_lshlrev_b32_e32 v24, 16, v16
	v_and_b32_e32 v17, 0xffff0000, v17
	v_and_b32_e32 v16, 0xffff0000, v16
	v_pk_mul_f32 v[20:21], v[20:21], v[24:25]
	v_pk_mul_f32 v[16:17], v[40:41], v[16:17]
	v_mad_u64_u32 v[22:23], s[0:1], v14, s46, v[2:3]
	v_cvt_pk_bf16_f32 v15, v20, v20
	v_cvt_pk_bf16_f32 v9, v21, v21
	v_cvt_pk_bf16_f32 v23, v17, v17
	v_cvt_pk_bf16_f32 v20, v16, v16
	v_and_b32_e32 v16, 0xffff0000, v23
	v_and_b32_e32 v21, 0xffff0000, v20
	v_or_b32_sdwa v17, v16, v9 dst_sel:DWORD dst_unused:UNUSED_PAD src0_sel:DWORD src1_sel:WORD_1
	v_or_b32_sdwa v16, v21, v15 dst_sel:DWORD dst_unused:UNUSED_PAD src0_sel:DWORD src1_sel:WORD_1
	v_lshlrev_b32_e32 v14, 1, v14
	ds_write2st64_b64 v22, v[18:19], v[16:17] offset1:66
	v_add3_u32 v22, s27, v14, v48
	v_lshl_add_u32 v14, v8, 9, v37
	ds_write_b16_d16_hi v22, v15
	ds_read_b128 v[14:17], v14
	ds_write_b16_d16_hi v22, v20 offset:144
	ds_read_b128 v[18:21], v54
	ds_write_b16_d16_hi v22, v9 offset:288
	ds_write_b16_d16_hi v22, v23 offset:432
	s_waitcnt lgkmcnt(4)
	v_mul_f32_e32 v9, 0x3fb8aa3b, v14
	v_exp_f32_e32 v22, v9
	s_waitcnt lgkmcnt(2)
	v_sub_f32_e32 v9, v14, v18
	v_mul_f32_e32 v9, 0x3fb8aa3b, v9
	v_exp_f32_e32 v24, v9
	v_sub_f32_e32 v9, v18, v14
	v_mul_f32_e32 v9, 0x3fb8aa3b, v9
	v_exp_f32_e32 v14, v9
	v_mul_f32_e32 v9, 0x3fb8aa3b, v15
	v_exp_f32_e32 v18, v9
	v_sub_f32_e32 v9, v15, v19
	v_mul_f32_e32 v9, 0x3fb8aa3b, v9
	v_exp_f32_e32 v26, v9
	v_sub_f32_e32 v9, v19, v15
	v_mul_f32_e32 v9, 0x3fb8aa3b, v9
	v_exp_f32_e32 v28, v9
	v_mul_f32_e32 v9, 0x3fb8aa3b, v16
	v_exp_f32_e32 v23, v9
	v_sub_f32_e32 v9, v16, v20
	v_mul_f32_e32 v9, 0x3fb8aa3b, v9
	v_exp_f32_e32 v25, v9
	v_sub_f32_e32 v9, v20, v16
	v_mul_f32_e32 v9, 0x3fb8aa3b, v9
	v_exp_f32_e32 v15, v9
	v_mul_f32_e32 v9, 0x3fb8aa3b, v17
	v_exp_f32_e32 v19, v9
	v_sub_f32_e32 v9, v17, v21
	v_mul_f32_e32 v9, 0x3fb8aa3b, v9
	v_exp_f32_e32 v27, v9
	v_sub_f32_e32 v9, v21, v17
	v_lshlrev_b32_e32 v17, 16, v13
	v_lshlrev_b32_e32 v16, 16, v12
	v_and_b32_e32 v13, 0xffff0000, v13
	v_and_b32_e32 v12, 0xffff0000, v12
	v_pk_mul_f32 v[16:17], v[16:17], s[12:13] op_sel_hi:[1,0]
	v_mul_f32_e32 v9, 0x3fb8aa3b, v9
	v_pk_mul_f32 v[12:13], v[12:13], s[12:13] op_sel_hi:[1,0]
	v_pk_mul_f32 v[20:21], v[16:17], v[22:23]
	v_exp_f32_e32 v29, v9
	v_pk_mul_f32 v[18:19], v[12:13], v[18:19]
	v_cvt_pk_bf16_f32 v19, v21, v19
	v_cvt_pk_bf16_f32 v18, v20, v18
	v_ashrrev_i32_e32 v9, 31, v8
	v_lshlrev_b64 v[20:21], 8, v[8:9]
	v_lshl_add_u64 v[20:21], v[34:35], 0, v[20:21]
	v_pk_mul_f32 v[16:17], v[16:17], v[24:25]
	global_store_dwordx2 v[20:21], v[18:19], off
	v_pk_mul_f32 v[12:13], v[12:13], v[26:27]
	v_cvt_pk_bf16_f32 v13, v17, v13
	v_cvt_pk_bf16_f32 v12, v16, v12
	v_lshlrev_b32_e32 v19, 16, v11
	v_lshlrev_b32_e32 v18, 16, v10
	v_and_b32_e32 v11, 0xffff0000, v11
	v_and_b32_e32 v10, 0xffff0000, v10
	v_pk_mul_f32 v[14:15], v[14:15], v[18:19]
	v_mad_u64_u32 v[16:17], s[0:1], v8, s46, v[2:3]
	v_pk_mul_f32 v[10:11], v[28:29], v[10:11]
	v_cvt_pk_bf16_f32 v9, v14, v14
	v_cvt_pk_bf16_f32 v2, v15, v15
	v_cvt_pk_bf16_f32 v14, v11, v11
	v_cvt_pk_bf16_f32 v15, v10, v10
	v_and_b32_e32 v10, 0xffff0000, v14
	v_and_b32_e32 v17, 0xffff0000, v15
	v_lshlrev_b32_e32 v8, 1, v8
	v_or_b32_sdwa v11, v10, v2 dst_sel:DWORD dst_unused:UNUSED_PAD src0_sel:DWORD src1_sel:WORD_1
	v_or_b32_sdwa v10, v17, v9 dst_sel:DWORD dst_unused:UNUSED_PAD src0_sel:DWORD src1_sel:WORD_1
	v_add3_u32 v8, s27, v8, v48
	ds_write2st64_b64 v16, v[12:13], v[10:11] offset1:66
	ds_write_b16_d16_hi v8, v9
	ds_write_b16_d16_hi v8, v15 offset:144
	ds_write_b16_d16_hi v8, v2 offset:288
	ds_write_b16_d16_hi v8, v14 offset:432
	v_lshlrev_b32_e32 v2, 3, v36
	v_and_or_b32 v8, v2, s48, v39
	v_lshl_add_u32 v2, v7, 4, 0
	v_mad_u64_u32 v[28:29], s[0:1], v8, s46, v[2:3]
	s_waitcnt lgkmcnt(0)
	s_barrier
	ds_read_b128 v[8:11], v28
	v_lshlrev_b32_e32 v12, 5, v36
	v_and_or_b32 v36, v12, 32, v39
	v_mad_u32_u24 v2, v36, s46, v2
	ds_read_b128 v[12:15], v28 offset:64
	ds_read_b128 v[16:19], v2 offset:33792
	ds_read_b128 v[20:23], v2 offset:33856
	ds_read_b128 v[24:27], v28 offset:128
	s_waitcnt lgkmcnt(2)
	v_mfma_f32_16x16x32_bf16 v[16:19], v[8:11], v[16:19], 0
	s_waitcnt lgkmcnt(1)
	v_mfma_f32_16x16x32_bf16 v[16:19], v[12:15], v[20:23], v[16:19]
	ds_read_b128 v[20:23], v28 offset:192
	ds_read_b128 v[28:31], v2 offset:33920
	ds_read_b128 v[32:35], v2 offset:33984
	s_waitcnt lgkmcnt(1)
	v_mfma_f32_16x16x32_bf16 v[16:19], v[24:27], v[28:31], v[16:19]
	s_waitcnt lgkmcnt(0)
	v_mfma_f32_16x16x32_bf16 v[16:19], v[20:23], v[32:35], v[16:19]
	ds_read_b128 v[28:31], v2 offset:42240
	ds_read_b128 v[32:35], v2 offset:42304
	s_waitcnt lgkmcnt(1)
	v_mfma_f32_16x16x32_bf16 v[8:11], v[8:11], v[28:31], 0
	s_waitcnt lgkmcnt(0)
	v_mfma_f32_16x16x32_bf16 v[8:11], v[12:15], v[32:35], v[8:11]
	ds_read_b128 v[12:15], v2 offset:42368
	ds_read_b128 v[28:31], v2 offset:42432
	v_ashrrev_i32_e32 v2, 3, v6
	v_and_b32_e32 v2, -16, v2
	v_lshl_or_b32 v2, v7, 2, v2
	v_cmp_le_i32_e64 s[0:1], v36, v2
	s_waitcnt lgkmcnt(1)
	v_mfma_f32_16x16x32_bf16 v[8:11], v[24:27], v[12:15], v[8:11]
	v_lshl_add_u32 v6, v36, 1, s49
	v_cndmask_b32_e64 v7, 0, 1, s[0:1]
	v_cmp_ge_i32_e64 s[0:1], v36, v2
	s_waitcnt lgkmcnt(0)
	v_mfma_f32_16x16x32_bf16 v[8:11], v[20:23], v[28:31], v[8:11]
	v_cndmask_b32_e64 v12, 0, 1, s[0:1]
	v_cndmask_b32_e32 v7, v12, v7, vcc
	v_and_b32_e32 v7, 1, v7
	v_cmp_eq_u32_e64 s[0:1], 1, v7
	s_nop 1
	v_cndmask_b32_e64 v7, 0, v16, s[0:1]
	v_cvt_pk_bf16_f32 v7, v7, v7
	v_mul_lo_u32 v12, v2, s47
	v_add_u32_e32 v13, v6, v12
	ds_write_b16_d16_hi v13, v7
	v_or_b32_e32 v7, 1, v2
	v_cmp_gt_i32_e64 s[0:1], v36, v2
	s_nop 1
	v_cndmask_b32_e64 v13, 0, 1, s[0:1]
	v_cmp_le_i32_e64 s[0:1], v36, v7
	s_nop 1
	v_cndmask_b32_e64 v14, 0, 1, s[0:1]
	v_cndmask_b32_e32 v13, v13, v14, vcc
	v_and_b32_e32 v13, 1, v13
	v_cmp_eq_u32_e64 s[0:1], 1, v13
	s_nop 1
	v_cndmask_b32_e64 v13, 0, v17, s[0:1]
	v_cvt_pk_bf16_f32 v13, v13, v13
	v_add_u32_e32 v14, 0x90, v12
	v_add_u32_e32 v15, v6, v14
	ds_write_b16_d16_hi v15, v13
	v_or_b32_e32 v13, 2, v2
	v_cmp_le_i32_e64 s[0:1], v36, v13
	s_nop 1
	v_cndmask_b32_e64 v15, 0, 1, s[0:1]
	v_cmp_ge_i32_e64 s[0:1], v36, v13
	s_nop 1
	v_cndmask_b32_e64 v16, 0, 1, s[0:1]
	v_cndmask_b32_e32 v15, v16, v15, vcc
	v_and_b32_e32 v15, 1, v15
	v_cmp_eq_u32_e64 s[0:1], 1, v15
	s_nop 1
	v_cndmask_b32_e64 v15, 0, v18, s[0:1]
	v_cvt_pk_bf16_f32 v15, v15, v15
	v_add_u32_e32 v16, 0x120, v12
	v_add_u32_e32 v17, v6, v16
	ds_write_b16_d16_hi v17, v15
	v_or_b32_e32 v15, 3, v2
	v_cmp_le_i32_e64 s[0:1], v36, v15
	s_nop 1
	v_cndmask_b32_e64 v17, 0, 1, s[0:1]
	v_cmp_ge_i32_e64 s[0:1], v36, v15
	s_nop 1
	v_cndmask_b32_e64 v18, 0, 1, s[0:1]
	v_cndmask_b32_e32 v17, v18, v17, vcc
	v_and_b32_e32 v17, 1, v17
	v_cmp_eq_u32_e64 s[0:1], 1, v17
	s_nop 1
	v_cndmask_b32_e64 v17, 0, v19, s[0:1]
	v_cvt_pk_bf16_f32 v17, v17, v17
	v_add_u32_e32 v18, 0x1b0, v12
	v_add_u32_e32 v6, v6, v18
	ds_write_b16_d16_hi v6, v17
	v_or_b32_e32 v6, 16, v36
	v_cmp_le_i32_e64 s[0:1], v6, v2
	s_nop 1
	v_cndmask_b32_e64 v17, 0, 1, s[0:1]
	v_cmp_ge_i32_e64 s[0:1], v6, v2
	s_nop 1
	v_cndmask_b32_e64 v19, 0, 1, s[0:1]
	v_cndmask_b32_e32 v17, v19, v17, vcc
	v_and_b32_e32 v17, 1, v17
	v_cmp_eq_u32_e64 s[0:1], 1, v17
	s_nop 1
	v_cndmask_b32_e64 v8, 0, v8, s[0:1]
	v_cmp_le_i32_e64 s[0:1], v6, v7
	s_nop 0
	v_cvt_pk_bf16_f32 v8, v8, v8
	v_cndmask_b32_e64 v7, 0, 1, s[0:1]
	v_cmp_gt_i32_e64 s[0:1], v6, v2
	v_lshlrev_b32_e32 v17, 1, v6
	v_add3_u32 v12, s49, v12, v17
	v_cndmask_b32_e64 v2, 0, 1, s[0:1]
	v_cndmask_b32_e32 v2, v2, v7, vcc
	v_and_b32_e32 v2, 1, v2
	v_cmp_eq_u32_e64 s[0:1], 1, v2
	ds_write_b16_d16_hi v12, v8
	s_nop 0
	v_cndmask_b32_e64 v2, 0, v9, s[0:1]
	v_cvt_pk_bf16_f32 v2, v2, v2
	v_add3_u32 v7, s49, v14, v17
	v_cmp_le_i32_e64 s[0:1], v6, v13
	ds_write_b16_d16_hi v7, v2
	s_nop 0
	v_cndmask_b32_e64 v2, 0, 1, s[0:1]
	v_cmp_ge_i32_e64 s[0:1], v6, v13
	s_nop 1
	v_cndmask_b32_e64 v7, 0, 1, s[0:1]
	v_cndmask_b32_e32 v2, v7, v2, vcc
	v_and_b32_e32 v2, 1, v2
	v_cmp_eq_u32_e64 s[0:1], 1, v2
	s_nop 1
	v_cndmask_b32_e64 v2, 0, v10, s[0:1]
	v_cvt_pk_bf16_f32 v2, v2, v2
	v_add3_u32 v7, s49, v16, v17
	v_cmp_le_i32_e64 s[0:1], v6, v15
	ds_write_b16_d16_hi v7, v2
	s_nop 0
	v_cndmask_b32_e64 v2, 0, 1, s[0:1]
	v_cmp_ge_i32_e64 s[0:1], v6, v15
	s_nop 1
	v_cndmask_b32_e64 v6, 0, 1, s[0:1]
	v_cndmask_b32_e32 v2, v6, v2, vcc
	v_and_b32_e32 v2, 1, v2
	v_cmp_eq_u32_e64 s[0:1], 1, v2
	s_nop 1
	v_cndmask_b32_e64 v2, 0, v11, s[0:1]
	v_cvt_pk_bf16_f32 v2, v2, v2
	v_add3_u32 v6, s49, v18, v17
	ds_write_b16_d16_hi v6, v2
	v_mov_b32_e32 v6, v0
	s_waitcnt lgkmcnt(0)
	s_barrier
	s_nop 0
	v_cmp_gt_i32_e64 s[0:1], s23, v6
	s_and_saveexec_b64 s[18:19], s[0:1]
	s_cbranch_execz .LBB0_3676
	s_lshl_b64 s[0:1], s[14:15], 13
	s_add_u32 s14, s64, s0
	s_addc_u32 s15, s61, s1
	v_lshlrev_b32_e32 v7, 3, v6
	s_mov_b64 s[20:21], 0

.LBB0_3744:
	v_add_u32_e32 v27, 0x400, v26
	v_lshlrev_b32_e32 v38, 16, v10
	ds_read2_b32 v[30:31], v26 offset1:65
	ds_read2_b32 v[32:33], v26 offset0:130 offset1:195
	ds_read2_b32 v[34:35], v27 offset0:4 offset1:69
	ds_read2_b32 v[36:37], v27 offset0:134 offset1:199
	v_mul_f32_e32 v27, 0xbfb8aa3b, v38
	v_exp_f32_e32 v27, v27
	v_lshlrev_b32_e32 v39, 16, v11
	v_mul_f32_e32 v40, 0xbfb8aa3b, v39
	v_exp_f32_e32 v41, v40
	v_and_b32_e32 v10, 0xffff0000, v10
	v_add_f32_e32 v27, 1.0, v27
	v_and_b32_e32 v11, 0xffff0000, v11
	v_rcp_f32_e32 v40, v27
	v_mul_f32_e32 v27, 0xbfb8aa3b, v10
	v_exp_f32_e32 v27, v27
	v_add_f32_e32 v41, 1.0, v41
	v_mul_f32_e32 v42, 0xbfb8aa3b, v11
	v_rcp_f32_e32 v41, v41
	v_exp_f32_e32 v43, v42
	v_add_f32_e32 v27, 1.0, v27
	v_rcp_f32_e32 v42, v27
	v_pk_mul_f32 v[38:39], v[40:41], v[38:39]
	v_add_f32_e32 v27, 1.0, v43
	s_waitcnt lgkmcnt(3)
	v_mov_b32_e32 v40, v30
	v_lshlrev_b32_e32 v30, 16, v12
	v_rcp_f32_e32 v43, v27
	v_mul_f32_e32 v27, 0xbfb8aa3b, v30
	v_exp_f32_e32 v27, v27
	s_waitcnt lgkmcnt(2)
	v_mov_b32_e32 v41, v32
	v_pk_mul_f32 v[10:11], v[42:43], v[10:11]
	v_mov_b32_e32 v32, v31
	v_lshlrev_b32_e32 v31, 16, v13
	v_pk_mul_f32 v[10:11], v[10:11], v[32:33]
	v_and_b32_e32 v12, 0xffff0000, v12
	v_add_f32_e32 v27, 1.0, v27
	v_mul_f32_e32 v32, 0xbfb8aa3b, v31
	v_and_b32_e32 v13, 0xffff0000, v13
	v_exp_f32_e32 v33, v32
	v_rcp_f32_e32 v32, v27
	v_mul_f32_e32 v27, 0xbfb8aa3b, v12
	v_pk_mul_f32 v[38:39], v[38:39], v[40:41]
	v_exp_f32_e32 v27, v27
	v_mul_f32_e32 v40, 0xbfb8aa3b, v13
	v_exp_f32_e32 v41, v40
	v_add_f32_e32 v33, 1.0, v33
	v_add_f32_e32 v27, 1.0, v27
	v_rcp_f32_e32 v40, v27
	v_add_f32_e32 v27, 1.0, v41
	v_rcp_f32_e32 v33, v33
	v_rcp_f32_e32 v41, v27
	s_and_b32 s6, s39, 0xffffffc0
	v_add_u32_e32 v28, s6, v23
	v_pk_mul_f32 v[30:31], v[32:33], v[30:31]
	s_waitcnt lgkmcnt(0)
	v_mov_b32_e32 v33, v36
	v_pk_mul_f32 v[12:13], v[40:41], v[12:13]
	v_mov_b32_e32 v36, v35
	v_mov_b32_e32 v32, v34
	v_pk_mul_f32 v[12:13], v[12:13], v[36:37]
	v_ashrrev_i32_e32 v29, 31, v28
	v_pk_mul_f32 v[30:31], v[30:31], v[32:33]
	v_cvt_pk_bf16_f32 v13, v31, v13
	v_cvt_pk_bf16_f32 v12, v30, v12
	v_cvt_pk_bf16_f32 v11, v39, v11
	v_cvt_pk_bf16_f32 v10, v38, v10
	s_and_b32 s22, s38, 0x3c0
	v_lshlrev_b64 v[28:29], 13, v[28:29]
	v_lshl_add_u64 v[28:29], s[12:13], 0, v[28:29]
	s_lshl_b32 s6, s22, 1
	v_lshl_add_u64 v[28:29], v[28:29], 0, s[6:7]
	v_lshl_add_u64 v[28:29], v[28:29], 0, v[18:19]
	global_store_dwordx4 v[28:29], v[10:13], off offset:2048
	s_waitcnt lgkmcnt(0)
	s_barrier
	s_andn2_b64 vcc, exec, s[20:21]
	s_mov_b32 s38, s37
	s_waitcnt vmcnt(1)
	v_mov_b64_e32 v[10:11], v[14:15]
	s_mov_b32 s39, s29
	v_mov_b64_e32 v[12:13], v[16:17]
	s_cbranch_vccz .LBB0_3749

.LBB0_3752:
	v_ashrrev_i32_e32 v37, 8, v18
	v_and_b32_e32 v34, 0xff, v18
	v_lshlrev_b32_e32 v19, 13, v37
	v_lshlrev_b32_e32 v20, 1, v34
	v_add3_u32 v38, s25, v19, v20
	v_add3_u32 v19, s53, v19, v20
	ds_read_u16 v20, v38
	ds_read_u16 v22, v38 offset:512
	ds_read_u16 v24, v38 offset:1024
	ds_read_u16 v26, v38 offset:1536
	ds_read_u16 v28, v38 offset:2048
	ds_read_u16 v39, v38 offset:2560
	ds_read_u16 v42, v38 offset:3072
	ds_read_u16 v44, v38 offset:3584
	ds_read_u16 v21, v19
	ds_read_u16 v23, v19 offset:512
	ds_read_u16 v25, v19 offset:1024
	ds_read_u16 v27, v19 offset:1536
	ds_read_u16 v29, v19 offset:2048
	ds_read_u16 v41, v19 offset:2560
	ds_read_u16 v43, v19 offset:3072
	ds_read_u16 v45, v19 offset:3584
	s_waitcnt lgkmcnt(7)
	v_lshlrev_b32_e32 v21, 16, v21
	v_lshlrev_b32_e32 v40, 16, v39
	s_waitcnt lgkmcnt(2)
	v_lshlrev_b32_e32 v39, 16, v41
	v_xor_b32_e32 v41, 0x80000000, v39
	s_waitcnt lgkmcnt(1)
	v_lshlrev_b32_e32 v39, 16, v43
	v_xor_b32_e32 v43, 0x80000000, v39
	s_waitcnt lgkmcnt(0)
	v_lshlrev_b32_e32 v39, 16, v45
	v_xor_b32_e32 v45, 0x80000000, v39
	ds_read_u16 v39, v38 offset:4096
	ds_read_u16 v48, v38 offset:4608
	ds_read_u16 v50, v38 offset:5120
	ds_read_u16 v52, v38 offset:5632
	ds_read_u16 v54, v38 offset:6144
	ds_read_u16 v56, v38 offset:6656
	ds_read_u16 v58, v38 offset:7168
	ds_read_u16 v38, v38 offset:7680
	s_waitcnt lgkmcnt(7)
	v_lshlrev_b32_e32 v46, 16, v39
	ds_read_u16 v39, v19 offset:4096
	ds_read_u16 v49, v19 offset:4608
	ds_read_u16 v51, v19 offset:5120
	ds_read_u16 v53, v19 offset:5632
	ds_read_u16 v55, v19 offset:6144
	ds_read_u16 v57, v19 offset:6656
	ds_read_u16 v59, v19 offset:7168
	ds_read_u16 v19, v19 offset:7680
	s_waitcnt lgkmcnt(7)
	v_lshlrev_b32_e32 v39, 16, v39
	v_xor_b32_e32 v47, 0x80000000, v39
	s_waitcnt lgkmcnt(6)
	v_lshlrev_b32_e32 v39, 16, v49
	v_xor_b32_e32 v49, 0x80000000, v39
	s_waitcnt lgkmcnt(5)
	v_lshlrev_b32_e32 v39, 16, v51
	v_xor_b32_e32 v51, 0x80000000, v39
	s_waitcnt lgkmcnt(4)
	v_lshlrev_b32_e32 v39, 16, v53
	v_lshlrev_b32_e32 v29, 16, v29
	v_xor_b32_e32 v53, 0x80000000, v39
	s_waitcnt lgkmcnt(3)
	v_lshlrev_b32_e32 v39, 16, v55
	v_lshlrev_b32_e32 v20, 16, v20
	v_xor_b32_e32 v21, 0x80000000, v21
	v_lshlrev_b32_e32 v23, 16, v23
	v_lshlrev_b32_e32 v28, 16, v28
	v_xor_b32_e32 v29, 0x80000000, v29
	v_lshlrev_b32_e32 v54, 16, v54
	v_xor_b32_e32 v55, 0x80000000, v39
	s_waitcnt lgkmcnt(2)
	v_lshlrev_b32_e32 v39, 16, v57
	s_waitcnt lgkmcnt(0)
	v_lshlrev_b32_e32 v19, 16, v19
	v_lshlrev_b32_e32 v22, 16, v22
	v_xor_b32_e32 v23, 0x80000000, v23
	v_lshlrev_b32_e32 v25, 16, v25
	v_lshlrev_b32_e32 v48, 16, v48
	v_lshlrev_b32_e32 v56, 16, v56
	v_xor_b32_e32 v57, 0x80000000, v39
	v_lshlrev_b32_e32 v39, 16, v59
	v_lshlrev_b32_e32 v60, 16, v38
	v_xor_b32_e32 v61, 0x80000000, v19
	v_bfe_u32 v38, v18, 4, 4
	v_pk_add_f32 v[18:19], v[20:21], v[46:47]
	v_pk_add_f32 v[20:21], v[20:21], v[46:47] neg_lo:[0,1] neg_hi:[0,1]
	v_pk_add_f32 v[46:47], v[28:29], v[54:55]
	v_pk_add_f32 v[28:29], v[28:29], v[54:55] neg_lo:[0,1] neg_hi:[0,1]
	v_lshlrev_b32_e32 v24, 16, v24
	v_xor_b32_e32 v25, 0x80000000, v25
	v_lshlrev_b32_e32 v27, 16, v27
	v_lshlrev_b32_e32 v42, 16, v42
	v_lshlrev_b32_e32 v50, 16, v50
	v_lshlrev_b32_e32 v58, 16, v58
	v_xor_b32_e32 v59, 0x80000000, v39
	v_pk_add_f32 v[54:55], v[18:19], v[46:47]
	v_pk_add_f32 v[46:47], v[18:19], v[46:47] neg_lo:[0,1] neg_hi:[0,1]
	v_pk_add_f32 v[62:63], v[20:21], v[28:29] op_sel:[0,1] op_sel_hi:[1,0] neg_hi:[0,1]
	v_pk_add_f32 v[64:65], v[20:21], v[28:29] op_sel:[0,1] op_sel_hi:[1,0] neg_lo:[0,1]
	v_pk_add_f32 v[18:19], v[22:23], v[48:49]
	v_pk_add_f32 v[20:21], v[22:23], v[48:49] neg_lo:[0,1] neg_hi:[0,1]
	v_pk_add_f32 v[22:23], v[40:41], v[56:57]
	v_pk_add_f32 v[28:29], v[40:41], v[56:57] neg_lo:[0,1] neg_hi:[0,1]
	v_lshlrev_b32_e32 v26, 16, v26
	v_xor_b32_e32 v27, 0x80000000, v27
	v_lshlrev_b32_e32 v44, 16, v44
	v_lshlrev_b32_e32 v52, 16, v52
	v_pk_add_f32 v[40:41], v[18:19], v[22:23]
	v_pk_add_f32 v[22:23], v[18:19], v[22:23] neg_lo:[0,1] neg_hi:[0,1]
	v_pk_add_f32 v[18:19], v[20:21], v[28:29] op_sel:[0,1] op_sel_hi:[1,0] neg_hi:[0,1]
	v_pk_add_f32 v[28:29], v[20:21], v[28:29] op_sel:[0,1] op_sel_hi:[1,0] neg_lo:[0,1]
	v_pk_add_f32 v[20:21], v[24:25], v[50:51]
	v_pk_add_f32 v[24:25], v[24:25], v[50:51] neg_lo:[0,1] neg_hi:[0,1]
	v_pk_add_f32 v[48:49], v[42:43], v[58:59]
	v_pk_add_f32 v[42:43], v[42:43], v[58:59] neg_lo:[0,1] neg_hi:[0,1]
	v_pk_add_f32 v[50:51], v[20:21], v[48:49]
	v_pk_add_f32 v[48:49], v[20:21], v[48:49] neg_lo:[0,1] neg_hi:[0,1]
	v_pk_add_f32 v[56:57], v[24:25], v[42:43] op_sel:[0,1] op_sel_hi:[1,0] neg_hi:[0,1]
	v_pk_add_f32 v[42:43], v[24:25], v[42:43] op_sel:[0,1] op_sel_hi:[1,0] neg_lo:[0,1]
	v_pk_add_f32 v[20:21], v[26:27], v[52:53]
	v_pk_add_f32 v[24:25], v[26:27], v[52:53] neg_lo:[0,1] neg_hi:[0,1]
	v_pk_add_f32 v[26:27], v[44:45], v[60:61]
	v_pk_add_f32 v[44:45], v[44:45], v[60:61] neg_lo:[0,1] neg_hi:[0,1]
	v_pk_add_f32 v[52:53], v[20:21], v[26:27]
	v_pk_add_f32 v[58:59], v[20:21], v[26:27] neg_lo:[0,1] neg_hi:[0,1]
	v_pk_add_f32 v[26:27], v[24:25], v[44:45] op_sel:[0,1] op_sel_hi:[1,0] neg_hi:[0,1]
	v_pk_add_f32 v[44:45], v[24:25], v[44:45] op_sel:[0,1] op_sel_hi:[1,0] neg_lo:[0,1]
	v_mov_b64_e32 v[24:25], s[26:27]
	v_pk_mul_f32 v[20:21], v[18:19], v[24:25] op_sel:[0,0] op_sel_hi:[0,1]
	v_mad_i32_i24 v35, v37, s3, 0
	v_pk_fma_f32 v[60:61], v[18:19], v[24:25], v[20:21] op_sel:[1,1,0] op_sel_hi:[1,0,1] neg_lo:[0,1,0]
	v_mov_b64_e32 v[20:21], s[34:35]
	v_pk_mul_f32 v[18:19], v[56:57], v[20:21] op_sel:[0,0] op_sel_hi:[0,1]
	v_lshlrev_b32_e32 v39, 3, v34
	v_pk_fma_f32 v[56:57], v[56:57], v[20:21], v[18:19] op_sel:[1,1,0] op_sel_hi:[1,0,1] neg_lo:[0,1,0]
	v_mov_b64_e32 v[18:19], s[36:37]
	v_pk_mul_f32 v[66:67], v[26:27], v[18:19] op_sel:[0,0] op_sel_hi:[0,1]
	v_lshlrev_b32_e32 v74, 3, v38
	v_pk_fma_f32 v[66:67], v[26:27], v[18:19], v[66:67] op_sel:[1,1,0] op_sel_hi:[1,0,1] neg_lo:[0,1,0]
	v_pk_mul_f32 v[26:27], v[22:23], v[20:21] op_sel:[0,0] op_sel_hi:[0,1]
	v_add3_u32 v74, v35, v39, v74
	v_pk_fma_f32 v[68:69], v[22:23], v[20:21], v[26:27] op_sel:[1,1,0] op_sel_hi:[1,0,1] neg_lo:[0,1,0]
	v_mov_b64_e32 v[26:27], s[22:23]
	v_pk_mul_f32 v[22:23], v[48:49], v[26:27] op_sel:[0,0] op_sel_hi:[0,1]
	v_lshl_add_u32 v78, v38, 11, v35
	v_pk_fma_f32 v[48:49], v[48:49], v[26:27], v[22:23] op_sel:[1,1,0] op_sel_hi:[1,0,1] neg_lo:[0,1,0]
	v_mov_b64_e32 v[22:23], s[38:39]
	v_pk_mul_f32 v[70:71], v[58:59], v[22:23] op_sel:[0,0] op_sel_hi:[0,1]
	v_add_u32_e32 v39, v78, v39
	v_pk_fma_f32 v[58:59], v[58:59], v[22:23], v[70:71] op_sel:[1,1,0] op_sel_hi:[1,0,1] neg_lo:[0,1,0]
	v_pk_mul_f32 v[70:71], v[28:29], v[18:19] op_sel:[0,0] op_sel_hi:[0,1]
	v_pk_fma_f32 v[70:71], v[28:29], v[18:19], v[70:71] op_sel:[1,1,0] op_sel_hi:[1,0,1] neg_lo:[0,1,0]
	v_pk_mul_f32 v[28:29], v[42:43], v[22:23] op_sel:[0,0] op_sel_hi:[0,1]
	v_pk_fma_f32 v[42:43], v[42:43], v[22:23], v[28:29] op_sel:[1,1,0] op_sel_hi:[1,0,1] neg_lo:[0,1,0]
	v_mov_b64_e32 v[28:29], s[40:41]
	v_pk_mul_f32 v[72:73], v[44:45], v[28:29] op_sel:[0,0] op_sel_hi:[0,1]
	v_pk_fma_f32 v[44:45], v[44:45], v[28:29], v[72:73] op_sel:[1,1,0] op_sel_hi:[1,0,1] neg_lo:[0,1,0]
	v_pk_add_f32 v[72:73], v[54:55], v[50:51]
	v_pk_add_f32 v[50:51], v[54:55], v[50:51] neg_lo:[0,1] neg_hi:[0,1]
	v_pk_add_f32 v[54:55], v[40:41], v[52:53]
	v_pk_add_f32 v[40:41], v[40:41], v[52:53] neg_lo:[0,1] neg_hi:[0,1]
	v_pk_add_f32 v[52:53], v[72:73], v[54:55]
	v_pk_add_f32 v[54:55], v[72:73], v[54:55] neg_lo:[0,1] neg_hi:[0,1]
	v_pk_add_f32 v[72:73], v[50:51], v[40:41] op_sel:[0,1] op_sel_hi:[1,0] neg_hi:[0,1]
	v_pk_add_f32 v[40:41], v[50:51], v[40:41] op_sel:[0,1] op_sel_hi:[1,0] neg_lo:[0,1]
	v_pk_add_f32 v[50:51], v[62:63], v[56:57]
	v_pk_add_f32 v[56:57], v[62:63], v[56:57] neg_lo:[0,1] neg_hi:[0,1]
	v_pk_add_f32 v[62:63], v[60:61], v[66:67]
	v_pk_add_f32 v[60:61], v[60:61], v[66:67] neg_lo:[0,1] neg_hi:[0,1]
	v_pk_add_f32 v[66:67], v[50:51], v[62:63]
	v_pk_add_f32 v[50:51], v[50:51], v[62:63] neg_lo:[0,1] neg_hi:[0,1]
	v_pk_add_f32 v[62:63], v[56:57], v[60:61] op_sel:[0,1] op_sel_hi:[1,0] neg_hi:[0,1]
	v_pk_add_f32 v[56:57], v[56:57], v[60:61] op_sel:[0,1] op_sel_hi:[1,0] neg_lo:[0,1]
	v_pk_add_f32 v[60:61], v[46:47], v[48:49]
	v_pk_add_f32 v[46:47], v[46:47], v[48:49] neg_lo:[0,1] neg_hi:[0,1]
	v_pk_add_f32 v[48:49], v[68:69], v[58:59]
	v_pk_add_f32 v[58:59], v[68:69], v[58:59] neg_lo:[0,1] neg_hi:[0,1]
	v_pk_add_f32 v[68:69], v[60:61], v[48:49]
	v_pk_add_f32 v[48:49], v[60:61], v[48:49] neg_lo:[0,1] neg_hi:[0,1]
	v_pk_add_f32 v[60:61], v[46:47], v[58:59] op_sel:[0,1] op_sel_hi:[1,0] neg_hi:[0,1]
	v_pk_add_f32 v[46:47], v[46:47], v[58:59] op_sel:[0,1] op_sel_hi:[1,0] neg_lo:[0,1]
	v_pk_add_f32 v[58:59], v[64:65], v[42:43]
	v_pk_add_f32 v[42:43], v[64:65], v[42:43] neg_lo:[0,1] neg_hi:[0,1]
	v_pk_add_f32 v[64:65], v[70:71], v[44:45]
	v_pk_add_f32 v[44:45], v[70:71], v[44:45] neg_lo:[0,1] neg_hi:[0,1]
	v_pk_add_f32 v[70:71], v[58:59], v[64:65]
	v_pk_add_f32 v[58:59], v[58:59], v[64:65] neg_lo:[0,1] neg_hi:[0,1]
	v_pk_add_f32 v[64:65], v[42:43], v[44:45] op_sel:[0,1] op_sel_hi:[1,0] neg_hi:[0,1]
	v_pk_add_f32 v[42:43], v[42:43], v[44:45] op_sel:[0,1] op_sel_hi:[1,0] neg_lo:[0,1]
	v_mov_b32_e32 v45, v31
	v_mov_b32_e32 v44, v1
	ds_write_b64 v74, v[52:53]
	v_pk_mul_f32 v[52:53], v[66:67], v[44:45] op_sel:[0,0] op_sel_hi:[0,1]
	v_pk_fma_f32 v[52:53], v[66:67], v[44:45], v[52:53] op_sel:[1,1,0] op_sel_hi:[1,0,1] neg_lo:[0,1,0]
	ds_write_b64 v74, v[52:53] offset:2176
	v_pk_mul_f32 v[52:53], v[44:45], v[44:45] op_sel:[0,0] op_sel_hi:[0,1]
	v_pk_fma_f32 v[52:53], v[44:45], v[44:45], v[52:53] op_sel:[1,1,0] op_sel_hi:[1,0,1] neg_lo:[0,1,0]
	v_pk_mul_f32 v[66:67], v[68:69], v[52:53] op_sel:[0,0] op_sel_hi:[0,1]
	v_pk_fma_f32 v[66:67], v[68:69], v[52:53], v[66:67] op_sel:[1,1,0] op_sel_hi:[1,0,1] neg_lo:[0,1,0]
	ds_write_b64 v74, v[66:67] offset:4352
	v_pk_mul_f32 v[66:67], v[52:53], v[44:45] op_sel:[0,0] op_sel_hi:[0,1]
	v_pk_fma_f32 v[52:53], v[52:53], v[44:45], v[66:67] op_sel:[1,1,0] op_sel_hi:[1,0,1] neg_lo:[0,1,0]
	v_pk_mul_f32 v[66:67], v[70:71], v[52:53] op_sel:[0,0] op_sel_hi:[0,1]
	v_pk_fma_f32 v[66:67], v[70:71], v[52:53], v[66:67] op_sel:[1,1,0] op_sel_hi:[1,0,1] neg_lo:[0,1,0]
	ds_write_b64 v74, v[66:67] offset:6528
	v_pk_mul_f32 v[66:67], v[52:53], v[44:45] op_sel:[0,0] op_sel_hi:[0,1]
	v_pk_fma_f32 v[52:53], v[52:53], v[44:45], v[66:67] op_sel:[1,1,0] op_sel_hi:[1,0,1] neg_lo:[0,1,0]
	v_pk_mul_f32 v[66:67], v[72:73], v[52:53] op_sel:[0,0] op_sel_hi:[0,1]
	v_pk_fma_f32 v[66:67], v[72:73], v[52:53], v[66:67] op_sel:[1,1,0] op_sel_hi:[1,0,1] neg_lo:[0,1,0]
	ds_write_b64 v74, v[66:67] offset:8704
	v_pk_mul_f32 v[66:67], v[52:53], v[44:45] op_sel:[0,0] op_sel_hi:[0,1]
	v_pk_fma_f32 v[52:53], v[52:53], v[44:45], v[66:67] op_sel:[1,1,0] op_sel_hi:[1,0,1] neg_lo:[0,1,0]
	v_pk_mul_f32 v[66:67], v[62:63], v[52:53] op_sel:[0,0] op_sel_hi:[0,1]
	v_pk_fma_f32 v[62:63], v[62:63], v[52:53], v[66:67] op_sel:[1,1,0] op_sel_hi:[1,0,1] neg_lo:[0,1,0]
	ds_write_b64 v74, v[62:63] offset:10880
	v_pk_mul_f32 v[62:63], v[52:53], v[44:45] op_sel:[0,0] op_sel_hi:[0,1]
	v_pk_fma_f32 v[52:53], v[52:53], v[44:45], v[62:63] op_sel:[1,1,0] op_sel_hi:[1,0,1] neg_lo:[0,1,0]
	v_pk_mul_f32 v[62:63], v[60:61], v[52:53] op_sel:[0,0] op_sel_hi:[0,1]
	v_pk_fma_f32 v[60:61], v[60:61], v[52:53], v[62:63] op_sel:[1,1,0] op_sel_hi:[1,0,1] neg_lo:[0,1,0]
	ds_write_b64 v74, v[60:61] offset:13056
	v_pk_mul_f32 v[60:61], v[52:53], v[44:45] op_sel:[0,0] op_sel_hi:[0,1]
	v_pk_fma_f32 v[52:53], v[52:53], v[44:45], v[60:61] op_sel:[1,1,0] op_sel_hi:[1,0,1] neg_lo:[0,1,0]
	v_pk_mul_f32 v[60:61], v[64:65], v[52:53] op_sel:[0,0] op_sel_hi:[0,1]
	v_pk_fma_f32 v[60:61], v[64:65], v[52:53], v[60:61] op_sel:[1,1,0] op_sel_hi:[1,0,1] neg_lo:[0,1,0]
	ds_write_b64 v74, v[60:61] offset:15232
	v_pk_mul_f32 v[60:61], v[52:53], v[44:45] op_sel:[0,0] op_sel_hi:[0,1]
	v_pk_fma_f32 v[52:53], v[52:53], v[44:45], v[60:61] op_sel:[1,1,0] op_sel_hi:[1,0,1] neg_lo:[0,1,0]
	v_pk_mul_f32 v[60:61], v[54:55], v[52:53] op_sel:[0,0] op_sel_hi:[0,1]
	v_pk_fma_f32 v[54:55], v[54:55], v[52:53], v[60:61] op_sel:[1,1,0] op_sel_hi:[1,0,1] neg_lo:[0,1,0]
	ds_write_b64 v74, v[54:55] offset:17408
	v_pk_mul_f32 v[54:55], v[52:53], v[44:45] op_sel:[0,0] op_sel_hi:[0,1]
	v_pk_fma_f32 v[52:53], v[52:53], v[44:45], v[54:55] op_sel:[1,1,0] op_sel_hi:[1,0,1] neg_lo:[0,1,0]
	v_pk_mul_f32 v[54:55], v[50:51], v[52:53] op_sel:[0,0] op_sel_hi:[0,1]
	v_pk_fma_f32 v[50:51], v[50:51], v[52:53], v[54:55] op_sel:[1,1,0] op_sel_hi:[1,0,1] neg_lo:[0,1,0]
	ds_write_b64 v74, v[50:51] offset:19584
	v_pk_mul_f32 v[50:51], v[52:53], v[44:45] op_sel:[0,0] op_sel_hi:[0,1]
	v_pk_fma_f32 v[50:51], v[52:53], v[44:45], v[50:51] op_sel:[1,1,0] op_sel_hi:[1,0,1] neg_lo:[0,1,0]
	v_pk_mul_f32 v[52:53], v[48:49], v[50:51] op_sel:[0,0] op_sel_hi:[0,1]
	v_pk_fma_f32 v[48:49], v[48:49], v[50:51], v[52:53] op_sel:[1,1,0] op_sel_hi:[1,0,1] neg_lo:[0,1,0]
	ds_write_b64 v74, v[48:49] offset:21760
	v_pk_mul_f32 v[48:49], v[50:51], v[44:45] op_sel:[0,0] op_sel_hi:[0,1]
	v_pk_fma_f32 v[48:49], v[50:51], v[44:45], v[48:49] op_sel:[1,1,0] op_sel_hi:[1,0,1] neg_lo:[0,1,0]
	v_pk_mul_f32 v[50:51], v[58:59], v[48:49] op_sel:[0,0] op_sel_hi:[0,1]
	v_pk_fma_f32 v[50:51], v[58:59], v[48:49], v[50:51] op_sel:[1,1,0] op_sel_hi:[1,0,1] neg_lo:[0,1,0]
	ds_write_b64 v74, v[50:51] offset:23936
	v_pk_mul_f32 v[50:51], v[48:49], v[44:45] op_sel:[0,0] op_sel_hi:[0,1]
	v_pk_fma_f32 v[48:49], v[48:49], v[44:45], v[50:51] op_sel:[1,1,0] op_sel_hi:[1,0,1] neg_lo:[0,1,0]
	v_pk_mul_f32 v[50:51], v[40:41], v[48:49] op_sel:[0,0] op_sel_hi:[0,1]
	v_pk_fma_f32 v[40:41], v[40:41], v[48:49], v[50:51] op_sel:[1,1,0] op_sel_hi:[1,0,1] neg_lo:[0,1,0]
	ds_write_b64 v74, v[40:41] offset:26112
	v_pk_mul_f32 v[40:41], v[48:49], v[44:45] op_sel:[0,0] op_sel_hi:[0,1]
	v_pk_fma_f32 v[40:41], v[48:49], v[44:45], v[40:41] op_sel:[1,1,0] op_sel_hi:[1,0,1] neg_lo:[0,1,0]
	v_pk_mul_f32 v[48:49], v[56:57], v[40:41] op_sel:[0,0] op_sel_hi:[0,1]
	v_pk_fma_f32 v[48:49], v[56:57], v[40:41], v[48:49] op_sel:[1,1,0] op_sel_hi:[1,0,1] neg_lo:[0,1,0]
	ds_write_b64 v74, v[48:49] offset:28288
	v_pk_mul_f32 v[48:49], v[40:41], v[44:45] op_sel:[0,0] op_sel_hi:[0,1]
	v_pk_fma_f32 v[40:41], v[40:41], v[44:45], v[48:49] op_sel:[1,1,0] op_sel_hi:[1,0,1] neg_lo:[0,1,0]
	v_pk_mul_f32 v[48:49], v[46:47], v[40:41] op_sel:[0,0] op_sel_hi:[0,1]
	v_pk_fma_f32 v[46:47], v[46:47], v[40:41], v[48:49] op_sel:[1,1,0] op_sel_hi:[1,0,1] neg_lo:[0,1,0]
	ds_write_b64 v74, v[46:47] offset:30464
	v_pk_mul_f32 v[46:47], v[40:41], v[44:45] op_sel:[0,0] op_sel_hi:[0,1]
	v_pk_fma_f32 v[40:41], v[40:41], v[44:45], v[46:47] op_sel:[1,1,0] op_sel_hi:[1,0,1] neg_lo:[0,1,0]
	v_pk_mul_f32 v[44:45], v[42:43], v[40:41] op_sel:[0,0] op_sel_hi:[0,1]
	v_pk_fma_f32 v[40:41], v[42:43], v[40:41], v[44:45] op_sel:[1,1,0] op_sel_hi:[1,0,1] neg_lo:[0,1,0]
	ds_write_b64 v74, v[40:41] offset:32640
	s_waitcnt lgkmcnt(0)
	s_barrier
	ds_read2_b64 v[40:43], v39 offset1:17
	ds_read2_b64 v[44:47], v39 offset0:34 offset1:51
	ds_read2_b64 v[48:51], v39 offset0:68 offset1:85
	ds_read2_b64 v[52:55], v39 offset0:136 offset1:153
	ds_read2_b64 v[56:59], v39 offset0:102 offset1:119
	ds_read2_b64 v[60:63], v39 offset0:204 offset1:221
	ds_read2_b64 v[64:67], v39 offset0:170 offset1:187
	ds_read2_b64 v[68:71], v39 offset0:238 offset1:255
	s_waitcnt lgkmcnt(4)
	v_pk_add_f32 v[72:73], v[40:41], v[52:53]
	v_pk_add_f32 v[40:41], v[40:41], v[52:53] neg_lo:[0,1] neg_hi:[0,1]
	s_waitcnt lgkmcnt(2)
	v_pk_add_f32 v[52:53], v[48:49], v[60:61]
	v_pk_add_f32 v[48:49], v[48:49], v[60:61] neg_lo:[0,1] neg_hi:[0,1]
	v_pk_add_f32 v[60:61], v[72:73], v[52:53]
	v_pk_add_f32 v[52:53], v[72:73], v[52:53] neg_lo:[0,1] neg_hi:[0,1]
	v_pk_add_f32 v[72:73], v[40:41], v[48:49] op_sel:[0,1] op_sel_hi:[1,0] neg_hi:[0,1]
	v_pk_add_f32 v[40:41], v[40:41], v[48:49] op_sel:[0,1] op_sel_hi:[1,0] neg_lo:[0,1]
	v_pk_add_f32 v[48:49], v[42:43], v[54:55]
	v_pk_add_f32 v[42:43], v[42:43], v[54:55] neg_lo:[0,1] neg_hi:[0,1]
	v_pk_add_f32 v[54:55], v[50:51], v[62:63]
	v_pk_add_f32 v[50:51], v[50:51], v[62:63] neg_lo:[0,1] neg_hi:[0,1]
	v_pk_add_f32 v[62:63], v[48:49], v[54:55]
	v_pk_add_f32 v[48:49], v[48:49], v[54:55] neg_lo:[0,1] neg_hi:[0,1]
	v_pk_add_f32 v[54:55], v[42:43], v[50:51] op_sel:[0,1] op_sel_hi:[1,0] neg_hi:[0,1]
	v_pk_add_f32 v[42:43], v[42:43], v[50:51] op_sel:[0,1] op_sel_hi:[1,0] neg_lo:[0,1]
	s_waitcnt lgkmcnt(1)
	v_pk_add_f32 v[50:51], v[44:45], v[64:65]
	v_pk_add_f32 v[44:45], v[44:45], v[64:65] neg_lo:[0,1] neg_hi:[0,1]
	s_waitcnt lgkmcnt(0)
	v_pk_add_f32 v[64:65], v[56:57], v[68:69]
	v_pk_add_f32 v[56:57], v[56:57], v[68:69] neg_lo:[0,1] neg_hi:[0,1]
	v_pk_add_f32 v[68:69], v[50:51], v[64:65]
	v_pk_add_f32 v[50:51], v[50:51], v[64:65] neg_lo:[0,1] neg_hi:[0,1]
	v_pk_add_f32 v[64:65], v[44:45], v[56:57] op_sel:[0,1] op_sel_hi:[1,0] neg_hi:[0,1]
	v_pk_add_f32 v[44:45], v[44:45], v[56:57] op_sel:[0,1] op_sel_hi:[1,0] neg_lo:[0,1]
	v_pk_add_f32 v[56:57], v[46:47], v[66:67]
	v_pk_add_f32 v[46:47], v[46:47], v[66:67] neg_lo:[0,1] neg_hi:[0,1]
	v_pk_add_f32 v[66:67], v[58:59], v[70:71]
	v_pk_add_f32 v[58:59], v[58:59], v[70:71] neg_lo:[0,1] neg_hi:[0,1]
	v_pk_add_f32 v[70:71], v[56:57], v[66:67]
	v_pk_add_f32 v[56:57], v[56:57], v[66:67] neg_lo:[0,1] neg_hi:[0,1]
	v_pk_add_f32 v[66:67], v[46:47], v[58:59] op_sel:[0,1] op_sel_hi:[1,0] neg_hi:[0,1]
	v_pk_add_f32 v[46:47], v[46:47], v[58:59] op_sel:[0,1] op_sel_hi:[1,0] neg_lo:[0,1]
	v_pk_mul_f32 v[58:59], v[54:55], v[24:25] op_sel:[0,0] op_sel_hi:[0,1]
	v_pk_fma_f32 v[54:55], v[54:55], v[24:25], v[58:59] op_sel:[1,1,0] op_sel_hi:[1,0,1] neg_lo:[0,1,0]
	v_pk_mul_f32 v[58:59], v[64:65], v[20:21] op_sel:[0,0] op_sel_hi:[0,1]
	v_pk_fma_f32 v[58:59], v[64:65], v[20:21], v[58:59] op_sel:[1,1,0] op_sel_hi:[1,0,1] neg_lo:[0,1,0]
	v_pk_mul_f32 v[64:65], v[66:67], v[18:19] op_sel:[0,0] op_sel_hi:[0,1]
	v_pk_fma_f32 v[64:65], v[66:67], v[18:19], v[64:65] op_sel:[1,1,0] op_sel_hi:[1,0,1] neg_lo:[0,1,0]
	v_pk_mul_f32 v[66:67], v[48:49], v[20:21] op_sel:[0,0] op_sel_hi:[0,1]
	v_pk_fma_f32 v[48:49], v[48:49], v[20:21], v[66:67] op_sel:[1,1,0] op_sel_hi:[1,0,1] neg_lo:[0,1,0]
	v_pk_mul_f32 v[66:67], v[50:51], v[26:27] op_sel:[0,0] op_sel_hi:[0,1]
	v_pk_fma_f32 v[50:51], v[50:51], v[26:27], v[66:67] op_sel:[1,1,0] op_sel_hi:[1,0,1] neg_lo:[0,1,0]
	v_pk_mul_f32 v[66:67], v[56:57], v[22:23] op_sel:[0,0] op_sel_hi:[0,1]
	v_pk_fma_f32 v[56:57], v[56:57], v[22:23], v[66:67] op_sel:[1,1,0] op_sel_hi:[1,0,1] neg_lo:[0,1,0]
	v_pk_mul_f32 v[66:67], v[42:43], v[18:19] op_sel:[0,0] op_sel_hi:[0,1]
	v_pk_fma_f32 v[42:43], v[42:43], v[18:19], v[66:67] op_sel:[1,1,0] op_sel_hi:[1,0,1] neg_lo:[0,1,0]
	v_pk_mul_f32 v[66:67], v[44:45], v[22:23] op_sel:[0,0] op_sel_hi:[0,1]
	v_pk_fma_f32 v[44:45], v[44:45], v[22:23], v[66:67] op_sel:[1,1,0] op_sel_hi:[1,0,1] neg_lo:[0,1,0]
	v_pk_mul_f32 v[66:67], v[46:47], v[28:29] op_sel:[0,0] op_sel_hi:[0,1]
	v_pk_fma_f32 v[46:47], v[46:47], v[28:29], v[66:67] op_sel:[1,1,0] op_sel_hi:[1,0,1] neg_lo:[0,1,0]
	v_pk_add_f32 v[66:67], v[60:61], v[68:69]
	v_pk_add_f32 v[60:61], v[60:61], v[68:69] neg_lo:[0,1] neg_hi:[0,1]
	v_pk_add_f32 v[68:69], v[62:63], v[70:71]
	v_pk_add_f32 v[62:63], v[62:63], v[70:71] neg_lo:[0,1] neg_hi:[0,1]
	v_pk_add_f32 v[70:71], v[66:67], v[68:69]
	v_pk_add_f32 v[66:67], v[66:67], v[68:69] neg_lo:[0,1] neg_hi:[0,1]
	v_pk_add_f32 v[68:69], v[60:61], v[62:63] op_sel:[0,1] op_sel_hi:[1,0] neg_hi:[0,1]
	v_pk_add_f32 v[60:61], v[60:61], v[62:63] op_sel:[0,1] op_sel_hi:[1,0] neg_lo:[0,1]
	v_pk_add_f32 v[62:63], v[72:73], v[58:59]
	v_pk_add_f32 v[58:59], v[72:73], v[58:59] neg_lo:[0,1] neg_hi:[0,1]
	v_pk_add_f32 v[72:73], v[54:55], v[64:65]
	v_pk_add_f32 v[54:55], v[54:55], v[64:65] neg_lo:[0,1] neg_hi:[0,1]
	v_pk_add_f32 v[64:65], v[62:63], v[72:73]
	v_pk_add_f32 v[62:63], v[62:63], v[72:73] neg_lo:[0,1] neg_hi:[0,1]
	v_pk_add_f32 v[72:73], v[58:59], v[54:55] op_sel:[0,1] op_sel_hi:[1,0] neg_hi:[0,1]
	v_pk_add_f32 v[54:55], v[58:59], v[54:55] op_sel:[0,1] op_sel_hi:[1,0] neg_lo:[0,1]
	v_pk_add_f32 v[58:59], v[52:53], v[50:51]
	v_pk_add_f32 v[50:51], v[52:53], v[50:51] neg_lo:[0,1] neg_hi:[0,1]
	v_pk_add_f32 v[52:53], v[48:49], v[56:57]
	v_pk_add_f32 v[48:49], v[48:49], v[56:57] neg_lo:[0,1] neg_hi:[0,1]
	v_pk_add_f32 v[56:57], v[58:59], v[52:53]
	v_pk_add_f32 v[52:53], v[58:59], v[52:53] neg_lo:[0,1] neg_hi:[0,1]
	v_pk_add_f32 v[58:59], v[50:51], v[48:49] op_sel:[0,1] op_sel_hi:[1,0] neg_hi:[0,1]
	v_pk_add_f32 v[48:49], v[50:51], v[48:49] op_sel:[0,1] op_sel_hi:[1,0] neg_lo:[0,1]
	v_pk_add_f32 v[50:51], v[40:41], v[44:45]
	v_pk_add_f32 v[40:41], v[40:41], v[44:45] neg_lo:[0,1] neg_hi:[0,1]
	v_pk_add_f32 v[44:45], v[42:43], v[46:47]
	v_pk_add_f32 v[42:43], v[42:43], v[46:47] neg_lo:[0,1] neg_hi:[0,1]
	v_pk_add_f32 v[46:47], v[50:51], v[44:45]
	v_pk_add_f32 v[44:45], v[50:51], v[44:45] neg_lo:[0,1] neg_hi:[0,1]
	v_pk_add_f32 v[50:51], v[40:41], v[42:43] op_sel:[0,1] op_sel_hi:[1,0] neg_hi:[0,1]
	v_pk_add_f32 v[40:41], v[40:41], v[42:43] op_sel:[0,1] op_sel_hi:[1,0] neg_lo:[0,1]
	v_mov_b32_e32 v42, v30
	v_mov_b32_e32 v43, v32
	s_nop 0
	v_pk_mul_f32 v[74:75], v[64:65], v[42:43] op_sel:[0,0] op_sel_hi:[0,1]
	v_pk_fma_f32 v[64:65], v[64:65], v[42:43], v[74:75] op_sel:[1,1,0] op_sel_hi:[1,0,1] neg_lo:[0,1,0]
	ds_write2_b64 v39, v[70:71], v[64:65] offset1:17
	v_pk_mul_f32 v[64:65], v[42:43], v[42:43] op_sel:[0,0] op_sel_hi:[0,1]
	v_pk_fma_f32 v[64:65], v[42:43], v[42:43], v[64:65] op_sel:[1,1,0] op_sel_hi:[1,0,1] neg_lo:[0,1,0]
	v_pk_mul_f32 v[70:71], v[56:57], v[64:65] op_sel:[0,0] op_sel_hi:[0,1]
	v_pk_fma_f32 v[56:57], v[56:57], v[64:65], v[70:71] op_sel:[1,1,0] op_sel_hi:[1,0,1] neg_lo:[0,1,0]
	v_pk_mul_f32 v[70:71], v[64:65], v[42:43] op_sel:[0,0] op_sel_hi:[0,1]
	v_pk_fma_f32 v[64:65], v[64:65], v[42:43], v[70:71] op_sel:[1,1,0] op_sel_hi:[1,0,1] neg_lo:[0,1,0]
	v_pk_mul_f32 v[70:71], v[46:47], v[64:65] op_sel:[0,0] op_sel_hi:[0,1]
	v_pk_fma_f32 v[46:47], v[46:47], v[64:65], v[70:71] op_sel:[1,1,0] op_sel_hi:[1,0,1] neg_lo:[0,1,0]
	ds_write2_b64 v39, v[56:57], v[46:47] offset0:34 offset1:51
	v_pk_mul_f32 v[46:47], v[64:65], v[42:43] op_sel:[0,0] op_sel_hi:[0,1]
	v_pk_fma_f32 v[46:47], v[64:65], v[42:43], v[46:47] op_sel:[1,1,0] op_sel_hi:[1,0,1] neg_lo:[0,1,0]
	v_pk_mul_f32 v[56:57], v[68:69], v[46:47] op_sel:[0,0] op_sel_hi:[0,1]
	v_pk_mul_f32 v[64:65], v[46:47], v[42:43] op_sel:[0,0] op_sel_hi:[0,1]
	v_pk_fma_f32 v[56:57], v[68:69], v[46:47], v[56:57] op_sel:[1,1,0] op_sel_hi:[1,0,1] neg_lo:[0,1,0]
	v_pk_fma_f32 v[46:47], v[46:47], v[42:43], v[64:65] op_sel:[1,1,0] op_sel_hi:[1,0,1] neg_lo:[0,1,0]
	v_pk_mul_f32 v[64:65], v[72:73], v[46:47] op_sel:[0,0] op_sel_hi:[0,1]
	v_pk_fma_f32 v[64:65], v[72:73], v[46:47], v[64:65] op_sel:[1,1,0] op_sel_hi:[1,0,1] neg_lo:[0,1,0]
	ds_write2_b64 v39, v[56:57], v[64:65] offset0:68 offset1:85
	v_pk_mul_f32 v[56:57], v[46:47], v[42:43] op_sel:[0,0] op_sel_hi:[0,1]
	v_pk_fma_f32 v[46:47], v[46:47], v[42:43], v[56:57] op_sel:[1,1,0] op_sel_hi:[1,0,1] neg_lo:[0,1,0]
	v_pk_mul_f32 v[56:57], v[58:59], v[46:47] op_sel:[0,0] op_sel_hi:[0,1]
	v_pk_fma_f32 v[56:57], v[58:59], v[46:47], v[56:57] op_sel:[1,1,0] op_sel_hi:[1,0,1] neg_lo:[0,1,0]
	v_pk_mul_f32 v[58:59], v[46:47], v[42:43] op_sel:[0,0] op_sel_hi:[0,1]
	v_pk_fma_f32 v[46:47], v[46:47], v[42:43], v[58:59] op_sel:[1,1,0] op_sel_hi:[1,0,1] neg_lo:[0,1,0]
	v_pk_mul_f32 v[58:59], v[50:51], v[46:47] op_sel:[0,0] op_sel_hi:[0,1]
	v_pk_fma_f32 v[50:51], v[50:51], v[46:47], v[58:59] op_sel:[1,1,0] op_sel_hi:[1,0,1] neg_lo:[0,1,0]
	ds_write2_b64 v39, v[56:57], v[50:51] offset0:102 offset1:119
	v_pk_mul_f32 v[50:51], v[46:47], v[42:43] op_sel:[0,0] op_sel_hi:[0,1]
	v_pk_fma_f32 v[46:47], v[46:47], v[42:43], v[50:51] op_sel:[1,1,0] op_sel_hi:[1,0,1] neg_lo:[0,1,0]
	v_pk_mul_f32 v[50:51], v[66:67], v[46:47] op_sel:[0,0] op_sel_hi:[0,1]
	v_pk_mul_f32 v[56:57], v[46:47], v[42:43] op_sel:[0,0] op_sel_hi:[0,1]
	v_pk_fma_f32 v[50:51], v[66:67], v[46:47], v[50:51] op_sel:[1,1,0] op_sel_hi:[1,0,1] neg_lo:[0,1,0]
	v_pk_fma_f32 v[46:47], v[46:47], v[42:43], v[56:57] op_sel:[1,1,0] op_sel_hi:[1,0,1] neg_lo:[0,1,0]
	v_pk_mul_f32 v[56:57], v[62:63], v[46:47] op_sel:[0,0] op_sel_hi:[0,1]
	v_pk_fma_f32 v[56:57], v[62:63], v[46:47], v[56:57] op_sel:[1,1,0] op_sel_hi:[1,0,1] neg_lo:[0,1,0]
	ds_write2_b64 v39, v[50:51], v[56:57] offset0:136 offset1:153
	v_pk_mul_f32 v[50:51], v[46:47], v[42:43] op_sel:[0,0] op_sel_hi:[0,1]
	v_pk_fma_f32 v[46:47], v[46:47], v[42:43], v[50:51] op_sel:[1,1,0] op_sel_hi:[1,0,1] neg_lo:[0,1,0]
	v_pk_mul_f32 v[50:51], v[52:53], v[46:47] op_sel:[0,0] op_sel_hi:[0,1]
	v_pk_fma_f32 v[50:51], v[52:53], v[46:47], v[50:51] op_sel:[1,1,0] op_sel_hi:[1,0,1] neg_lo:[0,1,0]
	v_pk_mul_f32 v[52:53], v[46:47], v[42:43] op_sel:[0,0] op_sel_hi:[0,1]
	v_pk_fma_f32 v[46:47], v[46:47], v[42:43], v[52:53] op_sel:[1,1,0] op_sel_hi:[1,0,1] neg_lo:[0,1,0]
	v_pk_mul_f32 v[52:53], v[44:45], v[46:47] op_sel:[0,0] op_sel_hi:[0,1]
	v_pk_fma_f32 v[44:45], v[44:45], v[46:47], v[52:53] op_sel:[1,1,0] op_sel_hi:[1,0,1] neg_lo:[0,1,0]
	ds_write2_b64 v39, v[50:51], v[44:45] offset0:170 offset1:187
	v_pk_mul_f32 v[44:45], v[46:47], v[42:43] op_sel:[0,0] op_sel_hi:[0,1]
	v_pk_fma_f32 v[44:45], v[46:47], v[42:43], v[44:45] op_sel:[1,1,0] op_sel_hi:[1,0,1] neg_lo:[0,1,0]
	v_pk_mul_f32 v[46:47], v[60:61], v[44:45] op_sel:[0,0] op_sel_hi:[0,1]
	v_pk_mul_f32 v[50:51], v[44:45], v[42:43] op_sel:[0,0] op_sel_hi:[0,1]
	v_pk_fma_f32 v[46:47], v[60:61], v[44:45], v[46:47] op_sel:[1,1,0] op_sel_hi:[1,0,1] neg_lo:[0,1,0]
	v_pk_fma_f32 v[44:45], v[44:45], v[42:43], v[50:51] op_sel:[1,1,0] op_sel_hi:[1,0,1] neg_lo:[0,1,0]
	v_pk_mul_f32 v[50:51], v[54:55], v[44:45] op_sel:[0,0] op_sel_hi:[0,1]
	v_pk_fma_f32 v[50:51], v[54:55], v[44:45], v[50:51] op_sel:[1,1,0] op_sel_hi:[1,0,1] neg_lo:[0,1,0]
	ds_write2_b64 v39, v[46:47], v[50:51] offset0:204 offset1:221
	v_pk_mul_f32 v[46:47], v[44:45], v[42:43] op_sel:[0,0] op_sel_hi:[0,1]
	v_pk_fma_f32 v[44:45], v[44:45], v[42:43], v[46:47] op_sel:[1,1,0] op_sel_hi:[1,0,1] neg_lo:[0,1,0]
	v_pk_mul_f32 v[46:47], v[48:49], v[44:45] op_sel:[0,0] op_sel_hi:[0,1]
	v_pk_fma_f32 v[46:47], v[48:49], v[44:45], v[46:47] op_sel:[1,1,0] op_sel_hi:[1,0,1] neg_lo:[0,1,0]
	v_pk_mul_f32 v[48:49], v[44:45], v[42:43] op_sel:[0,0] op_sel_hi:[0,1]
	v_pk_fma_f32 v[42:43], v[44:45], v[42:43], v[48:49] op_sel:[1,1,0] op_sel_hi:[1,0,1] neg_lo:[0,1,0]
	v_pk_mul_f32 v[44:45], v[40:41], v[42:43] op_sel:[0,0] op_sel_hi:[0,1]
	v_pk_fma_f32 v[40:41], v[40:41], v[42:43], v[44:45] op_sel:[1,1,0] op_sel_hi:[1,0,1] neg_lo:[0,1,0]
	ds_write2_b64 v39, v[46:47], v[40:41] offset0:238 offset1:255
	v_mad_u32_u24 v39, v34, s54, v35
	s_waitcnt lgkmcnt(0)
	s_barrier
	ds_read2_b64 v[40:43], v39 offset1:1
	ds_read2_b64 v[44:47], v39 offset0:2 offset1:3
	ds_read2_b64 v[48:51], v39 offset0:8 offset1:9
	ds_read2_b64 v[52:55], v39 offset0:4 offset1:5
	ds_read2_b64 v[56:59], v39 offset0:6 offset1:7
	ds_read2_b64 v[60:63], v39 offset0:12 offset1:13
	ds_read2_b64 v[64:67], v39 offset0:10 offset1:11
	ds_read2_b64 v[68:71], v39 offset0:14 offset1:15
	s_waitcnt lgkmcnt(5)
	v_pk_add_f32 v[72:73], v[40:41], v[48:49]
	v_pk_add_f32 v[40:41], v[40:41], v[48:49] neg_lo:[0,1] neg_hi:[0,1]
	s_waitcnt lgkmcnt(2)
	v_pk_add_f32 v[48:49], v[52:53], v[60:61]
	v_pk_add_f32 v[52:53], v[52:53], v[60:61] neg_lo:[0,1] neg_hi:[0,1]
	v_pk_add_f32 v[60:61], v[72:73], v[48:49]
	v_pk_add_f32 v[48:49], v[72:73], v[48:49] neg_lo:[0,1] neg_hi:[0,1]
	v_pk_add_f32 v[72:73], v[40:41], v[52:53] op_sel:[0,1] op_sel_hi:[1,0] neg_hi:[0,1]
	v_pk_add_f32 v[40:41], v[40:41], v[52:53] op_sel:[0,1] op_sel_hi:[1,0] neg_lo:[0,1]
	v_pk_add_f32 v[52:53], v[42:43], v[50:51]
	v_pk_add_f32 v[42:43], v[42:43], v[50:51] neg_lo:[0,1] neg_hi:[0,1]
	v_pk_add_f32 v[50:51], v[54:55], v[62:63]
	v_pk_add_f32 v[54:55], v[54:55], v[62:63] neg_lo:[0,1] neg_hi:[0,1]
	v_pk_add_f32 v[62:63], v[52:53], v[50:51]
	v_pk_add_f32 v[50:51], v[52:53], v[50:51] neg_lo:[0,1] neg_hi:[0,1]
	v_pk_add_f32 v[52:53], v[42:43], v[54:55] op_sel:[0,1] op_sel_hi:[1,0] neg_hi:[0,1]
	v_pk_add_f32 v[42:43], v[42:43], v[54:55] op_sel:[0,1] op_sel_hi:[1,0] neg_lo:[0,1]
	s_waitcnt lgkmcnt(1)
	v_pk_add_f32 v[54:55], v[44:45], v[64:65]
	v_pk_add_f32 v[44:45], v[44:45], v[64:65] neg_lo:[0,1] neg_hi:[0,1]
	s_waitcnt lgkmcnt(0)
	v_pk_add_f32 v[64:65], v[56:57], v[68:69]
	v_pk_add_f32 v[56:57], v[56:57], v[68:69] neg_lo:[0,1] neg_hi:[0,1]
	v_pk_add_f32 v[68:69], v[54:55], v[64:65]
	v_pk_add_f32 v[54:55], v[54:55], v[64:65] neg_lo:[0,1] neg_hi:[0,1]
	v_pk_add_f32 v[64:65], v[44:45], v[56:57] op_sel:[0,1] op_sel_hi:[1,0] neg_hi:[0,1]
	v_pk_add_f32 v[44:45], v[44:45], v[56:57] op_sel:[0,1] op_sel_hi:[1,0] neg_lo:[0,1]
	v_pk_add_f32 v[56:57], v[46:47], v[66:67]
	v_pk_add_f32 v[46:47], v[46:47], v[66:67] neg_lo:[0,1] neg_hi:[0,1]
	v_pk_add_f32 v[66:67], v[58:59], v[70:71]
	v_pk_add_f32 v[58:59], v[58:59], v[70:71] neg_lo:[0,1] neg_hi:[0,1]
	v_pk_add_f32 v[70:71], v[56:57], v[66:67]
	v_pk_add_f32 v[56:57], v[56:57], v[66:67] neg_lo:[0,1] neg_hi:[0,1]
	v_pk_add_f32 v[66:67], v[46:47], v[58:59] op_sel:[0,1] op_sel_hi:[1,0] neg_hi:[0,1]
	v_pk_add_f32 v[46:47], v[46:47], v[58:59] op_sel:[0,1] op_sel_hi:[1,0] neg_lo:[0,1]
	v_pk_mul_f32 v[58:59], v[52:53], v[24:25] op_sel:[0,0] op_sel_hi:[0,1]
	v_pk_fma_f32 v[24:25], v[52:53], v[24:25], v[58:59] op_sel:[1,1,0] op_sel_hi:[1,0,1] neg_lo:[0,1,0]
	v_pk_mul_f32 v[52:53], v[64:65], v[20:21] op_sel:[0,0] op_sel_hi:[0,1]
	v_pk_mul_f32 v[58:59], v[66:67], v[18:19] op_sel:[0,0] op_sel_hi:[0,1]
	s_barrier
	v_pk_fma_f32 v[52:53], v[64:65], v[20:21], v[52:53] op_sel:[1,1,0] op_sel_hi:[1,0,1] neg_lo:[0,1,0]
	v_pk_mul_f32 v[64:65], v[50:51], v[20:21] op_sel:[0,0] op_sel_hi:[0,1]
	v_pk_fma_f32 v[58:59], v[66:67], v[18:19], v[58:59] op_sel:[1,1,0] op_sel_hi:[1,0,1] neg_lo:[0,1,0]
	v_pk_fma_f32 v[20:21], v[50:51], v[20:21], v[64:65] op_sel:[1,1,0] op_sel_hi:[1,0,1] neg_lo:[0,1,0]
	v_pk_mul_f32 v[50:51], v[54:55], v[26:27] op_sel:[0,0] op_sel_hi:[0,1]
	v_pk_fma_f32 v[26:27], v[54:55], v[26:27], v[50:51] op_sel:[1,1,0] op_sel_hi:[1,0,1] neg_lo:[0,1,0]
	v_pk_mul_f32 v[50:51], v[56:57], v[22:23] op_sel:[0,0] op_sel_hi:[0,1]
	v_pk_mul_f32 v[54:55], v[42:43], v[18:19] op_sel:[0,0] op_sel_hi:[0,1]
	v_pk_fma_f32 v[18:19], v[42:43], v[18:19], v[54:55] op_sel:[1,1,0] op_sel_hi:[1,0,1] neg_lo:[0,1,0]
	v_pk_mul_f32 v[42:43], v[44:45], v[22:23] op_sel:[0,0] op_sel_hi:[0,1]
	v_pk_fma_f32 v[50:51], v[56:57], v[22:23], v[50:51] op_sel:[1,1,0] op_sel_hi:[1,0,1] neg_lo:[0,1,0]
	v_pk_add_f32 v[54:55], v[24:25], v[58:59] neg_lo:[0,1] neg_hi:[0,1]
	v_pk_fma_f32 v[22:23], v[44:45], v[22:23], v[42:43] op_sel:[1,1,0] op_sel_hi:[1,0,1] neg_lo:[0,1,0]
	v_pk_mul_f32 v[42:43], v[46:47], v[28:29] op_sel:[0,0] op_sel_hi:[0,1]
	v_pk_add_f32 v[44:45], v[62:63], v[70:71] neg_lo:[0,1] neg_hi:[0,1]
	v_pk_fma_f32 v[28:29], v[46:47], v[28:29], v[42:43] op_sel:[1,1,0] op_sel_hi:[1,0,1] neg_lo:[0,1,0]
	v_pk_add_f32 v[42:43], v[60:61], v[68:69] neg_lo:[0,1] neg_hi:[0,1]
	v_pk_add_f32 v[74:75], v[18:19], v[28:29] neg_lo:[0,1] neg_hi:[0,1]
	v_pk_add_f32 v[46:47], v[42:43], v[44:45] op_sel:[0,1] op_sel_hi:[1,0] neg_hi:[0,1]
	v_pk_add_f32 v[42:43], v[42:43], v[44:45] op_sel:[0,1] op_sel_hi:[1,0] neg_lo:[0,1]
	v_pk_add_f32 v[44:45], v[72:73], v[52:53] neg_lo:[0,1] neg_hi:[0,1]
	v_and_b32_e32 v19, 0xf0, v36
	v_pk_add_f32 v[56:57], v[44:45], v[54:55] op_sel:[0,1] op_sel_hi:[1,0] neg_hi:[0,1]
	v_pk_add_f32 v[44:45], v[44:45], v[54:55] op_sel:[0,1] op_sel_hi:[1,0] neg_lo:[0,1]
	v_pk_add_f32 v[54:55], v[48:49], v[26:27] neg_lo:[0,1] neg_hi:[0,1]
	v_pk_add_f32 v[64:65], v[20:21], v[50:51] neg_lo:[0,1] neg_hi:[0,1]
	v_mul_i32_i24_e32 v21, 0xfffff804, v38
	v_lshlrev_b32_e32 v19, 2, v19
	v_pk_add_f32 v[66:67], v[54:55], v[64:65] op_sel:[0,1] op_sel_hi:[1,0] neg_hi:[0,1]
	v_pk_add_f32 v[54:55], v[54:55], v[64:65] op_sel:[0,1] op_sel_hi:[1,0] neg_lo:[0,1]
	v_pk_add_f32 v[64:65], v[40:41], v[22:23] neg_lo:[0,1] neg_hi:[0,1]
	v_add3_u32 v19, v78, v21, v19
	v_add_f32_e32 v21, v62, v70
	v_add_f32_e32 v23, v60, v68
	v_add_f32_e32 v24, v24, v58
	v_add_f32_e32 v27, v72, v52
	v_add_f32_e32 v25, v23, v21
	v_add_f32_e32 v29, v27, v24
	v_mul_f32_e32 v25, 0x3a800000, v25
	v_mul_f32_e32 v29, 0x3a800000, v29
	ds_write2st64_b32 v19, v25, v29 offset1:4
	v_add_f32_e32 v20, v20, v50
	v_add_f32_e32 v25, v48, v26
	v_add_f32_e32 v18, v18, v28
	v_add_f32_e32 v22, v40, v22
	v_add_f32_e32 v26, v25, v20
	v_add_f32_e32 v28, v22, v18
	v_sub_f32_e32 v20, v25, v20
	v_sub_f32_e32 v18, v22, v18
	v_mul_f32_e32 v26, 0x3a800000, v26
	v_mul_f32_e32 v28, 0x3a800000, v28
	v_mul_f32_e32 v20, 0x3a800000, v20
	v_mul_f32_e32 v18, 0x3a800000, v18
	ds_write2st64_b32 v19, v26, v28 offset0:8 offset1:12
	v_mul_f32_e32 v26, 0x3a800000, v46
	v_mul_f32_e32 v28, 0x3a800000, v56
	v_sub_f32_e32 v21, v23, v21
	v_sub_f32_e32 v23, v27, v24
	ds_write2st64_b32 v19, v20, v18 offset0:40 offset1:44
	v_mul_f32_e32 v18, 0x3a800000, v42
	v_mul_f32_e32 v20, 0x3a800000, v44
	v_pk_add_f32 v[76:77], v[64:65], v[74:75] op_sel:[0,1] op_sel_hi:[1,0] neg_hi:[0,1]
	v_pk_add_f32 v[64:65], v[64:65], v[74:75] op_sel:[0,1] op_sel_hi:[1,0] neg_lo:[0,1]
	ds_write2st64_b32 v19, v26, v28 offset0:16 offset1:20
	v_mul_f32_e32 v26, 0x3a800000, v66
	v_mul_f32_e32 v28, 0x3a800000, v76
	v_mul_f32_e32 v21, 0x3a800000, v21
	v_mul_f32_e32 v23, 0x3a800000, v23
	ds_write2st64_b32 v19, v18, v20 offset0:48 offset1:52
	v_mul_f32_e32 v18, 0x3a800000, v54
	v_mul_f32_e32 v20, 0x3a800000, v64
	v_mov_b32_e32 v22, v34
	ds_write2st64_b32 v19, v26, v28 offset0:24 offset1:28
	ds_write2st64_b32 v19, v21, v23 offset0:32 offset1:36
	ds_write2st64_b32 v19, v18, v20 offset0:56 offset1:60
	s_waitcnt lgkmcnt(0)
	s_barrier
	v_lshlrev_b32_e32 v26, 12, v37
	v_lshl_add_u32 v23, v22, 5, v35
	ds_read_b128 v[18:21], v23
	v_lshlrev_b32_e32 v28, 3, v22
	ds_read_b128 v[22:25], v23 offset:16
	v_ashrrev_i32_e32 v27, 31, v26
	v_lshlrev_b64 v[26:27], 1, v[26:27]
	s_waitcnt lgkmcnt(1)
	v_cvt_pk_bf16_f32 v18, v18, v18
	v_lshrrev_b32_e32 v18, 16, v18
	v_cvt_pk_bf16_f32 v19, v19, v19
	v_and_or_b32 v18, v19, s56, v18
	v_cvt_pk_bf16_f32 v19, v20, v21
	s_waitcnt lgkmcnt(0)
	v_cvt_pk_bf16_f32 v20, v22, v23
	v_cvt_pk_bf16_f32 v21, v24, v25
	v_ashrrev_i32_e32 v29, 31, v28
	v_lshl_add_u64 v[22:23], v[28:29], 1, v[26:27]
	v_lshl_add_u64 v[22:23], s[6:7], 0, v[22:23]
	global_store_dwordx4 v[22:23], v[18:21], off
	s_nop 0
	v_lshl_add_u32 v22, v34, 5, v35
	ds_read_b128 v[18:21], v22 offset:8192
	ds_read_b128 v[22:25], v22 offset:8208
	v_lshl_add_u32 v28, v34, 3, v33
	s_waitcnt lgkmcnt(1)
	v_cvt_pk_bf16_f32 v18, v18, v18
	v_lshrrev_b32_e32 v18, 16, v18
	v_cvt_pk_bf16_f32 v19, v19, v19
	v_and_or_b32 v18, v19, s56, v18
	v_cvt_pk_bf16_f32 v19, v20, v21
	s_waitcnt lgkmcnt(0)
	v_cvt_pk_bf16_f32 v20, v22, v23
	v_cvt_pk_bf16_f32 v21, v24, v25
	v_ashrrev_i32_e32 v29, 31, v28
	v_lshl_add_u64 v[22:23], v[28:29], 1, v[26:27]
	v_lshl_add_u64 v[22:23], s[6:7], 0, v[22:23]
	s_add_u32 s6, s6, s20
	s_addc_u32 s7, s7, s21
	s_and_b64 vcc, exec, s[44:45]
	global_store_dwordx4 v[22:23], v[18:21], off
	s_barrier
	s_cbranch_vccnz .LBB0_3755

.LBB0_3805:
	s_or_b64 exec, exec, s[52:53]
	s_lshl_b64 s[52:53], s[50:51], 15
	v_ashrrev_i32_e32 v91, 6, v38
	s_add_u32 s28, s64, s52
	v_lshlrev_b32_e32 v50, 3, v91
	v_lshlrev_b32_e32 v34, 1, v34
	s_addc_u32 s29, s63, s53
	v_add_u32_e32 v90, 0, v34
	v_lshl_add_u64 v[54:55], s[28:29], 0, v[34:35]
	v_add_u32_e32 v34, s91, v50
	v_and_b32_e32 v34, 0xfffffef8, v34
	v_cmp_eq_u32_e32 vcc, 0, v34
	s_waitcnt vmcnt(25)
	v_lshlrev_b32_e32 v96, 16, v66
	v_and_b32_e32 v94, 0xffff0000, v66
	v_lshlrev_b32_e32 v97, 16, v67
	v_and_b32_e32 v95, 0xffff0000, v67
	v_lshlrev_b32_e32 v67, 16, v59
	v_lshlrev_b32_e32 v66, 16, v58
	v_and_b32_e32 v101, 0xffff0000, v59
	v_and_b32_e32 v100, 0xffff0000, v58
	s_waitcnt vmcnt(3)
	v_mov_b32_e32 v58, v2
	v_mov_b32_e32 v59, v4
	v_mov_b32_e32 v4, v3
	v_mov_b32_e32 v2, v30
	v_mov_b32_e32 v3, v32
	v_cndmask_b32_e64 v34, 1.0, 0, vcc
	v_lshlrev_b32_e32 v87, 16, v65
	v_lshlrev_b32_e32 v86, 16, v64
	v_and_b32_e32 v105, 0xffff0000, v65
	v_and_b32_e32 v104, 0xffff0000, v64
	v_pk_mul_f32 v[64:65], v[2:3], v[66:67]
	v_pk_mul_f32 v[102:103], v[58:59], v[86:87]
	v_pk_mul_f32 v[66:67], v[64:65], v[34:35] op_sel_hi:[1,0]
	v_mov_b32_e32 v64, v26
	v_mov_b32_e32 v65, v28
	v_lshlrev_b32_e32 v89, 16, v69
	v_lshlrev_b32_e32 v88, 16, v68
	v_and_b32_e32 v87, 0xffff0000, v69
	v_and_b32_e32 v86, 0xffff0000, v68
	v_pk_fma_f32 v[68:69], v[64:65], v[96:97], v[66:67]
	v_mov_b32_e32 v66, v18
	v_mov_b32_e32 v67, v20
	v_mov_b32_e32 v32, v31
	v_pk_fma_f32 v[106:107], v[66:67], v[88:89], v[68:69]
	v_mov_b32_e32 v68, v22
	v_mov_b32_e32 v69, v24
	v_pk_mul_f32 v[30:31], v[32:33], v[100:101]
	v_pk_add_f32 v[106:107], v[68:69], v[106:107]
	v_pk_mul_f32 v[30:31], v[30:31], v[34:35] op_sel_hi:[1,0]
	v_mov_b32_e32 v28, v27
	v_mul_f32_e32 v18, 0xbfb8aa3b, v106
	v_pk_fma_f32 v[26:27], v[28:29], v[94:95], v[30:31]
	v_mov_b32_e32 v20, v19
	v_exp_f32_e32 v22, v18
	v_pk_fma_f32 v[18:19], v[20:21], v[86:87], v[26:27]
	v_mov_b32_e32 v24, v23
	v_pk_add_f32 v[18:19], v[24:25], v[18:19]
	v_mul_f32_e32 v26, 0xbfb8aa3b, v107
	v_mul_f32_e32 v23, 0xbfb8aa3b, v18
	v_exp_f32_e32 v23, v23
	v_exp_f32_e32 v27, v26
	v_mul_f32_e32 v26, 0xbfb8aa3b, v19
	v_exp_f32_e32 v51, v26
	v_add_f32_e32 v23, 1.0, v23
	v_add_f32_e32 v22, 1.0, v22
	v_rcp_f32_e32 v26, v23
	v_add_f32_e32 v23, 1.0, v27
	v_rcp_f32_e32 v22, v22
	v_rcp_f32_e32 v23, v23
	v_add_f32_e32 v27, 1.0, v51
	v_rcp_f32_e32 v27, v27
	v_lshlrev_b32_e32 v93, 16, v81
	v_lshlrev_b32_e32 v92, 16, v80
	v_and_b32_e32 v101, 0xffff0000, v81
	v_and_b32_e32 v100, 0xffff0000, v80
	v_pk_mul_f32 v[80:81], v[106:107], v[22:23]
	v_pk_mul_f32 v[30:31], v[4:5], v[104:105]
	v_pk_mul_f32 v[104:105], v[18:19], v[26:27]
	v_cvt_pk_bf16_f32 v106, v80, v104
	v_cvt_pk_bf16_f32 v107, v81, v105
	v_pk_mul_f32 v[22:23], v[34:35], v[102:103] op_sel_hi:[0,1]
	s_waitcnt vmcnt(2)
	v_mov_b32_e32 v18, v14
	v_mov_b32_e32 v19, v16
	v_lshlrev_b32_e32 v84, 16, v82
	v_lshlrev_b32_e32 v85, 16, v83
	v_pk_fma_f32 v[26:27], v[18:19], v[92:93], v[22:23]
	s_waitcnt vmcnt(1)
	v_mov_b32_e32 v22, v10
	v_mov_b32_e32 v23, v12
	v_pk_fma_f32 v[102:103], v[22:23], v[84:85], v[26:27]
	s_waitcnt vmcnt(0)
	v_mov_b32_e32 v26, v6
	v_mov_b32_e32 v27, v8
	v_pk_mul_f32 v[30:31], v[34:35], v[30:31] op_sel_hi:[0,1]
	v_mov_b32_e32 v16, v15
	v_and_b32_e32 v82, 0xffff0000, v82
	v_and_b32_e32 v83, 0xffff0000, v83
	v_pk_add_f32 v[102:103], v[26:27], v[102:103]
	v_pk_fma_f32 v[14:15], v[16:17], v[100:101], v[30:31]
	v_mov_b32_e32 v12, v11
	v_mul_f32_e32 v6, 0xbfb8aa3b, v102
	v_pk_fma_f32 v[10:11], v[12:13], v[82:83], v[14:15]
	v_mov_b32_e32 v8, v7
	v_exp_f32_e32 v108, v6
	v_pk_add_f32 v[6:7], v[8:9], v[10:11]
	v_mul_f32_e32 v14, 0xbfb8aa3b, v103
	v_mul_f32_e32 v10, 0xbfb8aa3b, v6
	v_exp_f32_e32 v11, v10
	v_exp_f32_e32 v15, v14
	v_mul_f32_e32 v14, 0xbfb8aa3b, v7
	v_exp_f32_e32 v30, v14
	v_add_f32_e32 v11, 1.0, v11
	v_add_f32_e32 v10, 1.0, v108
	v_rcp_f32_e32 v14, v11
	v_add_f32_e32 v11, 1.0, v15
	v_rcp_f32_e32 v10, v10
	v_rcp_f32_e32 v11, v11
	v_add_f32_e32 v15, 1.0, v30
	v_rcp_f32_e32 v15, v15
	s_movk_i32 s28, 0x1080
	v_pk_mul_f32 v[10:11], v[102:103], v[10:11]
	v_mad_u64_u32 v[30:31], s[28:29], v91, s28, v[90:91]
	v_pk_mul_f32 v[10:11], v[10:11], s[48:49] op_sel_hi:[1,0]
	v_pk_mul_f32 v[6:7], v[6:7], v[14:15]
	v_pk_mul_f32 v[6:7], v[6:7], s[48:49] op_sel_hi:[1,0]
	v_cvt_pk_bf16_f32 v15, v11, v7
	v_cvt_pk_bf16_f32 v14, v10, v6
	s_add_i32 s54, 0, 0x1be00
	v_lshlrev_b32_e32 v34, 5, v91
	s_waitcnt lgkmcnt(0)
	s_barrier
	ds_write2st64_b64 v30, v[106:107], v[14:15] offset1:66
	v_add_u32_e32 v14, s54, v34
	ds_read_b32 v14, v14
	s_add_i32 s55, 0, 0x1bf00
	v_add_u32_e32 v15, s55, v34
	ds_read_b32 v102, v15
	v_ashrrev_i32_e32 v51, 31, v50
	s_waitcnt lgkmcnt(1)
	v_pk_mul_f32 v[30:31], v[80:81], v[14:15] op_sel_hi:[1,0]
	v_pk_mul_f32 v[14:15], v[104:105], v[14:15] op_sel_hi:[1,0]
	v_cvt_pk_bf16_f32 v15, v31, v15
	v_cvt_pk_bf16_f32 v14, v30, v14
	v_lshlrev_b64 v[30:31], 9, v[50:51]
	v_lshl_add_u64 v[30:31], v[54:55], 0, v[30:31]
	s_waitcnt lgkmcnt(0)
	v_mul_f32_e32 v10, v10, v102
	global_store_dwordx2 v[30:31], v[14:15], off
	v_cvt_pk_bf16_f32 v10, v10, v10
	v_mov_b32_e32 v14, s80
	s_movk_i32 s28, 0x240
	v_mad_u32_u24 v51, v99, s28, v14
	v_lshl_add_u32 v14, v91, 4, v51
	v_mul_f32_e32 v6, v6, v102
	ds_write_b16_d16_hi v14, v10
	v_cvt_pk_bf16_f32 v6, v6, v6
	ds_write_b16_d16_hi v14, v6 offset:144
	v_mul_f32_e32 v6, v11, v102
	v_cvt_pk_bf16_f32 v6, v6, v6
	ds_write_b16_d16_hi v14, v6 offset:288
	v_mul_f32_e32 v6, v7, v102
	v_cvt_pk_bf16_f32 v6, v6, v6
	ds_write_b16_d16_hi v14, v6 offset:432
	v_pk_mul_f32 v[6:7], v[64:65], v[88:89]
	v_lshlrev_b32_e32 v81, 16, v79
	v_lshlrev_b32_e32 v80, 16, v78
	v_pk_fma_f32 v[6:7], v[2:3], v[96:97], v[6:7]
	v_pk_mul_f32 v[14:15], v[28:29], v[86:87]
	v_and_b32_e32 v79, 0xffff0000, v79
	v_and_b32_e32 v78, 0xffff0000, v78
	v_pk_fma_f32 v[6:7], v[66:67], v[80:81], v[6:7]
	v_pk_fma_f32 v[14:15], v[32:33], v[94:95], v[14:15]
	v_pk_add_f32 v[6:7], v[68:69], v[6:7]
	v_pk_fma_f32 v[14:15], v[20:21], v[78:79], v[14:15]
	v_mul_f32_e32 v11, 0xbfb8aa3b, v6
	v_pk_add_f32 v[94:95], v[24:25], v[14:15]
	v_exp_f32_e32 v11, v11
	v_mul_f32_e32 v14, 0xbfb8aa3b, v94
	v_exp_f32_e32 v15, v14
	v_mul_f32_e32 v31, 0xbfb8aa3b, v95
	v_add_f32_e32 v11, 1.0, v11
	v_rcp_f32_e32 v96, v11
	v_add_f32_e32 v11, 1.0, v15
	v_mul_f32_e32 v15, 0xbfb8aa3b, v7
	v_exp_f32_e32 v15, v15
	v_exp_f32_e32 v31, v31
	v_rcp_f32_e32 v102, v11
	v_lshlrev_b32_e32 v10, 16, v76
	v_add_f32_e32 v11, 1.0, v15
	v_rcp_f32_e32 v97, v11
	v_add_f32_e32 v11, 1.0, v31
	v_rcp_f32_e32 v103, v11
	v_and_b32_e32 v14, 0xffff0000, v76
	v_lshlrev_b32_e32 v11, 16, v77
	v_and_b32_e32 v15, 0xffff0000, v77
	v_pk_mul_f32 v[94:95], v[94:95], v[102:103]
	v_pk_mul_f32 v[76:77], v[6:7], v[96:97]
	v_cvt_pk_bf16_f32 v97, v77, v95
	v_cvt_pk_bf16_f32 v96, v76, v94
	v_pk_mul_f32 v[6:7], v[18:19], v[84:85]
	v_or_b32_e32 v30, 1, v50
	v_pk_fma_f32 v[6:7], v[58:59], v[92:93], v[6:7]
	v_and_b32_e32 v39, 15, v38
	v_pk_fma_f32 v[6:7], v[22:23], v[10:11], v[6:7]
	s_nop 0
	v_pk_add_f32 v[92:93], v[26:27], v[6:7]
	s_nop 0
	v_mul_f32_e32 v6, 0xbfb8aa3b, v92
	v_exp_f32_e32 v31, v6
	v_pk_mul_f32 v[6:7], v[16:17], v[82:83]
	s_nop 0
	v_pk_fma_f32 v[6:7], v[4:5], v[100:101], v[6:7]
	s_nop 0
	v_pk_fma_f32 v[6:7], v[12:13], v[14:15], v[6:7]
	s_nop 0
	v_pk_add_f32 v[100:101], v[8:9], v[6:7]
	s_nop 0
	v_mul_f32_e32 v6, 0xbfb8aa3b, v100
	v_exp_f32_e32 v91, v6
	s_nop 0
	v_mad_u64_u32 v[6:7], s[28:29], v30, s81, v[90:91]
	v_add_f32_e32 v7, 1.0, v31
	v_mul_f32_e32 v31, 0xbfb8aa3b, v93
	v_rcp_f32_e32 v90, v7
	v_add_f32_e32 v7, 1.0, v91
	v_exp_f32_e32 v31, v31
	v_mul_f32_e32 v91, 0xbfb8aa3b, v101
	v_exp_f32_e32 v103, v91
	v_rcp_f32_e32 v102, v7
	v_add_f32_e32 v7, 1.0, v31
	v_rcp_f32_e32 v91, v7
	v_add_f32_e32 v7, 1.0, v103
	v_rcp_f32_e32 v103, v7
	ds_write_b64 v6, v[96:97]
	v_pk_mul_f32 v[90:91], v[92:93], v[90:91]
	s_mov_b32 s28, 0xffffff0
	v_pk_mul_f32 v[92:93], v[100:101], v[102:103]
	v_pk_mul_f32 v[90:91], v[90:91], s[48:49] op_sel_hi:[1,0]
	v_pk_mul_f32 v[92:93], v[92:93], s[48:49] op_sel_hi:[1,0]
	v_cvt_pk_bf16_f32 v97, v91, v93
	v_cvt_pk_bf16_f32 v96, v90, v92
	ds_write_b64 v6, v[96:97] offset:33792
	v_lshlrev_b32_e32 v97, 2, v30
	v_add_u32_e32 v7, s54, v97
	ds_read_b32 v96, v7
	v_add_u32_e32 v97, s55, v97
	ds_read_b32 v100, v97
	v_ashrrev_i32_e32 v31, 31, v30
	v_mul_u32_u24_e32 v7, 0x240, v99
	s_waitcnt lgkmcnt(1)
	v_pk_mul_f32 v[76:77], v[76:77], v[96:97] op_sel_hi:[1,0]
	v_pk_mul_f32 v[94:95], v[94:95], v[96:97] op_sel_hi:[1,0]
	v_cvt_pk_bf16_f32 v95, v77, v95
	v_cvt_pk_bf16_f32 v94, v76, v94
	v_lshlrev_b64 v[76:77], 9, v[30:31]
	s_waitcnt lgkmcnt(0)
	v_mul_f32_e32 v31, v90, v100
	v_lshl_add_u64 v[96:97], v[54:55], 0, v[76:77]
	v_lshlrev_b32_e32 v30, 1, v30
	v_cvt_pk_bf16_f32 v31, v31, v31
	v_add_u32_e32 v76, v51, v30
	ds_write_b16_d16_hi v76, v31
	v_mul_f32_e32 v31, v92, v100
	v_cvt_pk_bf16_f32 v31, v31, v31
	v_add3_u32 v30, s80, v30, v7
	ds_write_b16_d16_hi v30, v31 offset:144
	v_mul_f32_e32 v31, v91, v100
	v_cvt_pk_bf16_f32 v31, v31, v31
	ds_write_b16_d16_hi v30, v31 offset:288
	v_mul_f32_e32 v31, v93, v100
	v_pk_mul_f32 v[92:93], v[64:65], v[80:81]
	v_lshlrev_b32_e32 v91, 16, v75
	v_lshlrev_b32_e32 v90, 16, v74
	v_pk_fma_f32 v[88:89], v[2:3], v[88:89], v[92:93]
	v_pk_mul_f32 v[92:93], v[28:29], v[78:79]
	v_and_b32_e32 v75, 0xffff0000, v75
	v_and_b32_e32 v74, 0xffff0000, v74
	v_pk_fma_f32 v[88:89], v[66:67], v[90:91], v[88:89]
	v_pk_fma_f32 v[86:87], v[32:33], v[86:87], v[92:93]
	v_cvt_pk_bf16_f32 v31, v31, v31
	v_pk_add_f32 v[88:89], v[68:69], v[88:89]
	v_pk_fma_f32 v[86:87], v[20:21], v[74:75], v[86:87]
	ds_write_b16_d16_hi v30, v31 offset:432
	v_mul_f32_e32 v31, 0xbfb8aa3b, v88
	v_pk_add_f32 v[86:87], v[24:25], v[86:87]
	v_exp_f32_e32 v31, v31
	v_mul_f32_e32 v77, 0xbfb8aa3b, v86
	v_exp_f32_e32 v77, v77
	v_mul_f32_e32 v93, 0xbfb8aa3b, v87
	v_add_f32_e32 v31, 1.0, v31
	v_rcp_f32_e32 v92, v31
	v_add_f32_e32 v31, 1.0, v77
	v_mul_f32_e32 v77, 0xbfb8aa3b, v89
	v_exp_f32_e32 v77, v77
	v_exp_f32_e32 v101, v93
	v_rcp_f32_e32 v100, v31
	v_lshlrev_b32_e32 v76, 16, v72
	v_add_f32_e32 v31, 1.0, v77
	v_rcp_f32_e32 v93, v31
	v_add_f32_e32 v31, 1.0, v101
	v_rcp_f32_e32 v101, v31
	v_lshlrev_b32_e32 v77, 16, v73
	v_pk_mul_f32 v[88:89], v[88:89], v[92:93]
	v_and_b32_e32 v72, 0xffff0000, v72
	v_pk_mul_f32 v[86:87], v[86:87], v[100:101]
	v_and_b32_e32 v73, 0xffff0000, v73
	v_cvt_pk_bf16_f32 v92, v88, v86
	v_pk_mul_f32 v[100:101], v[18:19], v[10:11]
	v_cvt_pk_bf16_f32 v93, v89, v87
	v_pk_fma_f32 v[84:85], v[58:59], v[84:85], v[100:101]
	v_pk_mul_f32 v[100:101], v[16:17], v[14:15]
	v_pk_fma_f32 v[84:85], v[22:23], v[76:77], v[84:85]
	v_pk_fma_f32 v[82:83], v[4:5], v[82:83], v[100:101]
	v_pk_add_f32 v[84:85], v[26:27], v[84:85]
	v_pk_fma_f32 v[82:83], v[12:13], v[72:73], v[82:83]
	v_mul_f32_e32 v31, 0xbfb8aa3b, v84
	v_pk_add_f32 v[82:83], v[8:9], v[82:83]
	v_exp_f32_e32 v31, v31
	v_mul_f32_e32 v100, 0xbfb8aa3b, v82
	v_exp_f32_e32 v101, v100
	v_add_f32_e32 v31, 1.0, v31
	v_rcp_f32_e32 v100, v31
	v_add_f32_e32 v31, 1.0, v101
	v_mul_f32_e32 v101, 0xbfb8aa3b, v85
	v_exp_f32_e32 v101, v101
	v_mul_f32_e32 v102, 0xbfb8aa3b, v83
	v_exp_f32_e32 v103, v102
	v_rcp_f32_e32 v102, v31
	v_add_f32_e32 v31, 1.0, v101
	v_rcp_f32_e32 v101, v31
	v_add_f32_e32 v31, 1.0, v103
	v_rcp_f32_e32 v103, v31
	ds_write_b64 v6, v[92:93] offset:528
	v_pk_mul_f32 v[84:85], v[84:85], v[100:101]
	v_or_b32_e32 v30, 2, v50
	v_pk_mul_f32 v[82:83], v[82:83], v[102:103]
	v_pk_mul_f32 v[84:85], v[84:85], s[48:49] op_sel_hi:[1,0]
	v_pk_mul_f32 v[82:83], v[82:83], s[48:49] op_sel_hi:[1,0]
	v_cvt_pk_bf16_f32 v93, v85, v83
	v_cvt_pk_bf16_f32 v92, v84, v82
	ds_write_b64 v6, v[92:93] offset:34320
	v_lshlrev_b32_e32 v93, 2, v30
	v_add_u32_e32 v31, s54, v93
	v_add_u32_e32 v93, s55, v93
	ds_read_b32 v92, v31
	ds_read_b32 v93, v93
	global_store_dwordx2 v[96:97], v[94:95], off
	v_ashrrev_i32_e32 v31, 31, v30
	s_waitcnt lgkmcnt(0)
	v_pk_mul_f32 v[88:89], v[88:89], v[92:93] op_sel_hi:[1,0]
	v_pk_mul_f32 v[86:87], v[86:87], v[92:93] op_sel_hi:[1,0]
	v_cvt_pk_bf16_f32 v87, v89, v87
	v_cvt_pk_bf16_f32 v86, v88, v86
	v_lshlrev_b64 v[88:89], 9, v[30:31]
	v_mul_f32_e32 v31, v84, v93
	v_lshlrev_b32_e32 v30, 1, v30
	v_cvt_pk_bf16_f32 v31, v31, v31
	v_add_u32_e32 v84, v51, v30
	ds_write_b16_d16_hi v84, v31
	v_mul_f32_e32 v31, v82, v93
	v_cvt_pk_bf16_f32 v31, v31, v31
	v_add3_u32 v30, s80, v30, v7
	ds_write_b16_d16_hi v30, v31 offset:144
	v_mul_f32_e32 v31, v85, v93
	v_cvt_pk_bf16_f32 v31, v31, v31
	ds_write_b16_d16_hi v30, v31 offset:288
	v_mul_f32_e32 v31, v83, v93
	v_pk_mul_f32 v[92:93], v[64:65], v[90:91]
	v_cvt_pk_bf16_f32 v31, v31, v31
	v_lshlrev_b32_e32 v83, 16, v71
	v_lshlrev_b32_e32 v82, 16, v70
	v_pk_fma_f32 v[80:81], v[2:3], v[80:81], v[92:93]
	v_pk_mul_f32 v[92:93], v[28:29], v[74:75]
	v_and_b32_e32 v71, 0xffff0000, v71
	v_and_b32_e32 v70, 0xffff0000, v70
	v_pk_fma_f32 v[80:81], v[66:67], v[82:83], v[80:81]
	v_pk_fma_f32 v[78:79], v[32:33], v[78:79], v[92:93]
	v_pk_add_f32 v[80:81], v[68:69], v[80:81]
	v_pk_fma_f32 v[78:79], v[20:21], v[70:71], v[78:79]
	ds_write_b16_d16_hi v30, v31 offset:432
	v_mul_f32_e32 v31, 0xbfb8aa3b, v80
	v_pk_add_f32 v[78:79], v[24:25], v[78:79]
	v_exp_f32_e32 v31, v31
	v_mul_f32_e32 v85, 0xbfb8aa3b, v78
	v_exp_f32_e32 v85, v85
	v_mul_f32_e32 v93, 0xbfb8aa3b, v79
	v_add_f32_e32 v31, 1.0, v31
	v_rcp_f32_e32 v92, v31
	v_add_f32_e32 v31, 1.0, v85
	v_mul_f32_e32 v85, 0xbfb8aa3b, v81
	v_exp_f32_e32 v85, v85
	v_exp_f32_e32 v95, v93
	v_rcp_f32_e32 v94, v31
	v_lshlrev_b32_e32 v30, 16, v62
	v_add_f32_e32 v31, 1.0, v85
	v_rcp_f32_e32 v93, v31
	v_add_f32_e32 v31, 1.0, v95
	v_rcp_f32_e32 v95, v31
	v_lshlrev_b32_e32 v31, 16, v63
	v_pk_mul_f32 v[80:81], v[80:81], v[92:93]
	v_and_b32_e32 v62, 0xffff0000, v62
	v_pk_mul_f32 v[78:79], v[78:79], v[94:95]
	v_and_b32_e32 v63, 0xffff0000, v63
	v_cvt_pk_bf16_f32 v92, v80, v78
	v_pk_mul_f32 v[94:95], v[18:19], v[76:77]
	v_cvt_pk_bf16_f32 v93, v81, v79
	v_pk_fma_f32 v[10:11], v[58:59], v[10:11], v[94:95]
	v_pk_mul_f32 v[94:95], v[16:17], v[72:73]
	v_pk_fma_f32 v[10:11], v[22:23], v[30:31], v[10:11]
	v_pk_fma_f32 v[14:15], v[4:5], v[14:15], v[94:95]
	v_pk_add_f32 v[10:11], v[26:27], v[10:11]
	v_pk_fma_f32 v[14:15], v[12:13], v[62:63], v[14:15]
	v_mul_f32_e32 v85, 0xbfb8aa3b, v10
	v_pk_add_f32 v[14:15], v[8:9], v[14:15]
	v_exp_f32_e32 v85, v85
	v_mul_f32_e32 v94, 0xbfb8aa3b, v14
	v_exp_f32_e32 v95, v94
	v_add_f32_e32 v85, 1.0, v85
	v_rcp_f32_e32 v94, v85
	v_add_f32_e32 v85, 1.0, v95
	v_mul_f32_e32 v95, 0xbfb8aa3b, v11
	v_exp_f32_e32 v95, v95
	v_mul_f32_e32 v96, 0xbfb8aa3b, v15
	v_exp_f32_e32 v97, v96
	v_rcp_f32_e32 v96, v85
	v_add_f32_e32 v85, 1.0, v95
	v_rcp_f32_e32 v95, v85
	v_add_f32_e32 v85, 1.0, v97
	v_rcp_f32_e32 v97, v85
	ds_write_b64 v6, v[92:93] offset:1056
	v_pk_mul_f32 v[10:11], v[10:11], v[94:95]
	v_or_b32_e32 v84, 3, v50
	v_pk_mul_f32 v[14:15], v[14:15], v[96:97]
	v_pk_mul_f32 v[10:11], v[10:11], s[48:49] op_sel_hi:[1,0]
	v_pk_mul_f32 v[14:15], v[14:15], s[48:49] op_sel_hi:[1,0]
	v_cvt_pk_bf16_f32 v93, v11, v15
	v_cvt_pk_bf16_f32 v92, v10, v14
	ds_write_b64 v6, v[92:93] offset:34848
	v_lshlrev_b32_e32 v93, 2, v84
	v_add_u32_e32 v85, s54, v93
	ds_read_b32 v92, v85
	v_lshl_add_u64 v[88:89], v[54:55], 0, v[88:89]
	global_store_dwordx2 v[88:89], v[86:87], off
	v_add_u32_e32 v86, s55, v93
	ds_read_b32 v88, v86
	s_waitcnt lgkmcnt(1)
	v_pk_mul_f32 v[80:81], v[80:81], v[92:93] op_sel_hi:[1,0]
	v_pk_mul_f32 v[78:79], v[78:79], v[92:93] op_sel_hi:[1,0]
	v_cvt_pk_bf16_f32 v81, v81, v79
	v_cvt_pk_bf16_f32 v80, v80, v78
	v_ashrrev_i32_e32 v85, 31, v84
	v_lshlrev_b64 v[78:79], 9, v[84:85]
	s_waitcnt lgkmcnt(0)
	v_mul_f32_e32 v10, v10, v88
	v_lshl_add_u64 v[86:87], v[54:55], 0, v[78:79]
	v_lshlrev_b32_e32 v78, 1, v84
	v_cvt_pk_bf16_f32 v10, v10, v10
	v_add_u32_e32 v79, v51, v78
	ds_write_b16_d16_hi v79, v10
	v_mul_f32_e32 v10, v14, v88
	v_cvt_pk_bf16_f32 v10, v10, v10
	v_add3_u32 v14, s80, v78, v7
	ds_write_b16_d16_hi v14, v10 offset:144
	v_mul_f32_e32 v10, v11, v88
	v_cvt_pk_bf16_f32 v10, v10, v10
	v_pk_mul_f32 v[84:85], v[64:65], v[82:83]
	ds_write_b16_d16_hi v14, v10 offset:288
	v_mul_f32_e32 v10, v15, v88
	v_lshlrev_b32_e32 v79, 16, v61
	v_lshlrev_b32_e32 v78, 16, v60
	v_pk_fma_f32 v[84:85], v[2:3], v[90:91], v[84:85]
	v_pk_mul_f32 v[88:89], v[28:29], v[70:71]
	v_and_b32_e32 v61, 0xffff0000, v61
	v_and_b32_e32 v60, 0xffff0000, v60
	v_pk_fma_f32 v[84:85], v[66:67], v[78:79], v[84:85]
	v_pk_fma_f32 v[74:75], v[32:33], v[74:75], v[88:89]
	v_pk_add_f32 v[84:85], v[68:69], v[84:85]
	v_pk_fma_f32 v[74:75], v[20:21], v[60:61], v[74:75]
	v_cvt_pk_bf16_f32 v10, v10, v10
	v_mul_f32_e32 v11, 0xbfb8aa3b, v84
	v_pk_add_f32 v[74:75], v[24:25], v[74:75]
	v_exp_f32_e32 v11, v11
	v_mul_f32_e32 v15, 0xbfb8aa3b, v74
	v_exp_f32_e32 v15, v15
	v_mul_f32_e32 v89, 0xbfb8aa3b, v75
	v_add_f32_e32 v11, 1.0, v11
	v_rcp_f32_e32 v88, v11
	v_add_f32_e32 v11, 1.0, v15
	v_mul_f32_e32 v15, 0xbfb8aa3b, v85
	v_exp_f32_e32 v15, v15
	v_exp_f32_e32 v91, v89
	v_rcp_f32_e32 v90, v11
	ds_write_b16_d16_hi v14, v10 offset:432
	v_add_f32_e32 v11, 1.0, v15
	v_rcp_f32_e32 v89, v11
	v_add_f32_e32 v11, 1.0, v91
	v_rcp_f32_e32 v91, v11
	v_lshlrev_b32_e32 v14, 16, v56
	v_lshlrev_b32_e32 v15, 16, v57
	v_pk_mul_f32 v[84:85], v[84:85], v[88:89]
	v_pk_mul_f32 v[74:75], v[74:75], v[90:91]
	v_and_b32_e32 v56, 0xffff0000, v56
	v_cvt_pk_bf16_f32 v88, v84, v74
	v_pk_mul_f32 v[90:91], v[18:19], v[30:31]
	v_cvt_pk_bf16_f32 v89, v85, v75
	v_pk_fma_f32 v[76:77], v[58:59], v[76:77], v[90:91]
	v_pk_mul_f32 v[90:91], v[16:17], v[62:63]
	v_and_b32_e32 v57, 0xffff0000, v57
	v_pk_fma_f32 v[76:77], v[22:23], v[14:15], v[76:77]
	v_pk_fma_f32 v[72:73], v[4:5], v[72:73], v[90:91]
	v_pk_add_f32 v[76:77], v[26:27], v[76:77]
	v_pk_fma_f32 v[72:73], v[12:13], v[56:57], v[72:73]
	v_mul_f32_e32 v11, 0xbfb8aa3b, v76
	v_pk_add_f32 v[72:73], v[8:9], v[72:73]
	v_exp_f32_e32 v11, v11
	v_mul_f32_e32 v90, 0xbfb8aa3b, v72
	v_exp_f32_e32 v91, v90
	v_add_f32_e32 v11, 1.0, v11
	v_rcp_f32_e32 v90, v11
	v_add_f32_e32 v11, 1.0, v91
	v_mul_f32_e32 v91, 0xbfb8aa3b, v77
	v_exp_f32_e32 v91, v91
	v_mul_f32_e32 v92, 0xbfb8aa3b, v73
	v_exp_f32_e32 v93, v92
	v_rcp_f32_e32 v92, v11
	v_add_f32_e32 v11, 1.0, v91
	v_rcp_f32_e32 v91, v11
	v_add_f32_e32 v11, 1.0, v93
	v_rcp_f32_e32 v93, v11
	ds_write_b64 v6, v[88:89] offset:1584
	v_pk_mul_f32 v[76:77], v[76:77], v[90:91]
	v_or_b32_e32 v10, 4, v50
	v_pk_mul_f32 v[72:73], v[72:73], v[92:93]
	v_pk_mul_f32 v[76:77], v[76:77], s[48:49] op_sel_hi:[1,0]
	v_pk_mul_f32 v[72:73], v[72:73], s[48:49] op_sel_hi:[1,0]
	v_cvt_pk_bf16_f32 v89, v77, v73
	v_cvt_pk_bf16_f32 v88, v76, v72
	ds_write_b64 v6, v[88:89] offset:35376
	v_lshlrev_b32_e32 v89, 2, v10
	v_add_u32_e32 v11, s54, v89
	ds_read_b32 v88, v11
	global_store_dwordx2 v[86:87], v[80:81], off
	v_add_u32_e32 v80, s55, v89
	ds_read_b32 v86, v80
	v_ashrrev_i32_e32 v11, 31, v10
	s_waitcnt lgkmcnt(1)
	v_pk_mul_f32 v[80:81], v[84:85], v[88:89] op_sel_hi:[1,0]
	v_pk_mul_f32 v[74:75], v[74:75], v[88:89] op_sel_hi:[1,0]
	v_cvt_pk_bf16_f32 v75, v81, v75
	v_cvt_pk_bf16_f32 v74, v80, v74
	v_lshlrev_b64 v[80:81], 9, v[10:11]
	s_waitcnt lgkmcnt(0)
	v_mul_f32_e32 v11, v76, v86
	v_lshlrev_b32_e32 v10, 1, v10
	v_cvt_pk_bf16_f32 v11, v11, v11
	v_add_u32_e32 v76, v51, v10
	ds_write_b16_d16_hi v76, v11
	v_mul_f32_e32 v11, v72, v86
	v_cvt_pk_bf16_f32 v11, v11, v11
	v_add3_u32 v10, s80, v10, v7
	ds_write_b16_d16_hi v10, v11 offset:144
	v_mul_f32_e32 v11, v77, v86
	v_cvt_pk_bf16_f32 v11, v11, v11
	ds_write_b16_d16_hi v10, v11 offset:288
	v_mul_f32_e32 v11, v73, v86
	v_pk_mul_f32 v[84:85], v[64:65], v[78:79]
	v_cvt_pk_bf16_f32 v11, v11, v11
	v_lshlrev_b32_e32 v73, 16, v53
	v_lshlrev_b32_e32 v72, 16, v52
	v_pk_fma_f32 v[82:83], v[2:3], v[82:83], v[84:85]
	v_pk_mul_f32 v[84:85], v[28:29], v[60:61]
	v_and_b32_e32 v53, 0xffff0000, v53
	v_and_b32_e32 v52, 0xffff0000, v52
	v_pk_fma_f32 v[82:83], v[66:67], v[72:73], v[82:83]
	v_pk_fma_f32 v[70:71], v[32:33], v[70:71], v[84:85]
	v_pk_add_f32 v[82:83], v[68:69], v[82:83]
	v_pk_fma_f32 v[70:71], v[20:21], v[52:53], v[70:71]
	ds_write_b16_d16_hi v10, v11 offset:432
	v_mul_f32_e32 v11, 0xbfb8aa3b, v82
	v_pk_add_f32 v[70:71], v[24:25], v[70:71]
	v_exp_f32_e32 v11, v11
	v_mul_f32_e32 v77, 0xbfb8aa3b, v70
	v_exp_f32_e32 v77, v77
	v_mul_f32_e32 v85, 0xbfb8aa3b, v71
	v_add_f32_e32 v11, 1.0, v11
	v_rcp_f32_e32 v84, v11
	v_add_f32_e32 v11, 1.0, v77
	v_mul_f32_e32 v77, 0xbfb8aa3b, v83
	v_exp_f32_e32 v77, v77
	v_exp_f32_e32 v87, v85
	v_rcp_f32_e32 v86, v11
	v_lshlrev_b32_e32 v10, 16, v48
	v_add_f32_e32 v11, 1.0, v77
	v_rcp_f32_e32 v85, v11
	v_add_f32_e32 v11, 1.0, v87
	v_rcp_f32_e32 v87, v11
	v_lshlrev_b32_e32 v11, 16, v49
	v_pk_mul_f32 v[82:83], v[82:83], v[84:85]
	v_and_b32_e32 v48, 0xffff0000, v48
	v_pk_mul_f32 v[70:71], v[70:71], v[86:87]
	v_and_b32_e32 v49, 0xffff0000, v49
	v_cvt_pk_bf16_f32 v84, v82, v70
	v_pk_mul_f32 v[86:87], v[18:19], v[14:15]
	v_cvt_pk_bf16_f32 v85, v83, v71
	v_pk_fma_f32 v[30:31], v[58:59], v[30:31], v[86:87]
	v_pk_mul_f32 v[86:87], v[16:17], v[56:57]
	v_pk_fma_f32 v[30:31], v[22:23], v[10:11], v[30:31]
	v_pk_fma_f32 v[62:63], v[4:5], v[62:63], v[86:87]
	v_pk_add_f32 v[30:31], v[26:27], v[30:31]
	v_pk_fma_f32 v[62:63], v[12:13], v[48:49], v[62:63]
	v_mul_f32_e32 v77, 0xbfb8aa3b, v30
	v_pk_add_f32 v[62:63], v[8:9], v[62:63]
	v_exp_f32_e32 v77, v77
	v_mul_f32_e32 v86, 0xbfb8aa3b, v62
	v_exp_f32_e32 v87, v86
	v_add_f32_e32 v77, 1.0, v77
	v_rcp_f32_e32 v86, v77
	v_add_f32_e32 v77, 1.0, v87
	v_mul_f32_e32 v87, 0xbfb8aa3b, v31
	v_exp_f32_e32 v87, v87
	v_mul_f32_e32 v88, 0xbfb8aa3b, v63
	v_exp_f32_e32 v89, v88
	v_rcp_f32_e32 v88, v77
	v_add_f32_e32 v77, 1.0, v87
	v_rcp_f32_e32 v87, v77
	v_add_f32_e32 v77, 1.0, v89
	v_rcp_f32_e32 v89, v77
	ds_write_b64 v6, v[84:85] offset:2112
	v_pk_mul_f32 v[30:31], v[30:31], v[86:87]
	v_or_b32_e32 v76, 5, v50
	v_pk_mul_f32 v[62:63], v[62:63], v[88:89]
	v_pk_mul_f32 v[30:31], v[30:31], s[48:49] op_sel_hi:[1,0]
	v_pk_mul_f32 v[62:63], v[62:63], s[48:49] op_sel_hi:[1,0]
	v_cvt_pk_bf16_f32 v85, v31, v63
	v_cvt_pk_bf16_f32 v84, v30, v62
	ds_write_b64 v6, v[84:85] offset:35904
	v_lshlrev_b32_e32 v85, 2, v76
	v_add_u32_e32 v77, s54, v85
	ds_read_b32 v84, v77
	v_lshl_add_u64 v[80:81], v[54:55], 0, v[80:81]
	global_store_dwordx2 v[80:81], v[74:75], off
	v_add_u32_e32 v74, s55, v85
	ds_read_b32 v80, v74
	s_waitcnt lgkmcnt(1)
	v_pk_mul_f32 v[74:75], v[82:83], v[84:85] op_sel_hi:[1,0]
	v_pk_mul_f32 v[70:71], v[70:71], v[84:85] op_sel_hi:[1,0]
	v_cvt_pk_bf16_f32 v71, v75, v71
	v_cvt_pk_bf16_f32 v70, v74, v70
	v_ashrrev_i32_e32 v77, 31, v76
	s_waitcnt lgkmcnt(0)
	v_mul_f32_e32 v30, v30, v80
	v_lshlrev_b64 v[74:75], 9, v[76:77]
	v_lshlrev_b32_e32 v76, 1, v76
	v_cvt_pk_bf16_f32 v30, v30, v30
	v_add_u32_e32 v77, v51, v76
	ds_write_b16_d16_hi v77, v30
	v_mul_f32_e32 v30, v62, v80
	v_cvt_pk_bf16_f32 v30, v30, v30
	v_add3_u32 v62, s80, v76, v7
	ds_write_b16_d16_hi v62, v30 offset:144
	v_mul_f32_e32 v30, v31, v80
	v_cvt_pk_bf16_f32 v30, v30, v30
	ds_write_b16_d16_hi v62, v30 offset:288
	v_mul_f32_e32 v30, v63, v80
	v_pk_mul_f32 v[80:81], v[64:65], v[72:73]
	v_lshlrev_b32_e32 v77, 16, v47
	v_lshlrev_b32_e32 v76, 16, v46
	v_pk_fma_f32 v[78:79], v[2:3], v[78:79], v[80:81]
	v_pk_mul_f32 v[80:81], v[28:29], v[52:53]
	v_and_b32_e32 v47, 0xffff0000, v47
	v_and_b32_e32 v46, 0xffff0000, v46
	v_pk_fma_f32 v[78:79], v[66:67], v[76:77], v[78:79]
	v_pk_fma_f32 v[60:61], v[32:33], v[60:61], v[80:81]
	v_pk_add_f32 v[78:79], v[68:69], v[78:79]
	v_pk_fma_f32 v[60:61], v[20:21], v[46:47], v[60:61]
	v_cvt_pk_bf16_f32 v30, v30, v30
	v_mul_f32_e32 v31, 0xbfb8aa3b, v78
	v_pk_add_f32 v[60:61], v[24:25], v[60:61]
	v_exp_f32_e32 v31, v31
	v_mul_f32_e32 v63, 0xbfb8aa3b, v60
	v_exp_f32_e32 v63, v63
	v_mul_f32_e32 v81, 0xbfb8aa3b, v61
	v_add_f32_e32 v31, 1.0, v31
	v_rcp_f32_e32 v80, v31
	v_add_f32_e32 v31, 1.0, v63
	v_mul_f32_e32 v63, 0xbfb8aa3b, v79
	v_exp_f32_e32 v63, v63
	v_exp_f32_e32 v83, v81
	v_rcp_f32_e32 v82, v31
	ds_write_b16_d16_hi v62, v30 offset:432
	v_add_f32_e32 v31, 1.0, v63
	v_rcp_f32_e32 v81, v31
	v_add_f32_e32 v31, 1.0, v83
	v_rcp_f32_e32 v83, v31
	v_lshlrev_b32_e32 v62, 16, v44
	v_lshlrev_b32_e32 v63, 16, v45
	v_pk_mul_f32 v[78:79], v[78:79], v[80:81]
	v_pk_mul_f32 v[60:61], v[60:61], v[82:83]
	v_and_b32_e32 v44, 0xffff0000, v44
	v_cvt_pk_bf16_f32 v80, v78, v60
	v_pk_mul_f32 v[82:83], v[18:19], v[10:11]
	v_cvt_pk_bf16_f32 v81, v79, v61
	v_pk_fma_f32 v[14:15], v[58:59], v[14:15], v[82:83]
	v_pk_mul_f32 v[82:83], v[16:17], v[48:49]
	v_and_b32_e32 v45, 0xffff0000, v45
	v_pk_fma_f32 v[14:15], v[22:23], v[62:63], v[14:15]
	v_pk_fma_f32 v[56:57], v[4:5], v[56:57], v[82:83]
	v_pk_add_f32 v[14:15], v[26:27], v[14:15]
	v_pk_fma_f32 v[56:57], v[12:13], v[44:45], v[56:57]
	v_mul_f32_e32 v31, 0xbfb8aa3b, v14
	v_pk_add_f32 v[56:57], v[8:9], v[56:57]
	v_exp_f32_e32 v31, v31
	v_mul_f32_e32 v82, 0xbfb8aa3b, v56
	v_exp_f32_e32 v83, v82
	v_add_f32_e32 v31, 1.0, v31
	v_rcp_f32_e32 v82, v31
	v_add_f32_e32 v31, 1.0, v83
	v_mul_f32_e32 v83, 0xbfb8aa3b, v15
	v_exp_f32_e32 v83, v83
	v_mul_f32_e32 v84, 0xbfb8aa3b, v57
	v_exp_f32_e32 v85, v84
	v_rcp_f32_e32 v84, v31
	v_add_f32_e32 v31, 1.0, v83
	v_rcp_f32_e32 v83, v31
	v_add_f32_e32 v31, 1.0, v85
	v_rcp_f32_e32 v85, v31
	ds_write_b64 v6, v[80:81] offset:2640
	v_pk_mul_f32 v[14:15], v[14:15], v[82:83]
	v_or_b32_e32 v30, 6, v50
	v_pk_mul_f32 v[56:57], v[56:57], v[84:85]
	v_pk_mul_f32 v[14:15], v[14:15], s[48:49] op_sel_hi:[1,0]
	v_pk_mul_f32 v[56:57], v[56:57], s[48:49] op_sel_hi:[1,0]
	v_cvt_pk_bf16_f32 v81, v15, v57
	v_cvt_pk_bf16_f32 v80, v14, v56
	ds_write_b64 v6, v[80:81] offset:36432
	v_lshlrev_b32_e32 v81, 2, v30
	v_add_u32_e32 v31, s54, v81
	ds_read_b32 v80, v31
	v_lshl_add_u64 v[74:75], v[54:55], 0, v[74:75]
	global_store_dwordx2 v[74:75], v[70:71], off
	v_add_u32_e32 v70, s55, v81
	ds_read_b32 v74, v70
	s_waitcnt lgkmcnt(1)
	v_pk_mul_f32 v[70:71], v[78:79], v[80:81] op_sel_hi:[1,0]
	v_pk_mul_f32 v[60:61], v[60:61], v[80:81] op_sel_hi:[1,0]
	v_cvt_pk_bf16_f32 v61, v71, v61
	v_cvt_pk_bf16_f32 v60, v70, v60
	v_ashrrev_i32_e32 v31, 31, v30
	s_waitcnt lgkmcnt(0)
	v_mul_f32_e32 v14, v14, v74
	v_lshlrev_b64 v[70:71], 9, v[30:31]
	v_lshlrev_b32_e32 v30, 1, v30
	v_cvt_pk_bf16_f32 v14, v14, v14
	v_add_u32_e32 v31, v51, v30
	ds_write_b16_d16_hi v31, v14
	v_mul_f32_e32 v14, v56, v74
	v_bfe_u32 v31, v14, 16, 1
	v_add3_u32 v14, v14, v31, s79
	v_add3_u32 v30, s80, v30, v7
	ds_write_b16_d16_hi v30, v14 offset:144
	v_mul_f32_e32 v14, v15, v74
	v_cvt_pk_bf16_f32 v14, v14, v14
	ds_write_b16_d16_hi v30, v14 offset:288
	v_mul_f32_e32 v14, v57, v74
	v_cvt_pk_bf16_f32 v14, v14, v14
	ds_write_b16_d16_hi v30, v14 offset:432
	v_or_b32_e32 v14, 7, v50
	v_add_u32_e32 v15, s91, v14
	v_and_b32_e32 v15, 0xffffefff, v15
	v_cmp_eq_u32_e32 vcc, s82, v15
	v_lshlrev_b32_e32 v56, 16, v42
	v_lshlrev_b32_e32 v57, 16, v43
	v_pk_mul_f32 v[64:65], v[64:65], v[76:77]
	v_cndmask_b32_e64 v30, 1.0, 0, vcc
	v_and_b32_e32 v42, 0xffff0000, v42
	v_and_b32_e32 v43, 0xffff0000, v43
	v_pk_fma_f32 v[2:3], v[2:3], v[72:73], v[64:65]
	v_pk_mul_f32 v[56:57], v[66:67], v[56:57]
	v_pk_mul_f32 v[28:29], v[28:29], v[46:47]
	v_pk_fma_f32 v[2:3], v[56:57], v[30:31], v[2:3] op_sel_hi:[1,0,1]
	v_pk_fma_f32 v[28:29], v[32:33], v[52:53], v[28:29]
	v_pk_mul_f32 v[20:21], v[20:21], v[42:43]
	v_pk_add_f32 v[2:3], v[68:69], v[2:3]
	v_pk_fma_f32 v[20:21], v[20:21], v[30:31], v[28:29] op_sel_hi:[1,0,1]
	v_mul_f32_e32 v15, 0xbfb8aa3b, v2
	v_pk_add_f32 v[20:21], v[24:25], v[20:21]
	v_exp_f32_e32 v15, v15
	v_mul_f32_e32 v24, 0xbfb8aa3b, v20
	v_exp_f32_e32 v25, v24
	v_mul_f32_e32 v28, 0xbfb8aa3b, v21
	v_add_f32_e32 v15, 1.0, v15
	v_rcp_f32_e32 v24, v15
	v_add_f32_e32 v15, 1.0, v25
	v_mul_f32_e32 v25, 0xbfb8aa3b, v3
	v_exp_f32_e32 v25, v25
	v_exp_f32_e32 v29, v28
	v_rcp_f32_e32 v28, v15
	v_lshlrev_b32_e32 v75, 16, v41
	v_add_f32_e32 v15, 1.0, v25
	v_rcp_f32_e32 v25, v15
	v_add_f32_e32 v15, 1.0, v29
	v_rcp_f32_e32 v29, v15
	v_lshlrev_b32_e32 v74, 16, v40
	v_pk_mul_f32 v[18:19], v[18:19], v[62:63]
	v_pk_mul_f32 v[2:3], v[2:3], v[24:25]
	v_pk_mul_f32 v[20:21], v[20:21], v[28:29]
	v_pk_fma_f32 v[10:11], v[58:59], v[10:11], v[18:19]
	v_cvt_pk_bf16_f32 v25, v3, v21
	v_pk_mul_f32 v[18:19], v[22:23], v[74:75]
	v_and_b32_e32 v33, 0xffff0000, v41
	v_and_b32_e32 v32, 0xffff0000, v40
	v_pk_fma_f32 v[10:11], v[30:31], v[18:19], v[10:11] op_sel_hi:[0,1,1]
	v_pk_mul_f32 v[16:17], v[16:17], v[44:45]
	v_pk_add_f32 v[10:11], v[26:27], v[10:11]
	v_pk_fma_f32 v[4:5], v[4:5], v[48:49], v[16:17]
	v_pk_mul_f32 v[12:13], v[12:13], v[32:33]
	v_mul_f32_e32 v15, 0xbfb8aa3b, v10
	v_pk_fma_f32 v[4:5], v[30:31], v[12:13], v[4:5] op_sel_hi:[0,1,1]
	v_exp_f32_e32 v15, v15
	v_pk_add_f32 v[4:5], v[8:9], v[4:5]
	v_mul_f32_e32 v12, 0xbfb8aa3b, v11
	v_mul_f32_e32 v8, 0xbfb8aa3b, v4
	v_exp_f32_e32 v9, v8
	v_exp_f32_e32 v13, v12
	v_mul_f32_e32 v12, 0xbfb8aa3b, v5
	v_add_f32_e32 v8, 1.0, v15
	v_exp_f32_e32 v15, v12
	v_add_f32_e32 v9, 1.0, v9
	v_rcp_f32_e32 v12, v9
	v_add_f32_e32 v9, 1.0, v13
	v_rcp_f32_e32 v8, v8
	v_rcp_f32_e32 v9, v9
	v_add_f32_e32 v13, 1.0, v15
	v_rcp_f32_e32 v13, v13
	v_cvt_pk_bf16_f32 v24, v2, v20
	v_pk_mul_f32 v[8:9], v[10:11], v[8:9]
	v_pk_mul_f32 v[8:9], v[8:9], s[48:49] op_sel_hi:[1,0]
	v_pk_mul_f32 v[4:5], v[4:5], v[12:13]
	v_pk_mul_f32 v[4:5], v[4:5], s[48:49] op_sel_hi:[1,0]
	v_cvt_pk_bf16_f32 v11, v9, v5
	v_cvt_pk_bf16_f32 v10, v8, v4
	ds_write_b64 v6, v[10:11] offset:36960
	v_lshlrev_b32_e32 v10, 2, v14
	ds_write_b64 v6, v[24:25] offset:3168
	v_add_u32_e32 v6, s54, v10
	ds_read_b32 v6, v6
	v_add_u32_e32 v10, s55, v10
	ds_read_b32 v12, v10
	v_ashrrev_i32_e32 v15, 31, v14
	v_lshl_add_u64 v[70:71], v[54:55], 0, v[70:71]
	s_waitcnt lgkmcnt(1)
	v_pk_mul_f32 v[2:3], v[2:3], v[6:7] op_sel_hi:[1,0]
	v_pk_mul_f32 v[10:11], v[20:21], v[6:7] op_sel_hi:[1,0]
	v_cvt_pk_bf16_f32 v2, v2, v10
	v_cvt_pk_bf16_f32 v3, v3, v11
	v_lshlrev_b64 v[10:11], 9, v[14:15]
	v_lshl_add_u64 v[10:11], v[54:55], 0, v[10:11]
	global_store_dwordx2 v[10:11], v[2:3], off
	s_waitcnt lgkmcnt(0)
	v_mul_f32_e32 v3, v8, v12
	v_lshlrev_b32_e32 v2, 1, v14
	v_cvt_pk_bf16_f32 v3, v3, v3
	v_add_u32_e32 v6, v51, v2
	ds_write_b16_d16_hi v6, v3
	v_mul_f32_e32 v3, v4, v12
	v_cvt_pk_bf16_f32 v3, v3, v3
	v_add3_u32 v2, s80, v2, v7
	ds_write_b16_d16_hi v2, v3 offset:144
	v_mul_f32_e32 v3, v9, v12
	v_cvt_pk_bf16_f32 v3, v3, v3
	ds_write_b16_d16_hi v2, v3 offset:288
	v_mul_f32_e32 v3, v5, v12
	v_cvt_pk_bf16_f32 v3, v3, v3
	ds_write_b16_d16_hi v2, v3 offset:432
	v_and_b32_e32 v3, 48, v99
	v_and_or_b32 v2, v50, s28, v39
	v_add_u32_e32 v6, 0, v3
	v_mad_u64_u32 v[32:33], s[28:29], v2, s81, v[6:7]
	global_store_dwordx2 v[70:71], v[60:61], off
	s_waitcnt lgkmcnt(0)
	s_barrier
	ds_read_b128 v[2:5], v32
	v_and_or_b32 v10, v34, 32, v39
	v_mad_u32_u24 v11, v10, s81, v6
	ds_read_b128 v[12:15], v32 offset:64
	ds_read_b128 v[6:9], v11 offset:33792
	ds_read_b128 v[16:19], v11 offset:33856
	ds_read_b128 v[20:23], v32 offset:128
	s_waitcnt lgkmcnt(2)
	v_mfma_f32_16x16x32_bf16 v[6:9], v[2:5], v[6:9], 0
	s_add_i32 s28, 0, 0x1bd00
	s_waitcnt lgkmcnt(1)
	v_mfma_f32_16x16x32_bf16 v[6:9], v[12:15], v[16:19], v[6:9]
	ds_read_b128 v[16:19], v32 offset:192
	ds_read_b128 v[24:27], v11 offset:33920
	ds_read_b128 v[28:31], v11 offset:33984
	s_waitcnt lgkmcnt(1)
	v_mfma_f32_16x16x32_bf16 v[6:9], v[20:23], v[24:27], v[6:9]
	ds_read_b128 v[24:27], v32 offset:256
	s_waitcnt lgkmcnt(1)
	v_mfma_f32_16x16x32_bf16 v[6:9], v[16:19], v[28:31], v[6:9]
	ds_read_b128 v[28:31], v32 offset:320
	ds_read_b128 v[40:43], v11 offset:34048
	ds_read_b128 v[44:47], v11 offset:34112
	s_waitcnt lgkmcnt(1)
	v_mfma_f32_16x16x32_bf16 v[6:9], v[24:27], v[40:43], v[6:9]
	ds_read_b128 v[40:43], v32 offset:384
	s_waitcnt lgkmcnt(1)
	v_mfma_f32_16x16x32_bf16 v[6:9], v[28:31], v[44:47], v[6:9]
	ds_read_b128 v[44:47], v32 offset:448
	ds_read_b128 v[48:51], v11 offset:34176
	ds_read_b128 v[52:55], v11 offset:34240
	s_waitcnt lgkmcnt(1)
	v_mfma_f32_16x16x32_bf16 v[6:9], v[40:43], v[48:51], v[6:9]
	s_waitcnt lgkmcnt(0)
	v_mfma_f32_16x16x32_bf16 v[6:9], v[44:47], v[52:55], v[6:9]
	ds_read_b128 v[48:51], v11 offset:42240
	ds_read_b128 v[52:55], v11 offset:42304
	s_waitcnt lgkmcnt(1)
	v_mfma_f32_16x16x32_bf16 v[2:5], v[2:5], v[48:51], 0
	s_waitcnt lgkmcnt(0)
	v_mfma_f32_16x16x32_bf16 v[2:5], v[12:15], v[52:55], v[2:5]
	ds_read_b128 v[12:15], v11 offset:42368
	ds_read_b128 v[48:51], v11 offset:42432
	s_waitcnt lgkmcnt(1)
	v_mfma_f32_16x16x32_bf16 v[2:5], v[20:23], v[12:15], v[2:5]
	s_waitcnt lgkmcnt(0)
	v_mfma_f32_16x16x32_bf16 v[2:5], v[16:19], v[48:51], v[2:5]
	ds_read_b128 v[12:15], v11 offset:42496
	ds_read_b128 v[16:19], v11 offset:42560
	s_waitcnt lgkmcnt(1)
	v_mfma_f32_16x16x32_bf16 v[2:5], v[24:27], v[12:15], v[2:5]
	s_waitcnt lgkmcnt(0)
	v_mfma_f32_16x16x32_bf16 v[2:5], v[28:31], v[16:19], v[2:5]
	ds_read_b128 v[12:15], v11 offset:42624
	ds_read_b128 v[16:19], v11 offset:42688
	v_ashrrev_i32_e32 v11, 3, v38
	v_and_b32_e32 v11, -16, v11
	s_waitcnt lgkmcnt(1)
	v_mfma_f32_16x16x32_bf16 v[2:5], v[40:43], v[12:15], v[2:5]
	v_lshrrev_b32_e32 v12, 2, v99
	v_and_or_b32 v11, v12, 12, v11
	v_cmp_le_i32_e32 vcc, v10, v11
	s_waitcnt lgkmcnt(0)
	v_mfma_f32_16x16x32_bf16 v[2:5], v[44:47], v[16:19], v[2:5]
	v_mov_b32_e32 v15, 0
	v_cndmask_b32_e64 v12, 0, 1, vcc
	v_cmp_ge_i32_e32 vcc, v10, v11
	v_lshl_add_u32 v19, v10, 2, s28
	s_nop 0
	v_cndmask_b32_e64 v13, 0, 1, vcc
	v_cndmask_b32_e64 v12, v13, v12, s[6:7]
	v_and_b32_e32 v12, 1, v12
	v_cmp_eq_u32_e32 vcc, 1, v12
	v_lshl_add_u32 v12, v11, 2, 0
	v_mov_b32_e32 v13, 0
	s_and_saveexec_b64 s[54:55], vcc
	s_cbranch_execz .LBB0_3807
	v_add_u32_e32 v13, 0x1bc00, v12
	ds_read_b32 v13, v13
	ds_read_b32 v14, v19
	s_waitcnt lgkmcnt(0)
	v_add_f32_e32 v13, v13, v14
	v_mul_f32_e32 v13, 0x3fb8aa3b, v13
	v_exp_f32_e32 v13, v13
	s_nop 0
	v_mul_f32_e32 v13, v6, v13

.LBB0_3842:
	v_add_u32_e32 v27, 0x400, v26
	v_lshlrev_b32_e32 v38, 16, v10
	ds_read2_b32 v[30:31], v26 offset1:65
	ds_read2_b32 v[32:33], v26 offset0:130 offset1:195
	ds_read2_b32 v[34:35], v27 offset0:4 offset1:69
	ds_read2_b32 v[36:37], v27 offset0:134 offset1:199
	v_mul_f32_e32 v27, 0xbfb8aa3b, v38
	v_exp_f32_e32 v27, v27
	v_lshlrev_b32_e32 v39, 16, v11
	v_mul_f32_e32 v40, 0xbfb8aa3b, v39
	v_exp_f32_e32 v41, v40
	v_and_b32_e32 v10, 0xffff0000, v10
	v_add_f32_e32 v27, 1.0, v27
	v_and_b32_e32 v11, 0xffff0000, v11
	v_rcp_f32_e32 v40, v27
	v_mul_f32_e32 v27, 0xbfb8aa3b, v10
	v_exp_f32_e32 v27, v27
	v_add_f32_e32 v41, 1.0, v41
	v_mul_f32_e32 v42, 0xbfb8aa3b, v11
	v_rcp_f32_e32 v41, v41
	v_exp_f32_e32 v43, v42
	v_add_f32_e32 v27, 1.0, v27
	v_rcp_f32_e32 v42, v27
	v_pk_mul_f32 v[38:39], v[40:41], v[38:39]
	v_add_f32_e32 v27, 1.0, v43
	s_waitcnt lgkmcnt(3)
	v_mov_b32_e32 v40, v30
	v_lshlrev_b32_e32 v30, 16, v12
	v_rcp_f32_e32 v43, v27
	v_mul_f32_e32 v27, 0xbfb8aa3b, v30
	v_exp_f32_e32 v27, v27
	s_waitcnt lgkmcnt(2)
	v_mov_b32_e32 v41, v32
	v_pk_mul_f32 v[10:11], v[42:43], v[10:11]
	v_mov_b32_e32 v32, v31
	v_lshlrev_b32_e32 v31, 16, v13
	v_pk_mul_f32 v[10:11], v[10:11], v[32:33]
	v_and_b32_e32 v12, 0xffff0000, v12
	v_add_f32_e32 v27, 1.0, v27
	v_mul_f32_e32 v32, 0xbfb8aa3b, v31
	v_and_b32_e32 v13, 0xffff0000, v13
	v_exp_f32_e32 v33, v32
	v_rcp_f32_e32 v32, v27
	v_mul_f32_e32 v27, 0xbfb8aa3b, v12
	v_pk_mul_f32 v[38:39], v[38:39], v[40:41]
	v_exp_f32_e32 v27, v27
	v_mul_f32_e32 v40, 0xbfb8aa3b, v13
	v_exp_f32_e32 v41, v40
	v_add_f32_e32 v33, 1.0, v33
	v_add_f32_e32 v27, 1.0, v27
	v_rcp_f32_e32 v40, v27
	v_add_f32_e32 v27, 1.0, v41
	v_rcp_f32_e32 v33, v33
	v_rcp_f32_e32 v41, v27
	s_and_b32 s4, s33, 0xffffffc0
	v_add_u32_e32 v28, s4, v23
	v_pk_mul_f32 v[30:31], v[32:33], v[30:31]
	s_waitcnt lgkmcnt(0)
	v_mov_b32_e32 v33, v36
	v_pk_mul_f32 v[12:13], v[40:41], v[12:13]
	v_mov_b32_e32 v36, v35
	v_mov_b32_e32 v32, v34
	v_pk_mul_f32 v[12:13], v[12:13], v[36:37]
	v_ashrrev_i32_e32 v29, 31, v28
	v_pk_mul_f32 v[30:31], v[30:31], v[32:33]
	v_cvt_pk_bf16_f32 v13, v31, v13
	v_cvt_pk_bf16_f32 v12, v30, v12
	v_cvt_pk_bf16_f32 v11, v39, v11
	v_cvt_pk_bf16_f32 v10, v38, v10
	s_and_b32 s14, s31, 0x3c0
	v_lshlrev_b64 v[28:29], 13, v[28:29]
	v_lshl_add_u64 v[28:29], s[12:13], 0, v[28:29]
	s_lshl_b32 s4, s14, 1
	v_lshl_add_u64 v[28:29], v[28:29], 0, s[4:5]
	v_lshl_add_u64 v[28:29], v[28:29], 0, v[18:19]
	global_store_dwordx4 v[28:29], v[10:13], off offset:2048
	s_waitcnt lgkmcnt(0)
	s_barrier
	s_andn2_b64 vcc, exec, s[6:7]
	s_mov_b32 s31, s21
	s_waitcnt vmcnt(1)
	v_mov_b64_e32 v[10:11], v[14:15]
	s_mov_b32 s33, s20
	v_mov_b64_e32 v[12:13], v[16:17]
	s_cbranch_vccz .LBB0_3847

.LBB0_4050:
	v_pk_add_f32 v[28:29], v[28:29], v[32:33]
	v_pk_add_f32 v[30:31], v[30:31], v[34:35]
	v_pk_mul_f32 v[34:35], v[28:29], v[28:29]
	v_pk_mul_f32 v[32:33], v[30:31], v[30:31]
	v_add_f32_e32 v34, v34, v35
	v_add_f32_e32 v32, v32, v34
	v_add_f32_e32 v32, v33, v32
	ds_bpermute_b32 v33, v1, v32
	v_pk_add_f32 v[22:23], v[22:23], v[26:27]
	v_pk_add_f32 v[20:21], v[20:21], v[24:25]
	v_lshlrev_b32_e32 v25, 16, v60
	v_mul_f32_e32 v25, 0xbfb8aa3b, v25
	s_waitcnt lgkmcnt(0)
	v_add_f32_e32 v26, v32, v33
	ds_bpermute_b32 v27, v62, v26
	v_and_b32_e32 v32, 0xffff0000, v60
	v_exp_f32_e32 v25, v25
	v_lshlrev_b32_e32 v33, 16, v61
	v_and_b32_e32 v34, 0xffff0000, v61
	s_waitcnt lgkmcnt(0)
	v_add_f32_e32 v26, v26, v27
	ds_bpermute_b32 v27, v63, v26
	v_add_f32_e32 v25, 1.0, v25
	v_mul_f32_e32 v33, 0xbfb8aa3b, v33
	v_mul_f32_e32 v34, 0xbfb8aa3b, v34
	v_lshlrev_b32_e32 v24, 16, v58
	s_waitcnt lgkmcnt(0)
	v_add_f32_e32 v26, v26, v27
	ds_bpermute_b32 v27, v64, v26
	v_exp_f32_e32 v33, v33
	v_exp_f32_e32 v34, v34
	v_mul_f32_e32 v35, 0xbfb8aa3b, v24
	v_exp_f32_e32 v35, v35
	s_waitcnt lgkmcnt(0)
	v_add_f32_e32 v26, v26, v27
	ds_bpermute_b32 v27, v65, v26
	v_add_f32_e32 v33, 1.0, v33
	v_add_f32_e32 v34, 1.0, v34
	v_and_b32_e32 v58, 0xffff0000, v58
	v_add_f32_e32 v35, 1.0, v35
	s_waitcnt lgkmcnt(0)
	v_add_f32_e32 v27, v26, v27
	ds_bpermute_b32 v60, v66, v27
	v_rcp_f32_e32 v26, v25
	v_mov_b32_e32 v72, v20
	v_mul_f32_e32 v32, 0xbfb8aa3b, v32
	v_exp_f32_e32 v32, v32
	s_waitcnt lgkmcnt(0)
	v_add_f32_e32 v25, v27, v60
	v_fmamk_f32 v25, v25, 0x3b800000, v67
	v_mul_f32_e32 v27, 0x4b800000, v25
	v_cmp_gt_f32_e32 vcc, s3, v25
	v_mul_f32_e32 v60, 0xbfb8aa3b, v58
	v_exp_f32_e32 v61, v60
	v_cndmask_b32_e32 v25, v25, v27, vcc
	v_rsq_f32_e32 v25, v25
	v_rcp_f32_e32 v27, v33
	v_rcp_f32_e32 v33, v34
	v_rcp_f32_e32 v60, v35
	v_mul_f32_e32 v34, 0x45800000, v25
	v_cndmask_b32_e32 v34, v25, v34, vcc
	v_lshlrev_b32_e32 v25, 16, v59
	v_mul_f32_e32 v35, 0xbfb8aa3b, v25
	v_exp_f32_e32 v35, v35
	v_and_b32_e32 v59, 0xffff0000, v59
	v_add_f32_e32 v61, 1.0, v61
	v_rcp_f32_e32 v70, v61
	v_add_f32_e32 v20, 1.0, v35
	v_rcp_f32_e32 v61, v20
	v_mul_f32_e32 v20, 0xbfb8aa3b, v59
	v_exp_f32_e32 v20, v20
	v_add_f32_e32 v32, 1.0, v32
	v_rcp_f32_e32 v32, v32
	v_mov_b32_e32 v73, v22
	v_add_f32_e32 v20, 1.0, v20
	v_rcp_f32_e32 v71, v20
	v_pk_mul_f32 v[26:27], v[72:73], v[26:27]
	v_pk_mul_f32 v[24:25], v[60:61], v[24:25]
	v_mov_b32_e32 v22, v21
	v_pk_mul_f32 v[24:25], v[26:27], v[24:25]
	v_pk_mul_f32 v[20:21], v[22:23], v[32:33]
	v_pk_mul_f32 v[22:23], v[70:71], v[58:59]
	v_lshl_add_u64 v[40:41], v[40:41], 0, s[0:1]
	v_pk_mul_f32 v[20:21], v[20:21], v[22:23]
	v_cvt_pk_bf16_f32 v21, v25, v21
	v_cvt_pk_bf16_f32 v20, v24, v20
	v_lshl_add_u64 v[22:23], v[50:51], 0, v[36:37]
	v_add_co_u32_e32 v22, vcc, s10, v22
	v_and_b32_e32 v24, 0xffff0000, v44
	s_nop 0
	v_addc_co_u32_e32 v23, vcc, 0, v23, vcc
	global_store_dwordx2 v[22:23], v[20:21], off
	v_lshlrev_b32_e32 v20, 16, v44
	v_mul_f32_e32 v25, 0xbfb8aa3b, v20
	v_exp_f32_e32 v26, v25
	v_mul_f32_e32 v25, 0xbfb8aa3b, v24
	v_exp_f32_e32 v27, v25
	v_lshlrev_b32_e32 v21, 16, v45
	v_and_b32_e32 v25, 0xffff0000, v45
	v_add_f32_e32 v26, 1.0, v26
	v_add_f32_e32 v27, 1.0, v27
	v_rcp_f32_e32 v32, v27
	v_mul_f32_e32 v27, 0xbfb8aa3b, v21
	v_exp_f32_e32 v27, v27
	v_mov_b32_e32 v44, v28
	v_mul_f32_e32 v28, 0xbfb8aa3b, v25
	v_rcp_f32_e32 v26, v26
	v_add_f32_e32 v27, 1.0, v27
	v_rcp_f32_e32 v27, v27
	v_exp_f32_e32 v28, v28
	v_mov_b32_e32 v45, v30
	v_pk_mul_f32 v[44:45], v[44:45], v[34:35] op_sel_hi:[1,0]
	v_pk_mul_f32 v[20:21], v[26:27], v[20:21]
	v_add_f32_e32 v26, 1.0, v28
	v_rcp_f32_e32 v33, v26
	v_mov_b32_e32 v30, v29
	v_pk_mul_f32 v[44:45], v[2:3], v[44:45]
	v_pk_mul_f32 v[26:27], v[30:31], v[34:35] op_sel_hi:[1,0]
	v_pk_mul_f32 v[20:21], v[20:21], v[44:45]
	v_pk_mul_f32 v[26:27], v[38:39], v[26:27]
	v_pk_mul_f32 v[24:25], v[32:33], v[24:25]
	s_waitcnt vmcnt(5)
	v_mov_b64_e32 v[30:31], v[14:15]
	v_pk_mul_f32 v[24:25], v[24:25], v[26:27]
	v_cvt_pk_bf16_f32 v21, v21, v25
	v_cvt_pk_bf16_f32 v20, v20, v24
	global_store_dwordx2 v[22:23], v[20:21], off offset:2048
	v_mov_b64_e32 v[22:23], v[6:7]
	v_mov_b64_e32 v[26:27], v[10:11]
	s_waitcnt vmcnt(5)
	v_mov_b64_e32 v[34:35], v[18:19]
	v_lshl_add_u64 v[46:47], v[46:47], 0, s[20:21]
	v_lshl_add_u64 v[48:49], v[48:49], 0, s[20:21]
	v_lshl_add_u64 v[50:51], v[50:51], 0, s[22:23]
	s_andn2_b64 vcc, exec, s[26:27]
	v_mov_b64_e32 v[20:21], v[4:5]
	v_mov_b64_e32 v[24:25], v[8:9]
	v_mov_b64_e32 v[28:29], v[12:13]
	v_mov_b64_e32 v[32:33], v[16:17]
	s_waitcnt vmcnt(4)
	v_mov_b64_e32 v[60:61], v[54:55]
	s_waitcnt vmcnt(3)
	v_mov_b64_e32 v[58:59], v[52:53]
	s_waitcnt vmcnt(2)
	v_mov_b64_e32 v[44:45], v[56:57]
	s_cbranch_vccz .LBB0_4053

.LBB0_4057:
	v_pk_add_f32 v[28:29], v[28:29], v[32:33]
	v_pk_add_f32 v[30:31], v[30:31], v[34:35]
	v_pk_mul_f32 v[34:35], v[28:29], v[28:29]
	v_pk_mul_f32 v[32:33], v[30:31], v[30:31]
	v_add_f32_e32 v34, v34, v35
	v_add_f32_e32 v32, v32, v34
	v_add_f32_e32 v32, v33, v32
	ds_bpermute_b32 v33, v1, v32
	v_pk_add_f32 v[22:23], v[22:23], v[26:27]
	v_pk_add_f32 v[20:21], v[20:21], v[24:25]
	v_lshlrev_b32_e32 v25, 16, v60
	v_mul_f32_e32 v25, 0xbfb8aa3b, v25
	s_waitcnt lgkmcnt(0)
	v_add_f32_e32 v26, v32, v33
	ds_bpermute_b32 v27, v62, v26
	v_exp_f32_e32 v25, v25
	v_lshlrev_b32_e32 v33, 16, v61
	v_and_b32_e32 v34, 0xffff0000, v61
	v_mul_f32_e32 v33, 0xbfb8aa3b, v33
	s_waitcnt lgkmcnt(0)
	v_add_f32_e32 v26, v26, v27
	ds_bpermute_b32 v27, v63, v26
	v_add_f32_e32 v25, 1.0, v25
	v_mul_f32_e32 v34, 0xbfb8aa3b, v34
	v_exp_f32_e32 v33, v33
	v_exp_f32_e32 v34, v34
	s_waitcnt lgkmcnt(0)
	v_add_f32_e32 v26, v26, v27
	ds_bpermute_b32 v27, v64, v26
	v_add_f32_e32 v33, 1.0, v33
	v_add_f32_e32 v34, 1.0, v34
	v_lshlrev_b32_e32 v24, 16, v58
	v_and_b32_e32 v58, 0xffff0000, v58
	s_waitcnt lgkmcnt(0)
	v_add_f32_e32 v26, v26, v27
	ds_bpermute_b32 v27, v65, v26
	v_and_b32_e32 v32, 0xffff0000, v60
	v_mul_f32_e32 v60, 0xbfb8aa3b, v58
	v_exp_f32_e32 v61, v60
	v_mov_b32_e32 v72, v20
	s_waitcnt lgkmcnt(0)
	v_add_f32_e32 v27, v26, v27
	ds_bpermute_b32 v35, v66, v27
	v_rcp_f32_e32 v26, v25
	v_add_f32_e32 v61, 1.0, v61
	v_mul_f32_e32 v32, 0xbfb8aa3b, v32
	v_rcp_f32_e32 v70, v61
	s_waitcnt lgkmcnt(0)
	v_add_f32_e32 v25, v27, v35
	v_fmamk_f32 v25, v25, 0x3b800000, v67
	v_mul_f32_e32 v27, 0x4b800000, v25
	v_cmp_gt_f32_e32 vcc, s10, v25
	v_exp_f32_e32 v32, v32
	v_mov_b32_e32 v73, v22
	v_cndmask_b32_e32 v25, v25, v27, vcc
	v_rsq_f32_e32 v25, v25
	v_rcp_f32_e32 v27, v33
	v_rcp_f32_e32 v33, v34
	v_add_f32_e32 v32, 1.0, v32
	v_mul_f32_e32 v34, 0x45800000, v25
	v_cndmask_b32_e32 v34, v25, v34, vcc
	v_mul_f32_e32 v25, 0xbfb8aa3b, v24
	v_exp_f32_e32 v35, v25
	v_lshlrev_b32_e32 v25, 16, v59
	v_and_b32_e32 v59, 0xffff0000, v59
	v_rcp_f32_e32 v32, v32
	v_add_f32_e32 v35, 1.0, v35
	v_rcp_f32_e32 v60, v35
	v_mul_f32_e32 v35, 0xbfb8aa3b, v25
	v_exp_f32_e32 v35, v35
	v_pk_mul_f32 v[26:27], v[72:73], v[26:27]
	v_mov_b32_e32 v22, v21
	s_addk_i32 s20, 0x80
	v_add_f32_e32 v20, 1.0, v35
	v_rcp_f32_e32 v61, v20
	v_mul_f32_e32 v20, 0xbfb8aa3b, v59
	v_exp_f32_e32 v20, v20
	v_lshl_add_u64 v[40:41], v[40:41], 0, s[0:1]
	v_pk_mul_f32 v[24:25], v[60:61], v[24:25]
	v_lshl_add_u64 v[44:45], v[44:45], 0, s[22:23]
	v_add_f32_e32 v20, 1.0, v20
	v_rcp_f32_e32 v71, v20
	v_pk_mul_f32 v[24:25], v[26:27], v[24:25]
	v_pk_mul_f32 v[20:21], v[22:23], v[32:33]
	v_lshl_add_u64 v[46:47], v[46:47], 0, s[22:23]
	v_pk_mul_f32 v[22:23], v[70:71], v[58:59]
	s_waitcnt vmcnt(2)
	v_mov_b64_e32 v[60:61], v[54:55]
	v_pk_mul_f32 v[20:21], v[20:21], v[22:23]
	v_cvt_pk_bf16_f32 v21, v25, v21
	v_cvt_pk_bf16_f32 v20, v24, v20
	v_lshl_add_u64 v[22:23], v[50:51], 0, v[36:37]
	v_add_co_u32_e32 v22, vcc, s3, v22
	v_and_b32_e32 v24, 0xffff0000, v48
	s_nop 0
	v_addc_co_u32_e32 v23, vcc, 0, v23, vcc
	global_store_dwordx2 v[22:23], v[20:21], off
	v_lshlrev_b32_e32 v20, 16, v48
	v_mul_f32_e32 v25, 0xbfb8aa3b, v20
	v_exp_f32_e32 v26, v25
	v_mul_f32_e32 v25, 0xbfb8aa3b, v24
	v_exp_f32_e32 v27, v25
	v_lshlrev_b32_e32 v21, 16, v49
	v_and_b32_e32 v25, 0xffff0000, v49
	v_add_f32_e32 v26, 1.0, v26
	v_add_f32_e32 v27, 1.0, v27
	v_rcp_f32_e32 v32, v27
	v_mul_f32_e32 v27, 0xbfb8aa3b, v21
	v_exp_f32_e32 v27, v27
	v_mov_b32_e32 v48, v28
	v_mul_f32_e32 v28, 0xbfb8aa3b, v25
	v_rcp_f32_e32 v26, v26
	v_add_f32_e32 v27, 1.0, v27
	v_rcp_f32_e32 v27, v27
	v_exp_f32_e32 v28, v28
	v_mov_b32_e32 v49, v30
	v_pk_mul_f32 v[48:49], v[48:49], v[34:35] op_sel_hi:[1,0]
	v_pk_mul_f32 v[20:21], v[26:27], v[20:21]
	v_add_f32_e32 v26, 1.0, v28
	v_rcp_f32_e32 v33, v26
	v_mov_b32_e32 v30, v29
	v_pk_mul_f32 v[48:49], v[2:3], v[48:49]
	v_pk_mul_f32 v[26:27], v[30:31], v[34:35] op_sel_hi:[1,0]
	v_pk_mul_f32 v[20:21], v[20:21], v[48:49]
	v_pk_mul_f32 v[26:27], v[38:39], v[26:27]
	v_pk_mul_f32 v[24:25], v[32:33], v[24:25]
	v_mov_b64_e32 v[30:31], v[14:15]
	v_pk_mul_f32 v[24:25], v[24:25], v[26:27]
	v_cvt_pk_bf16_f32 v21, v21, v25
	v_cvt_pk_bf16_f32 v20, v20, v24
	global_store_dwordx2 v[22:23], v[20:21], off offset:2048
	v_mov_b64_e32 v[22:23], v[6:7]
	v_mov_b64_e32 v[26:27], v[10:11]
	v_mov_b64_e32 v[34:35], v[18:19]
	v_lshl_add_u64 v[50:51], v[50:51], 0, s[26:27]
	s_and_b64 vcc, exec, s[34:35]
	v_mov_b64_e32 v[20:21], v[4:5]
	v_mov_b64_e32 v[24:25], v[8:9]
	v_mov_b64_e32 v[28:29], v[12:13]
	v_mov_b64_e32 v[32:33], v[16:17]
	s_waitcnt vmcnt(3)
	v_mov_b64_e32 v[58:59], v[52:53]
	s_waitcnt vmcnt(2)
	v_mov_b64_e32 v[48:49], v[56:57]
	s_cbranch_vccnz .LBB0_4060

.LBB0_4064:
	v_pk_add_f32 v[28:29], v[28:29], v[32:33]
	v_pk_add_f32 v[30:31], v[30:31], v[34:35]
	v_pk_mul_f32 v[34:35], v[28:29], v[28:29]
	v_pk_mul_f32 v[32:33], v[30:31], v[30:31]
	v_add_f32_e32 v34, v34, v35
	v_add_f32_e32 v32, v32, v34
	v_add_f32_e32 v32, v33, v32
	ds_bpermute_b32 v33, v1, v32
	v_pk_add_f32 v[22:23], v[22:23], v[26:27]
	v_pk_add_f32 v[20:21], v[20:21], v[24:25]
	v_lshlrev_b32_e32 v25, 16, v60
	v_mul_f32_e32 v25, 0xbfb8aa3b, v25
	s_waitcnt lgkmcnt(0)
	v_add_f32_e32 v26, v32, v33
	ds_bpermute_b32 v27, v62, v26
	v_and_b32_e32 v32, 0xffff0000, v60
	v_exp_f32_e32 v25, v25
	v_lshlrev_b32_e32 v33, 16, v61
	v_and_b32_e32 v34, 0xffff0000, v61
	s_waitcnt lgkmcnt(0)
	v_add_f32_e32 v26, v26, v27
	ds_bpermute_b32 v27, v63, v26
	v_add_f32_e32 v25, 1.0, v25
	v_mul_f32_e32 v33, 0xbfb8aa3b, v33
	v_mul_f32_e32 v34, 0xbfb8aa3b, v34
	v_lshlrev_b32_e32 v24, 16, v58
	s_waitcnt lgkmcnt(0)
	v_add_f32_e32 v26, v26, v27
	ds_bpermute_b32 v27, v64, v26
	v_exp_f32_e32 v33, v33
	v_exp_f32_e32 v34, v34
	v_mul_f32_e32 v35, 0xbfb8aa3b, v24
	v_exp_f32_e32 v35, v35
	s_waitcnt lgkmcnt(0)
	v_add_f32_e32 v26, v26, v27
	ds_bpermute_b32 v27, v65, v26
	v_add_f32_e32 v33, 1.0, v33
	v_add_f32_e32 v34, 1.0, v34
	v_and_b32_e32 v58, 0xffff0000, v58
	v_add_f32_e32 v35, 1.0, v35
	s_waitcnt lgkmcnt(0)
	v_add_f32_e32 v27, v26, v27
	ds_bpermute_b32 v60, v66, v27
	v_rcp_f32_e32 v26, v25
	v_mov_b32_e32 v72, v20
	v_mul_f32_e32 v32, 0xbfb8aa3b, v32
	v_exp_f32_e32 v32, v32
	s_waitcnt lgkmcnt(0)
	v_add_f32_e32 v25, v27, v60
	v_fmamk_f32 v25, v25, 0x3b800000, v67
	v_mul_f32_e32 v27, 0x4b800000, v25
	v_cmp_gt_f32_e32 vcc, s11, v25
	v_mul_f32_e32 v60, 0xbfb8aa3b, v58
	v_exp_f32_e32 v61, v60
	v_cndmask_b32_e32 v25, v25, v27, vcc
	v_rsq_f32_e32 v25, v25
	v_rcp_f32_e32 v27, v33
	v_rcp_f32_e32 v33, v34
	v_rcp_f32_e32 v60, v35
	v_mul_f32_e32 v34, 0x45800000, v25
	v_cndmask_b32_e32 v34, v25, v34, vcc
	v_lshlrev_b32_e32 v25, 16, v59
	v_mul_f32_e32 v35, 0xbfb8aa3b, v25
	v_exp_f32_e32 v35, v35
	v_and_b32_e32 v59, 0xffff0000, v59
	v_add_f32_e32 v61, 1.0, v61
	v_rcp_f32_e32 v70, v61
	v_add_f32_e32 v20, 1.0, v35
	v_rcp_f32_e32 v61, v20
	v_mul_f32_e32 v20, 0xbfb8aa3b, v59
	v_exp_f32_e32 v20, v20
	v_add_f32_e32 v32, 1.0, v32
	v_rcp_f32_e32 v32, v32
	v_mov_b32_e32 v73, v22
	v_add_f32_e32 v20, 1.0, v20
	v_rcp_f32_e32 v71, v20
	v_pk_mul_f32 v[26:27], v[72:73], v[26:27]
	v_pk_mul_f32 v[24:25], v[60:61], v[24:25]
	v_mov_b32_e32 v22, v21
	v_pk_mul_f32 v[24:25], v[26:27], v[24:25]
	v_pk_mul_f32 v[20:21], v[22:23], v[32:33]
	v_pk_mul_f32 v[22:23], v[70:71], v[58:59]
	s_add_i32 s20, s20, s22
	v_pk_mul_f32 v[20:21], v[20:21], v[22:23]
	v_cvt_pk_bf16_f32 v21, v25, v21
	v_cvt_pk_bf16_f32 v20, v24, v20
	v_lshl_add_u64 v[22:23], v[50:51], 0, v[36:37]
	v_add_co_u32_e32 v22, vcc, s10, v22
	v_and_b32_e32 v24, 0xffff0000, v44
	s_nop 0
	v_addc_co_u32_e32 v23, vcc, 0, v23, vcc
	global_store_dwordx2 v[22:23], v[20:21], off
	v_lshlrev_b32_e32 v20, 16, v44
	v_mul_f32_e32 v25, 0xbfb8aa3b, v20
	v_exp_f32_e32 v26, v25
	v_mul_f32_e32 v25, 0xbfb8aa3b, v24
	v_exp_f32_e32 v27, v25
	v_lshlrev_b32_e32 v21, 16, v45
	v_and_b32_e32 v25, 0xffff0000, v45
	v_add_f32_e32 v26, 1.0, v26
	v_add_f32_e32 v27, 1.0, v27
	v_rcp_f32_e32 v32, v27
	v_mul_f32_e32 v27, 0xbfb8aa3b, v21
	v_exp_f32_e32 v27, v27
	v_mov_b32_e32 v44, v28
	v_mul_f32_e32 v28, 0xbfb8aa3b, v25
	v_rcp_f32_e32 v26, v26
	v_add_f32_e32 v27, 1.0, v27
	v_rcp_f32_e32 v27, v27
	v_exp_f32_e32 v28, v28
	v_mov_b32_e32 v45, v30
	v_pk_mul_f32 v[44:45], v[44:45], v[34:35] op_sel_hi:[1,0]
	v_pk_mul_f32 v[20:21], v[26:27], v[20:21]
	v_add_f32_e32 v26, 1.0, v28
	v_rcp_f32_e32 v33, v26
	v_mov_b32_e32 v30, v29
	v_pk_mul_f32 v[44:45], v[2:3], v[44:45]
	v_pk_mul_f32 v[26:27], v[30:31], v[34:35] op_sel_hi:[1,0]
	v_pk_mul_f32 v[20:21], v[20:21], v[44:45]
	v_pk_mul_f32 v[26:27], v[38:39], v[26:27]
	v_pk_mul_f32 v[24:25], v[32:33], v[24:25]
	s_waitcnt vmcnt(5)
	v_mov_b64_e32 v[30:31], v[14:15]
	v_pk_mul_f32 v[24:25], v[24:25], v[26:27]
	v_cvt_pk_bf16_f32 v21, v21, v25
	v_cvt_pk_bf16_f32 v20, v20, v24
	global_store_dwordx2 v[22:23], v[20:21], off offset:2048
	v_mov_b64_e32 v[22:23], v[6:7]
	v_mov_b64_e32 v[26:27], v[10:11]
	s_waitcnt vmcnt(5)
	v_mov_b64_e32 v[34:35], v[18:19]
	v_lshl_add_u64 v[40:41], v[40:41], 0, s[0:1]
	v_lshl_add_u64 v[46:47], v[46:47], 0, s[4:5]
	v_lshl_add_u64 v[48:49], v[48:49], 0, s[4:5]
	v_lshl_add_u64 v[50:51], v[50:51], 0, s[8:9]
	s_cmp_ge_i32 s20, s3
	v_mov_b64_e32 v[20:21], v[4:5]
	v_mov_b64_e32 v[24:25], v[8:9]
	v_mov_b64_e32 v[28:29], v[12:13]
	v_mov_b64_e32 v[32:33], v[16:17]
	s_waitcnt vmcnt(4)
	v_mov_b64_e32 v[60:61], v[54:55]
	s_waitcnt vmcnt(3)
	v_mov_b64_e32 v[58:59], v[52:53]
	s_waitcnt vmcnt(2)
	v_mov_b64_e32 v[44:45], v[56:57]
	s_cbranch_scc1 .LBB0_4067
